# GEMM main loops: the duplicated s_waitcnt lgkmcnt(0) at the head of each MFMA segment removed (60 sites)
# speedup vs baseline: 1.0006x; 1.0006x over previous
; #define LDA(dst, b, h) for (int m = 0; m < 4; ++m) for (int k = 0; k < 2; ++k) \
;     dst[m][k] = *reinterpret_cast<const bf16x8*>((char*)SA(b, h) + a_thr + (m * 2 + k) * 1024)
; #define LDB(dst, b, h) for (int n = 0; n < 2; ++n) for (int k = 0; k < 2; ++k) \
;     dst[n][k] = *reinterpret_cast<const bf16x8*>((char*)SB(b, h) + b_thr + (n * 2 + k) * 1024)
; #define MMA(ai, bj, At, Btf) do { __builtin_amdgcn_s_setprio(1); \
;     for (int m = 0; m < 4; ++m) for (int n = 0; n < 2; ++n) for (int k = 0; k < 2; ++k) \
;       acc[ai][bj][m][n] = __builtin_amdgcn_mfma_f32_16x16x32_bf16(Btf[n][k], At[m][k], acc[ai][bj][m][n], 0, 0, 0); \
;     __builtin_amdgcn_s_setprio(0); } while (0)
; #define WAIT_V(n) asm volatile("s_waitcnt vmcnt(" #n ")" ::: "memory")
; #define WAIT_L(n) asm volatile("s_waitcnt lgkmcnt(" #n ")" ::: "memory")
; #define BAR __builtin_amdgcn_s_barrier()
; #define SCHED __builtin_amdgcn_sched_barrier(0)
; template <bool OVL, bool PANEL = false, class Epi>
; __device__ __forceinline__ void gemm_phase(const bf16_t* __restrict__ A, long lda, const bf16_t* __restrict__ Bt, long ldb, int nM, int nN, int K,
;                                            const Epi& epi, bf16_t* shm, int w0) {
;     ...
;     if (wr == 1) BAR;
;     WAIT_V(4); BAR;
;     STAGE(SB(1, 0), Bt, ldb, boff, bcol, 1); STAGE(SA(1, 0), A, lda, aoff, brow, 1); STAGE(SB(1, 1), Bt, ldb, boff, bcol + HALF, 1);
;     WAIT_V(6); BAR;
;     for (int t = 0; t < nt - 2; t += 2) {
;       LDB(B0, 0, 0); SCHED; LDA(At, 0, 0); STAGE(SA(1, 1), A, lda, aoff, brow + HALF, t + 1);
;       WAIT_L(8); BAR; WAIT_L(0); MMA(0, 0, At, B0); BAR; SCHED;
;       LDB(B1, 0, 1); STAGE(SB(0, 0), Bt, ldb, boff, bcol, t + 2);
.LBB0_124:
	s_or_b64 exec, exec, s[0:1]
	s_mul_i32 s2, s29, 0xb0000
	v_readlane_b32 s40, v251, 49
	s_lshl_b32 s28, s10, 8
	s_lshl_b64 s[0:1], s[2:3], 1
	v_readlane_b32 s42, v251, 51
	v_readlane_b32 s43, v251, 52
	s_add_u32 s0, s42, s0
	s_addc_u32 s1, s43, s1
	v_mov_b32_e32 v0, v203
	v_add_u32_e32 v130, s96, v202
	s_waitcnt vmcnt(4)
	s_barrier
	v_readlane_b32 s41, v251, 50
	v_readlane_b32 s44, v251, 53
	v_readlane_b32 s45, v251, 54
	v_readlane_b32 s46, v251, 55
	v_readlane_b32 s47, v251, 56
	s_mov_b64 s[6:7], 0x80
	v_lshl_add_u64 v[2:3], s[0:1], 0, v[0:1]
	v_readfirstlane_b32 s2, v130
	v_add_u32_e32 v131, 0x2000, v130
	v_lshl_add_u64 v[4:5], v[2:3], 0, s[6:7]
	s_mov_b32 m0, s2
	v_readfirstlane_b32 s2, v131
	v_readlane_b32 s40, v252, 20
	global_load_lds_dwordx4 v[4:5], off
	s_mov_b32 m0, s2
	s_mul_i32 s2, s10, 0x160000
	v_readlane_b32 s54, v252, 34
	s_mov_b64 s[8:9], 0x58080
	s_mul_hi_i32 s5, s28, 0x1600
	v_readlane_b32 s55, v252, 35
	s_add_u32 s4, s54, s2
	v_lshl_add_u64 v[2:3], v[2:3], 0, s[8:9]
	s_addc_u32 s5, s55, s5
	v_mov_b32_e32 v0, v203
	v_add_u32_e32 v132, 0x8000, v206
	global_load_lds_dwordx4 v[2:3], off
	v_readfirstlane_b32 s2, v132
	v_lshl_add_u64 v[2:3], s[4:5], 0, v[0:1]
	v_add_u32_e32 v133, 0xa000, v206
	v_lshl_add_u64 v[4:5], v[2:3], 0, s[6:7]
	s_mov_b32 m0, s2
	v_readfirstlane_b32 s2, v133
	global_load_lds_dwordx4 v[4:5], off
	v_lshl_add_u64 v[2:3], v[2:3], 0, s[8:9]
	s_mov_b32 m0, s2
	v_mov_b32_e32 v0, v203
	v_add_u32_e32 v134, s75, v202
	global_load_lds_dwordx4 v[2:3], off
	s_mov_b64 s[14:15], 0xb0080
	v_lshl_add_u64 v[2:3], s[0:1], 0, v[0:1]
	v_readfirstlane_b32 s2, v134
	v_add_u32_e32 v135, 0x2000, v134
	v_lshl_add_u64 v[4:5], v[2:3], 0, s[14:15]
	s_mov_b32 m0, s2
	s_mov_b64 s[16:17], 0x108080
	v_readfirstlane_b32 s2, v135
	global_load_lds_dwordx4 v[4:5], off
	v_lshl_add_u64 v[2:3], v[2:3], 0, s[16:17]
	s_mov_b32 m0, s2
	v_readlane_b32 s41, v252, 21
	global_load_lds_dwordx4 v[2:3], off
	s_waitcnt vmcnt(6)
	v_readlane_b32 s42, v252, 22
	v_readlane_b32 s43, v252, 23
	s_mov_b32 s2, -2
	s_mov_b64 s[6:7], 0
	s_waitcnt vmcnt(0)
	s_waitcnt lgkmcnt(0)
	s_mov_b64 s[18:19], 0x58100
	s_mov_b64 s[30:31], 0xb0100
	s_mov_b64 s[40:41], 0x108100
	s_mov_b64 s[42:43], 0x58180
	v_readlane_b32 s44, v252, 24
	v_readlane_b32 s45, v252, 25
	v_readlane_b32 s46, v252, 26
	v_readlane_b32 s47, v252, 27
	v_readlane_b32 s48, v252, 28
	v_readlane_b32 s49, v252, 29
	v_readlane_b32 s50, v252, 30
	v_readlane_b32 s51, v252, 31
	v_readlane_b32 s52, v252, 32
	v_readlane_b32 s53, v252, 33
	s_barrier
	v_add_u32_e32 v218, s21, v212
	v_readfirstlane_b32 s25, v206
	s_add_u32 s25, s25, 0xc000
	v_readfirstlane_b32 s32, v206
	s_add_u32 s32, s32, 0xe000
	v_add_u32_e32 v219, s33, v212
	v_readfirstlane_b32 s44, v204
	v_readfirstlane_b32 s45, v205
	v_readfirstlane_b32 s46, v206
	v_readfirstlane_b32 s47, v207
	v_readfirstlane_b32 s48, v208
	v_readfirstlane_b32 s49, v209
	v_add_u32_e32 v220, s96, v212
	v_readfirstlane_b32 s50, v210
	v_readfirstlane_b32 s51, v211
	v_add_u32_e32 v221, s75, v212
	v_readfirstlane_b32 s52, v130
	v_readfirstlane_b32 s53, v131
	v_readfirstlane_b32 s54, v132
	v_readfirstlane_b32 s55, v133
	v_readfirstlane_b32 s60, v134
	v_readfirstlane_b32 s61, v135
	v_add_u32_e32 v136, 0xc000, v206
	v_add_u32_e32 v137, 0xe000, v206
	ds_read_b128 v[138:141], v218
	ds_read_b128 v[142:145], v218 offset:1024
	ds_read_b128 v[146:149], v218 offset:2048
	ds_read_b128 v[150:153], v218 offset:3072
	s_add_u32 s8, s4, s6
	s_addc_u32 s9, s5, s7
	ds_read_b128 v[154:157], v213
	ds_read_b128 v[158:161], v213 offset:1024
	ds_read_b128 v[162:165], v213 offset:2048
	ds_read_b128 v[166:169], v213 offset:3072
	ds_read_b128 v[170:173], v213 offset:4096
	ds_read_b128 v[174:177], v213 offset:5120
	ds_read_b128 v[178:181], v213 offset:6144
	ds_read_b128 v[182:185], v213 offset:7168
	s_mov_b32 m0, s25
	s_add_u32 s98, s8, s14
	s_addc_u32 s99, s9, s15
	global_load_lds_dwordx4 v203, s[98:99]
	s_mov_b32 m0, s32
	s_add_u32 s98, s8, s16
	s_addc_u32 s99, s9, s17
	global_load_lds_dwordx4 v203, s[98:99]
	s_waitcnt lgkmcnt(8)
	s_waitcnt vmcnt(10)
	s_barrier
	s_waitcnt lgkmcnt(0)
	v_mfma_f32_16x16x32_bf16 v[126:129], v[138:141], v[154:157], 0
	v_mfma_f32_16x16x32_bf16 v[122:125], v[146:149], v[154:157], 0
	v_mfma_f32_16x16x32_bf16 v[118:121], v[138:141], v[162:165], 0
	v_mfma_f32_16x16x32_bf16 v[114:117], v[146:149], v[162:165], 0
	v_mfma_f32_16x16x32_bf16 v[110:113], v[138:141], v[170:173], 0
	v_mfma_f32_16x16x32_bf16 v[106:109], v[146:149], v[170:173], 0
	v_mfma_f32_16x16x32_bf16 v[102:105], v[138:141], v[178:181], 0
	v_mfma_f32_16x16x32_bf16 v[98:101], v[146:149], v[178:181], 0
	v_mfma_f32_16x16x32_bf16 v[126:129], v[142:145], v[158:161], v[126:129]
	v_mfma_f32_16x16x32_bf16 v[122:125], v[150:153], v[158:161], v[122:125]
	v_mfma_f32_16x16x32_bf16 v[118:121], v[142:145], v[166:169], v[118:121]
	v_mfma_f32_16x16x32_bf16 v[114:117], v[150:153], v[166:169], v[114:117]
	v_mfma_f32_16x16x32_bf16 v[110:113], v[142:145], v[174:177], v[110:113]
	v_mfma_f32_16x16x32_bf16 v[106:109], v[150:153], v[174:177], v[106:109]
	v_mfma_f32_16x16x32_bf16 v[102:105], v[142:145], v[182:185], v[102:105]
	v_mfma_f32_16x16x32_bf16 v[98:101], v[150:153], v[182:185], v[98:101]
	s_barrier
	s_add_u32 vcc_lo, s0, s6
	ds_read_b128 v[186:189], v219
	ds_read_b128 v[190:193], v219 offset:1024
	ds_read_b128 v[194:197], v219 offset:2048
	ds_read_b128 v[198:201], v219 offset:3072
	s_addc_u32 vcc_hi, s1, s7
	s_mov_b32 m0, s44
	s_add_u32 s98, vcc_lo, s34
	s_addc_u32 s99, vcc_hi, s35
	global_load_lds_dwordx4 v203, s[98:99]
	s_mov_b32 m0, s45
	s_add_u32 s98, vcc_lo, s18
	s_addc_u32 s99, vcc_hi, s19
	global_load_lds_dwordx4 v203, s[98:99]
	s_waitcnt vmcnt(10)
	s_barrier
; #define LDA(dst, b, h) for (int m = 0; m < 4; ++m) for (int k = 0; k < 2; ++k) \
;     dst[m][k] = *reinterpret_cast<const bf16x8*>((char*)SA(b, h) + a_thr + (m * 2 + k) * 1024)
; #define LDB(dst, b, h) for (int n = 0; n < 2; ++n) for (int k = 0; k < 2; ++k) \
;     dst[n][k] = *reinterpret_cast<const bf16x8*>((char*)SB(b, h) + b_thr + (n * 2 + k) * 1024)
; #define MMA(ai, bj, At, Btf) do { __builtin_amdgcn_s_setprio(1); \
;     for (int m = 0; m < 4; ++m) for (int n = 0; n < 2; ++n) for (int k = 0; k < 2; ++k) \
;       acc[ai][bj][m][n] = __builtin_amdgcn_mfma_f32_16x16x32_bf16(Btf[n][k], At[m][k], acc[ai][bj][m][n], 0, 0, 0); \
;     __builtin_amdgcn_s_setprio(0); } while (0)
; #define WAIT_V(n) asm volatile("s_waitcnt vmcnt(" #n ")" ::: "memory")
; #define WAIT_L(n) asm volatile("s_waitcnt lgkmcnt(" #n ")" ::: "memory")
; #define BAR __builtin_amdgcn_s_barrier()
; #define SCHED __builtin_amdgcn_sched_barrier(0)
; template <bool OVL, bool PANEL = false, class Epi>
; __device__ __forceinline__ void gemm_phase(const bf16_t* __restrict__ A, long lda, const bf16_t* __restrict__ Bt, long ldb, int nM, int nN, int K,
;                                            const Epi& epi, bf16_t* shm, int w0) {
;     ...
;       LDB(B1, 0, 1); STAGE(SB(0, 0), Bt, ldb, boff, bcol, t + 2);
;       BAR; WAIT_L(0); MMA(0, 1, At, B1); BAR;
;       LDA(At, 0, 1); STAGE(SA(0, 0), A, lda, aoff, brow, t + 2);
;       BAR; WAIT_L(0); MMA(1, 0, At, B0); BAR; SCHED;
;       STAGE(SB(0, 1), Bt, ldb, boff, bcol + HALF, t + 2);
;       WAIT_V(6); BAR; MMA(1, 1, At, B1); BAR;
;       LDB(B0, 1, 0); SCHED; LDA(At, 1, 0); STAGE(SA(0, 1), A, lda, aoff, brow + HALF, t + 2);
;       WAIT_L(8); BAR; WAIT_L(0); MMA(0, 0, At, B0); BAR; SCHED;
	s_waitcnt lgkmcnt(0)
	v_mfma_f32_16x16x32_bf16 v[94:97], v[186:189], v[154:157], 0
	v_mfma_f32_16x16x32_bf16 v[90:93], v[194:197], v[154:157], 0
	v_mfma_f32_16x16x32_bf16 v[86:89], v[186:189], v[162:165], 0
	v_mfma_f32_16x16x32_bf16 v[82:85], v[194:197], v[162:165], 0
	v_mfma_f32_16x16x32_bf16 v[78:81], v[186:189], v[170:173], 0
	v_mfma_f32_16x16x32_bf16 v[74:77], v[194:197], v[170:173], 0
	v_mfma_f32_16x16x32_bf16 v[70:73], v[186:189], v[178:181], 0
	v_mfma_f32_16x16x32_bf16 v[66:69], v[194:197], v[178:181], 0
	v_mfma_f32_16x16x32_bf16 v[94:97], v[190:193], v[158:161], v[94:97]
	v_mfma_f32_16x16x32_bf16 v[90:93], v[198:201], v[158:161], v[90:93]
	v_mfma_f32_16x16x32_bf16 v[86:89], v[190:193], v[166:169], v[86:89]
	v_mfma_f32_16x16x32_bf16 v[82:85], v[198:201], v[166:169], v[82:85]
	v_mfma_f32_16x16x32_bf16 v[78:81], v[190:193], v[174:177], v[78:81]
	v_mfma_f32_16x16x32_bf16 v[74:77], v[198:201], v[174:177], v[74:77]
	v_mfma_f32_16x16x32_bf16 v[70:73], v[190:193], v[182:185], v[70:73]
	v_mfma_f32_16x16x32_bf16 v[66:69], v[198:201], v[182:185], v[66:69]
	s_barrier
	ds_read_b128 v[154:157], v213 offset:16384
	ds_read_b128 v[158:161], v213 offset:17408
	ds_read_b128 v[162:165], v213 offset:18432
	ds_read_b128 v[166:169], v213 offset:19456
	ds_read_b128 v[170:173], v213 offset:20480
	ds_read_b128 v[174:177], v213 offset:21504
	ds_read_b128 v[178:181], v213 offset:22528
	ds_read_b128 v[182:185], v213 offset:23552
	s_mov_b32 m0, s46
	s_add_u32 s98, s8, s34
	s_addc_u32 s99, s9, s35
	global_load_lds_dwordx4 v203, s[98:99]
	s_mov_b32 m0, s47
	s_add_u32 s98, s8, s18
	s_addc_u32 s99, s9, s19
	global_load_lds_dwordx4 v203, s[98:99]
	s_barrier
	s_waitcnt lgkmcnt(0)
	v_mfma_f32_16x16x32_bf16 v[62:65], v[138:141], v[154:157], 0
	v_mfma_f32_16x16x32_bf16 v[58:61], v[146:149], v[154:157], 0
	v_mfma_f32_16x16x32_bf16 v[54:57], v[138:141], v[162:165], 0
	v_mfma_f32_16x16x32_bf16 v[50:53], v[146:149], v[162:165], 0
	v_mfma_f32_16x16x32_bf16 v[46:49], v[138:141], v[170:173], 0
	v_mfma_f32_16x16x32_bf16 v[42:45], v[146:149], v[170:173], 0
	v_mfma_f32_16x16x32_bf16 v[38:41], v[138:141], v[178:181], 0
	v_mfma_f32_16x16x32_bf16 v[34:37], v[146:149], v[178:181], 0
	v_mfma_f32_16x16x32_bf16 v[62:65], v[142:145], v[158:161], v[62:65]
	v_mfma_f32_16x16x32_bf16 v[58:61], v[150:153], v[158:161], v[58:61]
	v_mfma_f32_16x16x32_bf16 v[54:57], v[142:145], v[166:169], v[54:57]
	v_mfma_f32_16x16x32_bf16 v[50:53], v[150:153], v[166:169], v[50:53]
	v_mfma_f32_16x16x32_bf16 v[46:49], v[142:145], v[174:177], v[46:49]
	v_mfma_f32_16x16x32_bf16 v[42:45], v[150:153], v[174:177], v[42:45]
	v_mfma_f32_16x16x32_bf16 v[38:41], v[142:145], v[182:185], v[38:41]
	v_mfma_f32_16x16x32_bf16 v[34:37], v[150:153], v[182:185], v[34:37]
	s_barrier
	s_mov_b32 m0, s48
	s_add_u32 s98, vcc_lo, s30
	s_addc_u32 s99, vcc_hi, s31
	global_load_lds_dwordx4 v203, s[98:99]
	s_mov_b32 m0, s49
	s_add_u32 s98, vcc_lo, s40
	s_addc_u32 s99, vcc_hi, s41
	global_load_lds_dwordx4 v203, s[98:99]
	s_waitcnt vmcnt(10)
	s_barrier
	v_mfma_f32_16x16x32_bf16 v[30:33], v[186:189], v[154:157], 0
	v_mfma_f32_16x16x32_bf16 v[26:29], v[194:197], v[154:157], 0
	v_mfma_f32_16x16x32_bf16 v[22:25], v[186:189], v[162:165], 0
	v_mfma_f32_16x16x32_bf16 v[18:21], v[194:197], v[162:165], 0
	v_mfma_f32_16x16x32_bf16 v[14:17], v[186:189], v[170:173], 0
	v_mfma_f32_16x16x32_bf16 v[10:13], v[194:197], v[170:173], 0
	v_mfma_f32_16x16x32_bf16 v[6:9], v[186:189], v[178:181], 0
	v_mfma_f32_16x16x32_bf16 v[2:5], v[194:197], v[178:181], 0
	v_mfma_f32_16x16x32_bf16 v[30:33], v[190:193], v[158:161], v[30:33]
	v_mfma_f32_16x16x32_bf16 v[26:29], v[198:201], v[158:161], v[26:29]
	v_mfma_f32_16x16x32_bf16 v[22:25], v[190:193], v[166:169], v[22:25]
	v_mfma_f32_16x16x32_bf16 v[18:21], v[198:201], v[166:169], v[18:21]
	v_mfma_f32_16x16x32_bf16 v[14:17], v[190:193], v[174:177], v[14:17]
	v_mfma_f32_16x16x32_bf16 v[10:13], v[198:201], v[174:177], v[10:13]
	v_mfma_f32_16x16x32_bf16 v[6:9], v[190:193], v[182:185], v[6:9]
	v_mfma_f32_16x16x32_bf16 v[2:5], v[198:201], v[182:185], v[2:5]
	s_barrier
	ds_read_b128 v[138:141], v220
	ds_read_b128 v[142:145], v220 offset:1024
	ds_read_b128 v[146:149], v220 offset:2048
	ds_read_b128 v[150:153], v220 offset:3072
	ds_read_b128 v[154:157], v213 offset:32768
	ds_read_b128 v[158:161], v213 offset:33792
	ds_read_b128 v[162:165], v213 offset:34816
	ds_read_b128 v[166:169], v213 offset:35840
	ds_read_b128 v[170:173], v213 offset:36864
	ds_read_b128 v[174:177], v213 offset:37888
	ds_read_b128 v[178:181], v213 offset:38912
	ds_read_b128 v[182:185], v213 offset:39936
	s_mov_b32 m0, s50
	s_add_u32 s98, s8, s30
	s_addc_u32 s99, s9, s31
	global_load_lds_dwordx4 v203, s[98:99]
	s_mov_b32 m0, s51
	s_add_u32 s98, s8, s40
	s_addc_u32 s99, s9, s41
	global_load_lds_dwordx4 v203, s[98:99]
	s_waitcnt lgkmcnt(8)
	s_waitcnt vmcnt(10)
	s_barrier
	s_waitcnt lgkmcnt(0)
	v_mfma_f32_16x16x32_bf16 v[126:129], v[138:141], v[154:157], v[126:129]
	v_mfma_f32_16x16x32_bf16 v[122:125], v[146:149], v[154:157], v[122:125]
	v_mfma_f32_16x16x32_bf16 v[118:121], v[138:141], v[162:165], v[118:121]
	v_mfma_f32_16x16x32_bf16 v[114:117], v[146:149], v[162:165], v[114:117]
	v_mfma_f32_16x16x32_bf16 v[110:113], v[138:141], v[170:173], v[110:113]
	v_mfma_f32_16x16x32_bf16 v[106:109], v[146:149], v[170:173], v[106:109]
	v_mfma_f32_16x16x32_bf16 v[102:105], v[138:141], v[178:181], v[102:105]
	v_mfma_f32_16x16x32_bf16 v[98:101], v[146:149], v[178:181], v[98:101]
	v_mfma_f32_16x16x32_bf16 v[126:129], v[142:145], v[158:161], v[126:129]
	v_mfma_f32_16x16x32_bf16 v[122:125], v[150:153], v[158:161], v[122:125]
	v_mfma_f32_16x16x32_bf16 v[118:121], v[142:145], v[166:169], v[118:121]
	v_mfma_f32_16x16x32_bf16 v[114:117], v[150:153], v[166:169], v[114:117]
	v_mfma_f32_16x16x32_bf16 v[110:113], v[142:145], v[174:177], v[110:113]
	v_mfma_f32_16x16x32_bf16 v[106:109], v[150:153], v[174:177], v[106:109]
	v_mfma_f32_16x16x32_bf16 v[102:105], v[142:145], v[182:185], v[102:105]
	v_mfma_f32_16x16x32_bf16 v[98:101], v[150:153], v[182:185], v[98:101]
	s_barrier
; #define LDA(dst, b, h) for (int m = 0; m < 4; ++m) for (int k = 0; k < 2; ++k) \
;     dst[m][k] = *reinterpret_cast<const bf16x8*>((char*)SA(b, h) + a_thr + (m * 2 + k) * 1024)
; #define LDB(dst, b, h) for (int n = 0; n < 2; ++n) for (int k = 0; k < 2; ++k) \
;     dst[n][k] = *reinterpret_cast<const bf16x8*>((char*)SB(b, h) + b_thr + (n * 2 + k) * 1024)
; #define MMA(ai, bj, At, Btf) do { __builtin_amdgcn_s_setprio(1); \
;     for (int m = 0; m < 4; ++m) for (int n = 0; n < 2; ++n) for (int k = 0; k < 2; ++k) \
;       acc[ai][bj][m][n] = __builtin_amdgcn_mfma_f32_16x16x32_bf16(Btf[n][k], At[m][k], acc[ai][bj][m][n], 0, 0, 0); \
;     __builtin_amdgcn_s_setprio(0); } while (0)
; #define WAIT_V(n) asm volatile("s_waitcnt vmcnt(" #n ")" ::: "memory")
; #define WAIT_L(n) asm volatile("s_waitcnt lgkmcnt(" #n ")" ::: "memory")
; #define BAR __builtin_amdgcn_s_barrier()
; #define SCHED __builtin_amdgcn_sched_barrier(0)
; template <bool OVL, bool PANEL = false, class Epi>
; __device__ __forceinline__ void gemm_phase(const bf16_t* __restrict__ A, long lda, const bf16_t* __restrict__ Bt, long ldb, int nM, int nN, int K,
;                                            const Epi& epi, bf16_t* shm, int w0) {
;     ...
;       LDB(B1, 1, 1); STAGE(SB(1, 0), Bt, ldb, boff, bcol, t + 3);
;       BAR; WAIT_L(0); MMA(0, 1, At, B1); BAR;
;       LDA(At, 1, 1); STAGE(SA(1, 0), A, lda, aoff, brow, t + 3);
;       BAR; WAIT_L(0); MMA(1, 0, At, B0); BAR; SCHED;
;       STAGE(SB(1, 1), Bt, ldb, boff, bcol + HALF, t + 3);
;       WAIT_V(6); BAR; MMA(1, 1, At, B1); BAR;
	ds_read_b128 v[186:189], v221
	ds_read_b128 v[190:193], v221 offset:1024
	ds_read_b128 v[194:197], v221 offset:2048
	ds_read_b128 v[198:201], v221 offset:3072
	s_mov_b32 m0, s52
	s_add_u32 s98, vcc_lo, s94
	s_addc_u32 s99, vcc_hi, s95
	global_load_lds_dwordx4 v203, s[98:99]
	s_mov_b32 m0, s53
	s_add_u32 s98, vcc_lo, s42
	s_addc_u32 s99, vcc_hi, s43
	global_load_lds_dwordx4 v203, s[98:99]
	s_waitcnt vmcnt(10)
	s_barrier
	s_waitcnt lgkmcnt(0)
	v_mfma_f32_16x16x32_bf16 v[94:97], v[186:189], v[154:157], v[94:97]
	v_mfma_f32_16x16x32_bf16 v[90:93], v[194:197], v[154:157], v[90:93]
	v_mfma_f32_16x16x32_bf16 v[86:89], v[186:189], v[162:165], v[86:89]
	v_mfma_f32_16x16x32_bf16 v[82:85], v[194:197], v[162:165], v[82:85]
	v_mfma_f32_16x16x32_bf16 v[78:81], v[186:189], v[170:173], v[78:81]
	v_mfma_f32_16x16x32_bf16 v[74:77], v[194:197], v[170:173], v[74:77]
	v_mfma_f32_16x16x32_bf16 v[70:73], v[186:189], v[178:181], v[70:73]
	v_mfma_f32_16x16x32_bf16 v[66:69], v[194:197], v[178:181], v[66:69]
	v_mfma_f32_16x16x32_bf16 v[94:97], v[190:193], v[158:161], v[94:97]
	v_mfma_f32_16x16x32_bf16 v[90:93], v[198:201], v[158:161], v[90:93]
	v_mfma_f32_16x16x32_bf16 v[86:89], v[190:193], v[166:169], v[86:89]
	v_mfma_f32_16x16x32_bf16 v[82:85], v[198:201], v[166:169], v[82:85]
	v_mfma_f32_16x16x32_bf16 v[78:81], v[190:193], v[174:177], v[78:81]
	v_mfma_f32_16x16x32_bf16 v[74:77], v[198:201], v[174:177], v[74:77]
	v_mfma_f32_16x16x32_bf16 v[70:73], v[190:193], v[182:185], v[70:73]
	v_mfma_f32_16x16x32_bf16 v[66:69], v[198:201], v[182:185], v[66:69]
	s_barrier
	ds_read_b128 v[154:157], v213 offset:49152
	ds_read_b128 v[158:161], v213 offset:50176
	ds_read_b128 v[162:165], v213 offset:51200
	ds_read_b128 v[166:169], v213 offset:52224
	ds_read_b128 v[170:173], v213 offset:53248
	ds_read_b128 v[174:177], v213 offset:54272
	ds_read_b128 v[178:181], v213 offset:55296
	ds_read_b128 v[182:185], v213 offset:56320
	s_mov_b32 m0, s54
	s_add_u32 s98, s8, s94
	s_addc_u32 s99, s9, s95
	global_load_lds_dwordx4 v203, s[98:99]
	s_mov_b32 m0, s55
	s_add_u32 s98, s8, s42
	s_addc_u32 s99, s9, s43
	global_load_lds_dwordx4 v203, s[98:99]
	s_barrier
	s_waitcnt lgkmcnt(0)
	v_mfma_f32_16x16x32_bf16 v[62:65], v[138:141], v[154:157], v[62:65]
	v_mfma_f32_16x16x32_bf16 v[58:61], v[146:149], v[154:157], v[58:61]
	v_mfma_f32_16x16x32_bf16 v[54:57], v[138:141], v[162:165], v[54:57]
	v_mfma_f32_16x16x32_bf16 v[50:53], v[146:149], v[162:165], v[50:53]
	v_mfma_f32_16x16x32_bf16 v[46:49], v[138:141], v[170:173], v[46:49]
	v_mfma_f32_16x16x32_bf16 v[42:45], v[146:149], v[170:173], v[42:45]
	v_mfma_f32_16x16x32_bf16 v[38:41], v[138:141], v[178:181], v[38:41]
	v_mfma_f32_16x16x32_bf16 v[34:37], v[146:149], v[178:181], v[34:37]
	v_mfma_f32_16x16x32_bf16 v[62:65], v[142:145], v[158:161], v[62:65]
	v_mfma_f32_16x16x32_bf16 v[58:61], v[150:153], v[158:161], v[58:61]
	v_mfma_f32_16x16x32_bf16 v[54:57], v[142:145], v[166:169], v[54:57]
	v_mfma_f32_16x16x32_bf16 v[50:53], v[150:153], v[166:169], v[50:53]
	v_mfma_f32_16x16x32_bf16 v[46:49], v[142:145], v[174:177], v[46:49]
	v_mfma_f32_16x16x32_bf16 v[42:45], v[150:153], v[174:177], v[42:45]
	v_mfma_f32_16x16x32_bf16 v[38:41], v[142:145], v[182:185], v[38:41]
	v_mfma_f32_16x16x32_bf16 v[34:37], v[150:153], v[182:185], v[34:37]
	s_barrier
	s_mov_b64 s[8:9], 0xb0180
	s_mov_b64 s[8:9], 0x108180
	s_mov_b32 m0, s60
	s_add_u32 s98, vcc_lo, 0xb0180
	s_addc_u32 s99, vcc_hi, 0
	global_load_lds_dwordx4 v203, s[98:99]
	s_mov_b32 m0, s61
	s_add_u32 s98, vcc_lo, 0x108180
	s_addc_u32 s99, vcc_hi, 0
	global_load_lds_dwordx4 v203, s[98:99]
	s_add_i32 s2, s2, 2
	s_add_u32 s6, s6, 0x100
	s_addc_u32 s7, s7, 0
	s_cmp_gt_u32 s2, 39
	s_waitcnt vmcnt(10)
	s_barrier
	v_mfma_f32_16x16x32_bf16 v[30:33], v[186:189], v[154:157], v[30:33]
	v_mfma_f32_16x16x32_bf16 v[26:29], v[194:197], v[154:157], v[26:29]
	v_mfma_f32_16x16x32_bf16 v[22:25], v[186:189], v[162:165], v[22:25]
	v_mfma_f32_16x16x32_bf16 v[18:21], v[194:197], v[162:165], v[18:21]
	v_mfma_f32_16x16x32_bf16 v[14:17], v[186:189], v[170:173], v[14:17]
	v_mfma_f32_16x16x32_bf16 v[10:13], v[194:197], v[170:173], v[10:13]
	v_mfma_f32_16x16x32_bf16 v[6:9], v[186:189], v[178:181], v[6:9]
	v_mfma_f32_16x16x32_bf16 v[2:5], v[194:197], v[178:181], v[2:5]
	v_mfma_f32_16x16x32_bf16 v[30:33], v[190:193], v[158:161], v[30:33]
	v_mfma_f32_16x16x32_bf16 v[26:29], v[198:201], v[158:161], v[26:29]
	v_mfma_f32_16x16x32_bf16 v[22:25], v[190:193], v[166:169], v[22:25]
	v_mfma_f32_16x16x32_bf16 v[18:21], v[198:201], v[166:169], v[18:21]
	v_mfma_f32_16x16x32_bf16 v[14:17], v[190:193], v[174:177], v[14:17]
	v_mfma_f32_16x16x32_bf16 v[10:13], v[198:201], v[174:177], v[10:13]
	v_mfma_f32_16x16x32_bf16 v[6:9], v[190:193], v[182:185], v[6:9]
	v_mfma_f32_16x16x32_bf16 v[2:5], v[198:201], v[182:185], v[2:5]
	s_barrier
; #define LDA(dst, b, h) for (int m = 0; m < 4; ++m) for (int k = 0; k < 2; ++k) \
;     dst[m][k] = *reinterpret_cast<const bf16x8*>((char*)SA(b, h) + a_thr + (m * 2 + k) * 1024)
; #define LDB(dst, b, h) for (int n = 0; n < 2; ++n) for (int k = 0; k < 2; ++k) \
;     dst[n][k] = *reinterpret_cast<const bf16x8*>((char*)SB(b, h) + b_thr + (n * 2 + k) * 1024)
; #define MMA(ai, bj, At, Btf) do { __builtin_amdgcn_s_setprio(1); \
;     for (int m = 0; m < 4; ++m) for (int n = 0; n < 2; ++n) for (int k = 0; k < 2; ++k) \
;       acc[ai][bj][m][n] = __builtin_amdgcn_mfma_f32_16x16x32_bf16(Btf[n][k], At[m][k], acc[ai][bj][m][n], 0, 0, 0); \
;     __builtin_amdgcn_s_setprio(0); } while (0)
; #define WAIT_L(n) asm volatile("s_waitcnt lgkmcnt(" #n ")" ::: "memory")
; #define BAR __builtin_amdgcn_s_barrier()
; #define SCHED __builtin_amdgcn_sched_barrier(0)
; template <bool OVL, bool PANEL = false, class Epi>
; __device__ __forceinline__ void gemm_phase(const bf16_t* __restrict__ A, long lda, const bf16_t* __restrict__ Bt, long ldb, int nM, int nN, int K,
;                                            const Epi& epi, bf16_t* shm, int w0) {
;     ...
;       LDB(B0, 0, 0); SCHED; LDA(At, 0, 0); STAGE(SA(1, 1), A, lda, aoff, brow + HALF, t + 1);
;       WAIT_L(8); BAR; WAIT_L(0); MMA(0, 0, At, B0); BAR; SCHED;
;       LDB(B1, 0, 1); STAGE(SB(0, 0), Bt, ldb, boff, bcol, t + 2);
;       BAR; WAIT_L(0); MMA(0, 1, At, B1); BAR;
;       LDA(At, 0, 1); STAGE(SA(0, 0), A, lda, aoff, brow, t + 2);
;       BAR; WAIT_L(0); MMA(1, 0, At, B0); BAR; SCHED;
;       STAGE(SB(0, 1), Bt, ldb, boff, bcol + HALF, t + 2);
.LBB0_125:
	ds_read_b128 v[138:141], v218
	ds_read_b128 v[142:145], v218 offset:1024
	ds_read_b128 v[146:149], v218 offset:2048
	ds_read_b128 v[150:153], v218 offset:3072
	s_add_u32 s8, s4, s6
	s_addc_u32 s9, s5, s7
	ds_read_b128 v[154:157], v213
	ds_read_b128 v[158:161], v213 offset:1024
	ds_read_b128 v[162:165], v213 offset:2048
	ds_read_b128 v[166:169], v213 offset:3072
	ds_read_b128 v[170:173], v213 offset:4096
	ds_read_b128 v[174:177], v213 offset:5120
	ds_read_b128 v[178:181], v213 offset:6144
	ds_read_b128 v[182:185], v213 offset:7168
	s_mov_b32 m0, s25
	s_add_u32 s98, s8, s14
	s_addc_u32 s99, s9, s15
	global_load_lds_dwordx4 v203, s[98:99]
	s_mov_b32 m0, s32
	s_add_u32 s98, s8, s16
	s_addc_u32 s99, s9, s17
	global_load_lds_dwordx4 v203, s[98:99]
	s_waitcnt lgkmcnt(8)
	s_waitcnt vmcnt(10)
	s_barrier
	s_waitcnt lgkmcnt(0)
	v_mfma_f32_16x16x32_bf16 v[126:129], v[138:141], v[154:157], v[126:129]
	v_mfma_f32_16x16x32_bf16 v[122:125], v[146:149], v[154:157], v[122:125]
	v_mfma_f32_16x16x32_bf16 v[118:121], v[138:141], v[162:165], v[118:121]
	v_mfma_f32_16x16x32_bf16 v[114:117], v[146:149], v[162:165], v[114:117]
	v_mfma_f32_16x16x32_bf16 v[110:113], v[138:141], v[170:173], v[110:113]
	v_mfma_f32_16x16x32_bf16 v[106:109], v[146:149], v[170:173], v[106:109]
	v_mfma_f32_16x16x32_bf16 v[102:105], v[138:141], v[178:181], v[102:105]
	v_mfma_f32_16x16x32_bf16 v[98:101], v[146:149], v[178:181], v[98:101]
	v_mfma_f32_16x16x32_bf16 v[126:129], v[142:145], v[158:161], v[126:129]
	v_mfma_f32_16x16x32_bf16 v[122:125], v[150:153], v[158:161], v[122:125]
	v_mfma_f32_16x16x32_bf16 v[118:121], v[142:145], v[166:169], v[118:121]
	v_mfma_f32_16x16x32_bf16 v[114:117], v[150:153], v[166:169], v[114:117]
	v_mfma_f32_16x16x32_bf16 v[110:113], v[142:145], v[174:177], v[110:113]
	v_mfma_f32_16x16x32_bf16 v[106:109], v[150:153], v[174:177], v[106:109]
	v_mfma_f32_16x16x32_bf16 v[102:105], v[142:145], v[182:185], v[102:105]
	v_mfma_f32_16x16x32_bf16 v[98:101], v[150:153], v[182:185], v[98:101]
	s_barrier
	s_add_u32 vcc_lo, s0, s6
	ds_read_b128 v[186:189], v219
	ds_read_b128 v[190:193], v219 offset:1024
	ds_read_b128 v[194:197], v219 offset:2048
	ds_read_b128 v[198:201], v219 offset:3072
	s_addc_u32 vcc_hi, s1, s7
	s_mov_b32 m0, s44
	s_add_u32 s98, vcc_lo, s34
	s_addc_u32 s99, vcc_hi, s35
	global_load_lds_dwordx4 v203, s[98:99]
	s_mov_b32 m0, s45
	s_add_u32 s98, vcc_lo, s18
	s_addc_u32 s99, vcc_hi, s19
	global_load_lds_dwordx4 v203, s[98:99]
	s_waitcnt vmcnt(10)
	s_barrier
	s_waitcnt lgkmcnt(0)
	v_mfma_f32_16x16x32_bf16 v[94:97], v[186:189], v[154:157], v[94:97]
	v_mfma_f32_16x16x32_bf16 v[90:93], v[194:197], v[154:157], v[90:93]
	v_mfma_f32_16x16x32_bf16 v[86:89], v[186:189], v[162:165], v[86:89]
	v_mfma_f32_16x16x32_bf16 v[82:85], v[194:197], v[162:165], v[82:85]
	v_mfma_f32_16x16x32_bf16 v[78:81], v[186:189], v[170:173], v[78:81]
	v_mfma_f32_16x16x32_bf16 v[74:77], v[194:197], v[170:173], v[74:77]
	v_mfma_f32_16x16x32_bf16 v[70:73], v[186:189], v[178:181], v[70:73]
	v_mfma_f32_16x16x32_bf16 v[66:69], v[194:197], v[178:181], v[66:69]
	v_mfma_f32_16x16x32_bf16 v[94:97], v[190:193], v[158:161], v[94:97]
	v_mfma_f32_16x16x32_bf16 v[90:93], v[198:201], v[158:161], v[90:93]
	v_mfma_f32_16x16x32_bf16 v[86:89], v[190:193], v[166:169], v[86:89]
	v_mfma_f32_16x16x32_bf16 v[82:85], v[198:201], v[166:169], v[82:85]
	v_mfma_f32_16x16x32_bf16 v[78:81], v[190:193], v[174:177], v[78:81]
	v_mfma_f32_16x16x32_bf16 v[74:77], v[198:201], v[174:177], v[74:77]
	v_mfma_f32_16x16x32_bf16 v[70:73], v[190:193], v[182:185], v[70:73]
	v_mfma_f32_16x16x32_bf16 v[66:69], v[198:201], v[182:185], v[66:69]
	s_barrier
	ds_read_b128 v[154:157], v213 offset:16384
	ds_read_b128 v[158:161], v213 offset:17408
	ds_read_b128 v[162:165], v213 offset:18432
	ds_read_b128 v[166:169], v213 offset:19456
	ds_read_b128 v[170:173], v213 offset:20480
	ds_read_b128 v[174:177], v213 offset:21504
	ds_read_b128 v[178:181], v213 offset:22528
	ds_read_b128 v[182:185], v213 offset:23552
	s_mov_b32 m0, s46
	s_add_u32 s98, s8, s34
	s_addc_u32 s99, s9, s35
	global_load_lds_dwordx4 v203, s[98:99]
	s_mov_b32 m0, s47
	s_add_u32 s98, s8, s18
	s_addc_u32 s99, s9, s19
	global_load_lds_dwordx4 v203, s[98:99]
	s_barrier
	s_waitcnt lgkmcnt(0)
	v_mfma_f32_16x16x32_bf16 v[62:65], v[138:141], v[154:157], v[62:65]
	v_mfma_f32_16x16x32_bf16 v[58:61], v[146:149], v[154:157], v[58:61]
	v_mfma_f32_16x16x32_bf16 v[54:57], v[138:141], v[162:165], v[54:57]
	v_mfma_f32_16x16x32_bf16 v[50:53], v[146:149], v[162:165], v[50:53]
	v_mfma_f32_16x16x32_bf16 v[46:49], v[138:141], v[170:173], v[46:49]
	v_mfma_f32_16x16x32_bf16 v[42:45], v[146:149], v[170:173], v[42:45]
	v_mfma_f32_16x16x32_bf16 v[38:41], v[138:141], v[178:181], v[38:41]
	v_mfma_f32_16x16x32_bf16 v[34:37], v[146:149], v[178:181], v[34:37]
	v_mfma_f32_16x16x32_bf16 v[62:65], v[142:145], v[158:161], v[62:65]
	v_mfma_f32_16x16x32_bf16 v[58:61], v[150:153], v[158:161], v[58:61]
	v_mfma_f32_16x16x32_bf16 v[54:57], v[142:145], v[166:169], v[54:57]
	v_mfma_f32_16x16x32_bf16 v[50:53], v[150:153], v[166:169], v[50:53]
	v_mfma_f32_16x16x32_bf16 v[46:49], v[142:145], v[174:177], v[46:49]
	v_mfma_f32_16x16x32_bf16 v[42:45], v[150:153], v[174:177], v[42:45]
	v_mfma_f32_16x16x32_bf16 v[38:41], v[142:145], v[182:185], v[38:41]
	v_mfma_f32_16x16x32_bf16 v[34:37], v[150:153], v[182:185], v[34:37]
	s_barrier
	s_mov_b32 m0, s48
	s_add_u32 s98, vcc_lo, s30
	s_addc_u32 s99, vcc_hi, s31
	global_load_lds_dwordx4 v203, s[98:99]
	s_mov_b32 m0, s49
	s_add_u32 s98, vcc_lo, s40
	s_addc_u32 s99, vcc_hi, s41
	global_load_lds_dwordx4 v203, s[98:99]
	s_waitcnt vmcnt(10)
	s_barrier
; #define LDA(dst, b, h) for (int m = 0; m < 4; ++m) for (int k = 0; k < 2; ++k) \
;     dst[m][k] = *reinterpret_cast<const bf16x8*>((char*)SA(b, h) + a_thr + (m * 2 + k) * 1024)
; #define LDB(dst, b, h) for (int n = 0; n < 2; ++n) for (int k = 0; k < 2; ++k) \
;     dst[n][k] = *reinterpret_cast<const bf16x8*>((char*)SB(b, h) + b_thr + (n * 2 + k) * 1024)
; #define MMA(ai, bj, At, Btf) do { __builtin_amdgcn_s_setprio(1); \
;     for (int m = 0; m < 4; ++m) for (int n = 0; n < 2; ++n) for (int k = 0; k < 2; ++k) \
;       acc[ai][bj][m][n] = __builtin_amdgcn_mfma_f32_16x16x32_bf16(Btf[n][k], At[m][k], acc[ai][bj][m][n], 0, 0, 0); \
;     __builtin_amdgcn_s_setprio(0); } while (0)
; #define WAIT_V(n) asm volatile("s_waitcnt vmcnt(" #n ")" ::: "memory")
; #define WAIT_L(n) asm volatile("s_waitcnt lgkmcnt(" #n ")" ::: "memory")
; #define BAR __builtin_amdgcn_s_barrier()
; #define SCHED __builtin_amdgcn_sched_barrier(0)
; template <bool OVL, bool PANEL = false, class Epi>
; __device__ __forceinline__ void gemm_phase(const bf16_t* __restrict__ A, long lda, const bf16_t* __restrict__ Bt, long ldb, int nM, int nN, int K,
;                                            const Epi& epi, bf16_t* shm, int w0) {
;     ...
;       WAIT_V(6); BAR; MMA(1, 1, At, B1); BAR;
;       LDB(B0, 1, 0); SCHED; LDA(At, 1, 0); STAGE(SA(0, 1), A, lda, aoff, brow + HALF, t + 2);
;       WAIT_L(8); BAR; WAIT_L(0); MMA(0, 0, At, B0); BAR; SCHED;
;       LDB(B1, 1, 1); STAGE(SB(1, 0), Bt, ldb, boff, bcol, t + 3);
;       BAR; WAIT_L(0); MMA(0, 1, At, B1); BAR;
	v_mfma_f32_16x16x32_bf16 v[30:33], v[186:189], v[154:157], v[30:33]
	v_mfma_f32_16x16x32_bf16 v[26:29], v[194:197], v[154:157], v[26:29]
	v_mfma_f32_16x16x32_bf16 v[22:25], v[186:189], v[162:165], v[22:25]
	v_mfma_f32_16x16x32_bf16 v[18:21], v[194:197], v[162:165], v[18:21]
	v_mfma_f32_16x16x32_bf16 v[14:17], v[186:189], v[170:173], v[14:17]
	v_mfma_f32_16x16x32_bf16 v[10:13], v[194:197], v[170:173], v[10:13]
	v_mfma_f32_16x16x32_bf16 v[6:9], v[186:189], v[178:181], v[6:9]
	v_mfma_f32_16x16x32_bf16 v[2:5], v[194:197], v[178:181], v[2:5]
	v_mfma_f32_16x16x32_bf16 v[30:33], v[190:193], v[158:161], v[30:33]
	v_mfma_f32_16x16x32_bf16 v[26:29], v[198:201], v[158:161], v[26:29]
	v_mfma_f32_16x16x32_bf16 v[22:25], v[190:193], v[166:169], v[22:25]
	v_mfma_f32_16x16x32_bf16 v[18:21], v[198:201], v[166:169], v[18:21]
	v_mfma_f32_16x16x32_bf16 v[14:17], v[190:193], v[174:177], v[14:17]
	v_mfma_f32_16x16x32_bf16 v[10:13], v[198:201], v[174:177], v[10:13]
	v_mfma_f32_16x16x32_bf16 v[6:9], v[190:193], v[182:185], v[6:9]
	v_mfma_f32_16x16x32_bf16 v[2:5], v[198:201], v[182:185], v[2:5]
	s_barrier
	ds_read_b128 v[138:141], v220
	ds_read_b128 v[142:145], v220 offset:1024
	ds_read_b128 v[146:149], v220 offset:2048
	ds_read_b128 v[150:153], v220 offset:3072
	ds_read_b128 v[154:157], v213 offset:32768
	ds_read_b128 v[158:161], v213 offset:33792
	ds_read_b128 v[162:165], v213 offset:34816
	ds_read_b128 v[166:169], v213 offset:35840
	ds_read_b128 v[170:173], v213 offset:36864
	ds_read_b128 v[174:177], v213 offset:37888
	ds_read_b128 v[178:181], v213 offset:38912
	ds_read_b128 v[182:185], v213 offset:39936
	s_mov_b32 m0, s50
	s_add_u32 s98, s8, s30
	s_addc_u32 s99, s9, s31
	global_load_lds_dwordx4 v203, s[98:99]
	s_mov_b32 m0, s51
	s_add_u32 s98, s8, s40
	s_addc_u32 s99, s9, s41
	global_load_lds_dwordx4 v203, s[98:99]
	s_waitcnt lgkmcnt(8)
	s_waitcnt vmcnt(10)
	s_barrier
	s_waitcnt lgkmcnt(0)
	v_mfma_f32_16x16x32_bf16 v[126:129], v[138:141], v[154:157], v[126:129]
	v_mfma_f32_16x16x32_bf16 v[122:125], v[146:149], v[154:157], v[122:125]
	v_mfma_f32_16x16x32_bf16 v[118:121], v[138:141], v[162:165], v[118:121]
	v_mfma_f32_16x16x32_bf16 v[114:117], v[146:149], v[162:165], v[114:117]
	v_mfma_f32_16x16x32_bf16 v[110:113], v[138:141], v[170:173], v[110:113]
	v_mfma_f32_16x16x32_bf16 v[106:109], v[146:149], v[170:173], v[106:109]
	v_mfma_f32_16x16x32_bf16 v[102:105], v[138:141], v[178:181], v[102:105]
	v_mfma_f32_16x16x32_bf16 v[98:101], v[146:149], v[178:181], v[98:101]
	v_mfma_f32_16x16x32_bf16 v[126:129], v[142:145], v[158:161], v[126:129]
	v_mfma_f32_16x16x32_bf16 v[122:125], v[150:153], v[158:161], v[122:125]
	v_mfma_f32_16x16x32_bf16 v[118:121], v[142:145], v[166:169], v[118:121]
	v_mfma_f32_16x16x32_bf16 v[114:117], v[150:153], v[166:169], v[114:117]
	v_mfma_f32_16x16x32_bf16 v[110:113], v[142:145], v[174:177], v[110:113]
	v_mfma_f32_16x16x32_bf16 v[106:109], v[150:153], v[174:177], v[106:109]
	v_mfma_f32_16x16x32_bf16 v[102:105], v[142:145], v[182:185], v[102:105]
	v_mfma_f32_16x16x32_bf16 v[98:101], v[150:153], v[182:185], v[98:101]
	s_barrier
	ds_read_b128 v[186:189], v221
	ds_read_b128 v[190:193], v221 offset:1024
	ds_read_b128 v[194:197], v221 offset:2048
	ds_read_b128 v[198:201], v221 offset:3072
	s_mov_b32 m0, s52
	s_add_u32 s98, vcc_lo, s94
	s_addc_u32 s99, vcc_hi, s95
	global_load_lds_dwordx4 v203, s[98:99]
	s_mov_b32 m0, s53
	s_add_u32 s98, vcc_lo, s42
	s_addc_u32 s99, vcc_hi, s43
	global_load_lds_dwordx4 v203, s[98:99]
	s_waitcnt vmcnt(10)
	s_barrier
	s_waitcnt lgkmcnt(0)
	v_mfma_f32_16x16x32_bf16 v[94:97], v[186:189], v[154:157], v[94:97]
	v_mfma_f32_16x16x32_bf16 v[90:93], v[194:197], v[154:157], v[90:93]
	v_mfma_f32_16x16x32_bf16 v[86:89], v[186:189], v[162:165], v[86:89]
	v_mfma_f32_16x16x32_bf16 v[82:85], v[194:197], v[162:165], v[82:85]
	v_mfma_f32_16x16x32_bf16 v[78:81], v[186:189], v[170:173], v[78:81]
	v_mfma_f32_16x16x32_bf16 v[74:77], v[194:197], v[170:173], v[74:77]
	v_mfma_f32_16x16x32_bf16 v[70:73], v[186:189], v[178:181], v[70:73]
	v_mfma_f32_16x16x32_bf16 v[66:69], v[194:197], v[178:181], v[66:69]
	v_mfma_f32_16x16x32_bf16 v[94:97], v[190:193], v[158:161], v[94:97]
	v_mfma_f32_16x16x32_bf16 v[90:93], v[198:201], v[158:161], v[90:93]
	v_mfma_f32_16x16x32_bf16 v[86:89], v[190:193], v[166:169], v[86:89]
	v_mfma_f32_16x16x32_bf16 v[82:85], v[198:201], v[166:169], v[82:85]
	v_mfma_f32_16x16x32_bf16 v[78:81], v[190:193], v[174:177], v[78:81]
	v_mfma_f32_16x16x32_bf16 v[74:77], v[198:201], v[174:177], v[74:77]
	v_mfma_f32_16x16x32_bf16 v[70:73], v[190:193], v[182:185], v[70:73]
	v_mfma_f32_16x16x32_bf16 v[66:69], v[198:201], v[182:185], v[66:69]
	s_barrier
; #define LDA(dst, b, h) for (int m = 0; m < 4; ++m) for (int k = 0; k < 2; ++k) \
;     dst[m][k] = *reinterpret_cast<const bf16x8*>((char*)SA(b, h) + a_thr + (m * 2 + k) * 1024)
; #define LDB(dst, b, h) for (int n = 0; n < 2; ++n) for (int k = 0; k < 2; ++k) \
;     dst[n][k] = *reinterpret_cast<const bf16x8*>((char*)SB(b, h) + b_thr + (n * 2 + k) * 1024)
; #define MMA(ai, bj, At, Btf) do { __builtin_amdgcn_s_setprio(1); \
;     for (int m = 0; m < 4; ++m) for (int n = 0; n < 2; ++n) for (int k = 0; k < 2; ++k) \
;       acc[ai][bj][m][n] = __builtin_amdgcn_mfma_f32_16x16x32_bf16(Btf[n][k], At[m][k], acc[ai][bj][m][n], 0, 0, 0); \
;     __builtin_amdgcn_s_setprio(0); } while (0)
; #define WAIT_V(n) asm volatile("s_waitcnt vmcnt(" #n ")" ::: "memory")
; #define WAIT_L(n) asm volatile("s_waitcnt lgkmcnt(" #n ")" ::: "memory")
; #define BAR __builtin_amdgcn_s_barrier()
; #define SCHED __builtin_amdgcn_sched_barrier(0)
; template <bool OVL, bool PANEL = false, class Epi>
; __device__ __forceinline__ void gemm_phase(const bf16_t* __restrict__ A, long lda, const bf16_t* __restrict__ Bt, long ldb, int nM, int nN, int K,
;                                            const Epi& epi, bf16_t* shm, int w0) {
;     ...
;       LDA(At, 1, 1); STAGE(SA(1, 0), A, lda, aoff, brow, t + 3);
;       BAR; WAIT_L(0); MMA(1, 0, At, B0); BAR; SCHED;
;       STAGE(SB(1, 1), Bt, ldb, boff, bcol + HALF, t + 3);
;       WAIT_V(6); BAR; MMA(1, 1, At, B1); BAR;
;     }
;     { LDB(B0, 0, 0); LDA(At, 0, 0); STAGE(SA(1, 1), A, lda, aoff, brow + HALF, nt - 1);
;       BAR; WAIT_L(0); MMA(0, 0, At, B0); BAR;
	ds_read_b128 v[154:157], v213 offset:49152
	ds_read_b128 v[158:161], v213 offset:50176
	ds_read_b128 v[162:165], v213 offset:51200
	ds_read_b128 v[166:169], v213 offset:52224
	ds_read_b128 v[170:173], v213 offset:53248
	ds_read_b128 v[174:177], v213 offset:54272
	ds_read_b128 v[178:181], v213 offset:55296
	ds_read_b128 v[182:185], v213 offset:56320
	s_mov_b32 m0, s54
	s_add_u32 s98, s8, s94
	s_addc_u32 s99, s9, s95
	global_load_lds_dwordx4 v203, s[98:99]
	s_mov_b32 m0, s55
	s_add_u32 s98, s8, s42
	s_addc_u32 s99, s9, s43
	global_load_lds_dwordx4 v203, s[98:99]
	s_barrier
	s_waitcnt lgkmcnt(0)
	v_mfma_f32_16x16x32_bf16 v[62:65], v[138:141], v[154:157], v[62:65]
	v_mfma_f32_16x16x32_bf16 v[58:61], v[146:149], v[154:157], v[58:61]
	v_mfma_f32_16x16x32_bf16 v[54:57], v[138:141], v[162:165], v[54:57]
	v_mfma_f32_16x16x32_bf16 v[50:53], v[146:149], v[162:165], v[50:53]
	v_mfma_f32_16x16x32_bf16 v[46:49], v[138:141], v[170:173], v[46:49]
	v_mfma_f32_16x16x32_bf16 v[42:45], v[146:149], v[170:173], v[42:45]
	v_mfma_f32_16x16x32_bf16 v[38:41], v[138:141], v[178:181], v[38:41]
	v_mfma_f32_16x16x32_bf16 v[34:37], v[146:149], v[178:181], v[34:37]
	v_mfma_f32_16x16x32_bf16 v[62:65], v[142:145], v[158:161], v[62:65]
	v_mfma_f32_16x16x32_bf16 v[58:61], v[150:153], v[158:161], v[58:61]
	v_mfma_f32_16x16x32_bf16 v[54:57], v[142:145], v[166:169], v[54:57]
	v_mfma_f32_16x16x32_bf16 v[50:53], v[150:153], v[166:169], v[50:53]
	v_mfma_f32_16x16x32_bf16 v[46:49], v[142:145], v[174:177], v[46:49]
	v_mfma_f32_16x16x32_bf16 v[42:45], v[150:153], v[174:177], v[42:45]
	v_mfma_f32_16x16x32_bf16 v[38:41], v[142:145], v[182:185], v[38:41]
	v_mfma_f32_16x16x32_bf16 v[34:37], v[150:153], v[182:185], v[34:37]
	s_barrier
	s_mov_b64 s[8:9], 0xb0180
	s_mov_b64 s[8:9], 0x108180
	s_mov_b32 m0, s60
	s_add_u32 s98, vcc_lo, 0xb0180
	s_addc_u32 s99, vcc_hi, 0
	global_load_lds_dwordx4 v203, s[98:99]
	s_mov_b32 m0, s61
	s_add_u32 s98, vcc_lo, 0x108180
	s_addc_u32 s99, vcc_hi, 0
	global_load_lds_dwordx4 v203, s[98:99]
	s_add_i32 s2, s2, 2
	s_add_u32 s6, s6, 0x100
	s_addc_u32 s7, s7, 0
	s_cmp_gt_u32 s2, 39
	s_waitcnt vmcnt(10)
	s_barrier
	v_mfma_f32_16x16x32_bf16 v[30:33], v[186:189], v[154:157], v[30:33]
	v_mfma_f32_16x16x32_bf16 v[26:29], v[194:197], v[154:157], v[26:29]
	v_mfma_f32_16x16x32_bf16 v[22:25], v[186:189], v[162:165], v[22:25]
	v_mfma_f32_16x16x32_bf16 v[18:21], v[194:197], v[162:165], v[18:21]
	v_mfma_f32_16x16x32_bf16 v[14:17], v[186:189], v[170:173], v[14:17]
	v_mfma_f32_16x16x32_bf16 v[10:13], v[194:197], v[170:173], v[10:13]
	v_mfma_f32_16x16x32_bf16 v[6:9], v[186:189], v[178:181], v[6:9]
	v_mfma_f32_16x16x32_bf16 v[2:5], v[194:197], v[178:181], v[2:5]
	v_mfma_f32_16x16x32_bf16 v[30:33], v[190:193], v[158:161], v[30:33]
	v_mfma_f32_16x16x32_bf16 v[26:29], v[198:201], v[158:161], v[26:29]
	v_mfma_f32_16x16x32_bf16 v[22:25], v[190:193], v[166:169], v[22:25]
	v_mfma_f32_16x16x32_bf16 v[18:21], v[198:201], v[166:169], v[18:21]
	v_mfma_f32_16x16x32_bf16 v[14:17], v[190:193], v[174:177], v[14:17]
	v_mfma_f32_16x16x32_bf16 v[10:13], v[198:201], v[174:177], v[10:13]
	v_mfma_f32_16x16x32_bf16 v[6:9], v[190:193], v[182:185], v[6:9]
	v_mfma_f32_16x16x32_bf16 v[2:5], v[198:201], v[182:185], v[2:5]
	s_barrier
	s_cbranch_scc0 .LBB0_125
	s_waitcnt vmcnt(6)
	s_or_b32 s0, s28, 0x80
	s_mul_hi_i32 s1, s0, 0x1600
	s_mulk_i32 s0, 0x1600
	v_readlane_b32 s2, v250, 49
	v_add_u32_e32 v227, 16, v212
	s_add_u32 s0, s2, s0
	v_readlane_b32 s2, v250, 50
	v_add_u32_e32 v0, 0x10000, v227
	s_addc_u32 s1, s2, s1
	v_readfirstlane_b32 s2, v136
	ds_read_b128 v[130:133], v0
	ds_read_b128 v[138:141], v0 offset:1024
	ds_read_b128 v[142:145], v0 offset:2048
	ds_read_b128 v[146:149], v0 offset:3072
	ds_read_b128 v[150:153], v213
	ds_read_b128 v[154:157], v213 offset:1024
	ds_read_b128 v[158:161], v213 offset:2048
	ds_read_b128 v[162:165], v213 offset:3072
	ds_read_b128 v[166:169], v213 offset:4096
	ds_read_b128 v[170:173], v213 offset:5120
	ds_read_b128 v[174:177], v213 offset:6144
	ds_read_b128 v[178:181], v213 offset:7168
	v_mov_b32_e32 v0, v203
	s_mov_b32 m0, s2
	s_nop 0
	v_lshl_add_u64 v[134:135], s[0:1], 0, v[0:1]
	global_load_lds_dwordx4 v0, s[0:1]
	v_readfirstlane_b32 s0, v137
	v_lshl_add_u64 v[134:135], v[134:135], 0, s[26:27]
	s_mov_b32 m0, s0
	s_nop 0
	global_load_lds_dwordx4 v[134:135], off
	s_barrier
	s_waitcnt lgkmcnt(0)

; #define LDA(dst, b, h) for (int m = 0; m < 4; ++m) for (int k = 0; k < 2; ++k) \
;     dst[m][k] = *reinterpret_cast<const bf16x8*>((char*)SA(b, h) + a_thr + (m * 2 + k) * 1024)
; #define LDB(dst, b, h) for (int n = 0; n < 2; ++n) for (int k = 0; k < 2; ++k) \
;     dst[n][k] = *reinterpret_cast<const bf16x8*>((char*)SB(b, h) + b_thr + (n * 2 + k) * 1024)
; #define MMA(ai, bj, At, Btf) do { __builtin_amdgcn_s_setprio(1); \
;     for (int m = 0; m < 4; ++m) for (int n = 0; n < 2; ++n) for (int k = 0; k < 2; ++k) \
;       acc[ai][bj][m][n] = __builtin_amdgcn_mfma_f32_16x16x32_bf16(Btf[n][k], At[m][k], acc[ai][bj][m][n], 0, 0, 0); \
;     __builtin_amdgcn_s_setprio(0); } while (0)
; #define WAIT_L(n) asm volatile("s_waitcnt lgkmcnt(" #n ")" ::: "memory")
; #define BAR __builtin_amdgcn_s_barrier()
; template <bool OVL, bool PANEL = false, class Epi>
; __device__ __forceinline__ void gemm_phase(const bf16_t* __restrict__ A, long lda, const bf16_t* __restrict__ Bt, long ldb, int nM, int nN, int K,
;                                            const Epi& epi, bf16_t* shm, int w0) {
;     ...
;     { LDB(B0, 0, 0); LDA(At, 0, 0); STAGE(SA(1, 1), A, lda, aoff, brow + HALF, nt - 1);
;       BAR; WAIT_L(0); MMA(0, 0, At, B0); BAR;
	s_waitcnt lgkmcnt(0)
	v_mfma_f32_16x16x32_bf16 v[126:129], v[130:133], v[150:153], v[126:129]
	v_mfma_f32_16x16x32_bf16 v[122:125], v[142:145], v[150:153], v[122:125]
	v_mfma_f32_16x16x32_bf16 v[118:121], v[130:133], v[158:161], v[118:121]
	v_mfma_f32_16x16x32_bf16 v[114:117], v[142:145], v[158:161], v[114:117]
	v_mfma_f32_16x16x32_bf16 v[110:113], v[130:133], v[166:169], v[110:113]
	v_mfma_f32_16x16x32_bf16 v[106:109], v[142:145], v[166:169], v[106:109]
	v_mfma_f32_16x16x32_bf16 v[102:105], v[130:133], v[174:177], v[102:105]
	v_mfma_f32_16x16x32_bf16 v[98:101], v[142:145], v[174:177], v[98:101]
	v_mfma_f32_16x16x32_bf16 v[126:129], v[138:141], v[154:157], v[126:129]
	v_mfma_f32_16x16x32_bf16 v[122:125], v[146:149], v[154:157], v[122:125]
	v_mfma_f32_16x16x32_bf16 v[118:121], v[138:141], v[162:165], v[118:121]
	v_mfma_f32_16x16x32_bf16 v[114:117], v[146:149], v[162:165], v[114:117]
	v_mfma_f32_16x16x32_bf16 v[110:113], v[138:141], v[170:173], v[110:113]
	v_mfma_f32_16x16x32_bf16 v[106:109], v[146:149], v[170:173], v[106:109]
	v_mfma_f32_16x16x32_bf16 v[102:105], v[138:141], v[178:181], v[102:105]
	v_mfma_f32_16x16x32_bf16 v[98:101], v[146:149], v[178:181], v[98:101]

; #define LDB(dst, b, h) for (int n = 0; n < 2; ++n) for (int k = 0; k < 2; ++k) \
;     dst[n][k] = *reinterpret_cast<const bf16x8*>((char*)SB(b, h) + b_thr + (n * 2 + k) * 1024)
; #define MMA(ai, bj, At, Btf) do { __builtin_amdgcn_s_setprio(1); \
;     for (int m = 0; m < 4; ++m) for (int n = 0; n < 2; ++n) for (int k = 0; k < 2; ++k) \
;       acc[ai][bj][m][n] = __builtin_amdgcn_mfma_f32_16x16x32_bf16(Btf[n][k], At[m][k], acc[ai][bj][m][n], 0, 0, 0); \
;     __builtin_amdgcn_s_setprio(0); } while (0)
; #define WAIT_L(n) asm volatile("s_waitcnt lgkmcnt(" #n ")" ::: "memory")
; #define BAR __builtin_amdgcn_s_barrier()
; template <bool OVL, bool PANEL = false, class Epi>
; __device__ __forceinline__ void gemm_phase(const bf16_t* __restrict__ A, long lda, const bf16_t* __restrict__ Bt, long ldb, int nM, int nN, int K,
;                                            const Epi& epi, bf16_t* shm, int w0) {
;     ...
;       BAR; WAIT_L(0); MMA(0, 0, At, B0); BAR;
;       LDB(B1, 0, 1); BAR; WAIT_L(0); MMA(0, 1, At, B1); BAR;
	v_add_u32_e32 v0, 0x14000, v227
	s_barrier
	ds_read_b128 v[134:137], v0
	ds_read_b128 v[182:185], v0 offset:1024
	ds_read_b128 v[186:189], v0 offset:2048
	ds_read_b128 v[190:193], v0 offset:3072
	s_barrier
	s_waitcnt lgkmcnt(0)

; #define LDB(dst, b, h) for (int n = 0; n < 2; ++n) for (int k = 0; k < 2; ++k) \
;     dst[n][k] = *reinterpret_cast<const bf16x8*>((char*)SB(b, h) + b_thr + (n * 2 + k) * 1024)
; #define MMA(ai, bj, At, Btf) do { __builtin_amdgcn_s_setprio(1); \
;     for (int m = 0; m < 4; ++m) for (int n = 0; n < 2; ++n) for (int k = 0; k < 2; ++k) \
;       acc[ai][bj][m][n] = __builtin_amdgcn_mfma_f32_16x16x32_bf16(Btf[n][k], At[m][k], acc[ai][bj][m][n], 0, 0, 0); \
;     __builtin_amdgcn_s_setprio(0); } while (0)
; #define WAIT_L(n) asm volatile("s_waitcnt lgkmcnt(" #n ")" ::: "memory")
; #define BAR __builtin_amdgcn_s_barrier()
; template <bool OVL, bool PANEL = false, class Epi>
; __device__ __forceinline__ void gemm_phase(const bf16_t* __restrict__ A, long lda, const bf16_t* __restrict__ Bt, long ldb, int nM, int nN, int K,
;                                            const Epi& epi, bf16_t* shm, int w0) {
;     ...
;       LDB(B1, 0, 1); BAR; WAIT_L(0); MMA(0, 1, At, B1); BAR;
	s_waitcnt lgkmcnt(0)
	v_mfma_f32_16x16x32_bf16 v[94:97], v[134:137], v[150:153], v[94:97]
	v_mfma_f32_16x16x32_bf16 v[90:93], v[186:189], v[150:153], v[90:93]
	v_mfma_f32_16x16x32_bf16 v[86:89], v[134:137], v[158:161], v[86:89]
	v_mfma_f32_16x16x32_bf16 v[82:85], v[186:189], v[158:161], v[82:85]
	v_mfma_f32_16x16x32_bf16 v[78:81], v[134:137], v[166:169], v[78:81]
	v_mfma_f32_16x16x32_bf16 v[66:69], v[186:189], v[174:177], v[66:69]
	v_mfma_f32_16x16x32_bf16 v[94:97], v[182:185], v[154:157], v[94:97]
	v_mfma_f32_16x16x32_bf16 v[90:93], v[190:193], v[154:157], v[90:93]
	v_mfma_f32_16x16x32_bf16 v[86:89], v[182:185], v[162:165], v[86:89]
	v_mfma_f32_16x16x32_bf16 v[82:85], v[190:193], v[162:165], v[82:85]
	v_mfma_f32_16x16x32_bf16 v[78:81], v[182:185], v[170:173], v[78:81]
	v_mfma_f32_16x16x32_bf16 v[74:77], v[186:189], v[166:169], v[74:77]
	v_mfma_f32_16x16x32_bf16 v[70:73], v[134:137], v[174:177], v[70:73]
	v_mfma_f32_16x16x32_bf16 v[66:69], v[190:193], v[178:181], v[66:69]
	v_mfma_f32_16x16x32_bf16 v[150:153], v[190:193], v[170:173], v[74:77]
	v_mfma_f32_16x16x32_bf16 v[154:157], v[182:185], v[178:181], v[70:73]

; #define LDA(dst, b, h) for (int m = 0; m < 4; ++m) for (int k = 0; k < 2; ++k) \
;     dst[m][k] = *reinterpret_cast<const bf16x8*>((char*)SA(b, h) + a_thr + (m * 2 + k) * 1024)
; #define LDB(dst, b, h) for (int n = 0; n < 2; ++n) for (int k = 0; k < 2; ++k) \
;     dst[n][k] = *reinterpret_cast<const bf16x8*>((char*)SB(b, h) + b_thr + (n * 2 + k) * 1024)
; #define MMA(ai, bj, At, Btf) do { __builtin_amdgcn_s_setprio(1); \
;     for (int m = 0; m < 4; ++m) for (int n = 0; n < 2; ++n) for (int k = 0; k < 2; ++k) \
;       acc[ai][bj][m][n] = __builtin_amdgcn_mfma_f32_16x16x32_bf16(Btf[n][k], At[m][k], acc[ai][bj][m][n], 0, 0, 0); \
;     __builtin_amdgcn_s_setprio(0); } while (0)
; #define WAIT_V(n) asm volatile("s_waitcnt vmcnt(" #n ")" ::: "memory")
; #define WAIT_L(n) asm volatile("s_waitcnt lgkmcnt(" #n ")" ::: "memory")
; #define BAR __builtin_amdgcn_s_barrier()
; template <bool OVL, bool PANEL = false, class Epi>
; __device__ __forceinline__ void gemm_phase(const bf16_t* __restrict__ A, long lda, const bf16_t* __restrict__ Bt, long ldb, int nM, int nN, int K,
;                                            const Epi& epi, bf16_t* shm, int w0) {
;     ...
;       LDB(B1, 0, 1); BAR; WAIT_L(0); MMA(0, 1, At, B1); BAR;
;       LDA(At, 0, 1); WAIT_V(4); BAR; WAIT_L(0); MMA(1, 0, At, B0); MMA(1, 1, At, B1); BAR; }
	s_barrier
	s_nop 2
	ds_read_b128 v[70:73], v213 offset:16384
	ds_read_b128 v[74:77], v213 offset:17408
	ds_read_b128 v[158:161], v213 offset:18432
	ds_read_b128 v[162:165], v213 offset:19456
	ds_read_b128 v[166:169], v213 offset:20480
	ds_read_b128 v[170:173], v213 offset:21504
	ds_read_b128 v[174:177], v213 offset:22528
	ds_read_b128 v[178:181], v213 offset:23552
	s_waitcnt vmcnt(4)
	s_barrier
	s_waitcnt lgkmcnt(0)

; #define LDA(dst, b, h) for (int m = 0; m < 4; ++m) for (int k = 0; k < 2; ++k) \
;     dst[m][k] = *reinterpret_cast<const bf16x8*>((char*)SA(b, h) + a_thr + (m * 2 + k) * 1024)
; #define MMA(ai, bj, At, Btf) do { __builtin_amdgcn_s_setprio(1); \
;     for (int m = 0; m < 4; ++m) for (int n = 0; n < 2; ++n) for (int k = 0; k < 2; ++k) \
;       acc[ai][bj][m][n] = __builtin_amdgcn_mfma_f32_16x16x32_bf16(Btf[n][k], At[m][k], acc[ai][bj][m][n], 0, 0, 0); \
;     __builtin_amdgcn_s_setprio(0); } while (0)
; #define WAIT_V(n) asm volatile("s_waitcnt vmcnt(" #n ")" ::: "memory")
; #define WAIT_L(n) asm volatile("s_waitcnt lgkmcnt(" #n ")" ::: "memory")
; #define BAR __builtin_amdgcn_s_barrier()
; template <bool OVL, bool PANEL = false, class Epi>
; __device__ __forceinline__ void gemm_phase(const bf16_t* __restrict__ A, long lda, const bf16_t* __restrict__ Bt, long ldb, int nM, int nN, int K,
;                                            const Epi& epi, bf16_t* shm, int w0) {
;     ...
;       LDA(At, 0, 1); WAIT_V(4); BAR; WAIT_L(0); MMA(1, 0, At, B0); MMA(1, 1, At, B1); BAR; }
	s_waitcnt lgkmcnt(0)
	v_mfma_f32_16x16x32_bf16 v[58:61], v[142:145], v[70:73], v[58:61]
	v_mfma_f32_16x16x32_bf16 v[54:57], v[130:133], v[158:161], v[54:57]
	v_mfma_f32_16x16x32_bf16 v[62:65], v[130:133], v[70:73], v[62:65]
	v_mfma_f32_16x16x32_bf16 v[58:61], v[146:149], v[74:77], v[58:61]
	v_mfma_f32_16x16x32_bf16 v[54:57], v[138:141], v[162:165], v[54:57]
	v_mfma_f32_16x16x32_bf16 v[50:53], v[142:145], v[158:161], v[50:53]
	v_mfma_f32_16x16x32_bf16 v[46:49], v[130:133], v[166:169], v[46:49]
	v_mfma_f32_16x16x32_bf16 v[42:45], v[142:145], v[166:169], v[42:45]
	v_mfma_f32_16x16x32_bf16 v[38:41], v[130:133], v[174:177], v[38:41]
	v_mfma_f32_16x16x32_bf16 v[34:37], v[142:145], v[174:177], v[34:37]
	v_mfma_f32_16x16x32_bf16 v[194:197], v[138:141], v[74:77], v[62:65]
	v_mfma_f32_16x16x32_bf16 v[198:201], v[146:149], v[162:165], v[50:53]
	v_mfma_f32_16x16x32_bf16 v[214:217], v[138:141], v[170:173], v[46:49]
	v_mfma_f32_16x16x32_bf16 v[218:221], v[146:149], v[170:173], v[42:45]
	v_mfma_f32_16x16x32_bf16 v[130:133], v[138:141], v[178:181], v[38:41]
	v_mfma_f32_16x16x32_bf16 v[138:141], v[146:149], v[178:181], v[34:37]


; #define LDA(dst, b, h) for (int m = 0; m < 4; ++m) for (int k = 0; k < 2; ++k) \
;     dst[m][k] = *reinterpret_cast<const bf16x8*>((char*)SA(b, h) + a_thr + (m * 2 + k) * 1024)
; #define MMA(ai, bj, At, Btf) do { __builtin_amdgcn_s_setprio(1); \
;     for (int m = 0; m < 4; ++m) for (int n = 0; n < 2; ++n) for (int k = 0; k < 2; ++k) \
;       acc[ai][bj][m][n] = __builtin_amdgcn_mfma_f32_16x16x32_bf16(Btf[n][k], At[m][k], acc[ai][bj][m][n], 0, 0, 0); \
;     __builtin_amdgcn_s_setprio(0); } while (0)
; #define WAIT_V(n) asm volatile("s_waitcnt vmcnt(" #n ")" ::: "memory")
; #define WAIT_L(n) asm volatile("s_waitcnt lgkmcnt(" #n ")" ::: "memory")
; #define BAR __builtin_amdgcn_s_barrier()
; template <bool OVL, bool PANEL = false, class Epi>
; __device__ __forceinline__ void gemm_phase(const bf16_t* __restrict__ A, long lda, const bf16_t* __restrict__ Bt, long ldb, int nM, int nN, int K,
;                                            const Epi& epi, bf16_t* shm, int w0) {
;     ...
;       LDA(At, 0, 1); WAIT_V(4); BAR; WAIT_L(0); MMA(1, 0, At, B0); MMA(1, 1, At, B1); BAR; }
	v_mfma_f32_16x16x32_bf16 v[30:33], v[134:137], v[70:73], v[30:33]
	v_mfma_f32_16x16x32_bf16 v[26:29], v[186:189], v[70:73], v[26:29]
	v_mfma_f32_16x16x32_bf16 v[22:25], v[134:137], v[158:161], v[22:25]
	v_mfma_f32_16x16x32_bf16 v[18:21], v[186:189], v[158:161], v[18:21]
	v_mfma_f32_16x16x32_bf16 v[14:17], v[134:137], v[166:169], v[14:17]
	v_mfma_f32_16x16x32_bf16 v[10:13], v[186:189], v[166:169], v[10:13]
	v_mfma_f32_16x16x32_bf16 v[6:9], v[134:137], v[174:177], v[6:9]
	v_mfma_f32_16x16x32_bf16 v[2:5], v[186:189], v[174:177], v[2:5]
	v_mfma_f32_16x16x32_bf16 v[142:145], v[182:185], v[74:77], v[30:33]
	v_mfma_f32_16x16x32_bf16 v[146:149], v[190:193], v[74:77], v[26:29]
	v_mfma_f32_16x16x32_bf16 v[222:225], v[182:185], v[162:165], v[22:25]
	v_mfma_f32_16x16x32_bf16 v[158:161], v[190:193], v[162:165], v[18:21]
	v_mfma_f32_16x16x32_bf16 v[162:165], v[182:185], v[170:173], v[14:17]
	v_mfma_f32_16x16x32_bf16 v[166:169], v[190:193], v[170:173], v[10:13]
	v_mfma_f32_16x16x32_bf16 v[134:137], v[182:185], v[178:181], v[6:9]
	v_mfma_f32_16x16x32_bf16 v[170:173], v[190:193], v[178:181], v[2:5]

; #define LDA(dst, b, h) for (int m = 0; m < 4; ++m) for (int k = 0; k < 2; ++k) \
;     dst[m][k] = *reinterpret_cast<const bf16x8*>((char*)SA(b, h) + a_thr + (m * 2 + k) * 1024)
; #define LDB(dst, b, h) for (int n = 0; n < 2; ++n) for (int k = 0; k < 2; ++k) \
;     dst[n][k] = *reinterpret_cast<const bf16x8*>((char*)SB(b, h) + b_thr + (n * 2 + k) * 1024)
; #define MMA(ai, bj, At, Btf) do { __builtin_amdgcn_s_setprio(1); \
;     for (int m = 0; m < 4; ++m) for (int n = 0; n < 2; ++n) for (int k = 0; k < 2; ++k) \
;       acc[ai][bj][m][n] = __builtin_amdgcn_mfma_f32_16x16x32_bf16(Btf[n][k], At[m][k], acc[ai][bj][m][n], 0, 0, 0); \
;     __builtin_amdgcn_s_setprio(0); } while (0)
; #define WAIT_V(n) asm volatile("s_waitcnt vmcnt(" #n ")" ::: "memory")
; #define WAIT_L(n) asm volatile("s_waitcnt lgkmcnt(" #n ")" ::: "memory")
; #define BAR __builtin_amdgcn_s_barrier()
; template <bool OVL, bool PANEL = false, class Epi>
; __device__ __forceinline__ void gemm_phase(const bf16_t* __restrict__ A, long lda, const bf16_t* __restrict__ Bt, long ldb, int nM, int nN, int K,
;                                            const Epi& epi, bf16_t* shm, int w0) {
;     ...
;       LDA(At, 0, 1); WAIT_V(4); BAR; WAIT_L(0); MMA(1, 0, At, B0); MMA(1, 1, At, B1); BAR; }
;     { LDB(B0, 1, 0); LDA(At, 1, 0); WAIT_V(2); BAR; WAIT_L(0); MMA(0, 0, At, B0); BAR;
	v_add_u32_e32 v0, 0x18000, v227
	s_barrier
	ds_read_b128 v[34:37], v0
	ds_read_b128 v[174:177], v0 offset:1024
	ds_read_b128 v[178:181], v0 offset:2048
	ds_read_b128 v[182:185], v0 offset:3072
	ds_read_b128 v[18:21], v213 offset:32768
	ds_read_b128 v[22:25], v213 offset:33792
	ds_read_b128 v[26:29], v213 offset:34816
	ds_read_b128 v[50:53], v213 offset:35840
	ds_read_b128 v[186:189], v213 offset:36864
	ds_read_b128 v[190:193], v213 offset:37888
	ds_read_b128 v[228:231], v213 offset:38912
	ds_read_b128 v[232:235], v213 offset:39936
	s_waitcnt vmcnt(2)
	s_barrier
	s_waitcnt lgkmcnt(0)

; #define LDA(dst, b, h) for (int m = 0; m < 4; ++m) for (int k = 0; k < 2; ++k) \
;     dst[m][k] = *reinterpret_cast<const bf16x8*>((char*)SA(b, h) + a_thr + (m * 2 + k) * 1024)
; #define LDB(dst, b, h) for (int n = 0; n < 2; ++n) for (int k = 0; k < 2; ++k) \
;     dst[n][k] = *reinterpret_cast<const bf16x8*>((char*)SB(b, h) + b_thr + (n * 2 + k) * 1024)
; #define MMA(ai, bj, At, Btf) do { __builtin_amdgcn_s_setprio(1); \
;     for (int m = 0; m < 4; ++m) for (int n = 0; n < 2; ++n) for (int k = 0; k < 2; ++k) \
;       acc[ai][bj][m][n] = __builtin_amdgcn_mfma_f32_16x16x32_bf16(Btf[n][k], At[m][k], acc[ai][bj][m][n], 0, 0, 0); \
;     __builtin_amdgcn_s_setprio(0); } while (0)
; #define WAIT_V(n) asm volatile("s_waitcnt vmcnt(" #n ")" ::: "memory")
; #define WAIT_L(n) asm volatile("s_waitcnt lgkmcnt(" #n ")" ::: "memory")
; #define BAR __builtin_amdgcn_s_barrier()
; template <bool OVL, bool PANEL = false, class Epi>
; __device__ __forceinline__ void gemm_phase(const bf16_t* __restrict__ A, long lda, const bf16_t* __restrict__ Bt, long ldb, int nM, int nN, int K,
;                                            const Epi& epi, bf16_t* shm, int w0) {
;     ...
;     { LDB(B0, 1, 0); LDA(At, 1, 0); WAIT_V(2); BAR; WAIT_L(0); MMA(0, 0, At, B0); BAR;
	s_waitcnt lgkmcnt(0)
	v_mfma_f32_16x16x32_bf16 v[6:9], v[178:181], v[18:21], v[122:125]
	v_mfma_f32_16x16x32_bf16 v[10:13], v[178:181], v[26:29], v[114:117]
	v_mfma_f32_16x16x32_bf16 v[14:17], v[178:181], v[186:189], v[106:109]
	v_mfma_f32_16x16x32_bf16 v[2:5], v[34:37], v[18:21], v[126:129]
	v_mfma_f32_16x16x32_bf16 v[30:33], v[182:185], v[22:25], v[6:9]
	v_mfma_f32_16x16x32_bf16 v[6:9], v[34:37], v[26:29], v[118:121]
	v_mfma_f32_16x16x32_bf16 v[38:41], v[182:185], v[50:53], v[10:13]
	v_mfma_f32_16x16x32_bf16 v[10:13], v[34:37], v[186:189], v[110:113]
	v_mfma_f32_16x16x32_bf16 v[42:45], v[182:185], v[190:193], v[14:17]
	v_mfma_f32_16x16x32_bf16 v[14:17], v[34:37], v[228:231], v[102:105]
	v_mfma_f32_16x16x32_bf16 v[46:49], v[178:181], v[228:231], v[98:101]
	v_mfma_f32_16x16x32_bf16 v[2:5], v[174:177], v[22:25], v[2:5]
	v_mfma_f32_16x16x32_bf16 v[6:9], v[174:177], v[50:53], v[6:9]
	v_mfma_f32_16x16x32_bf16 v[10:13], v[174:177], v[190:193], v[10:13]
	v_mfma_f32_16x16x32_bf16 v[14:17], v[174:177], v[232:235], v[14:17]
	v_mfma_f32_16x16x32_bf16 v[46:49], v[182:185], v[232:235], v[46:49]

; #define LDA(dst, b, h) for (int m = 0; m < 4; ++m) for (int k = 0; k < 2; ++k) \
;     dst[m][k] = *reinterpret_cast<const bf16x8*>((char*)SA(b, h) + a_thr + (m * 2 + k) * 1024)
; #define LDB(dst, b, h) for (int n = 0; n < 2; ++n) for (int k = 0; k < 2; ++k) \
;     dst[n][k] = *reinterpret_cast<const bf16x8*>((char*)SB(b, h) + b_thr + (n * 2 + k) * 1024)
; #define MMA(ai, bj, At, Btf) do { __builtin_amdgcn_s_setprio(1); \
;     for (int m = 0; m < 4; ++m) for (int n = 0; n < 2; ++n) for (int k = 0; k < 2; ++k) \
;       acc[ai][bj][m][n] = __builtin_amdgcn_mfma_f32_16x16x32_bf16(Btf[n][k], At[m][k], acc[ai][bj][m][n], 0, 0, 0); \
;     __builtin_amdgcn_s_setprio(0); } while (0)
; #define WAIT_V(n) asm volatile("s_waitcnt vmcnt(" #n ")" ::: "memory")
; #define WAIT_L(n) asm volatile("s_waitcnt lgkmcnt(" #n ")" ::: "memory")
; #define BAR __builtin_amdgcn_s_barrier()
; template <bool OVL, bool PANEL = false, class Epi>
; __device__ __forceinline__ void gemm_phase(const bf16_t* __restrict__ A, long lda, const bf16_t* __restrict__ Bt, long ldb, int nM, int nN, int K,
;                                            const Epi& epi, bf16_t* shm, int w0) {
;     ...
;     { LDB(B0, 1, 0); LDA(At, 1, 0); WAIT_V(2); BAR; WAIT_L(0); MMA(0, 0, At, B0); BAR;
;       LDB(B1, 1, 1); WAIT_V(0); BAR; WAIT_L(0); MMA(0, 1, At, B1); BAR;
	v_add_u32_e32 v0, 0x1c000, v227
	s_barrier
	ds_read_b128 v[102:105], v0
	ds_read_b128 v[236:239], v0 offset:1024
	ds_read_b128 v[240:243], v0 offset:2048
	ds_read_b128 v[244:247], v0 offset:3072
	s_waitcnt vmcnt(0)
	s_barrier
	s_waitcnt lgkmcnt(0)

; #define LDB(dst, b, h) for (int n = 0; n < 2; ++n) for (int k = 0; k < 2; ++k) \
;     dst[n][k] = *reinterpret_cast<const bf16x8*>((char*)SB(b, h) + b_thr + (n * 2 + k) * 1024)
; #define MMA(ai, bj, At, Btf) do { __builtin_amdgcn_s_setprio(1); \
;     for (int m = 0; m < 4; ++m) for (int n = 0; n < 2; ++n) for (int k = 0; k < 2; ++k) \
;       acc[ai][bj][m][n] = __builtin_amdgcn_mfma_f32_16x16x32_bf16(Btf[n][k], At[m][k], acc[ai][bj][m][n], 0, 0, 0); \
;     __builtin_amdgcn_s_setprio(0); } while (0)
; #define WAIT_V(n) asm volatile("s_waitcnt vmcnt(" #n ")" ::: "memory")
; #define WAIT_L(n) asm volatile("s_waitcnt lgkmcnt(" #n ")" ::: "memory")
; #define BAR __builtin_amdgcn_s_barrier()
; template <bool OVL, bool PANEL = false, class Epi>
; __device__ __forceinline__ void gemm_phase(const bf16_t* __restrict__ A, long lda, const bf16_t* __restrict__ Bt, long ldb, int nM, int nN, int K,
;                                            const Epi& epi, bf16_t* shm, int w0) {
;     ...
;       LDB(B1, 1, 1); WAIT_V(0); BAR; WAIT_L(0); MMA(0, 1, At, B1); BAR;
	s_waitcnt lgkmcnt(0)
	v_mfma_f32_16x16x32_bf16 v[62:65], v[102:105], v[18:21], v[94:97]
	v_mfma_f32_16x16x32_bf16 v[18:21], v[240:243], v[18:21], v[90:93]
	v_mfma_f32_16x16x32_bf16 v[98:101], v[244:247], v[22:25], v[18:21]
	v_mfma_f32_16x16x32_bf16 v[18:21], v[102:105], v[26:29], v[86:89]
	v_mfma_f32_16x16x32_bf16 v[70:73], v[236:239], v[50:53], v[18:21]
	v_mfma_f32_16x16x32_bf16 v[18:21], v[240:243], v[26:29], v[82:85]
	v_mfma_f32_16x16x32_bf16 v[106:109], v[244:247], v[50:53], v[18:21]
	v_mfma_f32_16x16x32_bf16 v[18:21], v[102:105], v[186:189], v[78:81]
	v_mfma_f32_16x16x32_bf16 v[74:77], v[236:239], v[190:193], v[18:21]
	v_mfma_f32_16x16x32_bf16 v[18:21], v[240:243], v[186:189], v[150:153]
	v_mfma_f32_16x16x32_bf16 v[110:113], v[244:247], v[190:193], v[18:21]
	v_mfma_f32_16x16x32_bf16 v[18:21], v[102:105], v[228:231], v[154:157]
	v_mfma_f32_16x16x32_bf16 v[78:81], v[236:239], v[232:235], v[18:21]
	v_mfma_f32_16x16x32_bf16 v[18:21], v[240:243], v[228:231], v[66:69]
	v_mfma_f32_16x16x32_bf16 v[62:65], v[236:239], v[22:25], v[62:65]
	v_mfma_f32_16x16x32_bf16 v[114:117], v[244:247], v[232:235], v[18:21]

; #define LDA(dst, b, h) for (int m = 0; m < 4; ++m) for (int k = 0; k < 2; ++k) \
;     dst[m][k] = *reinterpret_cast<const bf16x8*>((char*)SA(b, h) + a_thr + (m * 2 + k) * 1024)
; #define LDB(dst, b, h) for (int n = 0; n < 2; ++n) for (int k = 0; k < 2; ++k) \
;     dst[n][k] = *reinterpret_cast<const bf16x8*>((char*)SB(b, h) + b_thr + (n * 2 + k) * 1024)
; #define MMA(ai, bj, At, Btf) do { __builtin_amdgcn_s_setprio(1); \
;     for (int m = 0; m < 4; ++m) for (int n = 0; n < 2; ++n) for (int k = 0; k < 2; ++k) \
;       acc[ai][bj][m][n] = __builtin_amdgcn_mfma_f32_16x16x32_bf16(Btf[n][k], At[m][k], acc[ai][bj][m][n], 0, 0, 0); \
;     __builtin_amdgcn_s_setprio(0); } while (0)
; #define WAIT_V(n) asm volatile("s_waitcnt vmcnt(" #n ")" ::: "memory")
; #define WAIT_L(n) asm volatile("s_waitcnt lgkmcnt(" #n ")" ::: "memory")
; #define BAR __builtin_amdgcn_s_barrier()
; template <bool OVL, bool PANEL = false, class Epi>
; __device__ __forceinline__ void gemm_phase(const bf16_t* __restrict__ A, long lda, const bf16_t* __restrict__ Bt, long ldb, int nM, int nN, int K,
;                                            const Epi& epi, bf16_t* shm, int w0) {
;     ...
;       LDB(B1, 1, 1); WAIT_V(0); BAR; WAIT_L(0); MMA(0, 1, At, B1); BAR;
;       LDA(At, 1, 1); BAR; WAIT_L(0); MMA(1, 0, At, B0); MMA(1, 1, At, B1); BAR; }
	s_barrier
	ds_read_b128 v[86:89], v213 offset:49152
	ds_read_b128 v[90:93], v213 offset:50176
	ds_read_b128 v[94:97], v213 offset:51200
	ds_read_b128 v[118:121], v213 offset:52224
	ds_read_b128 v[150:153], v213 offset:53248
	ds_read_b128 v[154:157], v213 offset:54272
	ds_read_b128 v[186:189], v213 offset:55296
	ds_read_b128 v[190:193], v213 offset:56320
	s_barrier
	s_waitcnt lgkmcnt(0)

; #define LDA(dst, b, h) for (int m = 0; m < 4; ++m) for (int k = 0; k < 2; ++k) \
;     dst[m][k] = *reinterpret_cast<const bf16x8*>((char*)SA(b, h) + a_thr + (m * 2 + k) * 1024)
; #define MMA(ai, bj, At, Btf) do { __builtin_amdgcn_s_setprio(1); \
;     for (int m = 0; m < 4; ++m) for (int n = 0; n < 2; ++n) for (int k = 0; k < 2; ++k) \
;       acc[ai][bj][m][n] = __builtin_amdgcn_mfma_f32_16x16x32_bf16(Btf[n][k], At[m][k], acc[ai][bj][m][n], 0, 0, 0); \
;     __builtin_amdgcn_s_setprio(0); } while (0)
; #define WAIT_L(n) asm volatile("s_waitcnt lgkmcnt(" #n ")" ::: "memory")
; #define BAR __builtin_amdgcn_s_barrier()
; template <bool OVL, bool PANEL = false, class Epi>
; __device__ __forceinline__ void gemm_phase(const bf16_t* __restrict__ A, long lda, const bf16_t* __restrict__ Bt, long ldb, int nM, int nN, int K,
;                                            const Epi& epi, bf16_t* shm, int w0) {
;     ...
;       LDA(At, 1, 1); BAR; WAIT_L(0); MMA(1, 0, At, B0); MMA(1, 1, At, B1); BAR; }
	s_waitcnt lgkmcnt(0)
	v_mfma_f32_16x16x32_bf16 v[22:25], v[178:181], v[86:89], v[58:61]
	v_mfma_f32_16x16x32_bf16 v[26:29], v[178:181], v[94:97], v[198:201]
	v_mfma_f32_16x16x32_bf16 v[18:21], v[34:37], v[86:89], v[194:197]
	v_mfma_f32_16x16x32_bf16 v[50:53], v[182:185], v[90:93], v[22:25]
	v_mfma_f32_16x16x32_bf16 v[22:25], v[34:37], v[94:97], v[54:57]
	v_mfma_f32_16x16x32_bf16 v[54:57], v[182:185], v[118:121], v[26:29]
	v_mfma_f32_16x16x32_bf16 v[26:29], v[34:37], v[150:153], v[214:217]
	v_mfma_f32_16x16x32_bf16 v[58:61], v[178:181], v[150:153], v[218:221]
	v_mfma_f32_16x16x32_bf16 v[34:37], v[34:37], v[186:189], v[130:133]
	v_mfma_f32_16x16x32_bf16 v[66:69], v[178:181], v[186:189], v[138:141]
	v_mfma_f32_16x16x32_bf16 v[18:21], v[174:177], v[90:93], v[18:21]
	v_mfma_f32_16x16x32_bf16 v[22:25], v[174:177], v[118:121], v[22:25]
	v_mfma_f32_16x16x32_bf16 v[26:29], v[174:177], v[154:157], v[26:29]
	v_mfma_f32_16x16x32_bf16 v[58:61], v[182:185], v[154:157], v[58:61]
	v_mfma_f32_16x16x32_bf16 v[34:37], v[174:177], v[190:193], v[34:37]
	v_mfma_f32_16x16x32_bf16 v[66:69], v[182:185], v[190:193], v[66:69]


; #define LDA(dst, b, h) for (int m = 0; m < 4; ++m) for (int k = 0; k < 2; ++k) \
;     dst[m][k] = *reinterpret_cast<const bf16x8*>((char*)SA(b, h) + a_thr + (m * 2 + k) * 1024)
; #define MMA(ai, bj, At, Btf) do { __builtin_amdgcn_s_setprio(1); \
;     for (int m = 0; m < 4; ++m) for (int n = 0; n < 2; ++n) for (int k = 0; k < 2; ++k) \
;       acc[ai][bj][m][n] = __builtin_amdgcn_mfma_f32_16x16x32_bf16(Btf[n][k], At[m][k], acc[ai][bj][m][n], 0, 0, 0); \
;     __builtin_amdgcn_s_setprio(0); } while (0)
; #define WAIT_L(n) asm volatile("s_waitcnt lgkmcnt(" #n ")" ::: "memory")
; #define BAR __builtin_amdgcn_s_barrier()
; template <bool OVL, bool PANEL = false, class Epi>
; __device__ __forceinline__ void gemm_phase(const bf16_t* __restrict__ A, long lda, const bf16_t* __restrict__ Bt, long ldb, int nM, int nN, int K,
;                                            const Epi& epi, bf16_t* shm, int w0) {
;     ...
;       LDA(At, 1, 1); BAR; WAIT_L(0); MMA(1, 0, At, B0); MMA(1, 1, At, B1); BAR; }
	v_mfma_f32_16x16x32_bf16 v[82:85], v[102:105], v[86:89], v[142:145]
	v_mfma_f32_16x16x32_bf16 v[86:89], v[240:243], v[86:89], v[146:149]
	v_mfma_f32_16x16x32_bf16 v[82:85], v[236:239], v[90:93], v[82:85]
	v_mfma_f32_16x16x32_bf16 v[122:125], v[244:247], v[90:93], v[86:89]
	v_mfma_f32_16x16x32_bf16 v[86:89], v[102:105], v[94:97], v[222:225]
	v_mfma_f32_16x16x32_bf16 v[90:93], v[240:243], v[94:97], v[158:161]
	v_mfma_f32_16x16x32_bf16 v[94:97], v[240:243], v[150:153], v[166:169]
	v_mfma_f32_16x16x32_bf16 v[86:89], v[236:239], v[118:121], v[86:89]
	v_mfma_f32_16x16x32_bf16 v[126:129], v[244:247], v[118:121], v[90:93]
	v_mfma_f32_16x16x32_bf16 v[118:121], v[244:247], v[154:157], v[94:97]
	v_mfma_f32_16x16x32_bf16 v[94:97], v[102:105], v[186:189], v[134:137]
	v_mfma_f32_16x16x32_bf16 v[90:93], v[102:105], v[150:153], v[162:165]
	v_mfma_f32_16x16x32_bf16 v[102:105], v[236:239], v[190:193], v[94:97]
	v_mfma_f32_16x16x32_bf16 v[94:97], v[240:243], v[186:189], v[170:173]
	v_mfma_f32_16x16x32_bf16 v[90:93], v[236:239], v[154:157], v[90:93]
	v_mfma_f32_16x16x32_bf16 v[94:97], v[244:247], v[190:193], v[94:97]

; #define LDA(dst, b, h) for (int m = 0; m < 4; ++m) for (int k = 0; k < 2; ++k) \
;     dst[m][k] = *reinterpret_cast<const bf16x8*>((char*)SA(b, h) + a_thr + (m * 2 + k) * 1024)
; #define MMA(ai, bj, At, Btf) do { __builtin_amdgcn_s_setprio(1); \
;     for (int m = 0; m < 4; ++m) for (int n = 0; n < 2; ++n) for (int k = 0; k < 2; ++k) \
;       acc[ai][bj][m][n] = __builtin_amdgcn_mfma_f32_16x16x32_bf16(Btf[n][k], At[m][k], acc[ai][bj][m][n], 0, 0, 0); \
;     __builtin_amdgcn_s_setprio(0); } while (0)
; #define WAIT_L(n) asm volatile("s_waitcnt lgkmcnt(" #n ")" ::: "memory")
; #define BAR __builtin_amdgcn_s_barrier()
; template <bool OVL, bool PANEL = false, class Epi>
; __device__ __forceinline__ void gemm_phase(const bf16_t* __restrict__ A, long lda, const bf16_t* __restrict__ Bt, long ldb, int nM, int nN, int K,
;                                            const Epi& epi, bf16_t* shm, int w0) {
;     ...
;       LDA(At, 1, 1); BAR; WAIT_L(0); MMA(1, 0, At, B0); MMA(1, 1, At, B1); BAR; }
;     if (wr == 0) BAR;
	s_barrier
	s_and_saveexec_b64 s[0:1], s[58:59]
	s_cbranch_execz .LBB0_128
	s_barrier

; #define LDA(dst, b, h) for (int m = 0; m < 4; ++m) for (int k = 0; k < 2; ++k) \
;     dst[m][k] = *reinterpret_cast<const bf16x8*>((char*)SA(b, h) + a_thr + (m * 2 + k) * 1024)
; #define LDB(dst, b, h) for (int n = 0; n < 2; ++n) for (int k = 0; k < 2; ++k) \
;     dst[n][k] = *reinterpret_cast<const bf16x8*>((char*)SB(b, h) + b_thr + (n * 2 + k) * 1024)
; #define MMA(ai, bj, At, Btf) do { __builtin_amdgcn_s_setprio(1); \
;     for (int m = 0; m < 4; ++m) for (int n = 0; n < 2; ++n) for (int k = 0; k < 2; ++k) \
;       acc[ai][bj][m][n] = __builtin_amdgcn_mfma_f32_16x16x32_bf16(Btf[n][k], At[m][k], acc[ai][bj][m][n], 0, 0, 0); \
;     __builtin_amdgcn_s_setprio(0); } while (0)
; #define WAIT_V(n) asm volatile("s_waitcnt vmcnt(" #n ")" ::: "memory")
; #define WAIT_L(n) asm volatile("s_waitcnt lgkmcnt(" #n ")" ::: "memory")
; #define BAR __builtin_amdgcn_s_barrier()
; #define SCHED __builtin_amdgcn_sched_barrier(0)
; template <bool OVL, bool PANEL = false, class Epi>
; __device__ __forceinline__ void gemm_phase(const bf16_t* __restrict__ A, long lda, const bf16_t* __restrict__ Bt, long ldb, int nM, int nN, int K,
;                                            const Epi& epi, bf16_t* shm, int w0) {
;     ...
;     if (wr == 1) BAR;
;     WAIT_V(4); BAR;
;     STAGE(SB(1, 0), Bt, ldb, boff, bcol, 1); STAGE(SA(1, 0), A, lda, aoff, brow, 1); STAGE(SB(1, 1), Bt, ldb, boff, bcol + HALF, 1);
;     WAIT_V(6); BAR;
;     for (int t = 0; t < nt - 2; t += 2) {
;       LDB(B0, 0, 0); SCHED; LDA(At, 0, 0); STAGE(SA(1, 1), A, lda, aoff, brow + HALF, t + 1);
;       WAIT_L(8); BAR; WAIT_L(0); MMA(0, 0, At, B0); BAR; SCHED;
;       LDB(B1, 0, 1); STAGE(SB(0, 0), Bt, ldb, boff, bcol, t + 2);
.LBB0_385:
	s_or_b64 exec, exec, s[6:7]
	s_lshl_b32 s6, s24, 8
	s_ashr_i32 s7, s6, 31
	s_lshl_b32 s2, s25, 8
	s_lshl_b64 s[8:9], s[6:7], 11
	v_readlane_b32 s80, v251, 49
	v_readlane_b32 s81, v251, 50
	s_add_u32 s8, s80, s8
	s_addc_u32 s9, s81, s9
	v_mov_b32_e32 v0, v131
	v_add_u32_e32 v142, s96, v130
	s_waitcnt vmcnt(4)
	s_barrier
	s_mov_b64 s[30:31], 0x80
	v_lshl_add_u64 v[2:3], s[8:9], 0, v[0:1]
	v_readfirstlane_b32 s10, v142
	v_add_u32_e32 v143, 0x2000, v142
	v_lshl_add_u64 v[4:5], v[2:3], 0, s[30:31]
	s_mov_b32 m0, s10
	v_readfirstlane_b32 s10, v143
	v_readlane_b32 s44, v252, 20
	global_load_lds_dwordx4 v[4:5], off
	s_mov_b32 m0, s10
	s_lshl_b64 s[10:11], s[2:3], 11
	v_readlane_b32 s50, v252, 26
	v_readlane_b32 s51, v252, 27
	s_add_u32 s10, s50, s10
	s_mov_b64 s[42:43], 0x20080
	s_addc_u32 s11, s51, s11
	s_or_b32 s28, s6, 0x80
	v_lshl_add_u64 v[2:3], v[2:3], 0, s[42:43]
	v_mov_b32_e32 v0, v131
	v_add_u32_e32 v144, 0x8000, v134
	s_ashr_i32 s29, s28, 31
	global_load_lds_dwordx4 v[2:3], off
	v_readfirstlane_b32 s18, v144
	v_lshl_add_u64 v[2:3], s[10:11], 0, v[0:1]
	v_add_u32_e32 v145, 0xa000, v134
	s_lshl_b64 s[28:29], s[28:29], 11
	v_lshl_add_u64 v[4:5], v[2:3], 0, s[30:31]
	s_mov_b32 m0, s18
	v_readfirstlane_b32 s18, v145
	s_add_u32 s28, s80, s28
	global_load_lds_dwordx4 v[4:5], off
	v_lshl_add_u64 v[2:3], v[2:3], 0, s[42:43]
	s_mov_b32 m0, s18
	s_addc_u32 s29, s81, s29
	v_mov_b32_e32 v0, v131
	v_add_u32_e32 v146, s75, v130
	global_load_lds_dwordx4 v[2:3], off
	v_readfirstlane_b32 s18, v146
	v_lshl_add_u64 v[2:3], s[28:29], 0, v[0:1]
	v_add_u32_e32 v147, 0x2000, v146
	v_lshl_add_u64 v[4:5], v[2:3], 0, s[30:31]
	s_mov_b32 m0, s18
	v_readfirstlane_b32 s18, v147
	global_load_lds_dwordx4 v[4:5], off
	v_lshl_add_u64 v[2:3], v[2:3], 0, s[42:43]
	s_mov_b32 m0, s18
	v_readlane_b32 s45, v252, 21
	global_load_lds_dwordx4 v[2:3], off
	s_waitcnt vmcnt(6)
	s_mov_b32 s18, -2
	s_mov_b64 vcc, 0
	s_waitcnt vmcnt(0)
	s_waitcnt lgkmcnt(0)
	s_mov_b64 s[28:29], 0x40080
	s_mov_b64 s[30:31], 0x40180
	s_mov_b64 s[44:45], 0x60180
	v_readlane_b32 s82, v251, 51
	v_readlane_b32 s83, v251, 52
	v_readlane_b32 s84, v251, 53
	v_readlane_b32 s85, v251, 54
	v_readlane_b32 s86, v251, 55
	v_readlane_b32 s87, v251, 56
	v_readlane_b32 s46, v252, 22
	v_readlane_b32 s47, v252, 23
	v_readlane_b32 s48, v252, 24
	v_readlane_b32 s49, v252, 25
	v_readlane_b32 s52, v252, 28
	v_readlane_b32 s53, v252, 29
	v_readlane_b32 s54, v252, 30
	v_readlane_b32 s55, v252, 31
	v_readlane_b32 s56, v252, 32
	v_readlane_b32 s57, v252, 33
	v_readlane_b32 s58, v252, 34
	v_readlane_b32 s59, v252, 35
	s_barrier
	v_add_u32_e32 v218, s21, v140
	v_readfirstlane_b32 s16, v134
	s_add_u32 s16, s16, 0xc000
	v_readfirstlane_b32 s32, v134
	s_add_u32 s32, s32, 0xe000
	v_add_u32_e32 v219, s33, v140
	v_readfirstlane_b32 s46, v132
	v_readfirstlane_b32 s47, v133
	v_readfirstlane_b32 s48, v134
	v_readfirstlane_b32 s49, v135
	v_readfirstlane_b32 s50, v136
	v_readfirstlane_b32 s51, v137
	v_add_u32_e32 v220, s96, v140
	v_readfirstlane_b32 s52, v138
	v_readfirstlane_b32 s53, v139
	v_add_u32_e32 v221, s75, v140
	v_readfirstlane_b32 s54, v142
	v_readfirstlane_b32 s55, v143
	v_readfirstlane_b32 s56, v144
	v_readfirstlane_b32 s57, v145
	v_readfirstlane_b32 s58, v146
	v_readfirstlane_b32 s59, v147
	v_add_u32_e32 v148, 0xc000, v134
	v_add_u32_e32 v149, 0xe000, v134
	ds_read_b128 v[150:153], v218
	ds_read_b128 v[154:157], v218 offset:1024
	ds_read_b128 v[158:161], v218 offset:2048
	ds_read_b128 v[162:165], v218 offset:3072
	s_add_u32 s42, s10, vcc_lo
	s_addc_u32 s43, s11, vcc_hi
	ds_read_b128 v[166:169], v141
	ds_read_b128 v[170:173], v141 offset:1024
	ds_read_b128 v[174:177], v141 offset:2048
	ds_read_b128 v[178:181], v141 offset:3072
	ds_read_b128 v[182:185], v141 offset:4096
	ds_read_b128 v[186:189], v141 offset:5120
	ds_read_b128 v[190:193], v141 offset:6144
	ds_read_b128 v[194:197], v141 offset:7168
	s_mov_b32 m0, s16
	s_add_u32 s98, s42, s28
	s_addc_u32 s99, s43, s29
	global_load_lds_dwordx4 v131, s[98:99]
	s_mov_b32 m0, s32
	s_add_u32 s98, s42, s36
	s_addc_u32 s99, s43, s37
	global_load_lds_dwordx4 v131, s[98:99]
	s_waitcnt lgkmcnt(8)
	s_waitcnt vmcnt(10)
	s_barrier
	s_waitcnt lgkmcnt(0)
	v_mfma_f32_16x16x32_bf16 v[126:129], v[150:153], v[166:169], 0
	v_mfma_f32_16x16x32_bf16 v[122:125], v[158:161], v[166:169], 0
	v_mfma_f32_16x16x32_bf16 v[118:121], v[150:153], v[174:177], 0
	v_mfma_f32_16x16x32_bf16 v[114:117], v[158:161], v[174:177], 0
	v_mfma_f32_16x16x32_bf16 v[110:113], v[150:153], v[182:185], 0
	v_mfma_f32_16x16x32_bf16 v[106:109], v[158:161], v[182:185], 0
	v_mfma_f32_16x16x32_bf16 v[102:105], v[150:153], v[190:193], 0
	v_mfma_f32_16x16x32_bf16 v[98:101], v[158:161], v[190:193], 0
	v_mfma_f32_16x16x32_bf16 v[126:129], v[154:157], v[170:173], v[126:129]
	v_mfma_f32_16x16x32_bf16 v[122:125], v[162:165], v[170:173], v[122:125]
	v_mfma_f32_16x16x32_bf16 v[118:121], v[154:157], v[178:181], v[118:121]
	v_mfma_f32_16x16x32_bf16 v[114:117], v[162:165], v[178:181], v[114:117]
	v_mfma_f32_16x16x32_bf16 v[110:113], v[154:157], v[186:189], v[110:113]
	v_mfma_f32_16x16x32_bf16 v[106:109], v[162:165], v[186:189], v[106:109]
	v_mfma_f32_16x16x32_bf16 v[102:105], v[154:157], v[194:197], v[102:105]
	v_mfma_f32_16x16x32_bf16 v[98:101], v[162:165], v[194:197], v[98:101]
	s_barrier
	s_add_u32 s66, s8, vcc_lo
	ds_read_b128 v[198:201], v219
	ds_read_b128 v[202:205], v219 offset:1024
	ds_read_b128 v[206:209], v219 offset:2048
	ds_read_b128 v[210:213], v219 offset:3072
	s_addc_u32 s67, s9, vcc_hi
	s_mov_b32 m0, s46
	s_add_u32 s98, s66, s34
	s_addc_u32 s99, s67, s35
	global_load_lds_dwordx4 v131, s[98:99]
	s_mov_b32 m0, s47
	s_add_u32 s98, s66, s64
	s_addc_u32 s99, s67, s65
	global_load_lds_dwordx4 v131, s[98:99]
	s_waitcnt vmcnt(10)
	s_barrier
; #define LDA(dst, b, h) for (int m = 0; m < 4; ++m) for (int k = 0; k < 2; ++k) \
;     dst[m][k] = *reinterpret_cast<const bf16x8*>((char*)SA(b, h) + a_thr + (m * 2 + k) * 1024)
; #define LDB(dst, b, h) for (int n = 0; n < 2; ++n) for (int k = 0; k < 2; ++k) \
;     dst[n][k] = *reinterpret_cast<const bf16x8*>((char*)SB(b, h) + b_thr + (n * 2 + k) * 1024)
; #define MMA(ai, bj, At, Btf) do { __builtin_amdgcn_s_setprio(1); \
;     for (int m = 0; m < 4; ++m) for (int n = 0; n < 2; ++n) for (int k = 0; k < 2; ++k) \
;       acc[ai][bj][m][n] = __builtin_amdgcn_mfma_f32_16x16x32_bf16(Btf[n][k], At[m][k], acc[ai][bj][m][n], 0, 0, 0); \
;     __builtin_amdgcn_s_setprio(0); } while (0)
; #define WAIT_V(n) asm volatile("s_waitcnt vmcnt(" #n ")" ::: "memory")
; #define WAIT_L(n) asm volatile("s_waitcnt lgkmcnt(" #n ")" ::: "memory")
; #define BAR __builtin_amdgcn_s_barrier()
; #define SCHED __builtin_amdgcn_sched_barrier(0)
; template <bool OVL, bool PANEL = false, class Epi>
; __device__ __forceinline__ void gemm_phase(const bf16_t* __restrict__ A, long lda, const bf16_t* __restrict__ Bt, long ldb, int nM, int nN, int K,
;                                            const Epi& epi, bf16_t* shm, int w0) {
;     ...
;       LDB(B1, 0, 1); STAGE(SB(0, 0), Bt, ldb, boff, bcol, t + 2);
;       BAR; WAIT_L(0); MMA(0, 1, At, B1); BAR;
;       LDA(At, 0, 1); STAGE(SA(0, 0), A, lda, aoff, brow, t + 2);
;       BAR; WAIT_L(0); MMA(1, 0, At, B0); BAR; SCHED;
;       STAGE(SB(0, 1), Bt, ldb, boff, bcol + HALF, t + 2);
;       WAIT_V(6); BAR; MMA(1, 1, At, B1); BAR;
;       LDB(B0, 1, 0); SCHED; LDA(At, 1, 0); STAGE(SA(0, 1), A, lda, aoff, brow + HALF, t + 2);
;       WAIT_L(8); BAR; WAIT_L(0); MMA(0, 0, At, B0); BAR; SCHED;
	s_waitcnt lgkmcnt(0)
	v_mfma_f32_16x16x32_bf16 v[94:97], v[198:201], v[166:169], 0
	v_mfma_f32_16x16x32_bf16 v[90:93], v[206:209], v[166:169], 0
	v_mfma_f32_16x16x32_bf16 v[86:89], v[198:201], v[174:177], 0
	v_mfma_f32_16x16x32_bf16 v[82:85], v[206:209], v[174:177], 0
	v_mfma_f32_16x16x32_bf16 v[78:81], v[198:201], v[182:185], 0
	v_mfma_f32_16x16x32_bf16 v[74:77], v[206:209], v[182:185], 0
	v_mfma_f32_16x16x32_bf16 v[70:73], v[198:201], v[190:193], 0
	v_mfma_f32_16x16x32_bf16 v[66:69], v[206:209], v[190:193], 0
	v_mfma_f32_16x16x32_bf16 v[94:97], v[202:205], v[170:173], v[94:97]
	v_mfma_f32_16x16x32_bf16 v[90:93], v[210:213], v[170:173], v[90:93]
	v_mfma_f32_16x16x32_bf16 v[86:89], v[202:205], v[178:181], v[86:89]
	v_mfma_f32_16x16x32_bf16 v[82:85], v[210:213], v[178:181], v[82:85]
	v_mfma_f32_16x16x32_bf16 v[78:81], v[202:205], v[186:189], v[78:81]
	v_mfma_f32_16x16x32_bf16 v[74:77], v[210:213], v[186:189], v[74:77]
	v_mfma_f32_16x16x32_bf16 v[70:73], v[202:205], v[194:197], v[70:73]
	v_mfma_f32_16x16x32_bf16 v[66:69], v[210:213], v[194:197], v[66:69]
	s_barrier
	ds_read_b128 v[166:169], v141 offset:16384
	ds_read_b128 v[170:173], v141 offset:17408
	ds_read_b128 v[174:177], v141 offset:18432
	ds_read_b128 v[178:181], v141 offset:19456
	ds_read_b128 v[182:185], v141 offset:20480
	ds_read_b128 v[186:189], v141 offset:21504
	ds_read_b128 v[190:193], v141 offset:22528
	ds_read_b128 v[194:197], v141 offset:23552
	s_mov_b32 m0, s48
	s_add_u32 s98, s42, s34
	s_addc_u32 s99, s43, s35
	global_load_lds_dwordx4 v131, s[98:99]
	s_mov_b32 m0, s49
	s_add_u32 s98, s42, s64
	s_addc_u32 s99, s43, s65
	global_load_lds_dwordx4 v131, s[98:99]
	s_barrier
	s_waitcnt lgkmcnt(0)
	v_mfma_f32_16x16x32_bf16 v[62:65], v[150:153], v[166:169], 0
	v_mfma_f32_16x16x32_bf16 v[58:61], v[158:161], v[166:169], 0
	v_mfma_f32_16x16x32_bf16 v[54:57], v[150:153], v[174:177], 0
	v_mfma_f32_16x16x32_bf16 v[50:53], v[158:161], v[174:177], 0
	v_mfma_f32_16x16x32_bf16 v[46:49], v[150:153], v[182:185], 0
	v_mfma_f32_16x16x32_bf16 v[42:45], v[158:161], v[182:185], 0
	v_mfma_f32_16x16x32_bf16 v[38:41], v[150:153], v[190:193], 0
	v_mfma_f32_16x16x32_bf16 v[34:37], v[158:161], v[190:193], 0
	v_mfma_f32_16x16x32_bf16 v[62:65], v[154:157], v[170:173], v[62:65]
	v_mfma_f32_16x16x32_bf16 v[58:61], v[162:165], v[170:173], v[58:61]
	v_mfma_f32_16x16x32_bf16 v[54:57], v[154:157], v[178:181], v[54:57]
	v_mfma_f32_16x16x32_bf16 v[50:53], v[162:165], v[178:181], v[50:53]
	v_mfma_f32_16x16x32_bf16 v[46:49], v[154:157], v[186:189], v[46:49]
	v_mfma_f32_16x16x32_bf16 v[42:45], v[162:165], v[186:189], v[42:45]
	v_mfma_f32_16x16x32_bf16 v[38:41], v[154:157], v[194:197], v[38:41]
	v_mfma_f32_16x16x32_bf16 v[34:37], v[162:165], v[194:197], v[34:37]
	s_barrier
	s_mov_b32 m0, s50
	s_add_u32 s98, s66, s68
	s_addc_u32 s99, s67, s69
	global_load_lds_dwordx4 v131, s[98:99]
	s_mov_b32 m0, s51
	s_add_u32 s98, s66, s70
	s_addc_u32 s99, s67, s71
	global_load_lds_dwordx4 v131, s[98:99]
	s_waitcnt vmcnt(10)
	s_barrier
	v_mfma_f32_16x16x32_bf16 v[30:33], v[198:201], v[166:169], 0
	v_mfma_f32_16x16x32_bf16 v[26:29], v[206:209], v[166:169], 0
	v_mfma_f32_16x16x32_bf16 v[22:25], v[198:201], v[174:177], 0
	v_mfma_f32_16x16x32_bf16 v[18:21], v[206:209], v[174:177], 0
	v_mfma_f32_16x16x32_bf16 v[14:17], v[198:201], v[182:185], 0
	v_mfma_f32_16x16x32_bf16 v[10:13], v[206:209], v[182:185], 0
	v_mfma_f32_16x16x32_bf16 v[6:9], v[198:201], v[190:193], 0
	v_mfma_f32_16x16x32_bf16 v[2:5], v[206:209], v[190:193], 0
	v_mfma_f32_16x16x32_bf16 v[30:33], v[202:205], v[170:173], v[30:33]
	v_mfma_f32_16x16x32_bf16 v[26:29], v[210:213], v[170:173], v[26:29]
	v_mfma_f32_16x16x32_bf16 v[22:25], v[202:205], v[178:181], v[22:25]
	v_mfma_f32_16x16x32_bf16 v[18:21], v[210:213], v[178:181], v[18:21]
	v_mfma_f32_16x16x32_bf16 v[14:17], v[202:205], v[186:189], v[14:17]
	v_mfma_f32_16x16x32_bf16 v[10:13], v[210:213], v[186:189], v[10:13]
	v_mfma_f32_16x16x32_bf16 v[6:9], v[202:205], v[194:197], v[6:9]
	v_mfma_f32_16x16x32_bf16 v[2:5], v[210:213], v[194:197], v[2:5]
	s_barrier
	ds_read_b128 v[150:153], v220
	ds_read_b128 v[154:157], v220 offset:1024
	ds_read_b128 v[158:161], v220 offset:2048
	ds_read_b128 v[162:165], v220 offset:3072
	ds_read_b128 v[166:169], v141 offset:32768
	ds_read_b128 v[170:173], v141 offset:33792
	ds_read_b128 v[174:177], v141 offset:34816
	ds_read_b128 v[178:181], v141 offset:35840
	ds_read_b128 v[182:185], v141 offset:36864
	ds_read_b128 v[186:189], v141 offset:37888
	ds_read_b128 v[190:193], v141 offset:38912
	ds_read_b128 v[194:197], v141 offset:39936
	s_mov_b32 m0, s52
	s_add_u32 s98, s42, s68
	s_addc_u32 s99, s43, s69
	global_load_lds_dwordx4 v131, s[98:99]
	s_mov_b32 m0, s53
	s_add_u32 s98, s42, s70
	s_addc_u32 s99, s43, s71
	global_load_lds_dwordx4 v131, s[98:99]
	s_waitcnt lgkmcnt(8)
	s_waitcnt vmcnt(10)
	s_barrier
	s_waitcnt lgkmcnt(0)
	v_mfma_f32_16x16x32_bf16 v[126:129], v[150:153], v[166:169], v[126:129]
	v_mfma_f32_16x16x32_bf16 v[122:125], v[158:161], v[166:169], v[122:125]
	v_mfma_f32_16x16x32_bf16 v[118:121], v[150:153], v[174:177], v[118:121]
	v_mfma_f32_16x16x32_bf16 v[114:117], v[158:161], v[174:177], v[114:117]
	v_mfma_f32_16x16x32_bf16 v[110:113], v[150:153], v[182:185], v[110:113]
	v_mfma_f32_16x16x32_bf16 v[106:109], v[158:161], v[182:185], v[106:109]
	v_mfma_f32_16x16x32_bf16 v[102:105], v[150:153], v[190:193], v[102:105]
	v_mfma_f32_16x16x32_bf16 v[98:101], v[158:161], v[190:193], v[98:101]
	v_mfma_f32_16x16x32_bf16 v[126:129], v[154:157], v[170:173], v[126:129]
	v_mfma_f32_16x16x32_bf16 v[122:125], v[162:165], v[170:173], v[122:125]
	v_mfma_f32_16x16x32_bf16 v[118:121], v[154:157], v[178:181], v[118:121]
	v_mfma_f32_16x16x32_bf16 v[114:117], v[162:165], v[178:181], v[114:117]
	v_mfma_f32_16x16x32_bf16 v[110:113], v[154:157], v[186:189], v[110:113]
	v_mfma_f32_16x16x32_bf16 v[106:109], v[162:165], v[186:189], v[106:109]
	v_mfma_f32_16x16x32_bf16 v[102:105], v[154:157], v[194:197], v[102:105]
	v_mfma_f32_16x16x32_bf16 v[98:101], v[162:165], v[194:197], v[98:101]
	s_barrier
; #define LDA(dst, b, h) for (int m = 0; m < 4; ++m) for (int k = 0; k < 2; ++k) \
;     dst[m][k] = *reinterpret_cast<const bf16x8*>((char*)SA(b, h) + a_thr + (m * 2 + k) * 1024)
; #define LDB(dst, b, h) for (int n = 0; n < 2; ++n) for (int k = 0; k < 2; ++k) \
;     dst[n][k] = *reinterpret_cast<const bf16x8*>((char*)SB(b, h) + b_thr + (n * 2 + k) * 1024)
; #define MMA(ai, bj, At, Btf) do { __builtin_amdgcn_s_setprio(1); \
;     for (int m = 0; m < 4; ++m) for (int n = 0; n < 2; ++n) for (int k = 0; k < 2; ++k) \
;       acc[ai][bj][m][n] = __builtin_amdgcn_mfma_f32_16x16x32_bf16(Btf[n][k], At[m][k], acc[ai][bj][m][n], 0, 0, 0); \
;     __builtin_amdgcn_s_setprio(0); } while (0)
; #define WAIT_V(n) asm volatile("s_waitcnt vmcnt(" #n ")" ::: "memory")
; #define WAIT_L(n) asm volatile("s_waitcnt lgkmcnt(" #n ")" ::: "memory")
; #define BAR __builtin_amdgcn_s_barrier()
; #define SCHED __builtin_amdgcn_sched_barrier(0)
; template <bool OVL, bool PANEL = false, class Epi>
; __device__ __forceinline__ void gemm_phase(const bf16_t* __restrict__ A, long lda, const bf16_t* __restrict__ Bt, long ldb, int nM, int nN, int K,
;                                            const Epi& epi, bf16_t* shm, int w0) {
;     ...
;       LDB(B1, 1, 1); STAGE(SB(1, 0), Bt, ldb, boff, bcol, t + 3);
;       BAR; WAIT_L(0); MMA(0, 1, At, B1); BAR;
;       LDA(At, 1, 1); STAGE(SA(1, 0), A, lda, aoff, brow, t + 3);
;       BAR; WAIT_L(0); MMA(1, 0, At, B0); BAR; SCHED;
;       STAGE(SB(1, 1), Bt, ldb, boff, bcol + HALF, t + 3);
;       WAIT_V(6); BAR; MMA(1, 1, At, B1); BAR;
	ds_read_b128 v[198:201], v221
	ds_read_b128 v[202:205], v221 offset:1024
	ds_read_b128 v[206:209], v221 offset:2048
	ds_read_b128 v[210:213], v221 offset:3072
	s_mov_b32 m0, s54
	s_add_u32 s98, s66, s94
	s_addc_u32 s99, s67, s95
	global_load_lds_dwordx4 v131, s[98:99]
	s_mov_b32 m0, s55
	s_add_u32 s98, s66, s72
	s_addc_u32 s99, s67, s73
	global_load_lds_dwordx4 v131, s[98:99]
	s_waitcnt vmcnt(10)
	s_barrier
	s_waitcnt lgkmcnt(0)
	v_mfma_f32_16x16x32_bf16 v[94:97], v[198:201], v[166:169], v[94:97]
	v_mfma_f32_16x16x32_bf16 v[90:93], v[206:209], v[166:169], v[90:93]
	v_mfma_f32_16x16x32_bf16 v[86:89], v[198:201], v[174:177], v[86:89]
	v_mfma_f32_16x16x32_bf16 v[82:85], v[206:209], v[174:177], v[82:85]
	v_mfma_f32_16x16x32_bf16 v[78:81], v[198:201], v[182:185], v[78:81]
	v_mfma_f32_16x16x32_bf16 v[74:77], v[206:209], v[182:185], v[74:77]
	v_mfma_f32_16x16x32_bf16 v[70:73], v[198:201], v[190:193], v[70:73]
	v_mfma_f32_16x16x32_bf16 v[66:69], v[206:209], v[190:193], v[66:69]
	v_mfma_f32_16x16x32_bf16 v[94:97], v[202:205], v[170:173], v[94:97]
	v_mfma_f32_16x16x32_bf16 v[90:93], v[210:213], v[170:173], v[90:93]
	v_mfma_f32_16x16x32_bf16 v[86:89], v[202:205], v[178:181], v[86:89]
	v_mfma_f32_16x16x32_bf16 v[82:85], v[210:213], v[178:181], v[82:85]
	v_mfma_f32_16x16x32_bf16 v[78:81], v[202:205], v[186:189], v[78:81]
	v_mfma_f32_16x16x32_bf16 v[74:77], v[210:213], v[186:189], v[74:77]
	v_mfma_f32_16x16x32_bf16 v[70:73], v[202:205], v[194:197], v[70:73]
	v_mfma_f32_16x16x32_bf16 v[66:69], v[210:213], v[194:197], v[66:69]
	s_barrier
	ds_read_b128 v[166:169], v141 offset:49152
	ds_read_b128 v[170:173], v141 offset:50176
	ds_read_b128 v[174:177], v141 offset:51200
	ds_read_b128 v[178:181], v141 offset:52224
	ds_read_b128 v[182:185], v141 offset:53248
	ds_read_b128 v[186:189], v141 offset:54272
	ds_read_b128 v[190:193], v141 offset:55296
	ds_read_b128 v[194:197], v141 offset:56320
	s_mov_b32 m0, s56
	s_add_u32 s98, s42, s94
	s_addc_u32 s99, s43, s95
	global_load_lds_dwordx4 v131, s[98:99]
	s_mov_b32 m0, s57
	s_add_u32 s98, s42, s72
	s_addc_u32 s99, s43, s73
	global_load_lds_dwordx4 v131, s[98:99]
	s_barrier
	s_waitcnt lgkmcnt(0)
	v_mfma_f32_16x16x32_bf16 v[62:65], v[150:153], v[166:169], v[62:65]
	v_mfma_f32_16x16x32_bf16 v[58:61], v[158:161], v[166:169], v[58:61]
	v_mfma_f32_16x16x32_bf16 v[54:57], v[150:153], v[174:177], v[54:57]
	v_mfma_f32_16x16x32_bf16 v[50:53], v[158:161], v[174:177], v[50:53]
	v_mfma_f32_16x16x32_bf16 v[46:49], v[150:153], v[182:185], v[46:49]
	v_mfma_f32_16x16x32_bf16 v[42:45], v[158:161], v[182:185], v[42:45]
	v_mfma_f32_16x16x32_bf16 v[38:41], v[150:153], v[190:193], v[38:41]
	v_mfma_f32_16x16x32_bf16 v[34:37], v[158:161], v[190:193], v[34:37]
	v_mfma_f32_16x16x32_bf16 v[62:65], v[154:157], v[170:173], v[62:65]
	v_mfma_f32_16x16x32_bf16 v[58:61], v[162:165], v[170:173], v[58:61]
	v_mfma_f32_16x16x32_bf16 v[54:57], v[154:157], v[178:181], v[54:57]
	v_mfma_f32_16x16x32_bf16 v[50:53], v[162:165], v[178:181], v[50:53]
	v_mfma_f32_16x16x32_bf16 v[46:49], v[154:157], v[186:189], v[46:49]
	v_mfma_f32_16x16x32_bf16 v[42:45], v[162:165], v[186:189], v[42:45]
	v_mfma_f32_16x16x32_bf16 v[38:41], v[154:157], v[194:197], v[38:41]
	v_mfma_f32_16x16x32_bf16 v[34:37], v[162:165], v[194:197], v[34:37]
	s_barrier
	s_mov_b32 m0, s58
	s_add_u32 s98, s66, s30
	s_addc_u32 s99, s67, s31
	global_load_lds_dwordx4 v131, s[98:99]
	s_mov_b32 m0, s59
	s_add_u32 s98, s66, s44
	s_addc_u32 s99, s67, s45
	global_load_lds_dwordx4 v131, s[98:99]
	s_add_i32 s18, s18, 2
	s_add_u32 vcc_lo, vcc_lo, 0x100
	s_addc_u32 vcc_hi, vcc_hi, 0
	s_cmp_lt_u32 s18, 12
	s_waitcnt vmcnt(10)
	s_barrier
	v_mfma_f32_16x16x32_bf16 v[30:33], v[198:201], v[166:169], v[30:33]
	v_mfma_f32_16x16x32_bf16 v[26:29], v[206:209], v[166:169], v[26:29]
	v_mfma_f32_16x16x32_bf16 v[22:25], v[198:201], v[174:177], v[22:25]
	v_mfma_f32_16x16x32_bf16 v[18:21], v[206:209], v[174:177], v[18:21]
	v_mfma_f32_16x16x32_bf16 v[14:17], v[198:201], v[182:185], v[14:17]
	v_mfma_f32_16x16x32_bf16 v[10:13], v[206:209], v[182:185], v[10:13]
	v_mfma_f32_16x16x32_bf16 v[6:9], v[198:201], v[190:193], v[6:9]
	v_mfma_f32_16x16x32_bf16 v[2:5], v[206:209], v[190:193], v[2:5]
	v_mfma_f32_16x16x32_bf16 v[30:33], v[202:205], v[170:173], v[30:33]
	v_mfma_f32_16x16x32_bf16 v[26:29], v[210:213], v[170:173], v[26:29]
	v_mfma_f32_16x16x32_bf16 v[22:25], v[202:205], v[178:181], v[22:25]
	v_mfma_f32_16x16x32_bf16 v[18:21], v[210:213], v[178:181], v[18:21]
	v_mfma_f32_16x16x32_bf16 v[14:17], v[202:205], v[186:189], v[14:17]
	v_mfma_f32_16x16x32_bf16 v[10:13], v[210:213], v[186:189], v[10:13]
	v_mfma_f32_16x16x32_bf16 v[6:9], v[202:205], v[194:197], v[6:9]
	v_mfma_f32_16x16x32_bf16 v[2:5], v[210:213], v[194:197], v[2:5]
	s_barrier
; #define LDA(dst, b, h) for (int m = 0; m < 4; ++m) for (int k = 0; k < 2; ++k) \
;     dst[m][k] = *reinterpret_cast<const bf16x8*>((char*)SA(b, h) + a_thr + (m * 2 + k) * 1024)
; #define LDB(dst, b, h) for (int n = 0; n < 2; ++n) for (int k = 0; k < 2; ++k) \
;     dst[n][k] = *reinterpret_cast<const bf16x8*>((char*)SB(b, h) + b_thr + (n * 2 + k) * 1024)
; #define MMA(ai, bj, At, Btf) do { __builtin_amdgcn_s_setprio(1); \
;     for (int m = 0; m < 4; ++m) for (int n = 0; n < 2; ++n) for (int k = 0; k < 2; ++k) \
;       acc[ai][bj][m][n] = __builtin_amdgcn_mfma_f32_16x16x32_bf16(Btf[n][k], At[m][k], acc[ai][bj][m][n], 0, 0, 0); \
;     __builtin_amdgcn_s_setprio(0); } while (0)
; #define WAIT_L(n) asm volatile("s_waitcnt lgkmcnt(" #n ")" ::: "memory")
; #define BAR __builtin_amdgcn_s_barrier()
; #define SCHED __builtin_amdgcn_sched_barrier(0)
; template <bool OVL, bool PANEL = false, class Epi>
; __device__ __forceinline__ void gemm_phase(const bf16_t* __restrict__ A, long lda, const bf16_t* __restrict__ Bt, long ldb, int nM, int nN, int K,
;                                            const Epi& epi, bf16_t* shm, int w0) {
;     ...
;       LDB(B0, 0, 0); SCHED; LDA(At, 0, 0); STAGE(SA(1, 1), A, lda, aoff, brow + HALF, t + 1);
;       WAIT_L(8); BAR; WAIT_L(0); MMA(0, 0, At, B0); BAR; SCHED;
;       LDB(B1, 0, 1); STAGE(SB(0, 0), Bt, ldb, boff, bcol, t + 2);
;       BAR; WAIT_L(0); MMA(0, 1, At, B1); BAR;
;       LDA(At, 0, 1); STAGE(SA(0, 0), A, lda, aoff, brow, t + 2);
;       BAR; WAIT_L(0); MMA(1, 0, At, B0); BAR; SCHED;
;       STAGE(SB(0, 1), Bt, ldb, boff, bcol + HALF, t + 2);
.LBB0_386:
	ds_read_b128 v[150:153], v218
	ds_read_b128 v[154:157], v218 offset:1024
	ds_read_b128 v[158:161], v218 offset:2048
	ds_read_b128 v[162:165], v218 offset:3072
	s_add_u32 s42, s10, vcc_lo
	s_addc_u32 s43, s11, vcc_hi
	ds_read_b128 v[166:169], v141
	ds_read_b128 v[170:173], v141 offset:1024
	ds_read_b128 v[174:177], v141 offset:2048
	ds_read_b128 v[178:181], v141 offset:3072
	ds_read_b128 v[182:185], v141 offset:4096
	ds_read_b128 v[186:189], v141 offset:5120
	ds_read_b128 v[190:193], v141 offset:6144
	ds_read_b128 v[194:197], v141 offset:7168
	s_mov_b32 m0, s16
	s_add_u32 s98, s42, s28
	s_addc_u32 s99, s43, s29
	global_load_lds_dwordx4 v131, s[98:99]
	s_mov_b32 m0, s32
	s_add_u32 s98, s42, s36
	s_addc_u32 s99, s43, s37
	global_load_lds_dwordx4 v131, s[98:99]
	s_waitcnt lgkmcnt(8)
	s_waitcnt vmcnt(10)
	s_barrier
	s_waitcnt lgkmcnt(0)
	v_mfma_f32_16x16x32_bf16 v[126:129], v[150:153], v[166:169], v[126:129]
	v_mfma_f32_16x16x32_bf16 v[122:125], v[158:161], v[166:169], v[122:125]
	v_mfma_f32_16x16x32_bf16 v[118:121], v[150:153], v[174:177], v[118:121]
	v_mfma_f32_16x16x32_bf16 v[114:117], v[158:161], v[174:177], v[114:117]
	v_mfma_f32_16x16x32_bf16 v[110:113], v[150:153], v[182:185], v[110:113]
	v_mfma_f32_16x16x32_bf16 v[106:109], v[158:161], v[182:185], v[106:109]
	v_mfma_f32_16x16x32_bf16 v[102:105], v[150:153], v[190:193], v[102:105]
	v_mfma_f32_16x16x32_bf16 v[98:101], v[158:161], v[190:193], v[98:101]
	v_mfma_f32_16x16x32_bf16 v[126:129], v[154:157], v[170:173], v[126:129]
	v_mfma_f32_16x16x32_bf16 v[122:125], v[162:165], v[170:173], v[122:125]
	v_mfma_f32_16x16x32_bf16 v[118:121], v[154:157], v[178:181], v[118:121]
	v_mfma_f32_16x16x32_bf16 v[114:117], v[162:165], v[178:181], v[114:117]
	v_mfma_f32_16x16x32_bf16 v[110:113], v[154:157], v[186:189], v[110:113]
	v_mfma_f32_16x16x32_bf16 v[106:109], v[162:165], v[186:189], v[106:109]
	v_mfma_f32_16x16x32_bf16 v[102:105], v[154:157], v[194:197], v[102:105]
	v_mfma_f32_16x16x32_bf16 v[98:101], v[162:165], v[194:197], v[98:101]
	s_barrier
	s_add_u32 s66, s8, vcc_lo
	ds_read_b128 v[198:201], v219
	ds_read_b128 v[202:205], v219 offset:1024
	ds_read_b128 v[206:209], v219 offset:2048
	ds_read_b128 v[210:213], v219 offset:3072
	s_addc_u32 s67, s9, vcc_hi
	s_mov_b32 m0, s46
	s_add_u32 s98, s66, s34
	s_addc_u32 s99, s67, s35
	global_load_lds_dwordx4 v131, s[98:99]
	s_mov_b32 m0, s47
	s_add_u32 s98, s66, s64
	s_addc_u32 s99, s67, s65
	global_load_lds_dwordx4 v131, s[98:99]
	s_waitcnt vmcnt(10)
	s_barrier
	s_waitcnt lgkmcnt(0)
	v_mfma_f32_16x16x32_bf16 v[94:97], v[198:201], v[166:169], v[94:97]
	v_mfma_f32_16x16x32_bf16 v[90:93], v[206:209], v[166:169], v[90:93]
	v_mfma_f32_16x16x32_bf16 v[86:89], v[198:201], v[174:177], v[86:89]
	v_mfma_f32_16x16x32_bf16 v[82:85], v[206:209], v[174:177], v[82:85]
	v_mfma_f32_16x16x32_bf16 v[78:81], v[198:201], v[182:185], v[78:81]
	v_mfma_f32_16x16x32_bf16 v[74:77], v[206:209], v[182:185], v[74:77]
	v_mfma_f32_16x16x32_bf16 v[70:73], v[198:201], v[190:193], v[70:73]
	v_mfma_f32_16x16x32_bf16 v[66:69], v[206:209], v[190:193], v[66:69]
	v_mfma_f32_16x16x32_bf16 v[94:97], v[202:205], v[170:173], v[94:97]
	v_mfma_f32_16x16x32_bf16 v[90:93], v[210:213], v[170:173], v[90:93]
	v_mfma_f32_16x16x32_bf16 v[86:89], v[202:205], v[178:181], v[86:89]
	v_mfma_f32_16x16x32_bf16 v[82:85], v[210:213], v[178:181], v[82:85]
	v_mfma_f32_16x16x32_bf16 v[78:81], v[202:205], v[186:189], v[78:81]
	v_mfma_f32_16x16x32_bf16 v[74:77], v[210:213], v[186:189], v[74:77]
	v_mfma_f32_16x16x32_bf16 v[70:73], v[202:205], v[194:197], v[70:73]
	v_mfma_f32_16x16x32_bf16 v[66:69], v[210:213], v[194:197], v[66:69]
	s_barrier
	ds_read_b128 v[166:169], v141 offset:16384
	ds_read_b128 v[170:173], v141 offset:17408
	ds_read_b128 v[174:177], v141 offset:18432
	ds_read_b128 v[178:181], v141 offset:19456
	ds_read_b128 v[182:185], v141 offset:20480
	ds_read_b128 v[186:189], v141 offset:21504
	ds_read_b128 v[190:193], v141 offset:22528
	ds_read_b128 v[194:197], v141 offset:23552
	s_mov_b32 m0, s48
	s_add_u32 s98, s42, s34
	s_addc_u32 s99, s43, s35
	global_load_lds_dwordx4 v131, s[98:99]
	s_mov_b32 m0, s49
	s_add_u32 s98, s42, s64
	s_addc_u32 s99, s43, s65
	global_load_lds_dwordx4 v131, s[98:99]
	s_barrier
	s_waitcnt lgkmcnt(0)
	v_mfma_f32_16x16x32_bf16 v[62:65], v[150:153], v[166:169], v[62:65]
	v_mfma_f32_16x16x32_bf16 v[58:61], v[158:161], v[166:169], v[58:61]
	v_mfma_f32_16x16x32_bf16 v[54:57], v[150:153], v[174:177], v[54:57]
	v_mfma_f32_16x16x32_bf16 v[50:53], v[158:161], v[174:177], v[50:53]
	v_mfma_f32_16x16x32_bf16 v[46:49], v[150:153], v[182:185], v[46:49]
	v_mfma_f32_16x16x32_bf16 v[42:45], v[158:161], v[182:185], v[42:45]
	v_mfma_f32_16x16x32_bf16 v[38:41], v[150:153], v[190:193], v[38:41]
	v_mfma_f32_16x16x32_bf16 v[34:37], v[158:161], v[190:193], v[34:37]
	v_mfma_f32_16x16x32_bf16 v[62:65], v[154:157], v[170:173], v[62:65]
	v_mfma_f32_16x16x32_bf16 v[58:61], v[162:165], v[170:173], v[58:61]
	v_mfma_f32_16x16x32_bf16 v[54:57], v[154:157], v[178:181], v[54:57]
	v_mfma_f32_16x16x32_bf16 v[50:53], v[162:165], v[178:181], v[50:53]
	v_mfma_f32_16x16x32_bf16 v[46:49], v[154:157], v[186:189], v[46:49]
	v_mfma_f32_16x16x32_bf16 v[42:45], v[162:165], v[186:189], v[42:45]
	v_mfma_f32_16x16x32_bf16 v[38:41], v[154:157], v[194:197], v[38:41]
	v_mfma_f32_16x16x32_bf16 v[34:37], v[162:165], v[194:197], v[34:37]
	s_barrier
	s_mov_b32 m0, s50
	s_add_u32 s98, s66, s68
	s_addc_u32 s99, s67, s69
	global_load_lds_dwordx4 v131, s[98:99]
	s_mov_b32 m0, s51
	s_add_u32 s98, s66, s70
	s_addc_u32 s99, s67, s71
	global_load_lds_dwordx4 v131, s[98:99]
	s_waitcnt vmcnt(10)
	s_barrier
; #define LDA(dst, b, h) for (int m = 0; m < 4; ++m) for (int k = 0; k < 2; ++k) \
;     dst[m][k] = *reinterpret_cast<const bf16x8*>((char*)SA(b, h) + a_thr + (m * 2 + k) * 1024)
; #define LDB(dst, b, h) for (int n = 0; n < 2; ++n) for (int k = 0; k < 2; ++k) \
;     dst[n][k] = *reinterpret_cast<const bf16x8*>((char*)SB(b, h) + b_thr + (n * 2 + k) * 1024)
; #define MMA(ai, bj, At, Btf) do { __builtin_amdgcn_s_setprio(1); \
;     for (int m = 0; m < 4; ++m) for (int n = 0; n < 2; ++n) for (int k = 0; k < 2; ++k) \
;       acc[ai][bj][m][n] = __builtin_amdgcn_mfma_f32_16x16x32_bf16(Btf[n][k], At[m][k], acc[ai][bj][m][n], 0, 0, 0); \
;     __builtin_amdgcn_s_setprio(0); } while (0)
; #define WAIT_V(n) asm volatile("s_waitcnt vmcnt(" #n ")" ::: "memory")
; #define WAIT_L(n) asm volatile("s_waitcnt lgkmcnt(" #n ")" ::: "memory")
; #define BAR __builtin_amdgcn_s_barrier()
; #define SCHED __builtin_amdgcn_sched_barrier(0)
; template <bool OVL, bool PANEL = false, class Epi>
; __device__ __forceinline__ void gemm_phase(const bf16_t* __restrict__ A, long lda, const bf16_t* __restrict__ Bt, long ldb, int nM, int nN, int K,
;                                            const Epi& epi, bf16_t* shm, int w0) {
;     ...
;       WAIT_V(6); BAR; MMA(1, 1, At, B1); BAR;
;       LDB(B0, 1, 0); SCHED; LDA(At, 1, 0); STAGE(SA(0, 1), A, lda, aoff, brow + HALF, t + 2);
;       WAIT_L(8); BAR; WAIT_L(0); MMA(0, 0, At, B0); BAR; SCHED;
;       LDB(B1, 1, 1); STAGE(SB(1, 0), Bt, ldb, boff, bcol, t + 3);
;       BAR; WAIT_L(0); MMA(0, 1, At, B1); BAR;
	v_mfma_f32_16x16x32_bf16 v[30:33], v[198:201], v[166:169], v[30:33]
	v_mfma_f32_16x16x32_bf16 v[26:29], v[206:209], v[166:169], v[26:29]
	v_mfma_f32_16x16x32_bf16 v[22:25], v[198:201], v[174:177], v[22:25]
	v_mfma_f32_16x16x32_bf16 v[18:21], v[206:209], v[174:177], v[18:21]
	v_mfma_f32_16x16x32_bf16 v[14:17], v[198:201], v[182:185], v[14:17]
	v_mfma_f32_16x16x32_bf16 v[10:13], v[206:209], v[182:185], v[10:13]
	v_mfma_f32_16x16x32_bf16 v[6:9], v[198:201], v[190:193], v[6:9]
	v_mfma_f32_16x16x32_bf16 v[2:5], v[206:209], v[190:193], v[2:5]
	v_mfma_f32_16x16x32_bf16 v[30:33], v[202:205], v[170:173], v[30:33]
	v_mfma_f32_16x16x32_bf16 v[26:29], v[210:213], v[170:173], v[26:29]
	v_mfma_f32_16x16x32_bf16 v[22:25], v[202:205], v[178:181], v[22:25]
	v_mfma_f32_16x16x32_bf16 v[18:21], v[210:213], v[178:181], v[18:21]
	v_mfma_f32_16x16x32_bf16 v[14:17], v[202:205], v[186:189], v[14:17]
	v_mfma_f32_16x16x32_bf16 v[10:13], v[210:213], v[186:189], v[10:13]
	v_mfma_f32_16x16x32_bf16 v[6:9], v[202:205], v[194:197], v[6:9]
	v_mfma_f32_16x16x32_bf16 v[2:5], v[210:213], v[194:197], v[2:5]
	s_barrier
	ds_read_b128 v[150:153], v220
	ds_read_b128 v[154:157], v220 offset:1024
	ds_read_b128 v[158:161], v220 offset:2048
	ds_read_b128 v[162:165], v220 offset:3072
	ds_read_b128 v[166:169], v141 offset:32768
	ds_read_b128 v[170:173], v141 offset:33792
	ds_read_b128 v[174:177], v141 offset:34816
	ds_read_b128 v[178:181], v141 offset:35840
	ds_read_b128 v[182:185], v141 offset:36864
	ds_read_b128 v[186:189], v141 offset:37888
	ds_read_b128 v[190:193], v141 offset:38912
	ds_read_b128 v[194:197], v141 offset:39936
	s_mov_b32 m0, s52
	s_add_u32 s98, s42, s68
	s_addc_u32 s99, s43, s69
	global_load_lds_dwordx4 v131, s[98:99]
	s_mov_b32 m0, s53
	s_add_u32 s98, s42, s70
	s_addc_u32 s99, s43, s71
	global_load_lds_dwordx4 v131, s[98:99]
	s_waitcnt lgkmcnt(8)
	s_waitcnt vmcnt(10)
	s_barrier
	s_waitcnt lgkmcnt(0)
	v_mfma_f32_16x16x32_bf16 v[126:129], v[150:153], v[166:169], v[126:129]
	v_mfma_f32_16x16x32_bf16 v[122:125], v[158:161], v[166:169], v[122:125]
	v_mfma_f32_16x16x32_bf16 v[118:121], v[150:153], v[174:177], v[118:121]
	v_mfma_f32_16x16x32_bf16 v[114:117], v[158:161], v[174:177], v[114:117]
	v_mfma_f32_16x16x32_bf16 v[110:113], v[150:153], v[182:185], v[110:113]
	v_mfma_f32_16x16x32_bf16 v[106:109], v[158:161], v[182:185], v[106:109]
	v_mfma_f32_16x16x32_bf16 v[102:105], v[150:153], v[190:193], v[102:105]
	v_mfma_f32_16x16x32_bf16 v[98:101], v[158:161], v[190:193], v[98:101]
	v_mfma_f32_16x16x32_bf16 v[126:129], v[154:157], v[170:173], v[126:129]
	v_mfma_f32_16x16x32_bf16 v[122:125], v[162:165], v[170:173], v[122:125]
	v_mfma_f32_16x16x32_bf16 v[118:121], v[154:157], v[178:181], v[118:121]
	v_mfma_f32_16x16x32_bf16 v[114:117], v[162:165], v[178:181], v[114:117]
	v_mfma_f32_16x16x32_bf16 v[110:113], v[154:157], v[186:189], v[110:113]
	v_mfma_f32_16x16x32_bf16 v[106:109], v[162:165], v[186:189], v[106:109]
	v_mfma_f32_16x16x32_bf16 v[102:105], v[154:157], v[194:197], v[102:105]
	v_mfma_f32_16x16x32_bf16 v[98:101], v[162:165], v[194:197], v[98:101]
	s_barrier
	ds_read_b128 v[198:201], v221
	ds_read_b128 v[202:205], v221 offset:1024
	ds_read_b128 v[206:209], v221 offset:2048
	ds_read_b128 v[210:213], v221 offset:3072
	s_mov_b32 m0, s54
	s_add_u32 s98, s66, s94
	s_addc_u32 s99, s67, s95
	global_load_lds_dwordx4 v131, s[98:99]
	s_mov_b32 m0, s55
	s_add_u32 s98, s66, s72
	s_addc_u32 s99, s67, s73
	global_load_lds_dwordx4 v131, s[98:99]
	s_waitcnt vmcnt(10)
	s_barrier
	s_waitcnt lgkmcnt(0)
	v_mfma_f32_16x16x32_bf16 v[94:97], v[198:201], v[166:169], v[94:97]
	v_mfma_f32_16x16x32_bf16 v[90:93], v[206:209], v[166:169], v[90:93]
	v_mfma_f32_16x16x32_bf16 v[86:89], v[198:201], v[174:177], v[86:89]
	v_mfma_f32_16x16x32_bf16 v[82:85], v[206:209], v[174:177], v[82:85]
	v_mfma_f32_16x16x32_bf16 v[78:81], v[198:201], v[182:185], v[78:81]
	v_mfma_f32_16x16x32_bf16 v[74:77], v[206:209], v[182:185], v[74:77]
	v_mfma_f32_16x16x32_bf16 v[70:73], v[198:201], v[190:193], v[70:73]
	v_mfma_f32_16x16x32_bf16 v[66:69], v[206:209], v[190:193], v[66:69]
	v_mfma_f32_16x16x32_bf16 v[94:97], v[202:205], v[170:173], v[94:97]
	v_mfma_f32_16x16x32_bf16 v[90:93], v[210:213], v[170:173], v[90:93]
	v_mfma_f32_16x16x32_bf16 v[86:89], v[202:205], v[178:181], v[86:89]
	v_mfma_f32_16x16x32_bf16 v[82:85], v[210:213], v[178:181], v[82:85]
	v_mfma_f32_16x16x32_bf16 v[78:81], v[202:205], v[186:189], v[78:81]
	v_mfma_f32_16x16x32_bf16 v[74:77], v[210:213], v[186:189], v[74:77]
	v_mfma_f32_16x16x32_bf16 v[70:73], v[202:205], v[194:197], v[70:73]
	v_mfma_f32_16x16x32_bf16 v[66:69], v[210:213], v[194:197], v[66:69]
	s_barrier
; #define LDA(dst, b, h) for (int m = 0; m < 4; ++m) for (int k = 0; k < 2; ++k) \
;     dst[m][k] = *reinterpret_cast<const bf16x8*>((char*)SA(b, h) + a_thr + (m * 2 + k) * 1024)
; #define LDB(dst, b, h) for (int n = 0; n < 2; ++n) for (int k = 0; k < 2; ++k) \
;     dst[n][k] = *reinterpret_cast<const bf16x8*>((char*)SB(b, h) + b_thr + (n * 2 + k) * 1024)
; #define MMA(ai, bj, At, Btf) do { __builtin_amdgcn_s_setprio(1); \
;     for (int m = 0; m < 4; ++m) for (int n = 0; n < 2; ++n) for (int k = 0; k < 2; ++k) \
;       acc[ai][bj][m][n] = __builtin_amdgcn_mfma_f32_16x16x32_bf16(Btf[n][k], At[m][k], acc[ai][bj][m][n], 0, 0, 0); \
;     __builtin_amdgcn_s_setprio(0); } while (0)
; #define WAIT_V(n) asm volatile("s_waitcnt vmcnt(" #n ")" ::: "memory")
; #define WAIT_L(n) asm volatile("s_waitcnt lgkmcnt(" #n ")" ::: "memory")
; #define BAR __builtin_amdgcn_s_barrier()
; #define SCHED __builtin_amdgcn_sched_barrier(0)
; template <bool OVL, bool PANEL = false, class Epi>
; __device__ __forceinline__ void gemm_phase(const bf16_t* __restrict__ A, long lda, const bf16_t* __restrict__ Bt, long ldb, int nM, int nN, int K,
;                                            const Epi& epi, bf16_t* shm, int w0) {
;     ...
;       LDA(At, 1, 1); STAGE(SA(1, 0), A, lda, aoff, brow, t + 3);
;       BAR; WAIT_L(0); MMA(1, 0, At, B0); BAR; SCHED;
;       STAGE(SB(1, 1), Bt, ldb, boff, bcol + HALF, t + 3);
;       WAIT_V(6); BAR; MMA(1, 1, At, B1); BAR;
;     }
;     { LDB(B0, 0, 0); LDA(At, 0, 0); STAGE(SA(1, 1), A, lda, aoff, brow + HALF, nt - 1);
;       BAR; WAIT_L(0); MMA(0, 0, At, B0); BAR;
	ds_read_b128 v[166:169], v141 offset:49152
	ds_read_b128 v[170:173], v141 offset:50176
	ds_read_b128 v[174:177], v141 offset:51200
	ds_read_b128 v[178:181], v141 offset:52224
	ds_read_b128 v[182:185], v141 offset:53248
	ds_read_b128 v[186:189], v141 offset:54272
	ds_read_b128 v[190:193], v141 offset:55296
	ds_read_b128 v[194:197], v141 offset:56320
	s_mov_b32 m0, s56
	s_add_u32 s98, s42, s94
	s_addc_u32 s99, s43, s95
	global_load_lds_dwordx4 v131, s[98:99]
	s_mov_b32 m0, s57
	s_add_u32 s98, s42, s72
	s_addc_u32 s99, s43, s73
	global_load_lds_dwordx4 v131, s[98:99]
	s_barrier
	s_waitcnt lgkmcnt(0)
	v_mfma_f32_16x16x32_bf16 v[62:65], v[150:153], v[166:169], v[62:65]
	v_mfma_f32_16x16x32_bf16 v[58:61], v[158:161], v[166:169], v[58:61]
	v_mfma_f32_16x16x32_bf16 v[54:57], v[150:153], v[174:177], v[54:57]
	v_mfma_f32_16x16x32_bf16 v[50:53], v[158:161], v[174:177], v[50:53]
	v_mfma_f32_16x16x32_bf16 v[46:49], v[150:153], v[182:185], v[46:49]
	v_mfma_f32_16x16x32_bf16 v[42:45], v[158:161], v[182:185], v[42:45]
	v_mfma_f32_16x16x32_bf16 v[38:41], v[150:153], v[190:193], v[38:41]
	v_mfma_f32_16x16x32_bf16 v[34:37], v[158:161], v[190:193], v[34:37]
	v_mfma_f32_16x16x32_bf16 v[62:65], v[154:157], v[170:173], v[62:65]
	v_mfma_f32_16x16x32_bf16 v[58:61], v[162:165], v[170:173], v[58:61]
	v_mfma_f32_16x16x32_bf16 v[54:57], v[154:157], v[178:181], v[54:57]
	v_mfma_f32_16x16x32_bf16 v[50:53], v[162:165], v[178:181], v[50:53]
	v_mfma_f32_16x16x32_bf16 v[46:49], v[154:157], v[186:189], v[46:49]
	v_mfma_f32_16x16x32_bf16 v[42:45], v[162:165], v[186:189], v[42:45]
	v_mfma_f32_16x16x32_bf16 v[38:41], v[154:157], v[194:197], v[38:41]
	v_mfma_f32_16x16x32_bf16 v[34:37], v[162:165], v[194:197], v[34:37]
	s_barrier
	s_mov_b32 m0, s58
	s_add_u32 s98, s66, s30
	s_addc_u32 s99, s67, s31
	global_load_lds_dwordx4 v131, s[98:99]
	s_mov_b32 m0, s59
	s_add_u32 s98, s66, s44
	s_addc_u32 s99, s67, s45
	global_load_lds_dwordx4 v131, s[98:99]
	s_add_i32 s18, s18, 2
	s_add_u32 vcc_lo, vcc_lo, 0x100
	s_addc_u32 vcc_hi, vcc_hi, 0
	s_cmp_lt_u32 s18, 12
	s_waitcnt vmcnt(10)
	s_barrier
	v_mfma_f32_16x16x32_bf16 v[30:33], v[198:201], v[166:169], v[30:33]
	v_mfma_f32_16x16x32_bf16 v[26:29], v[206:209], v[166:169], v[26:29]
	v_mfma_f32_16x16x32_bf16 v[22:25], v[198:201], v[174:177], v[22:25]
	v_mfma_f32_16x16x32_bf16 v[18:21], v[206:209], v[174:177], v[18:21]
	v_mfma_f32_16x16x32_bf16 v[14:17], v[198:201], v[182:185], v[14:17]
	v_mfma_f32_16x16x32_bf16 v[10:13], v[206:209], v[182:185], v[10:13]
	v_mfma_f32_16x16x32_bf16 v[6:9], v[198:201], v[190:193], v[6:9]
	v_mfma_f32_16x16x32_bf16 v[2:5], v[206:209], v[190:193], v[2:5]
	v_mfma_f32_16x16x32_bf16 v[30:33], v[202:205], v[170:173], v[30:33]
	v_mfma_f32_16x16x32_bf16 v[26:29], v[210:213], v[170:173], v[26:29]
	v_mfma_f32_16x16x32_bf16 v[22:25], v[202:205], v[178:181], v[22:25]
	v_mfma_f32_16x16x32_bf16 v[18:21], v[210:213], v[178:181], v[18:21]
	v_mfma_f32_16x16x32_bf16 v[14:17], v[202:205], v[186:189], v[14:17]
	v_mfma_f32_16x16x32_bf16 v[10:13], v[210:213], v[186:189], v[10:13]
	v_mfma_f32_16x16x32_bf16 v[6:9], v[202:205], v[194:197], v[6:9]
	v_mfma_f32_16x16x32_bf16 v[2:5], v[210:213], v[194:197], v[2:5]
	s_barrier
	s_cbranch_scc1 .LBB0_386
	s_waitcnt vmcnt(6)
	s_or_b32 s8, s2, 0x80
	s_mov_b32 s9, s3
	v_readlane_b32 s44, v252, 20
	s_lshl_b64 s[8:9], s[8:9], 11
	v_readlane_b32 s50, v252, 26
	v_add_u32_e32 v214, 16, v140
	v_readlane_b32 s51, v252, 27
	s_add_u32 s8, s50, s8
	v_add_u32_e32 v0, 0x10000, v214
	s_addc_u32 s9, s51, s9
	ds_read_b128 v[142:145], v0
	ds_read_b128 v[150:153], v0 offset:1024
	ds_read_b128 v[154:157], v0 offset:2048
	ds_read_b128 v[158:161], v0 offset:3072
	ds_read_b128 v[162:165], v141
	ds_read_b128 v[166:169], v141 offset:1024
	ds_read_b128 v[170:173], v141 offset:2048
	ds_read_b128 v[174:177], v141 offset:3072
	ds_read_b128 v[178:181], v141 offset:4096
	ds_read_b128 v[182:185], v141 offset:5120
	ds_read_b128 v[186:189], v141 offset:6144
	ds_read_b128 v[190:193], v141 offset:7168
	v_mov_b32_e32 v0, v131
	v_readlane_b32 s45, v252, 21
	v_lshl_add_u64 v[146:147], s[8:9], 0, v[0:1]
	s_mov_b64 s[8:9], 0x780
	v_lshl_add_u64 v[194:195], v[146:147], 0, s[8:9]
	v_readfirstlane_b32 s8, v148
	s_mov_b32 m0, s8
	s_mov_b64 s[8:9], 0x20780
	v_lshl_add_u64 v[146:147], v[146:147], 0, s[8:9]
	v_readfirstlane_b32 s8, v149
	global_load_lds_dwordx4 v[194:195], off
	s_mov_b32 m0, s8
	v_readlane_b32 s46, v252, 22
	global_load_lds_dwordx4 v[146:147], off
	s_barrier
	s_waitcnt lgkmcnt(0)
	v_readlane_b32 s47, v252, 23
	v_readlane_b32 s48, v252, 24
	v_readlane_b32 s49, v252, 25
	v_readlane_b32 s52, v252, 28
	v_readlane_b32 s53, v252, 29
	v_readlane_b32 s54, v252, 30
	v_readlane_b32 s55, v252, 31
	v_readlane_b32 s56, v252, 32
	v_readlane_b32 s57, v252, 33
	v_readlane_b32 s58, v252, 34
	v_readlane_b32 s59, v252, 35

; #define LDA(dst, b, h) for (int m = 0; m < 4; ++m) for (int k = 0; k < 2; ++k) \
;     dst[m][k] = *reinterpret_cast<const bf16x8*>((char*)SA(b, h) + a_thr + (m * 2 + k) * 1024)
; #define LDB(dst, b, h) for (int n = 0; n < 2; ++n) for (int k = 0; k < 2; ++k) \
;     dst[n][k] = *reinterpret_cast<const bf16x8*>((char*)SB(b, h) + b_thr + (n * 2 + k) * 1024)
; #define MMA(ai, bj, At, Btf) do { __builtin_amdgcn_s_setprio(1); \
;     for (int m = 0; m < 4; ++m) for (int n = 0; n < 2; ++n) for (int k = 0; k < 2; ++k) \
;       acc[ai][bj][m][n] = __builtin_amdgcn_mfma_f32_16x16x32_bf16(Btf[n][k], At[m][k], acc[ai][bj][m][n], 0, 0, 0); \
;     __builtin_amdgcn_s_setprio(0); } while (0)
; #define WAIT_L(n) asm volatile("s_waitcnt lgkmcnt(" #n ")" ::: "memory")
; #define BAR __builtin_amdgcn_s_barrier()
; template <bool OVL, bool PANEL = false, class Epi>
; __device__ __forceinline__ void gemm_phase(const bf16_t* __restrict__ A, long lda, const bf16_t* __restrict__ Bt, long ldb, int nM, int nN, int K,
;                                            const Epi& epi, bf16_t* shm, int w0) {
;     ...
;     { LDB(B0, 0, 0); LDA(At, 0, 0); STAGE(SA(1, 1), A, lda, aoff, brow + HALF, nt - 1);
;       BAR; WAIT_L(0); MMA(0, 0, At, B0); BAR;
	s_waitcnt lgkmcnt(0)
	v_mfma_f32_16x16x32_bf16 v[126:129], v[142:145], v[162:165], v[126:129]
	v_mfma_f32_16x16x32_bf16 v[122:125], v[154:157], v[162:165], v[122:125]
	v_mfma_f32_16x16x32_bf16 v[118:121], v[142:145], v[170:173], v[118:121]
	v_mfma_f32_16x16x32_bf16 v[114:117], v[154:157], v[170:173], v[114:117]
	v_mfma_f32_16x16x32_bf16 v[110:113], v[142:145], v[178:181], v[110:113]
	v_mfma_f32_16x16x32_bf16 v[106:109], v[154:157], v[178:181], v[106:109]
	v_mfma_f32_16x16x32_bf16 v[98:101], v[154:157], v[186:189], v[98:101]
	v_mfma_f32_16x16x32_bf16 v[126:129], v[150:153], v[166:169], v[126:129]
	v_mfma_f32_16x16x32_bf16 v[122:125], v[158:161], v[166:169], v[122:125]
	v_mfma_f32_16x16x32_bf16 v[118:121], v[150:153], v[174:177], v[118:121]
	v_mfma_f32_16x16x32_bf16 v[114:117], v[158:161], v[174:177], v[114:117]
	v_mfma_f32_16x16x32_bf16 v[110:113], v[150:153], v[182:185], v[110:113]
	v_mfma_f32_16x16x32_bf16 v[106:109], v[158:161], v[182:185], v[106:109]
	v_mfma_f32_16x16x32_bf16 v[102:105], v[142:145], v[186:189], v[102:105]
	v_mfma_f32_16x16x32_bf16 v[98:101], v[158:161], v[190:193], v[98:101]
	v_mfma_f32_16x16x32_bf16 v[146:149], v[150:153], v[190:193], v[102:105]

; #define LDB(dst, b, h) for (int n = 0; n < 2; ++n) for (int k = 0; k < 2; ++k) \
;     dst[n][k] = *reinterpret_cast<const bf16x8*>((char*)SB(b, h) + b_thr + (n * 2 + k) * 1024)
; #define MMA(ai, bj, At, Btf) do { __builtin_amdgcn_s_setprio(1); \
;     for (int m = 0; m < 4; ++m) for (int n = 0; n < 2; ++n) for (int k = 0; k < 2; ++k) \
;       acc[ai][bj][m][n] = __builtin_amdgcn_mfma_f32_16x16x32_bf16(Btf[n][k], At[m][k], acc[ai][bj][m][n], 0, 0, 0); \
;     __builtin_amdgcn_s_setprio(0); } while (0)
; #define WAIT_L(n) asm volatile("s_waitcnt lgkmcnt(" #n ")" ::: "memory")
; #define BAR __builtin_amdgcn_s_barrier()
; template <bool OVL, bool PANEL = false, class Epi>
; __device__ __forceinline__ void gemm_phase(const bf16_t* __restrict__ A, long lda, const bf16_t* __restrict__ Bt, long ldb, int nM, int nN, int K,
;                                            const Epi& epi, bf16_t* shm, int w0) {
;     ...
;       BAR; WAIT_L(0); MMA(0, 0, At, B0); BAR;
;       LDB(B1, 0, 1); BAR; WAIT_L(0); MMA(0, 1, At, B1); BAR;
	v_add_u32_e32 v0, 0x14000, v214
	s_barrier
	s_nop 2
	ds_read_b128 v[102:105], v0
	ds_read_b128 v[194:197], v0 offset:1024
	ds_read_b128 v[198:201], v0 offset:2048
	ds_read_b128 v[202:205], v0 offset:3072
	s_barrier
	s_waitcnt lgkmcnt(0)

; #define LDB(dst, b, h) for (int n = 0; n < 2; ++n) for (int k = 0; k < 2; ++k) \
;     dst[n][k] = *reinterpret_cast<const bf16x8*>((char*)SB(b, h) + b_thr + (n * 2 + k) * 1024)
; #define MMA(ai, bj, At, Btf) do { __builtin_amdgcn_s_setprio(1); \
;     for (int m = 0; m < 4; ++m) for (int n = 0; n < 2; ++n) for (int k = 0; k < 2; ++k) \
;       acc[ai][bj][m][n] = __builtin_amdgcn_mfma_f32_16x16x32_bf16(Btf[n][k], At[m][k], acc[ai][bj][m][n], 0, 0, 0); \
;     __builtin_amdgcn_s_setprio(0); } while (0)
; #define WAIT_L(n) asm volatile("s_waitcnt lgkmcnt(" #n ")" ::: "memory")
; #define BAR __builtin_amdgcn_s_barrier()
; template <bool OVL, bool PANEL = false, class Epi>
; __device__ __forceinline__ void gemm_phase(const bf16_t* __restrict__ A, long lda, const bf16_t* __restrict__ Bt, long ldb, int nM, int nN, int K,
;                                            const Epi& epi, bf16_t* shm, int w0) {
;     ...
;       LDB(B1, 0, 1); BAR; WAIT_L(0); MMA(0, 1, At, B1); BAR;
	s_waitcnt lgkmcnt(0)
	v_mfma_f32_16x16x32_bf16 v[94:97], v[102:105], v[162:165], v[94:97]
	v_mfma_f32_16x16x32_bf16 v[86:89], v[102:105], v[170:173], v[86:89]
	v_mfma_f32_16x16x32_bf16 v[78:81], v[102:105], v[178:181], v[78:81]
	v_mfma_f32_16x16x32_bf16 v[74:77], v[198:201], v[178:181], v[74:77]
	v_mfma_f32_16x16x32_bf16 v[94:97], v[194:197], v[166:169], v[94:97]
	v_mfma_f32_16x16x32_bf16 v[90:93], v[198:201], v[162:165], v[90:93]
	v_mfma_f32_16x16x32_bf16 v[86:89], v[194:197], v[174:177], v[86:89]
	v_mfma_f32_16x16x32_bf16 v[82:85], v[198:201], v[170:173], v[82:85]
	v_mfma_f32_16x16x32_bf16 v[78:81], v[194:197], v[182:185], v[78:81]
	v_mfma_f32_16x16x32_bf16 v[74:77], v[202:205], v[182:185], v[74:77]
	v_mfma_f32_16x16x32_bf16 v[70:73], v[102:105], v[186:189], v[70:73]
	v_mfma_f32_16x16x32_bf16 v[66:69], v[198:201], v[186:189], v[66:69]
	v_mfma_f32_16x16x32_bf16 v[162:165], v[202:205], v[166:169], v[90:93]
	v_mfma_f32_16x16x32_bf16 v[166:169], v[202:205], v[174:177], v[82:85]
	v_mfma_f32_16x16x32_bf16 v[170:173], v[194:197], v[190:193], v[70:73]
	v_mfma_f32_16x16x32_bf16 v[174:177], v[202:205], v[190:193], v[66:69]

; #define LDA(dst, b, h) for (int m = 0; m < 4; ++m) for (int k = 0; k < 2; ++k) \
;     dst[m][k] = *reinterpret_cast<const bf16x8*>((char*)SA(b, h) + a_thr + (m * 2 + k) * 1024)
; #define LDB(dst, b, h) for (int n = 0; n < 2; ++n) for (int k = 0; k < 2; ++k) \
;     dst[n][k] = *reinterpret_cast<const bf16x8*>((char*)SB(b, h) + b_thr + (n * 2 + k) * 1024)
; #define MMA(ai, bj, At, Btf) do { __builtin_amdgcn_s_setprio(1); \
;     for (int m = 0; m < 4; ++m) for (int n = 0; n < 2; ++n) for (int k = 0; k < 2; ++k) \
;       acc[ai][bj][m][n] = __builtin_amdgcn_mfma_f32_16x16x32_bf16(Btf[n][k], At[m][k], acc[ai][bj][m][n], 0, 0, 0); \
;     __builtin_amdgcn_s_setprio(0); } while (0)
; #define WAIT_V(n) asm volatile("s_waitcnt vmcnt(" #n ")" ::: "memory")
; #define WAIT_L(n) asm volatile("s_waitcnt lgkmcnt(" #n ")" ::: "memory")
; #define BAR __builtin_amdgcn_s_barrier()
; template <bool OVL, bool PANEL = false, class Epi>
; __device__ __forceinline__ void gemm_phase(const bf16_t* __restrict__ A, long lda, const bf16_t* __restrict__ Bt, long ldb, int nM, int nN, int K,
;                                            const Epi& epi, bf16_t* shm, int w0) {
;     ...
;       LDB(B1, 0, 1); BAR; WAIT_L(0); MMA(0, 1, At, B1); BAR;
;       LDA(At, 0, 1); WAIT_V(4); BAR; WAIT_L(0); MMA(1, 0, At, B0); MMA(1, 1, At, B1); BAR; }
	s_barrier
	s_nop 1
	ds_read_b128 v[66:69], v141 offset:16384
	ds_read_b128 v[70:73], v141 offset:17408
	ds_read_b128 v[82:85], v141 offset:18432
	ds_read_b128 v[90:93], v141 offset:19456
	ds_read_b128 v[178:181], v141 offset:20480
	ds_read_b128 v[182:185], v141 offset:21504
	ds_read_b128 v[186:189], v141 offset:22528
	ds_read_b128 v[190:193], v141 offset:23552
	s_waitcnt vmcnt(4)
	s_barrier
	s_waitcnt lgkmcnt(0)

; #define LDA(dst, b, h) for (int m = 0; m < 4; ++m) for (int k = 0; k < 2; ++k) \
;     dst[m][k] = *reinterpret_cast<const bf16x8*>((char*)SA(b, h) + a_thr + (m * 2 + k) * 1024)
; #define MMA(ai, bj, At, Btf) do { __builtin_amdgcn_s_setprio(1); \
;     for (int m = 0; m < 4; ++m) for (int n = 0; n < 2; ++n) for (int k = 0; k < 2; ++k) \
;       acc[ai][bj][m][n] = __builtin_amdgcn_mfma_f32_16x16x32_bf16(Btf[n][k], At[m][k], acc[ai][bj][m][n], 0, 0, 0); \
;     __builtin_amdgcn_s_setprio(0); } while (0)
; #define WAIT_V(n) asm volatile("s_waitcnt vmcnt(" #n ")" ::: "memory")
; #define WAIT_L(n) asm volatile("s_waitcnt lgkmcnt(" #n ")" ::: "memory")
; #define BAR __builtin_amdgcn_s_barrier()
; template <bool OVL, bool PANEL = false, class Epi>
; __device__ __forceinline__ void gemm_phase(const bf16_t* __restrict__ A, long lda, const bf16_t* __restrict__ Bt, long ldb, int nM, int nN, int K,
;                                            const Epi& epi, bf16_t* shm, int w0) {
;     ...
;       LDA(At, 0, 1); WAIT_V(4); BAR; WAIT_L(0); MMA(1, 0, At, B0); MMA(1, 1, At, B1); BAR; }
	s_waitcnt lgkmcnt(0)
	v_mfma_f32_16x16x32_bf16 v[62:65], v[142:145], v[66:69], v[62:65]
	v_mfma_f32_16x16x32_bf16 v[54:57], v[142:145], v[82:85], v[54:57]
	v_mfma_f32_16x16x32_bf16 v[46:49], v[142:145], v[178:181], v[46:49]
	v_mfma_f32_16x16x32_bf16 v[42:45], v[154:157], v[178:181], v[42:45]
	v_mfma_f32_16x16x32_bf16 v[38:41], v[142:145], v[186:189], v[38:41]
	v_mfma_f32_16x16x32_bf16 v[34:37], v[154:157], v[186:189], v[34:37]
	v_mfma_f32_16x16x32_bf16 v[62:65], v[150:153], v[70:73], v[62:65]
	v_mfma_f32_16x16x32_bf16 v[58:61], v[154:157], v[66:69], v[58:61]
	v_mfma_f32_16x16x32_bf16 v[54:57], v[150:153], v[90:93], v[54:57]
	v_mfma_f32_16x16x32_bf16 v[50:53], v[154:157], v[82:85], v[50:53]
	v_mfma_f32_16x16x32_bf16 v[46:49], v[150:153], v[182:185], v[46:49]
	v_mfma_f32_16x16x32_bf16 v[42:45], v[158:161], v[182:185], v[42:45]
	v_mfma_f32_16x16x32_bf16 v[38:41], v[150:153], v[190:193], v[38:41]
	v_mfma_f32_16x16x32_bf16 v[34:37], v[158:161], v[190:193], v[34:37]
	v_mfma_f32_16x16x32_bf16 v[206:209], v[158:161], v[70:73], v[58:61]
	v_mfma_f32_16x16x32_bf16 v[210:213], v[158:161], v[90:93], v[50:53]


; #define LDA(dst, b, h) for (int m = 0; m < 4; ++m) for (int k = 0; k < 2; ++k) \
;     dst[m][k] = *reinterpret_cast<const bf16x8*>((char*)SA(b, h) + a_thr + (m * 2 + k) * 1024)
; #define MMA(ai, bj, At, Btf) do { __builtin_amdgcn_s_setprio(1); \
;     for (int m = 0; m < 4; ++m) for (int n = 0; n < 2; ++n) for (int k = 0; k < 2; ++k) \
;       acc[ai][bj][m][n] = __builtin_amdgcn_mfma_f32_16x16x32_bf16(Btf[n][k], At[m][k], acc[ai][bj][m][n], 0, 0, 0); \
;     __builtin_amdgcn_s_setprio(0); } while (0)
; #define WAIT_V(n) asm volatile("s_waitcnt vmcnt(" #n ")" ::: "memory")
; #define WAIT_L(n) asm volatile("s_waitcnt lgkmcnt(" #n ")" ::: "memory")
; #define BAR __builtin_amdgcn_s_barrier()
; template <bool OVL, bool PANEL = false, class Epi>
; __device__ __forceinline__ void gemm_phase(const bf16_t* __restrict__ A, long lda, const bf16_t* __restrict__ Bt, long ldb, int nM, int nN, int K,
;                                            const Epi& epi, bf16_t* shm, int w0) {
;     ...
;       LDA(At, 0, 1); WAIT_V(4); BAR; WAIT_L(0); MMA(1, 0, At, B0); MMA(1, 1, At, B1); BAR; }
	v_mfma_f32_16x16x32_bf16 v[30:33], v[102:105], v[66:69], v[30:33]
	v_mfma_f32_16x16x32_bf16 v[26:29], v[198:201], v[66:69], v[26:29]
	v_mfma_f32_16x16x32_bf16 v[22:25], v[102:105], v[82:85], v[22:25]
	v_mfma_f32_16x16x32_bf16 v[18:21], v[198:201], v[82:85], v[18:21]
	v_mfma_f32_16x16x32_bf16 v[14:17], v[102:105], v[178:181], v[14:17]
	v_mfma_f32_16x16x32_bf16 v[10:13], v[198:201], v[178:181], v[10:13]
	v_mfma_f32_16x16x32_bf16 v[6:9], v[102:105], v[186:189], v[6:9]
	v_mfma_f32_16x16x32_bf16 v[2:5], v[198:201], v[186:189], v[2:5]
	v_mfma_f32_16x16x32_bf16 v[30:33], v[194:197], v[70:73], v[30:33]
	v_mfma_f32_16x16x32_bf16 v[26:29], v[202:205], v[70:73], v[26:29]
	v_mfma_f32_16x16x32_bf16 v[22:25], v[194:197], v[90:93], v[22:25]
	v_mfma_f32_16x16x32_bf16 v[18:21], v[202:205], v[90:93], v[18:21]
	v_mfma_f32_16x16x32_bf16 v[14:17], v[194:197], v[182:185], v[14:17]
	v_mfma_f32_16x16x32_bf16 v[10:13], v[202:205], v[182:185], v[10:13]
	v_mfma_f32_16x16x32_bf16 v[6:9], v[194:197], v[190:193], v[6:9]
	v_mfma_f32_16x16x32_bf16 v[2:5], v[202:205], v[190:193], v[2:5]

; #define LDA(dst, b, h) for (int m = 0; m < 4; ++m) for (int k = 0; k < 2; ++k) \
;     dst[m][k] = *reinterpret_cast<const bf16x8*>((char*)SA(b, h) + a_thr + (m * 2 + k) * 1024)
; #define LDB(dst, b, h) for (int n = 0; n < 2; ++n) for (int k = 0; k < 2; ++k) \
;     dst[n][k] = *reinterpret_cast<const bf16x8*>((char*)SB(b, h) + b_thr + (n * 2 + k) * 1024)
; #define MMA(ai, bj, At, Btf) do { __builtin_amdgcn_s_setprio(1); \
;     for (int m = 0; m < 4; ++m) for (int n = 0; n < 2; ++n) for (int k = 0; k < 2; ++k) \
;       acc[ai][bj][m][n] = __builtin_amdgcn_mfma_f32_16x16x32_bf16(Btf[n][k], At[m][k], acc[ai][bj][m][n], 0, 0, 0); \
;     __builtin_amdgcn_s_setprio(0); } while (0)
; #define WAIT_V(n) asm volatile("s_waitcnt vmcnt(" #n ")" ::: "memory")
; #define WAIT_L(n) asm volatile("s_waitcnt lgkmcnt(" #n ")" ::: "memory")
; #define BAR __builtin_amdgcn_s_barrier()
; template <bool OVL, bool PANEL = false, class Epi>
; __device__ __forceinline__ void gemm_phase(const bf16_t* __restrict__ A, long lda, const bf16_t* __restrict__ Bt, long ldb, int nM, int nN, int K,
;                                            const Epi& epi, bf16_t* shm, int w0) {
;     ...
;       LDA(At, 0, 1); WAIT_V(4); BAR; WAIT_L(0); MMA(1, 0, At, B0); MMA(1, 1, At, B1); BAR; }
;     { LDB(B0, 1, 0); LDA(At, 1, 0); WAIT_V(2); BAR; WAIT_L(0); MMA(0, 0, At, B0); BAR;
	v_add_u32_e32 v0, 0x18000, v214
	s_barrier
	ds_read_b128 v[142:145], v0
	ds_read_b128 v[150:153], v0 offset:1024
	ds_read_b128 v[154:157], v0 offset:2048
	ds_read_b128 v[158:161], v0 offset:3072
	ds_read_b128 v[50:53], v141 offset:32768
	ds_read_b128 v[58:61], v141 offset:33792
	ds_read_b128 v[66:69], v141 offset:34816
	ds_read_b128 v[70:73], v141 offset:35840
	ds_read_b128 v[178:181], v141 offset:36864
	ds_read_b128 v[182:185], v141 offset:37888
	ds_read_b128 v[186:189], v141 offset:38912
	ds_read_b128 v[190:193], v141 offset:39936
	s_waitcnt vmcnt(2)
	s_barrier
	s_waitcnt lgkmcnt(0)

; #define LDA(dst, b, h) for (int m = 0; m < 4; ++m) for (int k = 0; k < 2; ++k) \
;     dst[m][k] = *reinterpret_cast<const bf16x8*>((char*)SA(b, h) + a_thr + (m * 2 + k) * 1024)
; #define LDB(dst, b, h) for (int n = 0; n < 2; ++n) for (int k = 0; k < 2; ++k) \
;     dst[n][k] = *reinterpret_cast<const bf16x8*>((char*)SB(b, h) + b_thr + (n * 2 + k) * 1024)
; #define MMA(ai, bj, At, Btf) do { __builtin_amdgcn_s_setprio(1); \
;     for (int m = 0; m < 4; ++m) for (int n = 0; n < 2; ++n) for (int k = 0; k < 2; ++k) \
;       acc[ai][bj][m][n] = __builtin_amdgcn_mfma_f32_16x16x32_bf16(Btf[n][k], At[m][k], acc[ai][bj][m][n], 0, 0, 0); \
;     __builtin_amdgcn_s_setprio(0); } while (0)
; #define WAIT_V(n) asm volatile("s_waitcnt vmcnt(" #n ")" ::: "memory")
; #define WAIT_L(n) asm volatile("s_waitcnt lgkmcnt(" #n ")" ::: "memory")
; #define BAR __builtin_amdgcn_s_barrier()
; template <bool OVL, bool PANEL = false, class Epi>
; __device__ __forceinline__ void gemm_phase(const bf16_t* __restrict__ A, long lda, const bf16_t* __restrict__ Bt, long ldb, int nM, int nN, int K,
;                                            const Epi& epi, bf16_t* shm, int w0) {
;     ...
;     { LDB(B0, 1, 0); LDA(At, 1, 0); WAIT_V(2); BAR; WAIT_L(0); MMA(0, 0, At, B0); BAR;
	s_waitcnt lgkmcnt(0)
	v_mfma_f32_16x16x32_bf16 v[82:85], v[142:145], v[50:53], v[126:129]
	v_mfma_f32_16x16x32_bf16 v[126:129], v[150:153], v[58:61], v[82:85]
	v_mfma_f32_16x16x32_bf16 v[82:85], v[154:157], v[50:53], v[122:125]
	v_mfma_f32_16x16x32_bf16 v[122:125], v[158:161], v[58:61], v[82:85]
	v_mfma_f32_16x16x32_bf16 v[82:85], v[142:145], v[66:69], v[118:121]
	v_mfma_f32_16x16x32_bf16 v[118:121], v[150:153], v[70:73], v[82:85]
	v_mfma_f32_16x16x32_bf16 v[82:85], v[154:157], v[66:69], v[114:117]
	v_mfma_f32_16x16x32_bf16 v[114:117], v[158:161], v[70:73], v[82:85]
	v_mfma_f32_16x16x32_bf16 v[82:85], v[142:145], v[178:181], v[110:113]
	v_mfma_f32_16x16x32_bf16 v[110:113], v[150:153], v[182:185], v[82:85]
	v_mfma_f32_16x16x32_bf16 v[82:85], v[154:157], v[178:181], v[106:109]
	v_mfma_f32_16x16x32_bf16 v[102:105], v[158:161], v[182:185], v[82:85]
	v_mfma_f32_16x16x32_bf16 v[82:85], v[142:145], v[186:189], v[146:149]
	v_mfma_f32_16x16x32_bf16 v[90:93], v[150:153], v[190:193], v[82:85]
	v_mfma_f32_16x16x32_bf16 v[82:85], v[154:157], v[186:189], v[98:101]
	v_mfma_f32_16x16x32_bf16 v[82:85], v[158:161], v[190:193], v[82:85]

; #define LDA(dst, b, h) for (int m = 0; m < 4; ++m) for (int k = 0; k < 2; ++k) \
;     dst[m][k] = *reinterpret_cast<const bf16x8*>((char*)SA(b, h) + a_thr + (m * 2 + k) * 1024)
; #define LDB(dst, b, h) for (int n = 0; n < 2; ++n) for (int k = 0; k < 2; ++k) \
;     dst[n][k] = *reinterpret_cast<const bf16x8*>((char*)SB(b, h) + b_thr + (n * 2 + k) * 1024)
; #define MMA(ai, bj, At, Btf) do { __builtin_amdgcn_s_setprio(1); \
;     for (int m = 0; m < 4; ++m) for (int n = 0; n < 2; ++n) for (int k = 0; k < 2; ++k) \
;       acc[ai][bj][m][n] = __builtin_amdgcn_mfma_f32_16x16x32_bf16(Btf[n][k], At[m][k], acc[ai][bj][m][n], 0, 0, 0); \
;     __builtin_amdgcn_s_setprio(0); } while (0)
; #define WAIT_V(n) asm volatile("s_waitcnt vmcnt(" #n ")" ::: "memory")
; #define WAIT_L(n) asm volatile("s_waitcnt lgkmcnt(" #n ")" ::: "memory")
; #define BAR __builtin_amdgcn_s_barrier()
; template <bool OVL, bool PANEL = false, class Epi>
; __device__ __forceinline__ void gemm_phase(const bf16_t* __restrict__ A, long lda, const bf16_t* __restrict__ Bt, long ldb, int nM, int nN, int K,
;                                            const Epi& epi, bf16_t* shm, int w0) {
;     ...
;     { LDB(B0, 1, 0); LDA(At, 1, 0); WAIT_V(2); BAR; WAIT_L(0); MMA(0, 0, At, B0); BAR;
;       LDB(B1, 1, 1); WAIT_V(0); BAR; WAIT_L(0); MMA(0, 1, At, B1); BAR;
	v_add_u32_e32 v0, 0x1c000, v214
	s_barrier
	ds_read_b128 v[146:149], v0
	ds_read_b128 v[194:197], v0 offset:1024
	ds_read_b128 v[198:201], v0 offset:2048
	ds_read_b128 v[202:205], v0 offset:3072
	s_waitcnt vmcnt(0)
	s_barrier
	s_waitcnt lgkmcnt(0)

; #define LDB(dst, b, h) for (int n = 0; n < 2; ++n) for (int k = 0; k < 2; ++k) \
;     dst[n][k] = *reinterpret_cast<const bf16x8*>((char*)SB(b, h) + b_thr + (n * 2 + k) * 1024)
; #define MMA(ai, bj, At, Btf) do { __builtin_amdgcn_s_setprio(1); \
;     for (int m = 0; m < 4; ++m) for (int n = 0; n < 2; ++n) for (int k = 0; k < 2; ++k) \
;       acc[ai][bj][m][n] = __builtin_amdgcn_mfma_f32_16x16x32_bf16(Btf[n][k], At[m][k], acc[ai][bj][m][n], 0, 0, 0); \
;     __builtin_amdgcn_s_setprio(0); } while (0)
; #define WAIT_V(n) asm volatile("s_waitcnt vmcnt(" #n ")" ::: "memory")
; #define WAIT_L(n) asm volatile("s_waitcnt lgkmcnt(" #n ")" ::: "memory")
; #define BAR __builtin_amdgcn_s_barrier()
; template <bool OVL, bool PANEL = false, class Epi>
; __device__ __forceinline__ void gemm_phase(const bf16_t* __restrict__ A, long lda, const bf16_t* __restrict__ Bt, long ldb, int nM, int nN, int K,
;                                            const Epi& epi, bf16_t* shm, int w0) {
;     ...
;       LDB(B1, 1, 1); WAIT_V(0); BAR; WAIT_L(0); MMA(0, 1, At, B1); BAR;
	s_waitcnt lgkmcnt(0)
	v_mfma_f32_16x16x32_bf16 v[94:97], v[146:149], v[50:53], v[94:97]
	v_mfma_f32_16x16x32_bf16 v[50:53], v[198:201], v[50:53], v[162:165]
	v_mfma_f32_16x16x32_bf16 v[98:101], v[202:205], v[58:61], v[50:53]
	v_mfma_f32_16x16x32_bf16 v[50:53], v[146:149], v[66:69], v[86:89]
	v_mfma_f32_16x16x32_bf16 v[106:109], v[194:197], v[58:61], v[94:97]
	v_mfma_f32_16x16x32_bf16 v[94:97], v[194:197], v[70:73], v[50:53]
	v_mfma_f32_16x16x32_bf16 v[50:53], v[198:201], v[66:69], v[166:169]
	v_mfma_f32_16x16x32_bf16 v[86:89], v[202:205], v[70:73], v[50:53]
	v_mfma_f32_16x16x32_bf16 v[50:53], v[146:149], v[178:181], v[78:81]
	v_mfma_f32_16x16x32_bf16 v[70:73], v[194:197], v[182:185], v[50:53]
	v_mfma_f32_16x16x32_bf16 v[50:53], v[198:201], v[178:181], v[74:77]
	v_mfma_f32_16x16x32_bf16 v[66:69], v[202:205], v[182:185], v[50:53]
	v_mfma_f32_16x16x32_bf16 v[50:53], v[146:149], v[186:189], v[170:173]
	v_mfma_f32_16x16x32_bf16 v[58:61], v[194:197], v[190:193], v[50:53]
	v_mfma_f32_16x16x32_bf16 v[50:53], v[198:201], v[186:189], v[174:177]
	v_mfma_f32_16x16x32_bf16 v[50:53], v[202:205], v[190:193], v[50:53]

; #define LDA(dst, b, h) for (int m = 0; m < 4; ++m) for (int k = 0; k < 2; ++k) \
;     dst[m][k] = *reinterpret_cast<const bf16x8*>((char*)SA(b, h) + a_thr + (m * 2 + k) * 1024)
; #define LDB(dst, b, h) for (int n = 0; n < 2; ++n) for (int k = 0; k < 2; ++k) \
;     dst[n][k] = *reinterpret_cast<const bf16x8*>((char*)SB(b, h) + b_thr + (n * 2 + k) * 1024)
; #define MMA(ai, bj, At, Btf) do { __builtin_amdgcn_s_setprio(1); \
;     for (int m = 0; m < 4; ++m) for (int n = 0; n < 2; ++n) for (int k = 0; k < 2; ++k) \
;       acc[ai][bj][m][n] = __builtin_amdgcn_mfma_f32_16x16x32_bf16(Btf[n][k], At[m][k], acc[ai][bj][m][n], 0, 0, 0); \
;     __builtin_amdgcn_s_setprio(0); } while (0)
; #define WAIT_V(n) asm volatile("s_waitcnt vmcnt(" #n ")" ::: "memory")
; #define WAIT_L(n) asm volatile("s_waitcnt lgkmcnt(" #n ")" ::: "memory")
; #define BAR __builtin_amdgcn_s_barrier()
; template <bool OVL, bool PANEL = false, class Epi>
; __device__ __forceinline__ void gemm_phase(const bf16_t* __restrict__ A, long lda, const bf16_t* __restrict__ Bt, long ldb, int nM, int nN, int K,
;                                            const Epi& epi, bf16_t* shm, int w0) {
;     ...
;       LDB(B1, 1, 1); WAIT_V(0); BAR; WAIT_L(0); MMA(0, 1, At, B1); BAR;
;       LDA(At, 1, 1); BAR; WAIT_L(0); MMA(1, 0, At, B0); MMA(1, 1, At, B1); BAR; }
	s_barrier
	ds_read_b128 v[162:165], v141 offset:49152
	ds_read_b128 v[166:169], v141 offset:50176
	ds_read_b128 v[170:173], v141 offset:51200
	ds_read_b128 v[174:177], v141 offset:52224
	ds_read_b128 v[178:181], v141 offset:53248
	ds_read_b128 v[182:185], v141 offset:54272
	ds_read_b128 v[186:189], v141 offset:55296
	ds_read_b128 v[190:193], v141 offset:56320
	s_barrier
	s_waitcnt lgkmcnt(0)

; #define LDA(dst, b, h) for (int m = 0; m < 4; ++m) for (int k = 0; k < 2; ++k) \
;     dst[m][k] = *reinterpret_cast<const bf16x8*>((char*)SA(b, h) + a_thr + (m * 2 + k) * 1024)
; #define MMA(ai, bj, At, Btf) do { __builtin_amdgcn_s_setprio(1); \
;     for (int m = 0; m < 4; ++m) for (int n = 0; n < 2; ++n) for (int k = 0; k < 2; ++k) \
;       acc[ai][bj][m][n] = __builtin_amdgcn_mfma_f32_16x16x32_bf16(Btf[n][k], At[m][k], acc[ai][bj][m][n], 0, 0, 0); \
;     __builtin_amdgcn_s_setprio(0); } while (0)
; #define WAIT_L(n) asm volatile("s_waitcnt lgkmcnt(" #n ")" ::: "memory")
; #define BAR __builtin_amdgcn_s_barrier()
; template <bool OVL, bool PANEL = false, class Epi>
; __device__ __forceinline__ void gemm_phase(const bf16_t* __restrict__ A, long lda, const bf16_t* __restrict__ Bt, long ldb, int nM, int nN, int K,
;                                            const Epi& epi, bf16_t* shm, int w0) {
;     ...
;       LDA(At, 1, 1); BAR; WAIT_L(0); MMA(1, 0, At, B0); MMA(1, 1, At, B1); BAR; }
	s_waitcnt lgkmcnt(0)
	v_mfma_f32_16x16x32_bf16 v[62:65], v[142:145], v[162:165], v[62:65]
	v_mfma_f32_16x16x32_bf16 v[78:81], v[150:153], v[166:169], v[62:65]
	v_mfma_f32_16x16x32_bf16 v[62:65], v[154:157], v[162:165], v[206:209]
	v_mfma_f32_16x16x32_bf16 v[54:57], v[142:145], v[170:173], v[54:57]
	v_mfma_f32_16x16x32_bf16 v[74:77], v[158:161], v[166:169], v[62:65]
	v_mfma_f32_16x16x32_bf16 v[62:65], v[150:153], v[174:177], v[54:57]
	v_mfma_f32_16x16x32_bf16 v[54:57], v[154:157], v[170:173], v[210:213]
	v_mfma_f32_16x16x32_bf16 v[46:49], v[142:145], v[178:181], v[46:49]
	v_mfma_f32_16x16x32_bf16 v[42:45], v[154:157], v[178:181], v[42:45]
	v_mfma_f32_16x16x32_bf16 v[38:41], v[142:145], v[186:189], v[38:41]
	v_mfma_f32_16x16x32_bf16 v[34:37], v[154:157], v[186:189], v[34:37]
	v_mfma_f32_16x16x32_bf16 v[54:57], v[158:161], v[174:177], v[54:57]
	v_mfma_f32_16x16x32_bf16 v[46:49], v[150:153], v[182:185], v[46:49]
	v_mfma_f32_16x16x32_bf16 v[42:45], v[158:161], v[182:185], v[42:45]
	v_mfma_f32_16x16x32_bf16 v[38:41], v[150:153], v[190:193], v[38:41]
	v_mfma_f32_16x16x32_bf16 v[34:37], v[158:161], v[190:193], v[34:37]


; #define LDA(dst, b, h) for (int m = 0; m < 4; ++m) for (int k = 0; k < 2; ++k) \
;     dst[m][k] = *reinterpret_cast<const bf16x8*>((char*)SA(b, h) + a_thr + (m * 2 + k) * 1024)
; #define MMA(ai, bj, At, Btf) do { __builtin_amdgcn_s_setprio(1); \
;     for (int m = 0; m < 4; ++m) for (int n = 0; n < 2; ++n) for (int k = 0; k < 2; ++k) \
;       acc[ai][bj][m][n] = __builtin_amdgcn_mfma_f32_16x16x32_bf16(Btf[n][k], At[m][k], acc[ai][bj][m][n], 0, 0, 0); \
;     __builtin_amdgcn_s_setprio(0); } while (0)
; #define WAIT_L(n) asm volatile("s_waitcnt lgkmcnt(" #n ")" ::: "memory")
; #define BAR __builtin_amdgcn_s_barrier()
; template <bool OVL, bool PANEL = false, class Epi>
; __device__ __forceinline__ void gemm_phase(const bf16_t* __restrict__ A, long lda, const bf16_t* __restrict__ Bt, long ldb, int nM, int nN, int K,
;                                            const Epi& epi, bf16_t* shm, int w0) {
;     ...
;       LDA(At, 1, 1); BAR; WAIT_L(0); MMA(1, 0, At, B0); MMA(1, 1, At, B1); BAR; }
	v_mfma_f32_16x16x32_bf16 v[30:33], v[146:149], v[162:165], v[30:33]
	v_mfma_f32_16x16x32_bf16 v[26:29], v[198:201], v[162:165], v[26:29]
	v_mfma_f32_16x16x32_bf16 v[22:25], v[146:149], v[170:173], v[22:25]
	v_mfma_f32_16x16x32_bf16 v[18:21], v[198:201], v[170:173], v[18:21]
	v_mfma_f32_16x16x32_bf16 v[14:17], v[146:149], v[178:181], v[14:17]
	v_mfma_f32_16x16x32_bf16 v[10:13], v[198:201], v[178:181], v[10:13]
	v_mfma_f32_16x16x32_bf16 v[6:9], v[146:149], v[186:189], v[6:9]
	v_mfma_f32_16x16x32_bf16 v[2:5], v[198:201], v[186:189], v[2:5]
	v_mfma_f32_16x16x32_bf16 v[30:33], v[194:197], v[166:169], v[30:33]
	v_mfma_f32_16x16x32_bf16 v[26:29], v[202:205], v[166:169], v[26:29]
	v_mfma_f32_16x16x32_bf16 v[22:25], v[194:197], v[174:177], v[22:25]
	v_mfma_f32_16x16x32_bf16 v[18:21], v[202:205], v[174:177], v[18:21]
	v_mfma_f32_16x16x32_bf16 v[14:17], v[194:197], v[182:185], v[14:17]
	v_mfma_f32_16x16x32_bf16 v[10:13], v[202:205], v[182:185], v[10:13]
	v_mfma_f32_16x16x32_bf16 v[6:9], v[194:197], v[190:193], v[6:9]
	v_mfma_f32_16x16x32_bf16 v[2:5], v[202:205], v[190:193], v[2:5]

; #define LDA(dst, b, h) for (int m = 0; m < 4; ++m) for (int k = 0; k < 2; ++k) \
;     dst[m][k] = *reinterpret_cast<const bf16x8*>((char*)SA(b, h) + a_thr + (m * 2 + k) * 1024)
; #define MMA(ai, bj, At, Btf) do { __builtin_amdgcn_s_setprio(1); \
;     for (int m = 0; m < 4; ++m) for (int n = 0; n < 2; ++n) for (int k = 0; k < 2; ++k) \
;       acc[ai][bj][m][n] = __builtin_amdgcn_mfma_f32_16x16x32_bf16(Btf[n][k], At[m][k], acc[ai][bj][m][n], 0, 0, 0); \
;     __builtin_amdgcn_s_setprio(0); } while (0)
; #define WAIT_L(n) asm volatile("s_waitcnt lgkmcnt(" #n ")" ::: "memory")
; #define BAR __builtin_amdgcn_s_barrier()
; template <bool OVL, bool PANEL = false, class Epi>
; __device__ __forceinline__ void gemm_phase(const bf16_t* __restrict__ A, long lda, const bf16_t* __restrict__ Bt, long ldb, int nM, int nN, int K,
;                                            const Epi& epi, bf16_t* shm, int w0) {
;     ...
;       LDA(At, 1, 1); BAR; WAIT_L(0); MMA(1, 0, At, B0); MMA(1, 1, At, B1); BAR; }
;     if (wr == 0) BAR;
	s_barrier
	s_and_saveexec_b64 s[8:9], s[78:79]
	s_cbranch_execz .LBB0_389
	s_barrier

; #define LDA(dst, b, h) for (int m = 0; m < 4; ++m) for (int k = 0; k < 2; ++k) \
;     dst[m][k] = *reinterpret_cast<const bf16x8*>((char*)SA(b, h) + a_thr + (m * 2 + k) * 1024)
; #define LDB(dst, b, h) for (int n = 0; n < 2; ++n) for (int k = 0; k < 2; ++k) \
;     dst[n][k] = *reinterpret_cast<const bf16x8*>((char*)SB(b, h) + b_thr + (n * 2 + k) * 1024)
; #define MMA(ai, bj, At, Btf) do { __builtin_amdgcn_s_setprio(1); \
;     for (int m = 0; m < 4; ++m) for (int n = 0; n < 2; ++n) for (int k = 0; k < 2; ++k) \
;       acc[ai][bj][m][n] = __builtin_amdgcn_mfma_f32_16x16x32_bf16(Btf[n][k], At[m][k], acc[ai][bj][m][n], 0, 0, 0); \
;     __builtin_amdgcn_s_setprio(0); } while (0)
; #define WAIT_V(n) asm volatile("s_waitcnt vmcnt(" #n ")" ::: "memory")
; #define WAIT_L(n) asm volatile("s_waitcnt lgkmcnt(" #n ")" ::: "memory")
; #define BAR __builtin_amdgcn_s_barrier()
; #define SCHED __builtin_amdgcn_sched_barrier(0)
; template <bool OVL, bool PANEL = false, class Epi>
; __device__ __forceinline__ void gemm_phase(const bf16_t* __restrict__ A, long lda, const bf16_t* __restrict__ Bt, long ldb, int nM, int nN, int K,
;                                            const Epi& epi, bf16_t* shm, int w0) {
;     ...
;     if (wr == 1) BAR;
;     WAIT_V(4); BAR;
;     STAGE(SB(1, 0), Bt, ldb, boff, bcol, 1); STAGE(SA(1, 0), A, lda, aoff, brow, 1); STAGE(SB(1, 1), Bt, ldb, boff, bcol + HALF, 1);
;     WAIT_V(6); BAR;
;     for (int t = 0; t < nt - 2; t += 2) {
;       LDB(B0, 0, 0); SCHED; LDA(At, 0, 0); STAGE(SA(1, 1), A, lda, aoff, brow + HALF, t + 1);
;       WAIT_L(8); BAR; WAIT_L(0); MMA(0, 0, At, B0); BAR; SCHED;
;       LDB(B1, 0, 1); STAGE(SB(0, 0), Bt, ldb, boff, bcol, t + 2);
.LBB0_409:
	s_or_b64 exec, exec, s[0:1]
	s_lshl_b32 s0, s18, 19
	v_readlane_b32 s8, v251, 49
	v_readlane_b32 s9, v251, 50
	s_add_u32 s0, s8, s0
	v_readlane_b32 s10, v251, 51
	v_readlane_b32 s11, v251, 52
	s_addc_u32 s1, s9, 0
	v_mov_b32_e32 v0, v131
	v_add_u32_e32 v144, s96, v130
	s_waitcnt vmcnt(4)
	s_barrier
	s_mov_b64 s[10:11], 0x80
	v_lshl_add_u64 v[2:3], s[0:1], 0, v[0:1]
	v_readfirstlane_b32 s8, v144
	v_add_u32_e32 v145, 0x2000, v144
	v_lshl_add_u64 v[4:5], v[2:3], 0, s[10:11]
	s_mov_b32 m0, s8
	v_readfirstlane_b32 s8, v145
	v_readlane_b32 s40, v252, 20
	v_readlane_b32 s12, v251, 53
	v_readlane_b32 s13, v251, 54
	global_load_lds_dwordx4 v[4:5], off
	s_mov_b32 m0, s8
	s_lshl_b32 s8, s20, 19
	v_readlane_b32 s50, v252, 30
	s_mov_b64 s[12:13], 0x20080
	v_readlane_b32 s51, v252, 31
	s_add_u32 s8, s50, s8
	v_lshl_add_u64 v[2:3], v[2:3], 0, s[12:13]
	s_addc_u32 s9, s51, 0
	v_mov_b32_e32 v0, v131
	global_load_lds_dwordx4 v[2:3], off
	v_add_u32_e32 v146, 0x8000, v134
	v_lshl_add_u64 v[2:3], s[8:9], 0, v[0:1]
	v_lshl_add_u64 v[4:5], v[2:3], 0, s[10:11]
	v_readfirstlane_b32 s10, v146
	v_add_u32_e32 v147, 0xa000, v134
	s_mov_b32 m0, s10
	v_readfirstlane_b32 s10, v147
	global_load_lds_dwordx4 v[4:5], off
	v_lshl_add_u64 v[2:3], v[2:3], 0, s[12:13]
	s_mov_b32 m0, s10
	v_mov_b32_e32 v0, v131
	v_add_u32_e32 v148, s75, v130
	global_load_lds_dwordx4 v[2:3], off
	s_mov_b64 s[24:25], 0x40080
	v_lshl_add_u64 v[2:3], s[0:1], 0, v[0:1]
	v_readfirstlane_b32 s10, v148
	v_add_u32_e32 v149, 0x2000, v148
	v_lshl_add_u64 v[4:5], v[2:3], 0, s[24:25]
	s_mov_b32 m0, s10
	v_readfirstlane_b32 s10, v149
	global_load_lds_dwordx4 v[4:5], off
	v_lshl_add_u64 v[2:3], v[2:3], 0, s[36:37]
	s_mov_b32 m0, s10
	s_mov_b32 s21, -2
	global_load_lds_dwordx4 v[2:3], off
	s_waitcnt vmcnt(6)
	s_mov_b64 s[10:11], 0
	s_waitcnt vmcnt(0)
	s_waitcnt lgkmcnt(0)
	s_mov_b64 s[26:27], 0x40180
	s_mov_b64 s[28:29], 0x60180
	v_readlane_b32 s14, v251, 55
	v_readlane_b32 s15, v251, 56
	v_readlane_b32 s41, v252, 21
	v_readlane_b32 s42, v252, 22
	v_readlane_b32 s43, v252, 23
	v_readlane_b32 s44, v252, 24
	v_readlane_b32 s45, v252, 25
	v_readlane_b32 s46, v252, 26
	v_readlane_b32 s47, v252, 27
	v_readlane_b32 s48, v252, 28
	v_readlane_b32 s49, v252, 29
	v_readlane_b32 s52, v252, 32
	v_readlane_b32 s53, v252, 33
	v_readlane_b32 s54, v252, 34
	v_readlane_b32 s55, v252, 35
	s_barrier
	v_add_u32_e32 v220, s2, v140
	v_readfirstlane_b32 s16, v134
	s_add_u32 s16, s16, 0xc000
	v_readfirstlane_b32 s23, v134
	s_add_u32 s23, s23, 0xe000
	v_add_u32_e32 v221, s33, v140
	v_readfirstlane_b32 s30, v132
	v_readfirstlane_b32 s31, v133
	v_readfirstlane_b32 s32, v134
	v_readfirstlane_b32 s40, v135
	v_readfirstlane_b32 s41, v136
	v_readfirstlane_b32 s42, v137
	v_add_u32_e32 v222, s96, v140
	v_readfirstlane_b32 s43, v138
	v_readfirstlane_b32 s44, v139
	v_add_u32_e32 v223, s75, v140
	v_readfirstlane_b32 s45, v144
	v_readfirstlane_b32 s46, v145
	v_readfirstlane_b32 s47, v146
	v_readfirstlane_b32 s48, v147
	v_readfirstlane_b32 s49, v148
	v_readfirstlane_b32 s50, v149
	v_add_u32_e32 v150, 0xc000, v134
	v_add_u32_e32 v151, 0xe000, v134
	ds_read_b128 v[152:155], v220
	ds_read_b128 v[156:159], v220 offset:1024
	ds_read_b128 v[160:163], v220 offset:2048
	ds_read_b128 v[164:167], v220 offset:3072
	s_add_u32 s12, s8, s10
	s_addc_u32 s13, s9, s11
	ds_read_b128 v[168:171], v143
	ds_read_b128 v[172:175], v143 offset:1024
	ds_read_b128 v[176:179], v143 offset:2048
	ds_read_b128 v[180:183], v143 offset:3072
	ds_read_b128 v[184:187], v143 offset:4096
	ds_read_b128 v[188:191], v143 offset:5120
	ds_read_b128 v[192:195], v143 offset:6144
	ds_read_b128 v[196:199], v143 offset:7168
	s_mov_b32 m0, s16
	s_add_u32 s98, s12, s24
	s_addc_u32 s99, s13, s25
	global_load_lds_dwordx4 v131, s[98:99]
	s_mov_b32 m0, s23
	s_add_u32 s98, s12, s36
	s_addc_u32 s99, s13, s37
	global_load_lds_dwordx4 v131, s[98:99]
	s_waitcnt lgkmcnt(8)
	s_waitcnt vmcnt(10)
	s_barrier
	s_waitcnt lgkmcnt(0)
	v_mfma_f32_16x16x32_bf16 v[126:129], v[152:155], v[168:171], 0
	v_mfma_f32_16x16x32_bf16 v[122:125], v[160:163], v[168:171], 0
	v_mfma_f32_16x16x32_bf16 v[118:121], v[152:155], v[176:179], 0
	v_mfma_f32_16x16x32_bf16 v[114:117], v[160:163], v[176:179], 0
	v_mfma_f32_16x16x32_bf16 v[110:113], v[152:155], v[184:187], 0
	v_mfma_f32_16x16x32_bf16 v[106:109], v[160:163], v[184:187], 0
	v_mfma_f32_16x16x32_bf16 v[102:105], v[152:155], v[192:195], 0
	v_mfma_f32_16x16x32_bf16 v[98:101], v[160:163], v[192:195], 0
	v_mfma_f32_16x16x32_bf16 v[126:129], v[156:159], v[172:175], v[126:129]
	v_mfma_f32_16x16x32_bf16 v[122:125], v[164:167], v[172:175], v[122:125]
	v_mfma_f32_16x16x32_bf16 v[118:121], v[156:159], v[180:183], v[118:121]
	v_mfma_f32_16x16x32_bf16 v[114:117], v[164:167], v[180:183], v[114:117]
	v_mfma_f32_16x16x32_bf16 v[110:113], v[156:159], v[188:191], v[110:113]
	v_mfma_f32_16x16x32_bf16 v[106:109], v[164:167], v[188:191], v[106:109]
	v_mfma_f32_16x16x32_bf16 v[102:105], v[156:159], v[196:199], v[102:105]
	v_mfma_f32_16x16x32_bf16 v[98:101], v[164:167], v[196:199], v[98:101]
	s_barrier
	s_add_u32 s14, s0, s10
	ds_read_b128 v[200:203], v221
	ds_read_b128 v[204:207], v221 offset:1024
	ds_read_b128 v[208:211], v221 offset:2048
	ds_read_b128 v[212:215], v221 offset:3072
	s_addc_u32 s15, s1, s11
	s_mov_b32 m0, s30
	s_add_u32 s98, s14, s34
	s_addc_u32 s99, s15, s35
	global_load_lds_dwordx4 v131, s[98:99]
	s_mov_b32 m0, s31
	s_add_u32 s98, s14, s64
	s_addc_u32 s99, s15, s65
	global_load_lds_dwordx4 v131, s[98:99]
	s_waitcnt vmcnt(10)
	s_barrier
; #define LDA(dst, b, h) for (int m = 0; m < 4; ++m) for (int k = 0; k < 2; ++k) \
;     dst[m][k] = *reinterpret_cast<const bf16x8*>((char*)SA(b, h) + a_thr + (m * 2 + k) * 1024)
; #define LDB(dst, b, h) for (int n = 0; n < 2; ++n) for (int k = 0; k < 2; ++k) \
;     dst[n][k] = *reinterpret_cast<const bf16x8*>((char*)SB(b, h) + b_thr + (n * 2 + k) * 1024)
; #define MMA(ai, bj, At, Btf) do { __builtin_amdgcn_s_setprio(1); \
;     for (int m = 0; m < 4; ++m) for (int n = 0; n < 2; ++n) for (int k = 0; k < 2; ++k) \
;       acc[ai][bj][m][n] = __builtin_amdgcn_mfma_f32_16x16x32_bf16(Btf[n][k], At[m][k], acc[ai][bj][m][n], 0, 0, 0); \
;     __builtin_amdgcn_s_setprio(0); } while (0)
; #define WAIT_V(n) asm volatile("s_waitcnt vmcnt(" #n ")" ::: "memory")
; #define WAIT_L(n) asm volatile("s_waitcnt lgkmcnt(" #n ")" ::: "memory")
; #define BAR __builtin_amdgcn_s_barrier()
; #define SCHED __builtin_amdgcn_sched_barrier(0)
; template <bool OVL, bool PANEL = false, class Epi>
; __device__ __forceinline__ void gemm_phase(const bf16_t* __restrict__ A, long lda, const bf16_t* __restrict__ Bt, long ldb, int nM, int nN, int K,
;                                            const Epi& epi, bf16_t* shm, int w0) {
;     ...
;       LDB(B1, 0, 1); STAGE(SB(0, 0), Bt, ldb, boff, bcol, t + 2);
;       BAR; WAIT_L(0); MMA(0, 1, At, B1); BAR;
;       LDA(At, 0, 1); STAGE(SA(0, 0), A, lda, aoff, brow, t + 2);
;       BAR; WAIT_L(0); MMA(1, 0, At, B0); BAR; SCHED;
;       STAGE(SB(0, 1), Bt, ldb, boff, bcol + HALF, t + 2);
;       WAIT_V(6); BAR; MMA(1, 1, At, B1); BAR;
;       LDB(B0, 1, 0); SCHED; LDA(At, 1, 0); STAGE(SA(0, 1), A, lda, aoff, brow + HALF, t + 2);
;       WAIT_L(8); BAR; WAIT_L(0); MMA(0, 0, At, B0); BAR; SCHED;
	s_waitcnt lgkmcnt(0)
	v_mfma_f32_16x16x32_bf16 v[94:97], v[200:203], v[168:171], 0
	v_mfma_f32_16x16x32_bf16 v[90:93], v[208:211], v[168:171], 0
	v_mfma_f32_16x16x32_bf16 v[86:89], v[200:203], v[176:179], 0
	v_mfma_f32_16x16x32_bf16 v[82:85], v[208:211], v[176:179], 0
	v_mfma_f32_16x16x32_bf16 v[78:81], v[200:203], v[184:187], 0
	v_mfma_f32_16x16x32_bf16 v[74:77], v[208:211], v[184:187], 0
	v_mfma_f32_16x16x32_bf16 v[70:73], v[200:203], v[192:195], 0
	v_mfma_f32_16x16x32_bf16 v[66:69], v[208:211], v[192:195], 0
	v_mfma_f32_16x16x32_bf16 v[94:97], v[204:207], v[172:175], v[94:97]
	v_mfma_f32_16x16x32_bf16 v[90:93], v[212:215], v[172:175], v[90:93]
	v_mfma_f32_16x16x32_bf16 v[86:89], v[204:207], v[180:183], v[86:89]
	v_mfma_f32_16x16x32_bf16 v[82:85], v[212:215], v[180:183], v[82:85]
	v_mfma_f32_16x16x32_bf16 v[78:81], v[204:207], v[188:191], v[78:81]
	v_mfma_f32_16x16x32_bf16 v[74:77], v[212:215], v[188:191], v[74:77]
	v_mfma_f32_16x16x32_bf16 v[70:73], v[204:207], v[196:199], v[70:73]
	v_mfma_f32_16x16x32_bf16 v[66:69], v[212:215], v[196:199], v[66:69]
	s_barrier
	ds_read_b128 v[168:171], v143 offset:16384
	ds_read_b128 v[172:175], v143 offset:17408
	ds_read_b128 v[176:179], v143 offset:18432
	ds_read_b128 v[180:183], v143 offset:19456
	ds_read_b128 v[184:187], v143 offset:20480
	ds_read_b128 v[188:191], v143 offset:21504
	ds_read_b128 v[192:195], v143 offset:22528
	ds_read_b128 v[196:199], v143 offset:23552
	s_mov_b32 m0, s32
	s_add_u32 s98, s12, s34
	s_addc_u32 s99, s13, s35
	global_load_lds_dwordx4 v131, s[98:99]
	s_mov_b32 m0, s40
	s_add_u32 s98, s12, s64
	s_addc_u32 s99, s13, s65
	global_load_lds_dwordx4 v131, s[98:99]
	s_barrier
	s_waitcnt lgkmcnt(0)
	v_mfma_f32_16x16x32_bf16 v[62:65], v[152:155], v[168:171], 0
	v_mfma_f32_16x16x32_bf16 v[58:61], v[160:163], v[168:171], 0
	v_mfma_f32_16x16x32_bf16 v[54:57], v[152:155], v[176:179], 0
	v_mfma_f32_16x16x32_bf16 v[50:53], v[160:163], v[176:179], 0
	v_mfma_f32_16x16x32_bf16 v[46:49], v[152:155], v[184:187], 0
	v_mfma_f32_16x16x32_bf16 v[42:45], v[160:163], v[184:187], 0
	v_mfma_f32_16x16x32_bf16 v[38:41], v[152:155], v[192:195], 0
	v_mfma_f32_16x16x32_bf16 v[34:37], v[160:163], v[192:195], 0
	v_mfma_f32_16x16x32_bf16 v[62:65], v[156:159], v[172:175], v[62:65]
	v_mfma_f32_16x16x32_bf16 v[58:61], v[164:167], v[172:175], v[58:61]
	v_mfma_f32_16x16x32_bf16 v[54:57], v[156:159], v[180:183], v[54:57]
	v_mfma_f32_16x16x32_bf16 v[50:53], v[164:167], v[180:183], v[50:53]
	v_mfma_f32_16x16x32_bf16 v[46:49], v[156:159], v[188:191], v[46:49]
	v_mfma_f32_16x16x32_bf16 v[42:45], v[164:167], v[188:191], v[42:45]
	v_mfma_f32_16x16x32_bf16 v[38:41], v[156:159], v[196:199], v[38:41]
	v_mfma_f32_16x16x32_bf16 v[34:37], v[164:167], v[196:199], v[34:37]
	s_barrier
	s_mov_b32 m0, s41
	s_add_u32 s98, s14, s68
	s_addc_u32 s99, s15, s69
	global_load_lds_dwordx4 v131, s[98:99]
	s_mov_b32 m0, s42
	s_add_u32 s98, s14, s70
	s_addc_u32 s99, s15, s71
	global_load_lds_dwordx4 v131, s[98:99]
	s_waitcnt vmcnt(10)
	s_barrier
	v_mfma_f32_16x16x32_bf16 v[30:33], v[200:203], v[168:171], 0
	v_mfma_f32_16x16x32_bf16 v[26:29], v[208:211], v[168:171], 0
	v_mfma_f32_16x16x32_bf16 v[22:25], v[200:203], v[176:179], 0
	v_mfma_f32_16x16x32_bf16 v[18:21], v[208:211], v[176:179], 0
	v_mfma_f32_16x16x32_bf16 v[14:17], v[200:203], v[184:187], 0
	v_mfma_f32_16x16x32_bf16 v[10:13], v[208:211], v[184:187], 0
	v_mfma_f32_16x16x32_bf16 v[6:9], v[200:203], v[192:195], 0
	v_mfma_f32_16x16x32_bf16 v[2:5], v[208:211], v[192:195], 0
	v_mfma_f32_16x16x32_bf16 v[30:33], v[204:207], v[172:175], v[30:33]
	v_mfma_f32_16x16x32_bf16 v[26:29], v[212:215], v[172:175], v[26:29]
	v_mfma_f32_16x16x32_bf16 v[22:25], v[204:207], v[180:183], v[22:25]
	v_mfma_f32_16x16x32_bf16 v[18:21], v[212:215], v[180:183], v[18:21]
	v_mfma_f32_16x16x32_bf16 v[14:17], v[204:207], v[188:191], v[14:17]
	v_mfma_f32_16x16x32_bf16 v[10:13], v[212:215], v[188:191], v[10:13]
	v_mfma_f32_16x16x32_bf16 v[6:9], v[204:207], v[196:199], v[6:9]
	v_mfma_f32_16x16x32_bf16 v[2:5], v[212:215], v[196:199], v[2:5]
	s_barrier
	ds_read_b128 v[152:155], v222
	ds_read_b128 v[156:159], v222 offset:1024
	ds_read_b128 v[160:163], v222 offset:2048
	ds_read_b128 v[164:167], v222 offset:3072
	ds_read_b128 v[168:171], v143 offset:32768
	ds_read_b128 v[172:175], v143 offset:33792
	ds_read_b128 v[176:179], v143 offset:34816
	ds_read_b128 v[180:183], v143 offset:35840
	ds_read_b128 v[184:187], v143 offset:36864
	ds_read_b128 v[188:191], v143 offset:37888
	ds_read_b128 v[192:195], v143 offset:38912
	ds_read_b128 v[196:199], v143 offset:39936
	s_mov_b32 m0, s43
	s_add_u32 s98, s12, s68
	s_addc_u32 s99, s13, s69
	global_load_lds_dwordx4 v131, s[98:99]
	s_mov_b32 m0, s44
	s_add_u32 s98, s12, s70
	s_addc_u32 s99, s13, s71
	global_load_lds_dwordx4 v131, s[98:99]
	s_waitcnt lgkmcnt(8)
	s_waitcnt vmcnt(10)
	s_barrier
	s_waitcnt lgkmcnt(0)
	v_mfma_f32_16x16x32_bf16 v[126:129], v[152:155], v[168:171], v[126:129]
	v_mfma_f32_16x16x32_bf16 v[122:125], v[160:163], v[168:171], v[122:125]
	v_mfma_f32_16x16x32_bf16 v[118:121], v[152:155], v[176:179], v[118:121]
	v_mfma_f32_16x16x32_bf16 v[114:117], v[160:163], v[176:179], v[114:117]
	v_mfma_f32_16x16x32_bf16 v[110:113], v[152:155], v[184:187], v[110:113]
	v_mfma_f32_16x16x32_bf16 v[106:109], v[160:163], v[184:187], v[106:109]
	v_mfma_f32_16x16x32_bf16 v[102:105], v[152:155], v[192:195], v[102:105]
	v_mfma_f32_16x16x32_bf16 v[98:101], v[160:163], v[192:195], v[98:101]
	v_mfma_f32_16x16x32_bf16 v[126:129], v[156:159], v[172:175], v[126:129]
	v_mfma_f32_16x16x32_bf16 v[122:125], v[164:167], v[172:175], v[122:125]
	v_mfma_f32_16x16x32_bf16 v[118:121], v[156:159], v[180:183], v[118:121]
	v_mfma_f32_16x16x32_bf16 v[114:117], v[164:167], v[180:183], v[114:117]
	v_mfma_f32_16x16x32_bf16 v[110:113], v[156:159], v[188:191], v[110:113]
	v_mfma_f32_16x16x32_bf16 v[106:109], v[164:167], v[188:191], v[106:109]
	v_mfma_f32_16x16x32_bf16 v[102:105], v[156:159], v[196:199], v[102:105]
	v_mfma_f32_16x16x32_bf16 v[98:101], v[164:167], v[196:199], v[98:101]
	s_barrier
; #define LDA(dst, b, h) for (int m = 0; m < 4; ++m) for (int k = 0; k < 2; ++k) \
;     dst[m][k] = *reinterpret_cast<const bf16x8*>((char*)SA(b, h) + a_thr + (m * 2 + k) * 1024)
; #define LDB(dst, b, h) for (int n = 0; n < 2; ++n) for (int k = 0; k < 2; ++k) \
;     dst[n][k] = *reinterpret_cast<const bf16x8*>((char*)SB(b, h) + b_thr + (n * 2 + k) * 1024)
; #define MMA(ai, bj, At, Btf) do { __builtin_amdgcn_s_setprio(1); \
;     for (int m = 0; m < 4; ++m) for (int n = 0; n < 2; ++n) for (int k = 0; k < 2; ++k) \
;       acc[ai][bj][m][n] = __builtin_amdgcn_mfma_f32_16x16x32_bf16(Btf[n][k], At[m][k], acc[ai][bj][m][n], 0, 0, 0); \
;     __builtin_amdgcn_s_setprio(0); } while (0)
; #define WAIT_V(n) asm volatile("s_waitcnt vmcnt(" #n ")" ::: "memory")
; #define WAIT_L(n) asm volatile("s_waitcnt lgkmcnt(" #n ")" ::: "memory")
; #define BAR __builtin_amdgcn_s_barrier()
; #define SCHED __builtin_amdgcn_sched_barrier(0)
; template <bool OVL, bool PANEL = false, class Epi>
; __device__ __forceinline__ void gemm_phase(const bf16_t* __restrict__ A, long lda, const bf16_t* __restrict__ Bt, long ldb, int nM, int nN, int K,
;                                            const Epi& epi, bf16_t* shm, int w0) {
;     ...
;       LDB(B1, 1, 1); STAGE(SB(1, 0), Bt, ldb, boff, bcol, t + 3);
;       BAR; WAIT_L(0); MMA(0, 1, At, B1); BAR;
;       LDA(At, 1, 1); STAGE(SA(1, 0), A, lda, aoff, brow, t + 3);
;       BAR; WAIT_L(0); MMA(1, 0, At, B0); BAR; SCHED;
;       STAGE(SB(1, 1), Bt, ldb, boff, bcol + HALF, t + 3);
;       WAIT_V(6); BAR; MMA(1, 1, At, B1); BAR;
	ds_read_b128 v[200:203], v223
	ds_read_b128 v[204:207], v223 offset:1024
	ds_read_b128 v[208:211], v223 offset:2048
	ds_read_b128 v[212:215], v223 offset:3072
	s_mov_b32 m0, s45
	s_add_u32 s98, s14, s94
	s_addc_u32 s99, s15, s95
	global_load_lds_dwordx4 v131, s[98:99]
	s_mov_b32 m0, s46
	s_add_u32 s98, s14, s72
	s_addc_u32 s99, s15, s73
	global_load_lds_dwordx4 v131, s[98:99]
	s_waitcnt vmcnt(10)
	s_barrier
	s_waitcnt lgkmcnt(0)
	v_mfma_f32_16x16x32_bf16 v[94:97], v[200:203], v[168:171], v[94:97]
	v_mfma_f32_16x16x32_bf16 v[90:93], v[208:211], v[168:171], v[90:93]
	v_mfma_f32_16x16x32_bf16 v[86:89], v[200:203], v[176:179], v[86:89]
	v_mfma_f32_16x16x32_bf16 v[82:85], v[208:211], v[176:179], v[82:85]
	v_mfma_f32_16x16x32_bf16 v[78:81], v[200:203], v[184:187], v[78:81]
	v_mfma_f32_16x16x32_bf16 v[74:77], v[208:211], v[184:187], v[74:77]
	v_mfma_f32_16x16x32_bf16 v[70:73], v[200:203], v[192:195], v[70:73]
	v_mfma_f32_16x16x32_bf16 v[66:69], v[208:211], v[192:195], v[66:69]
	v_mfma_f32_16x16x32_bf16 v[94:97], v[204:207], v[172:175], v[94:97]
	v_mfma_f32_16x16x32_bf16 v[90:93], v[212:215], v[172:175], v[90:93]
	v_mfma_f32_16x16x32_bf16 v[86:89], v[204:207], v[180:183], v[86:89]
	v_mfma_f32_16x16x32_bf16 v[82:85], v[212:215], v[180:183], v[82:85]
	v_mfma_f32_16x16x32_bf16 v[78:81], v[204:207], v[188:191], v[78:81]
	v_mfma_f32_16x16x32_bf16 v[74:77], v[212:215], v[188:191], v[74:77]
	v_mfma_f32_16x16x32_bf16 v[70:73], v[204:207], v[196:199], v[70:73]
	v_mfma_f32_16x16x32_bf16 v[66:69], v[212:215], v[196:199], v[66:69]
	s_barrier
	ds_read_b128 v[168:171], v143 offset:49152
	ds_read_b128 v[172:175], v143 offset:50176
	ds_read_b128 v[176:179], v143 offset:51200
	ds_read_b128 v[180:183], v143 offset:52224
	ds_read_b128 v[184:187], v143 offset:53248
	ds_read_b128 v[188:191], v143 offset:54272
	ds_read_b128 v[192:195], v143 offset:55296
	ds_read_b128 v[196:199], v143 offset:56320
	s_mov_b32 m0, s47
	s_add_u32 s98, s12, s94
	s_addc_u32 s99, s13, s95
	global_load_lds_dwordx4 v131, s[98:99]
	s_mov_b32 m0, s48
	s_add_u32 s98, s12, s72
	s_addc_u32 s99, s13, s73
	global_load_lds_dwordx4 v131, s[98:99]
	s_barrier
	s_waitcnt lgkmcnt(0)
	v_mfma_f32_16x16x32_bf16 v[62:65], v[152:155], v[168:171], v[62:65]
	v_mfma_f32_16x16x32_bf16 v[58:61], v[160:163], v[168:171], v[58:61]
	v_mfma_f32_16x16x32_bf16 v[54:57], v[152:155], v[176:179], v[54:57]
	v_mfma_f32_16x16x32_bf16 v[50:53], v[160:163], v[176:179], v[50:53]
	v_mfma_f32_16x16x32_bf16 v[46:49], v[152:155], v[184:187], v[46:49]
	v_mfma_f32_16x16x32_bf16 v[42:45], v[160:163], v[184:187], v[42:45]
	v_mfma_f32_16x16x32_bf16 v[38:41], v[152:155], v[192:195], v[38:41]
	v_mfma_f32_16x16x32_bf16 v[34:37], v[160:163], v[192:195], v[34:37]
	v_mfma_f32_16x16x32_bf16 v[62:65], v[156:159], v[172:175], v[62:65]
	v_mfma_f32_16x16x32_bf16 v[58:61], v[164:167], v[172:175], v[58:61]
	v_mfma_f32_16x16x32_bf16 v[54:57], v[156:159], v[180:183], v[54:57]
	v_mfma_f32_16x16x32_bf16 v[50:53], v[164:167], v[180:183], v[50:53]
	v_mfma_f32_16x16x32_bf16 v[46:49], v[156:159], v[188:191], v[46:49]
	v_mfma_f32_16x16x32_bf16 v[42:45], v[164:167], v[188:191], v[42:45]
	v_mfma_f32_16x16x32_bf16 v[38:41], v[156:159], v[196:199], v[38:41]
	v_mfma_f32_16x16x32_bf16 v[34:37], v[164:167], v[196:199], v[34:37]
	s_barrier
	s_mov_b32 m0, s49
	s_add_u32 s98, s14, s26
	s_addc_u32 s99, s15, s27
	global_load_lds_dwordx4 v131, s[98:99]
	s_mov_b32 m0, s50
	s_add_u32 s98, s14, s28
	s_addc_u32 s99, s15, s29
	global_load_lds_dwordx4 v131, s[98:99]
	s_add_i32 s21, s21, 2
	s_add_u32 s10, s10, 0x100
	s_addc_u32 s11, s11, 0
	s_cmp_lt_u32 s21, 12
	s_waitcnt vmcnt(10)
	s_barrier
	v_mfma_f32_16x16x32_bf16 v[30:33], v[200:203], v[168:171], v[30:33]
	v_mfma_f32_16x16x32_bf16 v[26:29], v[208:211], v[168:171], v[26:29]
	v_mfma_f32_16x16x32_bf16 v[22:25], v[200:203], v[176:179], v[22:25]
	v_mfma_f32_16x16x32_bf16 v[18:21], v[208:211], v[176:179], v[18:21]
	v_mfma_f32_16x16x32_bf16 v[14:17], v[200:203], v[184:187], v[14:17]
	v_mfma_f32_16x16x32_bf16 v[10:13], v[208:211], v[184:187], v[10:13]
	v_mfma_f32_16x16x32_bf16 v[6:9], v[200:203], v[192:195], v[6:9]
	v_mfma_f32_16x16x32_bf16 v[2:5], v[208:211], v[192:195], v[2:5]
	v_mfma_f32_16x16x32_bf16 v[30:33], v[204:207], v[172:175], v[30:33]
	v_mfma_f32_16x16x32_bf16 v[26:29], v[212:215], v[172:175], v[26:29]
	v_mfma_f32_16x16x32_bf16 v[22:25], v[204:207], v[180:183], v[22:25]
	v_mfma_f32_16x16x32_bf16 v[18:21], v[212:215], v[180:183], v[18:21]
	v_mfma_f32_16x16x32_bf16 v[14:17], v[204:207], v[188:191], v[14:17]
	v_mfma_f32_16x16x32_bf16 v[10:13], v[212:215], v[188:191], v[10:13]
	v_mfma_f32_16x16x32_bf16 v[6:9], v[204:207], v[196:199], v[6:9]
	v_mfma_f32_16x16x32_bf16 v[2:5], v[212:215], v[196:199], v[2:5]
	s_barrier
; #define LDA(dst, b, h) for (int m = 0; m < 4; ++m) for (int k = 0; k < 2; ++k) \
;     dst[m][k] = *reinterpret_cast<const bf16x8*>((char*)SA(b, h) + a_thr + (m * 2 + k) * 1024)
; #define LDB(dst, b, h) for (int n = 0; n < 2; ++n) for (int k = 0; k < 2; ++k) \
;     dst[n][k] = *reinterpret_cast<const bf16x8*>((char*)SB(b, h) + b_thr + (n * 2 + k) * 1024)
; #define MMA(ai, bj, At, Btf) do { __builtin_amdgcn_s_setprio(1); \
;     for (int m = 0; m < 4; ++m) for (int n = 0; n < 2; ++n) for (int k = 0; k < 2; ++k) \
;       acc[ai][bj][m][n] = __builtin_amdgcn_mfma_f32_16x16x32_bf16(Btf[n][k], At[m][k], acc[ai][bj][m][n], 0, 0, 0); \
;     __builtin_amdgcn_s_setprio(0); } while (0)
; #define WAIT_V(n) asm volatile("s_waitcnt vmcnt(" #n ")" ::: "memory")
; #define WAIT_L(n) asm volatile("s_waitcnt lgkmcnt(" #n ")" ::: "memory")
; #define BAR __builtin_amdgcn_s_barrier()
; #define SCHED __builtin_amdgcn_sched_barrier(0)
; template <bool OVL, bool PANEL = false, class Epi>
; __device__ __forceinline__ void gemm_phase(const bf16_t* __restrict__ A, long lda, const bf16_t* __restrict__ Bt, long ldb, int nM, int nN, int K,
;                                            const Epi& epi, bf16_t* shm, int w0) {
;     ...
;       LDB(B0, 0, 0); SCHED; LDA(At, 0, 0); STAGE(SA(1, 1), A, lda, aoff, brow + HALF, t + 1);
;       WAIT_L(8); BAR; WAIT_L(0); MMA(0, 0, At, B0); BAR; SCHED;
;       LDB(B1, 0, 1); STAGE(SB(0, 0), Bt, ldb, boff, bcol, t + 2);
;       BAR; WAIT_L(0); MMA(0, 1, At, B1); BAR;
;       LDA(At, 0, 1); STAGE(SA(0, 0), A, lda, aoff, brow, t + 2);
;       BAR; WAIT_L(0); MMA(1, 0, At, B0); BAR; SCHED;
;       STAGE(SB(0, 1), Bt, ldb, boff, bcol + HALF, t + 2);
;       WAIT_V(6); BAR; MMA(1, 1, At, B1); BAR;
.LBB0_410:
	ds_read_b128 v[152:155], v220
	ds_read_b128 v[156:159], v220 offset:1024
	ds_read_b128 v[160:163], v220 offset:2048
	ds_read_b128 v[164:167], v220 offset:3072
	s_add_u32 s12, s8, s10
	s_addc_u32 s13, s9, s11
	ds_read_b128 v[168:171], v143
	ds_read_b128 v[172:175], v143 offset:1024
	ds_read_b128 v[176:179], v143 offset:2048
	ds_read_b128 v[180:183], v143 offset:3072
	ds_read_b128 v[184:187], v143 offset:4096
	ds_read_b128 v[188:191], v143 offset:5120
	ds_read_b128 v[192:195], v143 offset:6144
	ds_read_b128 v[196:199], v143 offset:7168
	s_mov_b32 m0, s16
	s_add_u32 s98, s12, s24
	s_addc_u32 s99, s13, s25
	global_load_lds_dwordx4 v131, s[98:99]
	s_mov_b32 m0, s23
	s_add_u32 s98, s12, s36
	s_addc_u32 s99, s13, s37
	global_load_lds_dwordx4 v131, s[98:99]
	s_waitcnt lgkmcnt(8)
	s_waitcnt vmcnt(10)
	s_barrier
	s_waitcnt lgkmcnt(0)
	v_mfma_f32_16x16x32_bf16 v[126:129], v[152:155], v[168:171], v[126:129]
	v_mfma_f32_16x16x32_bf16 v[122:125], v[160:163], v[168:171], v[122:125]
	v_mfma_f32_16x16x32_bf16 v[118:121], v[152:155], v[176:179], v[118:121]
	v_mfma_f32_16x16x32_bf16 v[114:117], v[160:163], v[176:179], v[114:117]
	v_mfma_f32_16x16x32_bf16 v[110:113], v[152:155], v[184:187], v[110:113]
	v_mfma_f32_16x16x32_bf16 v[106:109], v[160:163], v[184:187], v[106:109]
	v_mfma_f32_16x16x32_bf16 v[102:105], v[152:155], v[192:195], v[102:105]
	v_mfma_f32_16x16x32_bf16 v[98:101], v[160:163], v[192:195], v[98:101]
	v_mfma_f32_16x16x32_bf16 v[126:129], v[156:159], v[172:175], v[126:129]
	v_mfma_f32_16x16x32_bf16 v[122:125], v[164:167], v[172:175], v[122:125]
	v_mfma_f32_16x16x32_bf16 v[118:121], v[156:159], v[180:183], v[118:121]
	v_mfma_f32_16x16x32_bf16 v[114:117], v[164:167], v[180:183], v[114:117]
	v_mfma_f32_16x16x32_bf16 v[110:113], v[156:159], v[188:191], v[110:113]
	v_mfma_f32_16x16x32_bf16 v[106:109], v[164:167], v[188:191], v[106:109]
	v_mfma_f32_16x16x32_bf16 v[102:105], v[156:159], v[196:199], v[102:105]
	v_mfma_f32_16x16x32_bf16 v[98:101], v[164:167], v[196:199], v[98:101]
	s_barrier
	s_add_u32 s14, s0, s10
	ds_read_b128 v[200:203], v221
	ds_read_b128 v[204:207], v221 offset:1024
	ds_read_b128 v[208:211], v221 offset:2048
	ds_read_b128 v[212:215], v221 offset:3072
	s_addc_u32 s15, s1, s11
	s_mov_b32 m0, s30
	s_add_u32 s98, s14, s34
	s_addc_u32 s99, s15, s35
	global_load_lds_dwordx4 v131, s[98:99]
	s_mov_b32 m0, s31
	s_add_u32 s98, s14, s64
	s_addc_u32 s99, s15, s65
	global_load_lds_dwordx4 v131, s[98:99]
	s_waitcnt vmcnt(10)
	s_barrier
	s_waitcnt lgkmcnt(0)
	v_mfma_f32_16x16x32_bf16 v[94:97], v[200:203], v[168:171], v[94:97]
	v_mfma_f32_16x16x32_bf16 v[90:93], v[208:211], v[168:171], v[90:93]
	v_mfma_f32_16x16x32_bf16 v[86:89], v[200:203], v[176:179], v[86:89]
	v_mfma_f32_16x16x32_bf16 v[82:85], v[208:211], v[176:179], v[82:85]
	v_mfma_f32_16x16x32_bf16 v[78:81], v[200:203], v[184:187], v[78:81]
	v_mfma_f32_16x16x32_bf16 v[74:77], v[208:211], v[184:187], v[74:77]
	v_mfma_f32_16x16x32_bf16 v[70:73], v[200:203], v[192:195], v[70:73]
	v_mfma_f32_16x16x32_bf16 v[66:69], v[208:211], v[192:195], v[66:69]
	v_mfma_f32_16x16x32_bf16 v[94:97], v[204:207], v[172:175], v[94:97]
	v_mfma_f32_16x16x32_bf16 v[90:93], v[212:215], v[172:175], v[90:93]
	v_mfma_f32_16x16x32_bf16 v[86:89], v[204:207], v[180:183], v[86:89]
	v_mfma_f32_16x16x32_bf16 v[82:85], v[212:215], v[180:183], v[82:85]
	v_mfma_f32_16x16x32_bf16 v[78:81], v[204:207], v[188:191], v[78:81]
	v_mfma_f32_16x16x32_bf16 v[74:77], v[212:215], v[188:191], v[74:77]
	v_mfma_f32_16x16x32_bf16 v[70:73], v[204:207], v[196:199], v[70:73]
	v_mfma_f32_16x16x32_bf16 v[66:69], v[212:215], v[196:199], v[66:69]
	s_barrier
	ds_read_b128 v[168:171], v143 offset:16384
	ds_read_b128 v[172:175], v143 offset:17408
	ds_read_b128 v[176:179], v143 offset:18432
	ds_read_b128 v[180:183], v143 offset:19456
	ds_read_b128 v[184:187], v143 offset:20480
	ds_read_b128 v[188:191], v143 offset:21504
	ds_read_b128 v[192:195], v143 offset:22528
	ds_read_b128 v[196:199], v143 offset:23552
	s_mov_b32 m0, s32
	s_add_u32 s98, s12, s34
	s_addc_u32 s99, s13, s35
	global_load_lds_dwordx4 v131, s[98:99]
	s_mov_b32 m0, s40
	s_add_u32 s98, s12, s64
	s_addc_u32 s99, s13, s65
	global_load_lds_dwordx4 v131, s[98:99]
	s_barrier
	s_waitcnt lgkmcnt(0)
	v_mfma_f32_16x16x32_bf16 v[62:65], v[152:155], v[168:171], v[62:65]
	v_mfma_f32_16x16x32_bf16 v[58:61], v[160:163], v[168:171], v[58:61]
	v_mfma_f32_16x16x32_bf16 v[54:57], v[152:155], v[176:179], v[54:57]
	v_mfma_f32_16x16x32_bf16 v[50:53], v[160:163], v[176:179], v[50:53]
	v_mfma_f32_16x16x32_bf16 v[46:49], v[152:155], v[184:187], v[46:49]
	v_mfma_f32_16x16x32_bf16 v[42:45], v[160:163], v[184:187], v[42:45]
	v_mfma_f32_16x16x32_bf16 v[38:41], v[152:155], v[192:195], v[38:41]
	v_mfma_f32_16x16x32_bf16 v[34:37], v[160:163], v[192:195], v[34:37]
	v_mfma_f32_16x16x32_bf16 v[62:65], v[156:159], v[172:175], v[62:65]
	v_mfma_f32_16x16x32_bf16 v[58:61], v[164:167], v[172:175], v[58:61]
	v_mfma_f32_16x16x32_bf16 v[54:57], v[156:159], v[180:183], v[54:57]
	v_mfma_f32_16x16x32_bf16 v[50:53], v[164:167], v[180:183], v[50:53]
	v_mfma_f32_16x16x32_bf16 v[46:49], v[156:159], v[188:191], v[46:49]
	v_mfma_f32_16x16x32_bf16 v[42:45], v[164:167], v[188:191], v[42:45]
	v_mfma_f32_16x16x32_bf16 v[38:41], v[156:159], v[196:199], v[38:41]
	v_mfma_f32_16x16x32_bf16 v[34:37], v[164:167], v[196:199], v[34:37]
	s_barrier
	s_mov_b32 m0, s41
	s_add_u32 s98, s14, s68
	s_addc_u32 s99, s15, s69
	global_load_lds_dwordx4 v131, s[98:99]
	s_mov_b32 m0, s42
	s_add_u32 s98, s14, s70
	s_addc_u32 s99, s15, s71
	global_load_lds_dwordx4 v131, s[98:99]
	s_waitcnt vmcnt(10)
	s_barrier
; #define LDA(dst, b, h) for (int m = 0; m < 4; ++m) for (int k = 0; k < 2; ++k) \
;     dst[m][k] = *reinterpret_cast<const bf16x8*>((char*)SA(b, h) + a_thr + (m * 2 + k) * 1024)
; #define LDB(dst, b, h) for (int n = 0; n < 2; ++n) for (int k = 0; k < 2; ++k) \
;     dst[n][k] = *reinterpret_cast<const bf16x8*>((char*)SB(b, h) + b_thr + (n * 2 + k) * 1024)
; #define MMA(ai, bj, At, Btf) do { __builtin_amdgcn_s_setprio(1); \
;     for (int m = 0; m < 4; ++m) for (int n = 0; n < 2; ++n) for (int k = 0; k < 2; ++k) \
;       acc[ai][bj][m][n] = __builtin_amdgcn_mfma_f32_16x16x32_bf16(Btf[n][k], At[m][k], acc[ai][bj][m][n], 0, 0, 0); \
;     __builtin_amdgcn_s_setprio(0); } while (0)
; #define WAIT_V(n) asm volatile("s_waitcnt vmcnt(" #n ")" ::: "memory")
; #define WAIT_L(n) asm volatile("s_waitcnt lgkmcnt(" #n ")" ::: "memory")
; #define BAR __builtin_amdgcn_s_barrier()
; #define SCHED __builtin_amdgcn_sched_barrier(0)
; template <bool OVL, bool PANEL = false, class Epi>
; __device__ __forceinline__ void gemm_phase(const bf16_t* __restrict__ A, long lda, const bf16_t* __restrict__ Bt, long ldb, int nM, int nN, int K,
;                                            const Epi& epi, bf16_t* shm, int w0) {
;     ...
;       WAIT_V(6); BAR; MMA(1, 1, At, B1); BAR;
;       LDB(B0, 1, 0); SCHED; LDA(At, 1, 0); STAGE(SA(0, 1), A, lda, aoff, brow + HALF, t + 2);
;       WAIT_L(8); BAR; WAIT_L(0); MMA(0, 0, At, B0); BAR; SCHED;
;       LDB(B1, 1, 1); STAGE(SB(1, 0), Bt, ldb, boff, bcol, t + 3);
;       BAR; WAIT_L(0); MMA(0, 1, At, B1); BAR;
	v_mfma_f32_16x16x32_bf16 v[30:33], v[200:203], v[168:171], v[30:33]
	v_mfma_f32_16x16x32_bf16 v[26:29], v[208:211], v[168:171], v[26:29]
	v_mfma_f32_16x16x32_bf16 v[22:25], v[200:203], v[176:179], v[22:25]
	v_mfma_f32_16x16x32_bf16 v[18:21], v[208:211], v[176:179], v[18:21]
	v_mfma_f32_16x16x32_bf16 v[14:17], v[200:203], v[184:187], v[14:17]
	v_mfma_f32_16x16x32_bf16 v[10:13], v[208:211], v[184:187], v[10:13]
	v_mfma_f32_16x16x32_bf16 v[6:9], v[200:203], v[192:195], v[6:9]
	v_mfma_f32_16x16x32_bf16 v[2:5], v[208:211], v[192:195], v[2:5]
	v_mfma_f32_16x16x32_bf16 v[30:33], v[204:207], v[172:175], v[30:33]
	v_mfma_f32_16x16x32_bf16 v[26:29], v[212:215], v[172:175], v[26:29]
	v_mfma_f32_16x16x32_bf16 v[22:25], v[204:207], v[180:183], v[22:25]
	v_mfma_f32_16x16x32_bf16 v[18:21], v[212:215], v[180:183], v[18:21]
	v_mfma_f32_16x16x32_bf16 v[14:17], v[204:207], v[188:191], v[14:17]
	v_mfma_f32_16x16x32_bf16 v[10:13], v[212:215], v[188:191], v[10:13]
	v_mfma_f32_16x16x32_bf16 v[6:9], v[204:207], v[196:199], v[6:9]
	v_mfma_f32_16x16x32_bf16 v[2:5], v[212:215], v[196:199], v[2:5]
	s_barrier
	ds_read_b128 v[152:155], v222
	ds_read_b128 v[156:159], v222 offset:1024
	ds_read_b128 v[160:163], v222 offset:2048
	ds_read_b128 v[164:167], v222 offset:3072
	ds_read_b128 v[168:171], v143 offset:32768
	ds_read_b128 v[172:175], v143 offset:33792
	ds_read_b128 v[176:179], v143 offset:34816
	ds_read_b128 v[180:183], v143 offset:35840
	ds_read_b128 v[184:187], v143 offset:36864
	ds_read_b128 v[188:191], v143 offset:37888
	ds_read_b128 v[192:195], v143 offset:38912
	ds_read_b128 v[196:199], v143 offset:39936
	s_mov_b32 m0, s43
	s_add_u32 s98, s12, s68
	s_addc_u32 s99, s13, s69
	global_load_lds_dwordx4 v131, s[98:99]
	s_mov_b32 m0, s44
	s_add_u32 s98, s12, s70
	s_addc_u32 s99, s13, s71
	global_load_lds_dwordx4 v131, s[98:99]
	s_waitcnt lgkmcnt(8)
	s_waitcnt vmcnt(10)
	s_barrier
	s_waitcnt lgkmcnt(0)
	v_mfma_f32_16x16x32_bf16 v[126:129], v[152:155], v[168:171], v[126:129]
	v_mfma_f32_16x16x32_bf16 v[122:125], v[160:163], v[168:171], v[122:125]
	v_mfma_f32_16x16x32_bf16 v[118:121], v[152:155], v[176:179], v[118:121]
	v_mfma_f32_16x16x32_bf16 v[114:117], v[160:163], v[176:179], v[114:117]
	v_mfma_f32_16x16x32_bf16 v[110:113], v[152:155], v[184:187], v[110:113]
	v_mfma_f32_16x16x32_bf16 v[106:109], v[160:163], v[184:187], v[106:109]
	v_mfma_f32_16x16x32_bf16 v[102:105], v[152:155], v[192:195], v[102:105]
	v_mfma_f32_16x16x32_bf16 v[98:101], v[160:163], v[192:195], v[98:101]
	v_mfma_f32_16x16x32_bf16 v[126:129], v[156:159], v[172:175], v[126:129]
	v_mfma_f32_16x16x32_bf16 v[122:125], v[164:167], v[172:175], v[122:125]
	v_mfma_f32_16x16x32_bf16 v[118:121], v[156:159], v[180:183], v[118:121]
	v_mfma_f32_16x16x32_bf16 v[114:117], v[164:167], v[180:183], v[114:117]
	v_mfma_f32_16x16x32_bf16 v[110:113], v[156:159], v[188:191], v[110:113]
	v_mfma_f32_16x16x32_bf16 v[106:109], v[164:167], v[188:191], v[106:109]
	v_mfma_f32_16x16x32_bf16 v[102:105], v[156:159], v[196:199], v[102:105]
	v_mfma_f32_16x16x32_bf16 v[98:101], v[164:167], v[196:199], v[98:101]
	s_barrier
	ds_read_b128 v[200:203], v223
	ds_read_b128 v[204:207], v223 offset:1024
	ds_read_b128 v[208:211], v223 offset:2048
	ds_read_b128 v[212:215], v223 offset:3072
	s_mov_b32 m0, s45
	s_add_u32 s98, s14, s94
	s_addc_u32 s99, s15, s95
	global_load_lds_dwordx4 v131, s[98:99]
	s_mov_b32 m0, s46
	s_add_u32 s98, s14, s72
	s_addc_u32 s99, s15, s73
	global_load_lds_dwordx4 v131, s[98:99]
	s_waitcnt vmcnt(10)
	s_barrier
	s_waitcnt lgkmcnt(0)
	v_mfma_f32_16x16x32_bf16 v[94:97], v[200:203], v[168:171], v[94:97]
	v_mfma_f32_16x16x32_bf16 v[90:93], v[208:211], v[168:171], v[90:93]
	v_mfma_f32_16x16x32_bf16 v[86:89], v[200:203], v[176:179], v[86:89]
	v_mfma_f32_16x16x32_bf16 v[82:85], v[208:211], v[176:179], v[82:85]
	v_mfma_f32_16x16x32_bf16 v[78:81], v[200:203], v[184:187], v[78:81]
	v_mfma_f32_16x16x32_bf16 v[74:77], v[208:211], v[184:187], v[74:77]
	v_mfma_f32_16x16x32_bf16 v[70:73], v[200:203], v[192:195], v[70:73]
	v_mfma_f32_16x16x32_bf16 v[66:69], v[208:211], v[192:195], v[66:69]
	v_mfma_f32_16x16x32_bf16 v[94:97], v[204:207], v[172:175], v[94:97]
	v_mfma_f32_16x16x32_bf16 v[90:93], v[212:215], v[172:175], v[90:93]
	v_mfma_f32_16x16x32_bf16 v[86:89], v[204:207], v[180:183], v[86:89]
	v_mfma_f32_16x16x32_bf16 v[82:85], v[212:215], v[180:183], v[82:85]
	v_mfma_f32_16x16x32_bf16 v[78:81], v[204:207], v[188:191], v[78:81]
	v_mfma_f32_16x16x32_bf16 v[74:77], v[212:215], v[188:191], v[74:77]
	v_mfma_f32_16x16x32_bf16 v[70:73], v[204:207], v[196:199], v[70:73]
	v_mfma_f32_16x16x32_bf16 v[66:69], v[212:215], v[196:199], v[66:69]
	s_barrier
; #define LDA(dst, b, h) for (int m = 0; m < 4; ++m) for (int k = 0; k < 2; ++k) \
;     dst[m][k] = *reinterpret_cast<const bf16x8*>((char*)SA(b, h) + a_thr + (m * 2 + k) * 1024)
; #define LDB(dst, b, h) for (int n = 0; n < 2; ++n) for (int k = 0; k < 2; ++k) \
;     dst[n][k] = *reinterpret_cast<const bf16x8*>((char*)SB(b, h) + b_thr + (n * 2 + k) * 1024)
; #define MMA(ai, bj, At, Btf) do { __builtin_amdgcn_s_setprio(1); \
;     for (int m = 0; m < 4; ++m) for (int n = 0; n < 2; ++n) for (int k = 0; k < 2; ++k) \
;       acc[ai][bj][m][n] = __builtin_amdgcn_mfma_f32_16x16x32_bf16(Btf[n][k], At[m][k], acc[ai][bj][m][n], 0, 0, 0); \
;     __builtin_amdgcn_s_setprio(0); } while (0)
; #define WAIT_V(n) asm volatile("s_waitcnt vmcnt(" #n ")" ::: "memory")
; #define WAIT_L(n) asm volatile("s_waitcnt lgkmcnt(" #n ")" ::: "memory")
; #define BAR __builtin_amdgcn_s_barrier()
; #define SCHED __builtin_amdgcn_sched_barrier(0)
; template <bool OVL, bool PANEL = false, class Epi>
; __device__ __forceinline__ void gemm_phase(const bf16_t* __restrict__ A, long lda, const bf16_t* __restrict__ Bt, long ldb, int nM, int nN, int K,
;                                            const Epi& epi, bf16_t* shm, int w0) {
;     ...
;       LDA(At, 1, 1); STAGE(SA(1, 0), A, lda, aoff, brow, t + 3);
;       BAR; WAIT_L(0); MMA(1, 0, At, B0); BAR; SCHED;
;       STAGE(SB(1, 1), Bt, ldb, boff, bcol + HALF, t + 3);
;       WAIT_V(6); BAR; MMA(1, 1, At, B1); BAR;
;     }
;     { LDB(B0, 0, 0); LDA(At, 0, 0); STAGE(SA(1, 1), A, lda, aoff, brow + HALF, nt - 1);
;       BAR; WAIT_L(0); MMA(0, 0, At, B0); BAR;
	ds_read_b128 v[168:171], v143 offset:49152
	ds_read_b128 v[172:175], v143 offset:50176
	ds_read_b128 v[176:179], v143 offset:51200
	ds_read_b128 v[180:183], v143 offset:52224
	ds_read_b128 v[184:187], v143 offset:53248
	ds_read_b128 v[188:191], v143 offset:54272
	ds_read_b128 v[192:195], v143 offset:55296
	ds_read_b128 v[196:199], v143 offset:56320
	s_mov_b32 m0, s47
	s_add_u32 s98, s12, s94
	s_addc_u32 s99, s13, s95
	global_load_lds_dwordx4 v131, s[98:99]
	s_mov_b32 m0, s48
	s_add_u32 s98, s12, s72
	s_addc_u32 s99, s13, s73
	global_load_lds_dwordx4 v131, s[98:99]
	s_barrier
	s_waitcnt lgkmcnt(0)
	v_mfma_f32_16x16x32_bf16 v[62:65], v[152:155], v[168:171], v[62:65]
	v_mfma_f32_16x16x32_bf16 v[58:61], v[160:163], v[168:171], v[58:61]
	v_mfma_f32_16x16x32_bf16 v[54:57], v[152:155], v[176:179], v[54:57]
	v_mfma_f32_16x16x32_bf16 v[50:53], v[160:163], v[176:179], v[50:53]
	v_mfma_f32_16x16x32_bf16 v[46:49], v[152:155], v[184:187], v[46:49]
	v_mfma_f32_16x16x32_bf16 v[42:45], v[160:163], v[184:187], v[42:45]
	v_mfma_f32_16x16x32_bf16 v[38:41], v[152:155], v[192:195], v[38:41]
	v_mfma_f32_16x16x32_bf16 v[34:37], v[160:163], v[192:195], v[34:37]
	v_mfma_f32_16x16x32_bf16 v[62:65], v[156:159], v[172:175], v[62:65]
	v_mfma_f32_16x16x32_bf16 v[58:61], v[164:167], v[172:175], v[58:61]
	v_mfma_f32_16x16x32_bf16 v[54:57], v[156:159], v[180:183], v[54:57]
	v_mfma_f32_16x16x32_bf16 v[50:53], v[164:167], v[180:183], v[50:53]
	v_mfma_f32_16x16x32_bf16 v[46:49], v[156:159], v[188:191], v[46:49]
	v_mfma_f32_16x16x32_bf16 v[42:45], v[164:167], v[188:191], v[42:45]
	v_mfma_f32_16x16x32_bf16 v[38:41], v[156:159], v[196:199], v[38:41]
	v_mfma_f32_16x16x32_bf16 v[34:37], v[164:167], v[196:199], v[34:37]
	s_barrier
	s_mov_b32 m0, s49
	s_add_u32 s98, s14, s26
	s_addc_u32 s99, s15, s27
	global_load_lds_dwordx4 v131, s[98:99]
	s_mov_b32 m0, s50
	s_add_u32 s98, s14, s28
	s_addc_u32 s99, s15, s29
	global_load_lds_dwordx4 v131, s[98:99]
	s_add_i32 s21, s21, 2
	s_add_u32 s10, s10, 0x100
	s_addc_u32 s11, s11, 0
	s_cmp_lt_u32 s21, 12
	s_waitcnt vmcnt(10)
	s_barrier
	v_mfma_f32_16x16x32_bf16 v[30:33], v[200:203], v[168:171], v[30:33]
	v_mfma_f32_16x16x32_bf16 v[26:29], v[208:211], v[168:171], v[26:29]
	v_mfma_f32_16x16x32_bf16 v[22:25], v[200:203], v[176:179], v[22:25]
	v_mfma_f32_16x16x32_bf16 v[18:21], v[208:211], v[176:179], v[18:21]
	v_mfma_f32_16x16x32_bf16 v[14:17], v[200:203], v[184:187], v[14:17]
	v_mfma_f32_16x16x32_bf16 v[10:13], v[208:211], v[184:187], v[10:13]
	v_mfma_f32_16x16x32_bf16 v[6:9], v[200:203], v[192:195], v[6:9]
	v_mfma_f32_16x16x32_bf16 v[2:5], v[208:211], v[192:195], v[2:5]
	v_mfma_f32_16x16x32_bf16 v[30:33], v[204:207], v[172:175], v[30:33]
	v_mfma_f32_16x16x32_bf16 v[26:29], v[212:215], v[172:175], v[26:29]
	v_mfma_f32_16x16x32_bf16 v[22:25], v[204:207], v[180:183], v[22:25]
	v_mfma_f32_16x16x32_bf16 v[18:21], v[212:215], v[180:183], v[18:21]
	v_mfma_f32_16x16x32_bf16 v[14:17], v[204:207], v[188:191], v[14:17]
	v_mfma_f32_16x16x32_bf16 v[10:13], v[212:215], v[188:191], v[10:13]
	v_mfma_f32_16x16x32_bf16 v[6:9], v[204:207], v[196:199], v[6:9]
	v_mfma_f32_16x16x32_bf16 v[2:5], v[212:215], v[196:199], v[2:5]
	s_barrier
	s_cbranch_scc1 .LBB0_410
	s_waitcnt vmcnt(6)
	v_add_u32_e32 v212, 16, v140
	v_add_u32_e32 v0, 0x10000, v212
	ds_read_b128 v[144:147], v0
	ds_read_b128 v[152:155], v0 offset:1024
	ds_read_b128 v[156:159], v0 offset:2048
	ds_read_b128 v[160:163], v0 offset:3072
	ds_read_b128 v[164:167], v143
	ds_read_b128 v[168:171], v143 offset:1024
	ds_read_b128 v[172:175], v143 offset:2048
	ds_read_b128 v[176:179], v143 offset:3072
	ds_read_b128 v[180:183], v143 offset:4096
	ds_read_b128 v[184:187], v143 offset:5120
	ds_read_b128 v[188:191], v143 offset:6144
	ds_read_b128 v[192:195], v143 offset:7168
	v_mov_b32_e32 v0, v131
	s_mov_b64 s[0:1], 0x40780
	v_lshl_add_u64 v[148:149], s[8:9], 0, v[0:1]
	v_lshl_add_u64 v[196:197], v[148:149], 0, s[0:1]
	v_readfirstlane_b32 s0, v150
	s_mov_b32 m0, s0
	s_mov_b64 s[0:1], 0x60780
	v_lshl_add_u64 v[148:149], v[148:149], 0, s[0:1]
	v_readfirstlane_b32 s0, v151
	global_load_lds_dwordx4 v[196:197], off
	s_mov_b32 m0, s0
	s_nop 0
	global_load_lds_dwordx4 v[148:149], off
	s_barrier
	s_waitcnt lgkmcnt(0)

; #define MMA(ai, bj, At, Btf) do { __builtin_amdgcn_s_setprio(1); \
;     for (int m = 0; m < 4; ++m) for (int n = 0; n < 2; ++n) for (int k = 0; k < 2; ++k) \
;       acc[ai][bj][m][n] = __builtin_amdgcn_mfma_f32_16x16x32_bf16(Btf[n][k], At[m][k], acc[ai][bj][m][n], 0, 0, 0); \
;     __builtin_amdgcn_s_setprio(0); } while (0)
; #define WAIT_L(n) asm volatile("s_waitcnt lgkmcnt(" #n ")" ::: "memory")
; #define BAR __builtin_amdgcn_s_barrier()
; template <bool OVL, bool PANEL = false, class Epi>
; __device__ __forceinline__ void gemm_phase(const bf16_t* __restrict__ A, long lda, const bf16_t* __restrict__ Bt, long ldb, int nM, int nN, int K,
;                                            const Epi& epi, bf16_t* shm, int w0) {
;     ...
;       BAR; WAIT_L(0); MMA(0, 0, At, B0); BAR;
	s_waitcnt lgkmcnt(0)
	v_mfma_f32_16x16x32_bf16 v[126:129], v[144:147], v[164:167], v[126:129]
	v_mfma_f32_16x16x32_bf16 v[122:125], v[156:159], v[164:167], v[122:125]
	v_mfma_f32_16x16x32_bf16 v[118:121], v[144:147], v[172:175], v[118:121]
	v_mfma_f32_16x16x32_bf16 v[114:117], v[156:159], v[172:175], v[114:117]
	v_mfma_f32_16x16x32_bf16 v[110:113], v[144:147], v[180:183], v[110:113]
	v_mfma_f32_16x16x32_bf16 v[106:109], v[156:159], v[180:183], v[106:109]
	v_mfma_f32_16x16x32_bf16 v[102:105], v[144:147], v[188:191], v[102:105]
	v_mfma_f32_16x16x32_bf16 v[126:129], v[152:155], v[168:171], v[126:129]
	v_mfma_f32_16x16x32_bf16 v[122:125], v[160:163], v[168:171], v[122:125]
	v_mfma_f32_16x16x32_bf16 v[118:121], v[152:155], v[176:179], v[118:121]
	v_mfma_f32_16x16x32_bf16 v[114:117], v[160:163], v[176:179], v[114:117]
	v_mfma_f32_16x16x32_bf16 v[110:113], v[152:155], v[184:187], v[110:113]
	v_mfma_f32_16x16x32_bf16 v[106:109], v[160:163], v[184:187], v[106:109]
	v_mfma_f32_16x16x32_bf16 v[102:105], v[152:155], v[192:195], v[102:105]
	v_mfma_f32_16x16x32_bf16 v[98:101], v[156:159], v[188:191], v[98:101]
	v_mfma_f32_16x16x32_bf16 v[148:151], v[160:163], v[192:195], v[98:101]

; #define LDB(dst, b, h) for (int n = 0; n < 2; ++n) for (int k = 0; k < 2; ++k) \
;     dst[n][k] = *reinterpret_cast<const bf16x8*>((char*)SB(b, h) + b_thr + (n * 2 + k) * 1024)
; #define MMA(ai, bj, At, Btf) do { __builtin_amdgcn_s_setprio(1); \
;     for (int m = 0; m < 4; ++m) for (int n = 0; n < 2; ++n) for (int k = 0; k < 2; ++k) \
;       acc[ai][bj][m][n] = __builtin_amdgcn_mfma_f32_16x16x32_bf16(Btf[n][k], At[m][k], acc[ai][bj][m][n], 0, 0, 0); \
;     __builtin_amdgcn_s_setprio(0); } while (0)
; #define WAIT_L(n) asm volatile("s_waitcnt lgkmcnt(" #n ")" ::: "memory")
; #define BAR __builtin_amdgcn_s_barrier()
; template <bool OVL, bool PANEL = false, class Epi>
; __device__ __forceinline__ void gemm_phase(const bf16_t* __restrict__ A, long lda, const bf16_t* __restrict__ Bt, long ldb, int nM, int nN, int K,
;                                            const Epi& epi, bf16_t* shm, int w0) {
;     ...
;       LDB(B1, 0, 1); BAR; WAIT_L(0); MMA(0, 1, At, B1); BAR;
	v_add_u32_e32 v0, 0x14000, v212
	s_barrier
	s_nop 3
	ds_read_b128 v[98:101], v0
	ds_read_b128 v[196:199], v0 offset:1024
	ds_read_b128 v[200:203], v0 offset:2048
	ds_read_b128 v[204:207], v0 offset:3072
	s_barrier
	s_waitcnt lgkmcnt(0)

; #define LDB(dst, b, h) for (int n = 0; n < 2; ++n) for (int k = 0; k < 2; ++k) \
;     dst[n][k] = *reinterpret_cast<const bf16x8*>((char*)SB(b, h) + b_thr + (n * 2 + k) * 1024)
; #define MMA(ai, bj, At, Btf) do { __builtin_amdgcn_s_setprio(1); \
;     for (int m = 0; m < 4; ++m) for (int n = 0; n < 2; ++n) for (int k = 0; k < 2; ++k) \
;       acc[ai][bj][m][n] = __builtin_amdgcn_mfma_f32_16x16x32_bf16(Btf[n][k], At[m][k], acc[ai][bj][m][n], 0, 0, 0); \
;     __builtin_amdgcn_s_setprio(0); } while (0)
; #define WAIT_L(n) asm volatile("s_waitcnt lgkmcnt(" #n ")" ::: "memory")
; #define BAR __builtin_amdgcn_s_barrier()
; template <bool OVL, bool PANEL = false, class Epi>
; __device__ __forceinline__ void gemm_phase(const bf16_t* __restrict__ A, long lda, const bf16_t* __restrict__ Bt, long ldb, int nM, int nN, int K,
;                                            const Epi& epi, bf16_t* shm, int w0) {
;     ...
;       LDB(B1, 0, 1); BAR; WAIT_L(0); MMA(0, 1, At, B1); BAR;
	s_waitcnt lgkmcnt(0)
	v_mfma_f32_16x16x32_bf16 v[94:97], v[98:101], v[164:167], v[94:97]
	v_mfma_f32_16x16x32_bf16 v[86:89], v[98:101], v[172:175], v[86:89]
	v_mfma_f32_16x16x32_bf16 v[82:85], v[200:203], v[172:175], v[82:85]
	v_mfma_f32_16x16x32_bf16 v[78:81], v[98:101], v[180:183], v[78:81]
	v_mfma_f32_16x16x32_bf16 v[74:77], v[200:203], v[180:183], v[74:77]
	v_mfma_f32_16x16x32_bf16 v[94:97], v[196:199], v[168:171], v[94:97]
	v_mfma_f32_16x16x32_bf16 v[90:93], v[200:203], v[164:167], v[90:93]
	v_mfma_f32_16x16x32_bf16 v[86:89], v[196:199], v[176:179], v[86:89]
	v_mfma_f32_16x16x32_bf16 v[82:85], v[204:207], v[176:179], v[82:85]
	v_mfma_f32_16x16x32_bf16 v[78:81], v[196:199], v[184:187], v[78:81]
	v_mfma_f32_16x16x32_bf16 v[74:77], v[204:207], v[184:187], v[74:77]
	v_mfma_f32_16x16x32_bf16 v[70:73], v[98:101], v[188:191], v[70:73]
	v_mfma_f32_16x16x32_bf16 v[66:69], v[200:203], v[188:191], v[66:69]
	v_mfma_f32_16x16x32_bf16 v[164:167], v[204:207], v[168:171], v[90:93]
	v_mfma_f32_16x16x32_bf16 v[168:171], v[196:199], v[192:195], v[70:73]
	v_mfma_f32_16x16x32_bf16 v[172:175], v[204:207], v[192:195], v[66:69]

; #define LDA(dst, b, h) for (int m = 0; m < 4; ++m) for (int k = 0; k < 2; ++k) \
;     dst[m][k] = *reinterpret_cast<const bf16x8*>((char*)SA(b, h) + a_thr + (m * 2 + k) * 1024)
; #define MMA(ai, bj, At, Btf) do { __builtin_amdgcn_s_setprio(1); \
;     for (int m = 0; m < 4; ++m) for (int n = 0; n < 2; ++n) for (int k = 0; k < 2; ++k) \
;       acc[ai][bj][m][n] = __builtin_amdgcn_mfma_f32_16x16x32_bf16(Btf[n][k], At[m][k], acc[ai][bj][m][n], 0, 0, 0); \
;     __builtin_amdgcn_s_setprio(0); } while (0)
; #define WAIT_V(n) asm volatile("s_waitcnt vmcnt(" #n ")" ::: "memory")
; #define WAIT_L(n) asm volatile("s_waitcnt lgkmcnt(" #n ")" ::: "memory")
; #define BAR __builtin_amdgcn_s_barrier()
; template <bool OVL, bool PANEL = false, class Epi>
; __device__ __forceinline__ void gemm_phase(const bf16_t* __restrict__ A, long lda, const bf16_t* __restrict__ Bt, long ldb, int nM, int nN, int K,
;                                            const Epi& epi, bf16_t* shm, int w0) {
;     ...
;       LDA(At, 0, 1); WAIT_V(4); BAR; WAIT_L(0); MMA(1, 0, At, B0); MMA(1, 1, At, B1); BAR; }
	s_barrier
	s_nop 2
	ds_read_b128 v[66:69], v143 offset:16384
	ds_read_b128 v[70:73], v143 offset:17408
	ds_read_b128 v[90:93], v143 offset:18432
	ds_read_b128 v[176:179], v143 offset:19456
	ds_read_b128 v[180:183], v143 offset:20480
	ds_read_b128 v[184:187], v143 offset:21504
	ds_read_b128 v[188:191], v143 offset:22528
	ds_read_b128 v[192:195], v143 offset:23552
	s_waitcnt vmcnt(4)
	s_barrier
	s_waitcnt lgkmcnt(0)

; #define LDA(dst, b, h) for (int m = 0; m < 4; ++m) for (int k = 0; k < 2; ++k) \
;     dst[m][k] = *reinterpret_cast<const bf16x8*>((char*)SA(b, h) + a_thr + (m * 2 + k) * 1024)
; #define MMA(ai, bj, At, Btf) do { __builtin_amdgcn_s_setprio(1); \
;     for (int m = 0; m < 4; ++m) for (int n = 0; n < 2; ++n) for (int k = 0; k < 2; ++k) \
;       acc[ai][bj][m][n] = __builtin_amdgcn_mfma_f32_16x16x32_bf16(Btf[n][k], At[m][k], acc[ai][bj][m][n], 0, 0, 0); \
;     __builtin_amdgcn_s_setprio(0); } while (0)
; #define WAIT_V(n) asm volatile("s_waitcnt vmcnt(" #n ")" ::: "memory")
; #define WAIT_L(n) asm volatile("s_waitcnt lgkmcnt(" #n ")" ::: "memory")
; #define BAR __builtin_amdgcn_s_barrier()
; template <bool OVL, bool PANEL = false, class Epi>
; __device__ __forceinline__ void gemm_phase(const bf16_t* __restrict__ A, long lda, const bf16_t* __restrict__ Bt, long ldb, int nM, int nN, int K,
;                                            const Epi& epi, bf16_t* shm, int w0) {
;     ...
;       LDA(At, 0, 1); WAIT_V(4); BAR; WAIT_L(0); MMA(1, 0, At, B0); MMA(1, 1, At, B1); BAR; }
	s_waitcnt lgkmcnt(0)
	v_mfma_f32_16x16x32_bf16 v[62:65], v[144:147], v[66:69], v[62:65]
	v_mfma_f32_16x16x32_bf16 v[54:57], v[144:147], v[90:93], v[54:57]
	v_mfma_f32_16x16x32_bf16 v[50:53], v[156:159], v[90:93], v[50:53]
	v_mfma_f32_16x16x32_bf16 v[46:49], v[144:147], v[180:183], v[46:49]
	v_mfma_f32_16x16x32_bf16 v[42:45], v[156:159], v[180:183], v[42:45]
	v_mfma_f32_16x16x32_bf16 v[38:41], v[144:147], v[188:191], v[38:41]
	v_mfma_f32_16x16x32_bf16 v[34:37], v[156:159], v[188:191], v[34:37]
	v_mfma_f32_16x16x32_bf16 v[62:65], v[152:155], v[70:73], v[62:65]
	v_mfma_f32_16x16x32_bf16 v[58:61], v[156:159], v[66:69], v[58:61]
	v_mfma_f32_16x16x32_bf16 v[54:57], v[152:155], v[176:179], v[54:57]
	v_mfma_f32_16x16x32_bf16 v[50:53], v[160:163], v[176:179], v[50:53]
	v_mfma_f32_16x16x32_bf16 v[46:49], v[152:155], v[184:187], v[46:49]
	v_mfma_f32_16x16x32_bf16 v[42:45], v[160:163], v[184:187], v[42:45]
	v_mfma_f32_16x16x32_bf16 v[38:41], v[152:155], v[192:195], v[38:41]
	v_mfma_f32_16x16x32_bf16 v[34:37], v[160:163], v[192:195], v[34:37]
	v_mfma_f32_16x16x32_bf16 v[208:211], v[160:163], v[70:73], v[58:61]


; #define LDA(dst, b, h) for (int m = 0; m < 4; ++m) for (int k = 0; k < 2; ++k) \
;     dst[m][k] = *reinterpret_cast<const bf16x8*>((char*)SA(b, h) + a_thr + (m * 2 + k) * 1024)
; #define MMA(ai, bj, At, Btf) do { __builtin_amdgcn_s_setprio(1); \
;     for (int m = 0; m < 4; ++m) for (int n = 0; n < 2; ++n) for (int k = 0; k < 2; ++k) \
;       acc[ai][bj][m][n] = __builtin_amdgcn_mfma_f32_16x16x32_bf16(Btf[n][k], At[m][k], acc[ai][bj][m][n], 0, 0, 0); \
;     __builtin_amdgcn_s_setprio(0); } while (0)
; #define WAIT_V(n) asm volatile("s_waitcnt vmcnt(" #n ")" ::: "memory")
; #define WAIT_L(n) asm volatile("s_waitcnt lgkmcnt(" #n ")" ::: "memory")
; #define BAR __builtin_amdgcn_s_barrier()
; template <bool OVL, bool PANEL = false, class Epi>
; __device__ __forceinline__ void gemm_phase(const bf16_t* __restrict__ A, long lda, const bf16_t* __restrict__ Bt, long ldb, int nM, int nN, int K,
;                                            const Epi& epi, bf16_t* shm, int w0) {
;     ...
;       LDA(At, 0, 1); WAIT_V(4); BAR; WAIT_L(0); MMA(1, 0, At, B0); MMA(1, 1, At, B1); BAR; }
	v_mfma_f32_16x16x32_bf16 v[30:33], v[98:101], v[66:69], v[30:33]
	v_mfma_f32_16x16x32_bf16 v[26:29], v[200:203], v[66:69], v[26:29]
	v_mfma_f32_16x16x32_bf16 v[22:25], v[98:101], v[90:93], v[22:25]
	v_mfma_f32_16x16x32_bf16 v[18:21], v[200:203], v[90:93], v[18:21]
	v_mfma_f32_16x16x32_bf16 v[14:17], v[98:101], v[180:183], v[14:17]
	v_mfma_f32_16x16x32_bf16 v[10:13], v[200:203], v[180:183], v[10:13]
	v_mfma_f32_16x16x32_bf16 v[6:9], v[98:101], v[188:191], v[6:9]
	v_mfma_f32_16x16x32_bf16 v[2:5], v[200:203], v[188:191], v[2:5]
	v_mfma_f32_16x16x32_bf16 v[30:33], v[196:199], v[70:73], v[30:33]
	v_mfma_f32_16x16x32_bf16 v[26:29], v[204:207], v[70:73], v[26:29]
	v_mfma_f32_16x16x32_bf16 v[22:25], v[196:199], v[176:179], v[22:25]
	v_mfma_f32_16x16x32_bf16 v[18:21], v[204:207], v[176:179], v[18:21]
	v_mfma_f32_16x16x32_bf16 v[14:17], v[196:199], v[184:187], v[14:17]
	v_mfma_f32_16x16x32_bf16 v[10:13], v[204:207], v[184:187], v[10:13]
	v_mfma_f32_16x16x32_bf16 v[6:9], v[196:199], v[192:195], v[6:9]
	v_mfma_f32_16x16x32_bf16 v[2:5], v[204:207], v[192:195], v[2:5]

; #define LDA(dst, b, h) for (int m = 0; m < 4; ++m) for (int k = 0; k < 2; ++k) \
;     dst[m][k] = *reinterpret_cast<const bf16x8*>((char*)SA(b, h) + a_thr + (m * 2 + k) * 1024)
; #define LDB(dst, b, h) for (int n = 0; n < 2; ++n) for (int k = 0; k < 2; ++k) \
;     dst[n][k] = *reinterpret_cast<const bf16x8*>((char*)SB(b, h) + b_thr + (n * 2 + k) * 1024)
; #define MMA(ai, bj, At, Btf) do { __builtin_amdgcn_s_setprio(1); \
;     for (int m = 0; m < 4; ++m) for (int n = 0; n < 2; ++n) for (int k = 0; k < 2; ++k) \
;       acc[ai][bj][m][n] = __builtin_amdgcn_mfma_f32_16x16x32_bf16(Btf[n][k], At[m][k], acc[ai][bj][m][n], 0, 0, 0); \
;     __builtin_amdgcn_s_setprio(0); } while (0)
; #define WAIT_V(n) asm volatile("s_waitcnt vmcnt(" #n ")" ::: "memory")
; #define WAIT_L(n) asm volatile("s_waitcnt lgkmcnt(" #n ")" ::: "memory")
; #define BAR __builtin_amdgcn_s_barrier()
; template <bool OVL, bool PANEL = false, class Epi>
; __device__ __forceinline__ void gemm_phase(const bf16_t* __restrict__ A, long lda, const bf16_t* __restrict__ Bt, long ldb, int nM, int nN, int K,
;                                            const Epi& epi, bf16_t* shm, int w0) {
;     ...
;     { LDB(B0, 1, 0); LDA(At, 1, 0); WAIT_V(2); BAR; WAIT_L(0); MMA(0, 0, At, B0); BAR;
	v_add_u32_e32 v0, 0x18000, v212
	s_barrier
	ds_read_b128 v[144:147], v0
	ds_read_b128 v[152:155], v0 offset:1024
	ds_read_b128 v[156:159], v0 offset:2048
	ds_read_b128 v[160:163], v0 offset:3072
	ds_read_b128 v[58:61], v143 offset:32768
	ds_read_b128 v[66:69], v143 offset:33792
	ds_read_b128 v[70:73], v143 offset:34816
	ds_read_b128 v[176:179], v143 offset:35840
	ds_read_b128 v[180:183], v143 offset:36864
	ds_read_b128 v[184:187], v143 offset:37888
	ds_read_b128 v[188:191], v143 offset:38912
	ds_read_b128 v[192:195], v143 offset:39936
	s_waitcnt vmcnt(2)
	s_barrier
	s_waitcnt lgkmcnt(0)

; #define LDA(dst, b, h) for (int m = 0; m < 4; ++m) for (int k = 0; k < 2; ++k) \
;     dst[m][k] = *reinterpret_cast<const bf16x8*>((char*)SA(b, h) + a_thr + (m * 2 + k) * 1024)
; #define LDB(dst, b, h) for (int n = 0; n < 2; ++n) for (int k = 0; k < 2; ++k) \
;     dst[n][k] = *reinterpret_cast<const bf16x8*>((char*)SB(b, h) + b_thr + (n * 2 + k) * 1024)
; #define MMA(ai, bj, At, Btf) do { __builtin_amdgcn_s_setprio(1); \
;     for (int m = 0; m < 4; ++m) for (int n = 0; n < 2; ++n) for (int k = 0; k < 2; ++k) \
;       acc[ai][bj][m][n] = __builtin_amdgcn_mfma_f32_16x16x32_bf16(Btf[n][k], At[m][k], acc[ai][bj][m][n], 0, 0, 0); \
;     __builtin_amdgcn_s_setprio(0); } while (0)
; #define WAIT_V(n) asm volatile("s_waitcnt vmcnt(" #n ")" ::: "memory")
; #define WAIT_L(n) asm volatile("s_waitcnt lgkmcnt(" #n ")" ::: "memory")
; #define BAR __builtin_amdgcn_s_barrier()
; template <bool OVL, bool PANEL = false, class Epi>
; __device__ __forceinline__ void gemm_phase(const bf16_t* __restrict__ A, long lda, const bf16_t* __restrict__ Bt, long ldb, int nM, int nN, int K,
;                                            const Epi& epi, bf16_t* shm, int w0) {
;     ...
;     { LDB(B0, 1, 0); LDA(At, 1, 0); WAIT_V(2); BAR; WAIT_L(0); MMA(0, 0, At, B0); BAR;
	s_waitcnt lgkmcnt(0)
	v_mfma_f32_16x16x32_bf16 v[90:93], v[144:147], v[58:61], v[126:129]
	v_mfma_f32_16x16x32_bf16 v[126:129], v[152:155], v[66:69], v[90:93]
	v_mfma_f32_16x16x32_bf16 v[90:93], v[156:159], v[58:61], v[122:125]
	v_mfma_f32_16x16x32_bf16 v[122:125], v[160:163], v[66:69], v[90:93]
	v_mfma_f32_16x16x32_bf16 v[90:93], v[144:147], v[70:73], v[118:121]
	v_mfma_f32_16x16x32_bf16 v[118:121], v[152:155], v[176:179], v[90:93]
	v_mfma_f32_16x16x32_bf16 v[90:93], v[156:159], v[70:73], v[114:117]
	v_mfma_f32_16x16x32_bf16 v[114:117], v[160:163], v[176:179], v[90:93]
	v_mfma_f32_16x16x32_bf16 v[90:93], v[144:147], v[180:183], v[110:113]
	v_mfma_f32_16x16x32_bf16 v[110:113], v[152:155], v[184:187], v[90:93]
	v_mfma_f32_16x16x32_bf16 v[90:93], v[156:159], v[180:183], v[106:109]
	v_mfma_f32_16x16x32_bf16 v[106:109], v[160:163], v[184:187], v[90:93]
	v_mfma_f32_16x16x32_bf16 v[90:93], v[144:147], v[188:191], v[102:105]
	v_mfma_f32_16x16x32_bf16 v[98:101], v[152:155], v[192:195], v[90:93]
	v_mfma_f32_16x16x32_bf16 v[90:93], v[156:159], v[188:191], v[148:151]
	v_mfma_f32_16x16x32_bf16 v[90:93], v[160:163], v[192:195], v[90:93]

; #define LDB(dst, b, h) for (int n = 0; n < 2; ++n) for (int k = 0; k < 2; ++k) \
;     dst[n][k] = *reinterpret_cast<const bf16x8*>((char*)SB(b, h) + b_thr + (n * 2 + k) * 1024)
; #define MMA(ai, bj, At, Btf) do { __builtin_amdgcn_s_setprio(1); \
;     for (int m = 0; m < 4; ++m) for (int n = 0; n < 2; ++n) for (int k = 0; k < 2; ++k) \
;       acc[ai][bj][m][n] = __builtin_amdgcn_mfma_f32_16x16x32_bf16(Btf[n][k], At[m][k], acc[ai][bj][m][n], 0, 0, 0); \
;     __builtin_amdgcn_s_setprio(0); } while (0)
; #define WAIT_V(n) asm volatile("s_waitcnt vmcnt(" #n ")" ::: "memory")
; #define WAIT_L(n) asm volatile("s_waitcnt lgkmcnt(" #n ")" ::: "memory")
; #define BAR __builtin_amdgcn_s_barrier()
; template <bool OVL, bool PANEL = false, class Epi>
; __device__ __forceinline__ void gemm_phase(const bf16_t* __restrict__ A, long lda, const bf16_t* __restrict__ Bt, long ldb, int nM, int nN, int K,
;                                            const Epi& epi, bf16_t* shm, int w0) {
;     ...
;       LDB(B1, 1, 1); WAIT_V(0); BAR; WAIT_L(0); MMA(0, 1, At, B1); BAR;
	v_add_u32_e32 v0, 0x1c000, v212
	s_barrier
	ds_read_b128 v[148:151], v0
	ds_read_b128 v[196:199], v0 offset:1024
	ds_read_b128 v[200:203], v0 offset:2048
	ds_read_b128 v[204:207], v0 offset:3072
	s_waitcnt vmcnt(0)
	s_barrier
	s_waitcnt lgkmcnt(0)

; #define LDB(dst, b, h) for (int n = 0; n < 2; ++n) for (int k = 0; k < 2; ++k) \
;     dst[n][k] = *reinterpret_cast<const bf16x8*>((char*)SB(b, h) + b_thr + (n * 2 + k) * 1024)
; #define MMA(ai, bj, At, Btf) do { __builtin_amdgcn_s_setprio(1); \
;     for (int m = 0; m < 4; ++m) for (int n = 0; n < 2; ++n) for (int k = 0; k < 2; ++k) \
;       acc[ai][bj][m][n] = __builtin_amdgcn_mfma_f32_16x16x32_bf16(Btf[n][k], At[m][k], acc[ai][bj][m][n], 0, 0, 0); \
;     __builtin_amdgcn_s_setprio(0); } while (0)
; #define WAIT_V(n) asm volatile("s_waitcnt vmcnt(" #n ")" ::: "memory")
; #define WAIT_L(n) asm volatile("s_waitcnt lgkmcnt(" #n ")" ::: "memory")
; #define BAR __builtin_amdgcn_s_barrier()
; template <bool OVL, bool PANEL = false, class Epi>
; __device__ __forceinline__ void gemm_phase(const bf16_t* __restrict__ A, long lda, const bf16_t* __restrict__ Bt, long ldb, int nM, int nN, int K,
;                                            const Epi& epi, bf16_t* shm, int w0) {
;     ...
;       LDB(B1, 1, 1); WAIT_V(0); BAR; WAIT_L(0); MMA(0, 1, At, B1); BAR;
	s_waitcnt lgkmcnt(0)
	v_mfma_f32_16x16x32_bf16 v[94:97], v[148:151], v[58:61], v[94:97]
	v_mfma_f32_16x16x32_bf16 v[58:61], v[200:203], v[58:61], v[164:167]
	v_mfma_f32_16x16x32_bf16 v[102:105], v[196:199], v[66:69], v[94:97]
	v_mfma_f32_16x16x32_bf16 v[94:97], v[204:207], v[66:69], v[58:61]
	v_mfma_f32_16x16x32_bf16 v[58:61], v[148:151], v[70:73], v[86:89]
	v_mfma_f32_16x16x32_bf16 v[86:89], v[196:199], v[176:179], v[58:61]
	v_mfma_f32_16x16x32_bf16 v[58:61], v[200:203], v[70:73], v[82:85]
	v_mfma_f32_16x16x32_bf16 v[82:85], v[204:207], v[176:179], v[58:61]
	v_mfma_f32_16x16x32_bf16 v[58:61], v[148:151], v[180:183], v[78:81]
	v_mfma_f32_16x16x32_bf16 v[78:81], v[196:199], v[184:187], v[58:61]
	v_mfma_f32_16x16x32_bf16 v[58:61], v[200:203], v[180:183], v[74:77]
	v_mfma_f32_16x16x32_bf16 v[70:73], v[204:207], v[184:187], v[58:61]
	v_mfma_f32_16x16x32_bf16 v[58:61], v[148:151], v[188:191], v[168:171]
	v_mfma_f32_16x16x32_bf16 v[66:69], v[196:199], v[192:195], v[58:61]
	v_mfma_f32_16x16x32_bf16 v[58:61], v[200:203], v[188:191], v[172:175]
	v_mfma_f32_16x16x32_bf16 v[58:61], v[204:207], v[192:195], v[58:61]

; #define LDA(dst, b, h) for (int m = 0; m < 4; ++m) for (int k = 0; k < 2; ++k) \
;     dst[m][k] = *reinterpret_cast<const bf16x8*>((char*)SA(b, h) + a_thr + (m * 2 + k) * 1024)
; #define MMA(ai, bj, At, Btf) do { __builtin_amdgcn_s_setprio(1); \
;     for (int m = 0; m < 4; ++m) for (int n = 0; n < 2; ++n) for (int k = 0; k < 2; ++k) \
;       acc[ai][bj][m][n] = __builtin_amdgcn_mfma_f32_16x16x32_bf16(Btf[n][k], At[m][k], acc[ai][bj][m][n], 0, 0, 0); \
;     __builtin_amdgcn_s_setprio(0); } while (0)
; #define WAIT_L(n) asm volatile("s_waitcnt lgkmcnt(" #n ")" ::: "memory")
; #define BAR __builtin_amdgcn_s_barrier()
; template <bool OVL, bool PANEL = false, class Epi>
; __device__ __forceinline__ void gemm_phase(const bf16_t* __restrict__ A, long lda, const bf16_t* __restrict__ Bt, long ldb, int nM, int nN, int K,
;                                            const Epi& epi, bf16_t* shm, int w0) {
;     ...
;       LDA(At, 1, 1); BAR; WAIT_L(0); MMA(1, 0, At, B0); MMA(1, 1, At, B1); BAR; }
	s_barrier
	ds_read_b128 v[164:167], v143 offset:49152
	ds_read_b128 v[168:171], v143 offset:50176
	ds_read_b128 v[172:175], v143 offset:51200
	ds_read_b128 v[176:179], v143 offset:52224
	ds_read_b128 v[180:183], v143 offset:53248
	ds_read_b128 v[184:187], v143 offset:54272
	ds_read_b128 v[188:191], v143 offset:55296
	ds_read_b128 v[192:195], v143 offset:56320
	s_barrier
	s_waitcnt lgkmcnt(0)

; #define LDA(dst, b, h) for (int m = 0; m < 4; ++m) for (int k = 0; k < 2; ++k) \
;     dst[m][k] = *reinterpret_cast<const bf16x8*>((char*)SA(b, h) + a_thr + (m * 2 + k) * 1024)
; #define MMA(ai, bj, At, Btf) do { __builtin_amdgcn_s_setprio(1); \
;     for (int m = 0; m < 4; ++m) for (int n = 0; n < 2; ++n) for (int k = 0; k < 2; ++k) \
;       acc[ai][bj][m][n] = __builtin_amdgcn_mfma_f32_16x16x32_bf16(Btf[n][k], At[m][k], acc[ai][bj][m][n], 0, 0, 0); \
;     __builtin_amdgcn_s_setprio(0); } while (0)
; #define WAIT_L(n) asm volatile("s_waitcnt lgkmcnt(" #n ")" ::: "memory")
; #define BAR __builtin_amdgcn_s_barrier()
; template <bool OVL, bool PANEL = false, class Epi>
; __device__ __forceinline__ void gemm_phase(const bf16_t* __restrict__ A, long lda, const bf16_t* __restrict__ Bt, long ldb, int nM, int nN, int K,
;                                            const Epi& epi, bf16_t* shm, int w0) {
;     ...
;       LDA(At, 1, 1); BAR; WAIT_L(0); MMA(1, 0, At, B0); MMA(1, 1, At, B1); BAR; }
	s_waitcnt lgkmcnt(0)
	v_mfma_f32_16x16x32_bf16 v[62:65], v[144:147], v[164:167], v[62:65]
	v_mfma_f32_16x16x32_bf16 v[74:77], v[152:155], v[168:171], v[62:65]
	v_mfma_f32_16x16x32_bf16 v[62:65], v[156:159], v[164:167], v[208:211]
	v_mfma_f32_16x16x32_bf16 v[54:57], v[144:147], v[172:175], v[54:57]
	v_mfma_f32_16x16x32_bf16 v[50:53], v[156:159], v[172:175], v[50:53]
	v_mfma_f32_16x16x32_bf16 v[46:49], v[144:147], v[180:183], v[46:49]
	v_mfma_f32_16x16x32_bf16 v[42:45], v[156:159], v[180:183], v[42:45]
	v_mfma_f32_16x16x32_bf16 v[38:41], v[144:147], v[188:191], v[38:41]
	v_mfma_f32_16x16x32_bf16 v[34:37], v[156:159], v[188:191], v[34:37]
	v_mfma_f32_16x16x32_bf16 v[62:65], v[160:163], v[168:171], v[62:65]
	v_mfma_f32_16x16x32_bf16 v[54:57], v[152:155], v[176:179], v[54:57]
	v_mfma_f32_16x16x32_bf16 v[50:53], v[160:163], v[176:179], v[50:53]
	v_mfma_f32_16x16x32_bf16 v[46:49], v[152:155], v[184:187], v[46:49]
	v_mfma_f32_16x16x32_bf16 v[42:45], v[160:163], v[184:187], v[42:45]
	v_mfma_f32_16x16x32_bf16 v[38:41], v[152:155], v[192:195], v[38:41]
	v_mfma_f32_16x16x32_bf16 v[34:37], v[160:163], v[192:195], v[34:37]


; #define LDA(dst, b, h) for (int m = 0; m < 4; ++m) for (int k = 0; k < 2; ++k) \
;     dst[m][k] = *reinterpret_cast<const bf16x8*>((char*)SA(b, h) + a_thr + (m * 2 + k) * 1024)
; #define MMA(ai, bj, At, Btf) do { __builtin_amdgcn_s_setprio(1); \
;     for (int m = 0; m < 4; ++m) for (int n = 0; n < 2; ++n) for (int k = 0; k < 2; ++k) \
;       acc[ai][bj][m][n] = __builtin_amdgcn_mfma_f32_16x16x32_bf16(Btf[n][k], At[m][k], acc[ai][bj][m][n], 0, 0, 0); \
;     __builtin_amdgcn_s_setprio(0); } while (0)
; #define WAIT_L(n) asm volatile("s_waitcnt lgkmcnt(" #n ")" ::: "memory")
; #define BAR __builtin_amdgcn_s_barrier()
; template <bool OVL, bool PANEL = false, class Epi>
; __device__ __forceinline__ void gemm_phase(const bf16_t* __restrict__ A, long lda, const bf16_t* __restrict__ Bt, long ldb, int nM, int nN, int K,
;                                            const Epi& epi, bf16_t* shm, int w0) {
;     ...
;       LDA(At, 1, 1); BAR; WAIT_L(0); MMA(1, 0, At, B0); MMA(1, 1, At, B1); BAR; }
	v_mfma_f32_16x16x32_bf16 v[30:33], v[148:151], v[164:167], v[30:33]
	v_mfma_f32_16x16x32_bf16 v[26:29], v[200:203], v[164:167], v[26:29]
	v_mfma_f32_16x16x32_bf16 v[22:25], v[148:151], v[172:175], v[22:25]
	v_mfma_f32_16x16x32_bf16 v[18:21], v[200:203], v[172:175], v[18:21]
	v_mfma_f32_16x16x32_bf16 v[14:17], v[148:151], v[180:183], v[14:17]
	v_mfma_f32_16x16x32_bf16 v[10:13], v[200:203], v[180:183], v[10:13]
	v_mfma_f32_16x16x32_bf16 v[6:9], v[148:151], v[188:191], v[6:9]
	v_mfma_f32_16x16x32_bf16 v[2:5], v[200:203], v[188:191], v[2:5]
	v_mfma_f32_16x16x32_bf16 v[30:33], v[196:199], v[168:171], v[30:33]
	v_mfma_f32_16x16x32_bf16 v[26:29], v[204:207], v[168:171], v[26:29]
	v_mfma_f32_16x16x32_bf16 v[22:25], v[196:199], v[176:179], v[22:25]
	v_mfma_f32_16x16x32_bf16 v[18:21], v[204:207], v[176:179], v[18:21]
	v_mfma_f32_16x16x32_bf16 v[14:17], v[196:199], v[184:187], v[14:17]
	v_mfma_f32_16x16x32_bf16 v[10:13], v[204:207], v[184:187], v[10:13]
	v_mfma_f32_16x16x32_bf16 v[6:9], v[196:199], v[192:195], v[6:9]
	v_mfma_f32_16x16x32_bf16 v[2:5], v[204:207], v[192:195], v[2:5]

; #define LDA(dst, b, h) for (int m = 0; m < 4; ++m) for (int k = 0; k < 2; ++k) \
;     dst[m][k] = *reinterpret_cast<const bf16x8*>((char*)SA(b, h) + a_thr + (m * 2 + k) * 1024)
; #define MMA(ai, bj, At, Btf) do { __builtin_amdgcn_s_setprio(1); \
;     for (int m = 0; m < 4; ++m) for (int n = 0; n < 2; ++n) for (int k = 0; k < 2; ++k) \
;       acc[ai][bj][m][n] = __builtin_amdgcn_mfma_f32_16x16x32_bf16(Btf[n][k], At[m][k], acc[ai][bj][m][n], 0, 0, 0); \
;     __builtin_amdgcn_s_setprio(0); } while (0)
; #define WAIT_L(n) asm volatile("s_waitcnt lgkmcnt(" #n ")" ::: "memory")
; #define BAR __builtin_amdgcn_s_barrier()
; template <bool OVL, bool PANEL = false, class Epi>
; __device__ __forceinline__ void gemm_phase(const bf16_t* __restrict__ A, long lda, const bf16_t* __restrict__ Bt, long ldb, int nM, int nN, int K,
;                                            const Epi& epi, bf16_t* shm, int w0) {
;     ...
;       LDA(At, 1, 1); BAR; WAIT_L(0); MMA(1, 0, At, B0); MMA(1, 1, At, B1); BAR; }
;     if (wr == 0) BAR;
	s_barrier
	s_and_saveexec_b64 s[0:1], s[6:7]
	s_cbranch_execz .LBB0_413
	s_barrier

; #define LDA(dst, b, h) for (int m = 0; m < 4; ++m) for (int k = 0; k < 2; ++k) \
;     dst[m][k] = *reinterpret_cast<const bf16x8*>((char*)SA(b, h) + a_thr + (m * 2 + k) * 1024)
; #define LDB(dst, b, h) for (int n = 0; n < 2; ++n) for (int k = 0; k < 2; ++k) \
;     dst[n][k] = *reinterpret_cast<const bf16x8*>((char*)SB(b, h) + b_thr + (n * 2 + k) * 1024)
; #define MMA(ai, bj, At, Btf) do { __builtin_amdgcn_s_setprio(1); \
;     for (int m = 0; m < 4; ++m) for (int n = 0; n < 2; ++n) for (int k = 0; k < 2; ++k) \
;       acc[ai][bj][m][n] = __builtin_amdgcn_mfma_f32_16x16x32_bf16(Btf[n][k], At[m][k], acc[ai][bj][m][n], 0, 0, 0); \
;     __builtin_amdgcn_s_setprio(0); } while (0)
; #define WAIT_V(n) asm volatile("s_waitcnt vmcnt(" #n ")" ::: "memory")
; #define WAIT_L(n) asm volatile("s_waitcnt lgkmcnt(" #n ")" ::: "memory")
; #define BAR __builtin_amdgcn_s_barrier()
; #define SCHED __builtin_amdgcn_sched_barrier(0)
; template <bool OVL, bool PANEL = false, class Epi>
; __device__ __forceinline__ void gemm_phase(const bf16_t* __restrict__ A, long lda, const bf16_t* __restrict__ Bt, long ldb, int nM, int nN, int K,
;                                            const Epi& epi, bf16_t* shm, int w0) {
;     ...
;     if (wr == 1) BAR;
;     WAIT_V(4); BAR;
;     STAGE(SB(1, 0), Bt, ldb, boff, bcol, 1); STAGE(SA(1, 0), A, lda, aoff, brow, 1); STAGE(SB(1, 1), Bt, ldb, boff, bcol + HALF, 1);
;     WAIT_V(6); BAR;
;     for (int t = 0; t < nt - 2; t += 2) {
;       LDB(B0, 0, 0); SCHED; LDA(At, 0, 0); STAGE(SA(1, 1), A, lda, aoff, brow + HALF, t + 1);
;       WAIT_L(8); BAR; WAIT_L(0); MMA(0, 0, At, B0); BAR; SCHED;
.LBB0_471:
	s_or_b64 exec, exec, s[0:1]
	s_lshl_b32 s2, s25, 18
	v_readlane_b32 s44, v252, 3
	s_lshl_b32 s82, s4, 8
	s_lshl_b64 s[0:1], s[2:3], 1
	v_readlane_b32 s58, v252, 17
	v_readlane_b32 s59, v252, 18
	s_add_u32 s6, s58, s0
	s_addc_u32 s7, s59, s1
	v_mov_b32_e32 v0, v221
	v_add_u32_e32 v130, s96, v220
	s_waitcnt vmcnt(4)
	s_barrier
	v_readlane_b32 s45, v252, 4
	v_readlane_b32 s46, v252, 5
	v_readlane_b32 s47, v252, 6
	v_readlane_b32 s48, v252, 7
	v_readlane_b32 s49, v252, 8
	v_readlane_b32 s50, v252, 9
	v_readlane_b32 s51, v252, 10
	v_readlane_b32 s52, v252, 11
	v_readlane_b32 s53, v252, 12
	v_readlane_b32 s54, v252, 13
	v_readlane_b32 s55, v252, 14
	v_readlane_b32 s56, v252, 15
	v_readlane_b32 s57, v252, 16
	s_mov_b64 s[12:13], 0x80
	v_lshl_add_u64 v[2:3], s[6:7], 0, v[0:1]
	v_readfirstlane_b32 s0, v130
	v_add_u32_e32 v131, 0x2000, v130
	v_lshl_add_u64 v[4:5], v[2:3], 0, s[12:13]
	s_mov_b32 m0, s0
	v_readfirstlane_b32 s0, v131
	s_ashr_i32 s83, s82, 31
	v_readlane_b32 s44, v252, 20
	global_load_lds_dwordx4 v[4:5], off
	s_mov_b32 m0, s0
	s_lshl_b64 s[0:1], s[82:83], 11
	v_readlane_b32 s50, v252, 26
	s_mov_b64 s[14:15], 0x20080
	v_readlane_b32 s51, v252, 27
	s_add_u32 s8, s50, s0
	v_lshl_add_u64 v[2:3], v[2:3], 0, s[14:15]
	s_addc_u32 s9, s51, s1
	v_mov_b32_e32 v0, v221
	v_add_u32_e32 v132, 0x8000, v234
	global_load_lds_dwordx4 v[2:3], off
	v_readfirstlane_b32 s0, v132
	v_lshl_add_u64 v[2:3], s[8:9], 0, v[0:1]
	v_add_u32_e32 v133, 0xa000, v234
	v_lshl_add_u64 v[4:5], v[2:3], 0, s[12:13]
	s_mov_b32 m0, s0
	v_readfirstlane_b32 s0, v133
	global_load_lds_dwordx4 v[4:5], off
	v_lshl_add_u64 v[2:3], v[2:3], 0, s[14:15]
	s_mov_b32 m0, s0
	v_mov_b32_e32 v0, v221
	v_add_u32_e32 v134, s75, v220
	global_load_lds_dwordx4 v[2:3], off
	s_mov_b64 s[12:13], 0x40080
	v_lshl_add_u64 v[2:3], s[6:7], 0, v[0:1]
	v_readfirstlane_b32 s0, v134
	v_add_u32_e32 v135, 0x2000, v134
	v_lshl_add_u64 v[4:5], v[2:3], 0, s[12:13]
	s_mov_b32 m0, s0
	v_readfirstlane_b32 s0, v135
	global_load_lds_dwordx4 v[4:5], off
	v_lshl_add_u64 v[2:3], v[2:3], 0, s[36:37]
	s_mov_b32 m0, s0
	s_mov_b32 s2, -2
	global_load_lds_dwordx4 v[2:3], off
	s_waitcnt vmcnt(6)
	s_mov_b64 s[80:81], 0
	s_waitcnt vmcnt(0)
	s_waitcnt lgkmcnt(0)
	s_mov_b64 s[14:15], 0x40180
	s_mov_b64 s[18:19], 0x60180
	v_readlane_b32 s45, v252, 21
	v_readlane_b32 s46, v252, 22
	v_readlane_b32 s47, v252, 23
	v_readlane_b32 s48, v252, 24
	v_readlane_b32 s49, v252, 25
	v_readlane_b32 s52, v252, 28
	v_readlane_b32 s53, v252, 29
	v_readlane_b32 s54, v252, 30
	v_readlane_b32 s55, v252, 31
	v_readlane_b32 s56, v252, 32
	v_readlane_b32 s57, v252, 33
	v_readlane_b32 s58, v252, 34
	v_readlane_b32 s59, v252, 35
	s_barrier
	v_add_u32_e32 v206, s20, v240
	v_readfirstlane_b32 s16, v234
	s_add_u32 s16, s16, 0xc000
	v_readfirstlane_b32 s32, v234
	s_add_u32 s32, s32, 0xe000
	v_add_u32_e32 v207, s33, v240
	v_readfirstlane_b32 s44, v222
	v_readfirstlane_b32 s45, v223
	v_readfirstlane_b32 s46, v234
	v_readfirstlane_b32 s47, v235
	v_readfirstlane_b32 s48, v236
	v_readfirstlane_b32 s49, v237
	v_add_u32_e32 v208, s96, v240
	v_readfirstlane_b32 s50, v238
	v_readfirstlane_b32 s51, v239
	v_add_u32_e32 v209, s75, v240
	v_readfirstlane_b32 s52, v130
	v_readfirstlane_b32 s53, v131
	v_readfirstlane_b32 s54, v132
	v_readfirstlane_b32 s55, v133
	v_readfirstlane_b32 s56, v134
	v_readfirstlane_b32 s57, v135
	v_add_u32_e32 v136, 0xc000, v234
	v_add_u32_e32 v137, 0xe000, v234
	ds_read_b128 v[138:141], v206
	ds_read_b128 v[142:145], v206 offset:1024
	ds_read_b128 v[146:149], v206 offset:2048
	ds_read_b128 v[150:153], v206 offset:3072
	s_add_u32 vcc_lo, s8, s80
	s_addc_u32 vcc_hi, s9, s81
	ds_read_b128 v[154:157], v241
	ds_read_b128 v[158:161], v241 offset:1024
	ds_read_b128 v[162:165], v241 offset:2048
	ds_read_b128 v[166:169], v241 offset:3072
	ds_read_b128 v[170:173], v241 offset:4096
	ds_read_b128 v[174:177], v241 offset:5120
	ds_read_b128 v[178:181], v241 offset:6144
	ds_read_b128 v[182:185], v241 offset:7168
	s_mov_b32 m0, s16
	s_add_u32 s98, vcc_lo, s12
	s_addc_u32 s99, vcc_hi, s13
	global_load_lds_dwordx4 v221, s[98:99]
	s_mov_b32 m0, s32
	s_add_u32 s98, vcc_lo, s36
	s_addc_u32 s99, vcc_hi, s37
	global_load_lds_dwordx4 v221, s[98:99]
	s_waitcnt lgkmcnt(8)
	s_waitcnt vmcnt(10)
	s_barrier
	s_waitcnt lgkmcnt(0)
	v_mfma_f32_16x16x32_bf16 v[126:129], v[138:141], v[154:157], 0
	v_mfma_f32_16x16x32_bf16 v[122:125], v[146:149], v[154:157], 0
	v_mfma_f32_16x16x32_bf16 v[118:121], v[138:141], v[162:165], 0
	v_mfma_f32_16x16x32_bf16 v[114:117], v[146:149], v[162:165], 0
	v_mfma_f32_16x16x32_bf16 v[110:113], v[138:141], v[170:173], 0
	v_mfma_f32_16x16x32_bf16 v[106:109], v[146:149], v[170:173], 0
	v_mfma_f32_16x16x32_bf16 v[102:105], v[138:141], v[178:181], 0
	v_mfma_f32_16x16x32_bf16 v[98:101], v[146:149], v[178:181], 0
	v_mfma_f32_16x16x32_bf16 v[126:129], v[142:145], v[158:161], v[126:129]
	v_mfma_f32_16x16x32_bf16 v[122:125], v[150:153], v[158:161], v[122:125]
	v_mfma_f32_16x16x32_bf16 v[118:121], v[142:145], v[166:169], v[118:121]
	v_mfma_f32_16x16x32_bf16 v[114:117], v[150:153], v[166:169], v[114:117]
	v_mfma_f32_16x16x32_bf16 v[110:113], v[142:145], v[174:177], v[110:113]
	v_mfma_f32_16x16x32_bf16 v[106:109], v[150:153], v[174:177], v[106:109]
	v_mfma_f32_16x16x32_bf16 v[102:105], v[142:145], v[182:185], v[102:105]
	v_mfma_f32_16x16x32_bf16 v[98:101], v[150:153], v[182:185], v[98:101]
	s_barrier
	s_add_u32 s0, s6, s80
	ds_read_b128 v[186:189], v207
	ds_read_b128 v[190:193], v207 offset:1024
	ds_read_b128 v[194:197], v207 offset:2048
	ds_read_b128 v[198:201], v207 offset:3072
	s_addc_u32 s1, s7, s81
	s_mov_b32 m0, s44
	s_add_u32 s98, s0, s34
	s_addc_u32 s99, s1, s35
	global_load_lds_dwordx4 v221, s[98:99]
	s_mov_b32 m0, s45
	s_add_u32 s98, s0, s64
	s_addc_u32 s99, s1, s65
	global_load_lds_dwordx4 v221, s[98:99]
	s_waitcnt vmcnt(10)
	s_barrier
; #define LDA(dst, b, h) for (int m = 0; m < 4; ++m) for (int k = 0; k < 2; ++k) \
;     dst[m][k] = *reinterpret_cast<const bf16x8*>((char*)SA(b, h) + a_thr + (m * 2 + k) * 1024)
; #define LDB(dst, b, h) for (int n = 0; n < 2; ++n) for (int k = 0; k < 2; ++k) \
;     dst[n][k] = *reinterpret_cast<const bf16x8*>((char*)SB(b, h) + b_thr + (n * 2 + k) * 1024)
; #define MMA(ai, bj, At, Btf) do { __builtin_amdgcn_s_setprio(1); \
;     for (int m = 0; m < 4; ++m) for (int n = 0; n < 2; ++n) for (int k = 0; k < 2; ++k) \
;       acc[ai][bj][m][n] = __builtin_amdgcn_mfma_f32_16x16x32_bf16(Btf[n][k], At[m][k], acc[ai][bj][m][n], 0, 0, 0); \
;     __builtin_amdgcn_s_setprio(0); } while (0)
; #define WAIT_V(n) asm volatile("s_waitcnt vmcnt(" #n ")" ::: "memory")
; #define WAIT_L(n) asm volatile("s_waitcnt lgkmcnt(" #n ")" ::: "memory")
; #define BAR __builtin_amdgcn_s_barrier()
; #define SCHED __builtin_amdgcn_sched_barrier(0)
; template <bool OVL, bool PANEL = false, class Epi>
; __device__ __forceinline__ void gemm_phase(const bf16_t* __restrict__ A, long lda, const bf16_t* __restrict__ Bt, long ldb, int nM, int nN, int K,
;                                            const Epi& epi, bf16_t* shm, int w0) {
;     ...
;       LDB(B1, 0, 1); STAGE(SB(0, 0), Bt, ldb, boff, bcol, t + 2);
;       BAR; WAIT_L(0); MMA(0, 1, At, B1); BAR;
;       LDA(At, 0, 1); STAGE(SA(0, 0), A, lda, aoff, brow, t + 2);
;       BAR; WAIT_L(0); MMA(1, 0, At, B0); BAR; SCHED;
;       STAGE(SB(0, 1), Bt, ldb, boff, bcol + HALF, t + 2);
;       WAIT_V(6); BAR; MMA(1, 1, At, B1); BAR;
;       LDB(B0, 1, 0); SCHED; LDA(At, 1, 0); STAGE(SA(0, 1), A, lda, aoff, brow + HALF, t + 2);
;       WAIT_L(8); BAR; WAIT_L(0); MMA(0, 0, At, B0); BAR; SCHED;
	s_waitcnt lgkmcnt(0)
	v_mfma_f32_16x16x32_bf16 v[94:97], v[186:189], v[154:157], 0
	v_mfma_f32_16x16x32_bf16 v[90:93], v[194:197], v[154:157], 0
	v_mfma_f32_16x16x32_bf16 v[86:89], v[186:189], v[162:165], 0
	v_mfma_f32_16x16x32_bf16 v[82:85], v[194:197], v[162:165], 0
	v_mfma_f32_16x16x32_bf16 v[78:81], v[186:189], v[170:173], 0
	v_mfma_f32_16x16x32_bf16 v[74:77], v[194:197], v[170:173], 0
	v_mfma_f32_16x16x32_bf16 v[70:73], v[186:189], v[178:181], 0
	v_mfma_f32_16x16x32_bf16 v[66:69], v[194:197], v[178:181], 0
	v_mfma_f32_16x16x32_bf16 v[94:97], v[190:193], v[158:161], v[94:97]
	v_mfma_f32_16x16x32_bf16 v[90:93], v[198:201], v[158:161], v[90:93]
	v_mfma_f32_16x16x32_bf16 v[86:89], v[190:193], v[166:169], v[86:89]
	v_mfma_f32_16x16x32_bf16 v[82:85], v[198:201], v[166:169], v[82:85]
	v_mfma_f32_16x16x32_bf16 v[78:81], v[190:193], v[174:177], v[78:81]
	v_mfma_f32_16x16x32_bf16 v[74:77], v[198:201], v[174:177], v[74:77]
	v_mfma_f32_16x16x32_bf16 v[70:73], v[190:193], v[182:185], v[70:73]
	v_mfma_f32_16x16x32_bf16 v[66:69], v[198:201], v[182:185], v[66:69]
	s_barrier
	ds_read_b128 v[154:157], v241 offset:16384
	ds_read_b128 v[158:161], v241 offset:17408
	ds_read_b128 v[162:165], v241 offset:18432
	ds_read_b128 v[166:169], v241 offset:19456
	ds_read_b128 v[170:173], v241 offset:20480
	ds_read_b128 v[174:177], v241 offset:21504
	ds_read_b128 v[178:181], v241 offset:22528
	ds_read_b128 v[182:185], v241 offset:23552
	s_mov_b32 m0, s46
	s_add_u32 s98, vcc_lo, s34
	s_addc_u32 s99, vcc_hi, s35
	global_load_lds_dwordx4 v221, s[98:99]
	s_mov_b32 m0, s47
	s_add_u32 s98, vcc_lo, s64
	s_addc_u32 s99, vcc_hi, s65
	global_load_lds_dwordx4 v221, s[98:99]
	s_barrier
	s_waitcnt lgkmcnt(0)
	v_mfma_f32_16x16x32_bf16 v[62:65], v[138:141], v[154:157], 0
	v_mfma_f32_16x16x32_bf16 v[58:61], v[146:149], v[154:157], 0
	v_mfma_f32_16x16x32_bf16 v[54:57], v[138:141], v[162:165], 0
	v_mfma_f32_16x16x32_bf16 v[50:53], v[146:149], v[162:165], 0
	v_mfma_f32_16x16x32_bf16 v[46:49], v[138:141], v[170:173], 0
	v_mfma_f32_16x16x32_bf16 v[42:45], v[146:149], v[170:173], 0
	v_mfma_f32_16x16x32_bf16 v[38:41], v[138:141], v[178:181], 0
	v_mfma_f32_16x16x32_bf16 v[34:37], v[146:149], v[178:181], 0
	v_mfma_f32_16x16x32_bf16 v[62:65], v[142:145], v[158:161], v[62:65]
	v_mfma_f32_16x16x32_bf16 v[58:61], v[150:153], v[158:161], v[58:61]
	v_mfma_f32_16x16x32_bf16 v[54:57], v[142:145], v[166:169], v[54:57]
	v_mfma_f32_16x16x32_bf16 v[50:53], v[150:153], v[166:169], v[50:53]
	v_mfma_f32_16x16x32_bf16 v[46:49], v[142:145], v[174:177], v[46:49]
	v_mfma_f32_16x16x32_bf16 v[42:45], v[150:153], v[174:177], v[42:45]
	v_mfma_f32_16x16x32_bf16 v[38:41], v[142:145], v[182:185], v[38:41]
	v_mfma_f32_16x16x32_bf16 v[34:37], v[150:153], v[182:185], v[34:37]
	s_barrier
	s_mov_b32 m0, s48
	s_add_u32 s98, s0, s68
	s_addc_u32 s99, s1, s69
	global_load_lds_dwordx4 v221, s[98:99]
	s_mov_b32 m0, s49
	s_add_u32 s98, s0, s70
	s_addc_u32 s99, s1, s71
	global_load_lds_dwordx4 v221, s[98:99]
	s_waitcnt vmcnt(10)
	s_barrier
	v_mfma_f32_16x16x32_bf16 v[30:33], v[186:189], v[154:157], 0
	v_mfma_f32_16x16x32_bf16 v[26:29], v[194:197], v[154:157], 0
	v_mfma_f32_16x16x32_bf16 v[22:25], v[186:189], v[162:165], 0
	v_mfma_f32_16x16x32_bf16 v[18:21], v[194:197], v[162:165], 0
	v_mfma_f32_16x16x32_bf16 v[14:17], v[186:189], v[170:173], 0
	v_mfma_f32_16x16x32_bf16 v[10:13], v[194:197], v[170:173], 0
	v_mfma_f32_16x16x32_bf16 v[6:9], v[186:189], v[178:181], 0
	v_mfma_f32_16x16x32_bf16 v[2:5], v[194:197], v[178:181], 0
	v_mfma_f32_16x16x32_bf16 v[30:33], v[190:193], v[158:161], v[30:33]
	v_mfma_f32_16x16x32_bf16 v[26:29], v[198:201], v[158:161], v[26:29]
	v_mfma_f32_16x16x32_bf16 v[22:25], v[190:193], v[166:169], v[22:25]
	v_mfma_f32_16x16x32_bf16 v[18:21], v[198:201], v[166:169], v[18:21]
	v_mfma_f32_16x16x32_bf16 v[14:17], v[190:193], v[174:177], v[14:17]
	v_mfma_f32_16x16x32_bf16 v[10:13], v[198:201], v[174:177], v[10:13]
	v_mfma_f32_16x16x32_bf16 v[6:9], v[190:193], v[182:185], v[6:9]
	v_mfma_f32_16x16x32_bf16 v[2:5], v[198:201], v[182:185], v[2:5]
	s_barrier
	ds_read_b128 v[138:141], v208
	ds_read_b128 v[142:145], v208 offset:1024
	ds_read_b128 v[146:149], v208 offset:2048
	ds_read_b128 v[150:153], v208 offset:3072
	ds_read_b128 v[154:157], v241 offset:32768
	ds_read_b128 v[158:161], v241 offset:33792
	ds_read_b128 v[162:165], v241 offset:34816
	ds_read_b128 v[166:169], v241 offset:35840
	ds_read_b128 v[170:173], v241 offset:36864
	ds_read_b128 v[174:177], v241 offset:37888
	ds_read_b128 v[178:181], v241 offset:38912
	ds_read_b128 v[182:185], v241 offset:39936
	s_mov_b32 m0, s50
	s_add_u32 s98, vcc_lo, s68
	s_addc_u32 s99, vcc_hi, s69
	global_load_lds_dwordx4 v221, s[98:99]
	s_mov_b32 m0, s51
	s_add_u32 s98, vcc_lo, s70
	s_addc_u32 s99, vcc_hi, s71
	global_load_lds_dwordx4 v221, s[98:99]
	s_waitcnt lgkmcnt(8)
	s_waitcnt vmcnt(10)
	s_barrier
	s_waitcnt lgkmcnt(0)
	v_mfma_f32_16x16x32_bf16 v[126:129], v[138:141], v[154:157], v[126:129]
	v_mfma_f32_16x16x32_bf16 v[122:125], v[146:149], v[154:157], v[122:125]
	v_mfma_f32_16x16x32_bf16 v[118:121], v[138:141], v[162:165], v[118:121]
	v_mfma_f32_16x16x32_bf16 v[114:117], v[146:149], v[162:165], v[114:117]
	v_mfma_f32_16x16x32_bf16 v[110:113], v[138:141], v[170:173], v[110:113]
	v_mfma_f32_16x16x32_bf16 v[106:109], v[146:149], v[170:173], v[106:109]
	v_mfma_f32_16x16x32_bf16 v[102:105], v[138:141], v[178:181], v[102:105]
	v_mfma_f32_16x16x32_bf16 v[98:101], v[146:149], v[178:181], v[98:101]
	v_mfma_f32_16x16x32_bf16 v[126:129], v[142:145], v[158:161], v[126:129]
	v_mfma_f32_16x16x32_bf16 v[122:125], v[150:153], v[158:161], v[122:125]
	v_mfma_f32_16x16x32_bf16 v[118:121], v[142:145], v[166:169], v[118:121]
	v_mfma_f32_16x16x32_bf16 v[114:117], v[150:153], v[166:169], v[114:117]
	v_mfma_f32_16x16x32_bf16 v[110:113], v[142:145], v[174:177], v[110:113]
	v_mfma_f32_16x16x32_bf16 v[106:109], v[150:153], v[174:177], v[106:109]
	v_mfma_f32_16x16x32_bf16 v[102:105], v[142:145], v[182:185], v[102:105]
	v_mfma_f32_16x16x32_bf16 v[98:101], v[150:153], v[182:185], v[98:101]
	s_barrier
; #define LDA(dst, b, h) for (int m = 0; m < 4; ++m) for (int k = 0; k < 2; ++k) \
;     dst[m][k] = *reinterpret_cast<const bf16x8*>((char*)SA(b, h) + a_thr + (m * 2 + k) * 1024)
; #define LDB(dst, b, h) for (int n = 0; n < 2; ++n) for (int k = 0; k < 2; ++k) \
;     dst[n][k] = *reinterpret_cast<const bf16x8*>((char*)SB(b, h) + b_thr + (n * 2 + k) * 1024)
; #define MMA(ai, bj, At, Btf) do { __builtin_amdgcn_s_setprio(1); \
;     for (int m = 0; m < 4; ++m) for (int n = 0; n < 2; ++n) for (int k = 0; k < 2; ++k) \
;       acc[ai][bj][m][n] = __builtin_amdgcn_mfma_f32_16x16x32_bf16(Btf[n][k], At[m][k], acc[ai][bj][m][n], 0, 0, 0); \
;     __builtin_amdgcn_s_setprio(0); } while (0)
; #define WAIT_V(n) asm volatile("s_waitcnt vmcnt(" #n ")" ::: "memory")
; #define WAIT_L(n) asm volatile("s_waitcnt lgkmcnt(" #n ")" ::: "memory")
; #define BAR __builtin_amdgcn_s_barrier()
; #define SCHED __builtin_amdgcn_sched_barrier(0)
; template <bool OVL, bool PANEL = false, class Epi>
; __device__ __forceinline__ void gemm_phase(const bf16_t* __restrict__ A, long lda, const bf16_t* __restrict__ Bt, long ldb, int nM, int nN, int K,
;                                            const Epi& epi, bf16_t* shm, int w0) {
;     ...
;       LDB(B1, 1, 1); STAGE(SB(1, 0), Bt, ldb, boff, bcol, t + 3);
;       BAR; WAIT_L(0); MMA(0, 1, At, B1); BAR;
;       LDA(At, 1, 1); STAGE(SA(1, 0), A, lda, aoff, brow, t + 3);
;       BAR; WAIT_L(0); MMA(1, 0, At, B0); BAR; SCHED;
;       STAGE(SB(1, 1), Bt, ldb, boff, bcol + HALF, t + 3);
;       WAIT_V(6); BAR; MMA(1, 1, At, B1); BAR;
	ds_read_b128 v[186:189], v209
	ds_read_b128 v[190:193], v209 offset:1024
	ds_read_b128 v[194:197], v209 offset:2048
	ds_read_b128 v[198:201], v209 offset:3072
	s_mov_b32 m0, s52
	s_add_u32 s98, s0, s94
	s_addc_u32 s99, s1, s95
	global_load_lds_dwordx4 v221, s[98:99]
	s_mov_b32 m0, s53
	s_add_u32 s98, s0, s72
	s_addc_u32 s99, s1, s73
	global_load_lds_dwordx4 v221, s[98:99]
	s_waitcnt vmcnt(10)
	s_barrier
	s_waitcnt lgkmcnt(0)
	v_mfma_f32_16x16x32_bf16 v[94:97], v[186:189], v[154:157], v[94:97]
	v_mfma_f32_16x16x32_bf16 v[90:93], v[194:197], v[154:157], v[90:93]
	v_mfma_f32_16x16x32_bf16 v[86:89], v[186:189], v[162:165], v[86:89]
	v_mfma_f32_16x16x32_bf16 v[82:85], v[194:197], v[162:165], v[82:85]
	v_mfma_f32_16x16x32_bf16 v[78:81], v[186:189], v[170:173], v[78:81]
	v_mfma_f32_16x16x32_bf16 v[74:77], v[194:197], v[170:173], v[74:77]
	v_mfma_f32_16x16x32_bf16 v[70:73], v[186:189], v[178:181], v[70:73]
	v_mfma_f32_16x16x32_bf16 v[66:69], v[194:197], v[178:181], v[66:69]
	v_mfma_f32_16x16x32_bf16 v[94:97], v[190:193], v[158:161], v[94:97]
	v_mfma_f32_16x16x32_bf16 v[90:93], v[198:201], v[158:161], v[90:93]
	v_mfma_f32_16x16x32_bf16 v[86:89], v[190:193], v[166:169], v[86:89]
	v_mfma_f32_16x16x32_bf16 v[82:85], v[198:201], v[166:169], v[82:85]
	v_mfma_f32_16x16x32_bf16 v[78:81], v[190:193], v[174:177], v[78:81]
	v_mfma_f32_16x16x32_bf16 v[74:77], v[198:201], v[174:177], v[74:77]
	v_mfma_f32_16x16x32_bf16 v[70:73], v[190:193], v[182:185], v[70:73]
	v_mfma_f32_16x16x32_bf16 v[66:69], v[198:201], v[182:185], v[66:69]
	s_barrier
	ds_read_b128 v[154:157], v241 offset:49152
	ds_read_b128 v[158:161], v241 offset:50176
	ds_read_b128 v[162:165], v241 offset:51200
	ds_read_b128 v[166:169], v241 offset:52224
	ds_read_b128 v[170:173], v241 offset:53248
	ds_read_b128 v[174:177], v241 offset:54272
	ds_read_b128 v[178:181], v241 offset:55296
	ds_read_b128 v[182:185], v241 offset:56320
	s_mov_b32 m0, s54
	s_add_u32 s98, vcc_lo, s94
	s_addc_u32 s99, vcc_hi, s95
	global_load_lds_dwordx4 v221, s[98:99]
	s_mov_b32 m0, s55
	s_add_u32 s98, vcc_lo, s72
	s_addc_u32 s99, vcc_hi, s73
	global_load_lds_dwordx4 v221, s[98:99]
	s_barrier
	s_waitcnt lgkmcnt(0)
	v_mfma_f32_16x16x32_bf16 v[62:65], v[138:141], v[154:157], v[62:65]
	v_mfma_f32_16x16x32_bf16 v[58:61], v[146:149], v[154:157], v[58:61]
	v_mfma_f32_16x16x32_bf16 v[54:57], v[138:141], v[162:165], v[54:57]
	v_mfma_f32_16x16x32_bf16 v[50:53], v[146:149], v[162:165], v[50:53]
	v_mfma_f32_16x16x32_bf16 v[46:49], v[138:141], v[170:173], v[46:49]
	v_mfma_f32_16x16x32_bf16 v[42:45], v[146:149], v[170:173], v[42:45]
	v_mfma_f32_16x16x32_bf16 v[38:41], v[138:141], v[178:181], v[38:41]
	v_mfma_f32_16x16x32_bf16 v[34:37], v[146:149], v[178:181], v[34:37]
	v_mfma_f32_16x16x32_bf16 v[62:65], v[142:145], v[158:161], v[62:65]
	v_mfma_f32_16x16x32_bf16 v[58:61], v[150:153], v[158:161], v[58:61]
	v_mfma_f32_16x16x32_bf16 v[54:57], v[142:145], v[166:169], v[54:57]
	v_mfma_f32_16x16x32_bf16 v[50:53], v[150:153], v[166:169], v[50:53]
	v_mfma_f32_16x16x32_bf16 v[46:49], v[142:145], v[174:177], v[46:49]
	v_mfma_f32_16x16x32_bf16 v[42:45], v[150:153], v[174:177], v[42:45]
	v_mfma_f32_16x16x32_bf16 v[38:41], v[142:145], v[182:185], v[38:41]
	v_mfma_f32_16x16x32_bf16 v[34:37], v[150:153], v[182:185], v[34:37]
	s_barrier
	s_mov_b32 m0, s56
	s_add_u32 s98, s0, s14
	s_addc_u32 s99, s1, s15
	global_load_lds_dwordx4 v221, s[98:99]
	s_mov_b32 m0, s57
	s_add_u32 s98, s0, s18
	s_addc_u32 s99, s1, s19
	global_load_lds_dwordx4 v221, s[98:99]
	s_add_i32 s2, s2, 2
	s_add_u32 s80, s80, 0x100
	s_addc_u32 s81, s81, 0
	s_cmp_gt_u32 s2, 11
	s_waitcnt vmcnt(10)
	s_barrier
	v_mfma_f32_16x16x32_bf16 v[30:33], v[186:189], v[154:157], v[30:33]
	v_mfma_f32_16x16x32_bf16 v[26:29], v[194:197], v[154:157], v[26:29]
	v_mfma_f32_16x16x32_bf16 v[22:25], v[186:189], v[162:165], v[22:25]
	v_mfma_f32_16x16x32_bf16 v[18:21], v[194:197], v[162:165], v[18:21]
	v_mfma_f32_16x16x32_bf16 v[14:17], v[186:189], v[170:173], v[14:17]
	v_mfma_f32_16x16x32_bf16 v[10:13], v[194:197], v[170:173], v[10:13]
	v_mfma_f32_16x16x32_bf16 v[6:9], v[186:189], v[178:181], v[6:9]
	v_mfma_f32_16x16x32_bf16 v[2:5], v[194:197], v[178:181], v[2:5]
	v_mfma_f32_16x16x32_bf16 v[30:33], v[190:193], v[158:161], v[30:33]
	v_mfma_f32_16x16x32_bf16 v[26:29], v[198:201], v[158:161], v[26:29]
	v_mfma_f32_16x16x32_bf16 v[22:25], v[190:193], v[166:169], v[22:25]
	v_mfma_f32_16x16x32_bf16 v[18:21], v[198:201], v[166:169], v[18:21]
	v_mfma_f32_16x16x32_bf16 v[14:17], v[190:193], v[174:177], v[14:17]
	v_mfma_f32_16x16x32_bf16 v[10:13], v[198:201], v[174:177], v[10:13]
	v_mfma_f32_16x16x32_bf16 v[6:9], v[190:193], v[182:185], v[6:9]
	v_mfma_f32_16x16x32_bf16 v[2:5], v[198:201], v[182:185], v[2:5]
	s_barrier
; #define LDA(dst, b, h) for (int m = 0; m < 4; ++m) for (int k = 0; k < 2; ++k) \
;     dst[m][k] = *reinterpret_cast<const bf16x8*>((char*)SA(b, h) + a_thr + (m * 2 + k) * 1024)
; #define LDB(dst, b, h) for (int n = 0; n < 2; ++n) for (int k = 0; k < 2; ++k) \
;     dst[n][k] = *reinterpret_cast<const bf16x8*>((char*)SB(b, h) + b_thr + (n * 2 + k) * 1024)
; #define MMA(ai, bj, At, Btf) do { __builtin_amdgcn_s_setprio(1); \
;     for (int m = 0; m < 4; ++m) for (int n = 0; n < 2; ++n) for (int k = 0; k < 2; ++k) \
;       acc[ai][bj][m][n] = __builtin_amdgcn_mfma_f32_16x16x32_bf16(Btf[n][k], At[m][k], acc[ai][bj][m][n], 0, 0, 0); \
;     __builtin_amdgcn_s_setprio(0); } while (0)
; #define WAIT_V(n) asm volatile("s_waitcnt vmcnt(" #n ")" ::: "memory")
; #define WAIT_L(n) asm volatile("s_waitcnt lgkmcnt(" #n ")" ::: "memory")
; #define BAR __builtin_amdgcn_s_barrier()
; #define SCHED __builtin_amdgcn_sched_barrier(0)
; template <bool OVL, bool PANEL = false, class Epi>
; __device__ __forceinline__ void gemm_phase(const bf16_t* __restrict__ A, long lda, const bf16_t* __restrict__ Bt, long ldb, int nM, int nN, int K,
;                                            const Epi& epi, bf16_t* shm, int w0) {
;     ...
;       LDB(B0, 0, 0); SCHED; LDA(At, 0, 0); STAGE(SA(1, 1), A, lda, aoff, brow + HALF, t + 1);
;       WAIT_L(8); BAR; WAIT_L(0); MMA(0, 0, At, B0); BAR; SCHED;
;       LDB(B1, 0, 1); STAGE(SB(0, 0), Bt, ldb, boff, bcol, t + 2);
;       BAR; WAIT_L(0); MMA(0, 1, At, B1); BAR;
;       LDA(At, 0, 1); STAGE(SA(0, 0), A, lda, aoff, brow, t + 2);
;       BAR; WAIT_L(0); MMA(1, 0, At, B0); BAR; SCHED;
;       STAGE(SB(0, 1), Bt, ldb, boff, bcol + HALF, t + 2);
;       WAIT_V(6); BAR; MMA(1, 1, At, B1); BAR;
.LBB0_472:
	ds_read_b128 v[138:141], v206
	ds_read_b128 v[142:145], v206 offset:1024
	ds_read_b128 v[146:149], v206 offset:2048
	ds_read_b128 v[150:153], v206 offset:3072
	s_add_u32 vcc_lo, s8, s80
	s_addc_u32 vcc_hi, s9, s81
	ds_read_b128 v[154:157], v241
	ds_read_b128 v[158:161], v241 offset:1024
	ds_read_b128 v[162:165], v241 offset:2048
	ds_read_b128 v[166:169], v241 offset:3072
	ds_read_b128 v[170:173], v241 offset:4096
	ds_read_b128 v[174:177], v241 offset:5120
	ds_read_b128 v[178:181], v241 offset:6144
	ds_read_b128 v[182:185], v241 offset:7168
	s_mov_b32 m0, s16
	s_add_u32 s98, vcc_lo, s12
	s_addc_u32 s99, vcc_hi, s13
	global_load_lds_dwordx4 v221, s[98:99]
	s_mov_b32 m0, s32
	s_add_u32 s98, vcc_lo, s36
	s_addc_u32 s99, vcc_hi, s37
	global_load_lds_dwordx4 v221, s[98:99]
	s_waitcnt lgkmcnt(8)
	s_waitcnt vmcnt(10)
	s_barrier
	s_waitcnt lgkmcnt(0)
	v_mfma_f32_16x16x32_bf16 v[126:129], v[138:141], v[154:157], v[126:129]
	v_mfma_f32_16x16x32_bf16 v[122:125], v[146:149], v[154:157], v[122:125]
	v_mfma_f32_16x16x32_bf16 v[118:121], v[138:141], v[162:165], v[118:121]
	v_mfma_f32_16x16x32_bf16 v[114:117], v[146:149], v[162:165], v[114:117]
	v_mfma_f32_16x16x32_bf16 v[110:113], v[138:141], v[170:173], v[110:113]
	v_mfma_f32_16x16x32_bf16 v[106:109], v[146:149], v[170:173], v[106:109]
	v_mfma_f32_16x16x32_bf16 v[102:105], v[138:141], v[178:181], v[102:105]
	v_mfma_f32_16x16x32_bf16 v[98:101], v[146:149], v[178:181], v[98:101]
	v_mfma_f32_16x16x32_bf16 v[126:129], v[142:145], v[158:161], v[126:129]
	v_mfma_f32_16x16x32_bf16 v[122:125], v[150:153], v[158:161], v[122:125]
	v_mfma_f32_16x16x32_bf16 v[118:121], v[142:145], v[166:169], v[118:121]
	v_mfma_f32_16x16x32_bf16 v[114:117], v[150:153], v[166:169], v[114:117]
	v_mfma_f32_16x16x32_bf16 v[110:113], v[142:145], v[174:177], v[110:113]
	v_mfma_f32_16x16x32_bf16 v[106:109], v[150:153], v[174:177], v[106:109]
	v_mfma_f32_16x16x32_bf16 v[102:105], v[142:145], v[182:185], v[102:105]
	v_mfma_f32_16x16x32_bf16 v[98:101], v[150:153], v[182:185], v[98:101]
	s_barrier
	s_add_u32 s0, s6, s80
	ds_read_b128 v[186:189], v207
	ds_read_b128 v[190:193], v207 offset:1024
	ds_read_b128 v[194:197], v207 offset:2048
	ds_read_b128 v[198:201], v207 offset:3072
	s_addc_u32 s1, s7, s81
	s_mov_b32 m0, s44
	s_add_u32 s98, s0, s34
	s_addc_u32 s99, s1, s35
	global_load_lds_dwordx4 v221, s[98:99]
	s_mov_b32 m0, s45
	s_add_u32 s98, s0, s64
	s_addc_u32 s99, s1, s65
	global_load_lds_dwordx4 v221, s[98:99]
	s_waitcnt vmcnt(10)
	s_barrier
	s_waitcnt lgkmcnt(0)
	v_mfma_f32_16x16x32_bf16 v[94:97], v[186:189], v[154:157], v[94:97]
	v_mfma_f32_16x16x32_bf16 v[90:93], v[194:197], v[154:157], v[90:93]
	v_mfma_f32_16x16x32_bf16 v[86:89], v[186:189], v[162:165], v[86:89]
	v_mfma_f32_16x16x32_bf16 v[82:85], v[194:197], v[162:165], v[82:85]
	v_mfma_f32_16x16x32_bf16 v[78:81], v[186:189], v[170:173], v[78:81]
	v_mfma_f32_16x16x32_bf16 v[74:77], v[194:197], v[170:173], v[74:77]
	v_mfma_f32_16x16x32_bf16 v[70:73], v[186:189], v[178:181], v[70:73]
	v_mfma_f32_16x16x32_bf16 v[66:69], v[194:197], v[178:181], v[66:69]
	v_mfma_f32_16x16x32_bf16 v[94:97], v[190:193], v[158:161], v[94:97]
	v_mfma_f32_16x16x32_bf16 v[90:93], v[198:201], v[158:161], v[90:93]
	v_mfma_f32_16x16x32_bf16 v[86:89], v[190:193], v[166:169], v[86:89]
	v_mfma_f32_16x16x32_bf16 v[82:85], v[198:201], v[166:169], v[82:85]
	v_mfma_f32_16x16x32_bf16 v[78:81], v[190:193], v[174:177], v[78:81]
	v_mfma_f32_16x16x32_bf16 v[74:77], v[198:201], v[174:177], v[74:77]
	v_mfma_f32_16x16x32_bf16 v[70:73], v[190:193], v[182:185], v[70:73]
	v_mfma_f32_16x16x32_bf16 v[66:69], v[198:201], v[182:185], v[66:69]
	s_barrier
	ds_read_b128 v[154:157], v241 offset:16384
	ds_read_b128 v[158:161], v241 offset:17408
	ds_read_b128 v[162:165], v241 offset:18432
	ds_read_b128 v[166:169], v241 offset:19456
	ds_read_b128 v[170:173], v241 offset:20480
	ds_read_b128 v[174:177], v241 offset:21504
	ds_read_b128 v[178:181], v241 offset:22528
	ds_read_b128 v[182:185], v241 offset:23552
	s_mov_b32 m0, s46
	s_add_u32 s98, vcc_lo, s34
	s_addc_u32 s99, vcc_hi, s35
	global_load_lds_dwordx4 v221, s[98:99]
	s_mov_b32 m0, s47
	s_add_u32 s98, vcc_lo, s64
	s_addc_u32 s99, vcc_hi, s65
	global_load_lds_dwordx4 v221, s[98:99]
	s_barrier
	s_waitcnt lgkmcnt(0)
	v_mfma_f32_16x16x32_bf16 v[62:65], v[138:141], v[154:157], v[62:65]
	v_mfma_f32_16x16x32_bf16 v[58:61], v[146:149], v[154:157], v[58:61]
	v_mfma_f32_16x16x32_bf16 v[54:57], v[138:141], v[162:165], v[54:57]
	v_mfma_f32_16x16x32_bf16 v[50:53], v[146:149], v[162:165], v[50:53]
	v_mfma_f32_16x16x32_bf16 v[46:49], v[138:141], v[170:173], v[46:49]
	v_mfma_f32_16x16x32_bf16 v[42:45], v[146:149], v[170:173], v[42:45]
	v_mfma_f32_16x16x32_bf16 v[38:41], v[138:141], v[178:181], v[38:41]
	v_mfma_f32_16x16x32_bf16 v[34:37], v[146:149], v[178:181], v[34:37]
	v_mfma_f32_16x16x32_bf16 v[62:65], v[142:145], v[158:161], v[62:65]
	v_mfma_f32_16x16x32_bf16 v[58:61], v[150:153], v[158:161], v[58:61]
	v_mfma_f32_16x16x32_bf16 v[54:57], v[142:145], v[166:169], v[54:57]
	v_mfma_f32_16x16x32_bf16 v[50:53], v[150:153], v[166:169], v[50:53]
	v_mfma_f32_16x16x32_bf16 v[46:49], v[142:145], v[174:177], v[46:49]
	v_mfma_f32_16x16x32_bf16 v[42:45], v[150:153], v[174:177], v[42:45]
	v_mfma_f32_16x16x32_bf16 v[38:41], v[142:145], v[182:185], v[38:41]
	v_mfma_f32_16x16x32_bf16 v[34:37], v[150:153], v[182:185], v[34:37]
	s_barrier
	s_mov_b32 m0, s48
	s_add_u32 s98, s0, s68
	s_addc_u32 s99, s1, s69
	global_load_lds_dwordx4 v221, s[98:99]
	s_mov_b32 m0, s49
	s_add_u32 s98, s0, s70
	s_addc_u32 s99, s1, s71
	global_load_lds_dwordx4 v221, s[98:99]
	s_waitcnt vmcnt(10)
	s_barrier
; #define LDA(dst, b, h) for (int m = 0; m < 4; ++m) for (int k = 0; k < 2; ++k) \
;     dst[m][k] = *reinterpret_cast<const bf16x8*>((char*)SA(b, h) + a_thr + (m * 2 + k) * 1024)
; #define LDB(dst, b, h) for (int n = 0; n < 2; ++n) for (int k = 0; k < 2; ++k) \
;     dst[n][k] = *reinterpret_cast<const bf16x8*>((char*)SB(b, h) + b_thr + (n * 2 + k) * 1024)
; #define MMA(ai, bj, At, Btf) do { __builtin_amdgcn_s_setprio(1); \
;     for (int m = 0; m < 4; ++m) for (int n = 0; n < 2; ++n) for (int k = 0; k < 2; ++k) \
;       acc[ai][bj][m][n] = __builtin_amdgcn_mfma_f32_16x16x32_bf16(Btf[n][k], At[m][k], acc[ai][bj][m][n], 0, 0, 0); \
;     __builtin_amdgcn_s_setprio(0); } while (0)
; #define WAIT_V(n) asm volatile("s_waitcnt vmcnt(" #n ")" ::: "memory")
; #define WAIT_L(n) asm volatile("s_waitcnt lgkmcnt(" #n ")" ::: "memory")
; #define BAR __builtin_amdgcn_s_barrier()
; #define SCHED __builtin_amdgcn_sched_barrier(0)
; template <bool OVL, bool PANEL = false, class Epi>
; __device__ __forceinline__ void gemm_phase(const bf16_t* __restrict__ A, long lda, const bf16_t* __restrict__ Bt, long ldb, int nM, int nN, int K,
;                                            const Epi& epi, bf16_t* shm, int w0) {
;     ...
;       WAIT_V(6); BAR; MMA(1, 1, At, B1); BAR;
;       LDB(B0, 1, 0); SCHED; LDA(At, 1, 0); STAGE(SA(0, 1), A, lda, aoff, brow + HALF, t + 2);
;       WAIT_L(8); BAR; WAIT_L(0); MMA(0, 0, At, B0); BAR; SCHED;
;       LDB(B1, 1, 1); STAGE(SB(1, 0), Bt, ldb, boff, bcol, t + 3);
;       BAR; WAIT_L(0); MMA(0, 1, At, B1); BAR;
	v_mfma_f32_16x16x32_bf16 v[30:33], v[186:189], v[154:157], v[30:33]
	v_mfma_f32_16x16x32_bf16 v[26:29], v[194:197], v[154:157], v[26:29]
	v_mfma_f32_16x16x32_bf16 v[22:25], v[186:189], v[162:165], v[22:25]
	v_mfma_f32_16x16x32_bf16 v[18:21], v[194:197], v[162:165], v[18:21]
	v_mfma_f32_16x16x32_bf16 v[14:17], v[186:189], v[170:173], v[14:17]
	v_mfma_f32_16x16x32_bf16 v[10:13], v[194:197], v[170:173], v[10:13]
	v_mfma_f32_16x16x32_bf16 v[6:9], v[186:189], v[178:181], v[6:9]
	v_mfma_f32_16x16x32_bf16 v[2:5], v[194:197], v[178:181], v[2:5]
	v_mfma_f32_16x16x32_bf16 v[30:33], v[190:193], v[158:161], v[30:33]
	v_mfma_f32_16x16x32_bf16 v[26:29], v[198:201], v[158:161], v[26:29]
	v_mfma_f32_16x16x32_bf16 v[22:25], v[190:193], v[166:169], v[22:25]
	v_mfma_f32_16x16x32_bf16 v[18:21], v[198:201], v[166:169], v[18:21]
	v_mfma_f32_16x16x32_bf16 v[14:17], v[190:193], v[174:177], v[14:17]
	v_mfma_f32_16x16x32_bf16 v[10:13], v[198:201], v[174:177], v[10:13]
	v_mfma_f32_16x16x32_bf16 v[6:9], v[190:193], v[182:185], v[6:9]
	v_mfma_f32_16x16x32_bf16 v[2:5], v[198:201], v[182:185], v[2:5]
	s_barrier
	ds_read_b128 v[138:141], v208
	ds_read_b128 v[142:145], v208 offset:1024
	ds_read_b128 v[146:149], v208 offset:2048
	ds_read_b128 v[150:153], v208 offset:3072
	ds_read_b128 v[154:157], v241 offset:32768
	ds_read_b128 v[158:161], v241 offset:33792
	ds_read_b128 v[162:165], v241 offset:34816
	ds_read_b128 v[166:169], v241 offset:35840
	ds_read_b128 v[170:173], v241 offset:36864
	ds_read_b128 v[174:177], v241 offset:37888
	ds_read_b128 v[178:181], v241 offset:38912
	ds_read_b128 v[182:185], v241 offset:39936
	s_mov_b32 m0, s50
	s_add_u32 s98, vcc_lo, s68
	s_addc_u32 s99, vcc_hi, s69
	global_load_lds_dwordx4 v221, s[98:99]
	s_mov_b32 m0, s51
	s_add_u32 s98, vcc_lo, s70
	s_addc_u32 s99, vcc_hi, s71
	global_load_lds_dwordx4 v221, s[98:99]
	s_waitcnt lgkmcnt(8)
	s_waitcnt vmcnt(10)
	s_barrier
	s_waitcnt lgkmcnt(0)
	v_mfma_f32_16x16x32_bf16 v[126:129], v[138:141], v[154:157], v[126:129]
	v_mfma_f32_16x16x32_bf16 v[122:125], v[146:149], v[154:157], v[122:125]
	v_mfma_f32_16x16x32_bf16 v[118:121], v[138:141], v[162:165], v[118:121]
	v_mfma_f32_16x16x32_bf16 v[114:117], v[146:149], v[162:165], v[114:117]
	v_mfma_f32_16x16x32_bf16 v[110:113], v[138:141], v[170:173], v[110:113]
	v_mfma_f32_16x16x32_bf16 v[106:109], v[146:149], v[170:173], v[106:109]
	v_mfma_f32_16x16x32_bf16 v[102:105], v[138:141], v[178:181], v[102:105]
	v_mfma_f32_16x16x32_bf16 v[98:101], v[146:149], v[178:181], v[98:101]
	v_mfma_f32_16x16x32_bf16 v[126:129], v[142:145], v[158:161], v[126:129]
	v_mfma_f32_16x16x32_bf16 v[122:125], v[150:153], v[158:161], v[122:125]
	v_mfma_f32_16x16x32_bf16 v[118:121], v[142:145], v[166:169], v[118:121]
	v_mfma_f32_16x16x32_bf16 v[114:117], v[150:153], v[166:169], v[114:117]
	v_mfma_f32_16x16x32_bf16 v[110:113], v[142:145], v[174:177], v[110:113]
	v_mfma_f32_16x16x32_bf16 v[106:109], v[150:153], v[174:177], v[106:109]
	v_mfma_f32_16x16x32_bf16 v[102:105], v[142:145], v[182:185], v[102:105]
	v_mfma_f32_16x16x32_bf16 v[98:101], v[150:153], v[182:185], v[98:101]
	s_barrier
	ds_read_b128 v[186:189], v209
	ds_read_b128 v[190:193], v209 offset:1024
	ds_read_b128 v[194:197], v209 offset:2048
	ds_read_b128 v[198:201], v209 offset:3072
	s_mov_b32 m0, s52
	s_add_u32 s98, s0, s94
	s_addc_u32 s99, s1, s95
	global_load_lds_dwordx4 v221, s[98:99]
	s_mov_b32 m0, s53
	s_add_u32 s98, s0, s72
	s_addc_u32 s99, s1, s73
	global_load_lds_dwordx4 v221, s[98:99]
	s_waitcnt vmcnt(10)
	s_barrier
	s_waitcnt lgkmcnt(0)
	v_mfma_f32_16x16x32_bf16 v[94:97], v[186:189], v[154:157], v[94:97]
	v_mfma_f32_16x16x32_bf16 v[90:93], v[194:197], v[154:157], v[90:93]
	v_mfma_f32_16x16x32_bf16 v[86:89], v[186:189], v[162:165], v[86:89]
	v_mfma_f32_16x16x32_bf16 v[82:85], v[194:197], v[162:165], v[82:85]
	v_mfma_f32_16x16x32_bf16 v[78:81], v[186:189], v[170:173], v[78:81]
	v_mfma_f32_16x16x32_bf16 v[74:77], v[194:197], v[170:173], v[74:77]
	v_mfma_f32_16x16x32_bf16 v[70:73], v[186:189], v[178:181], v[70:73]
	v_mfma_f32_16x16x32_bf16 v[66:69], v[194:197], v[178:181], v[66:69]
	v_mfma_f32_16x16x32_bf16 v[94:97], v[190:193], v[158:161], v[94:97]
	v_mfma_f32_16x16x32_bf16 v[90:93], v[198:201], v[158:161], v[90:93]
	v_mfma_f32_16x16x32_bf16 v[86:89], v[190:193], v[166:169], v[86:89]
	v_mfma_f32_16x16x32_bf16 v[82:85], v[198:201], v[166:169], v[82:85]
	v_mfma_f32_16x16x32_bf16 v[78:81], v[190:193], v[174:177], v[78:81]
	v_mfma_f32_16x16x32_bf16 v[74:77], v[198:201], v[174:177], v[74:77]
	v_mfma_f32_16x16x32_bf16 v[70:73], v[190:193], v[182:185], v[70:73]
	v_mfma_f32_16x16x32_bf16 v[66:69], v[198:201], v[182:185], v[66:69]
	s_barrier
; #define LDA(dst, b, h) for (int m = 0; m < 4; ++m) for (int k = 0; k < 2; ++k) \
;     dst[m][k] = *reinterpret_cast<const bf16x8*>((char*)SA(b, h) + a_thr + (m * 2 + k) * 1024)
; #define LDB(dst, b, h) for (int n = 0; n < 2; ++n) for (int k = 0; k < 2; ++k) \
;     dst[n][k] = *reinterpret_cast<const bf16x8*>((char*)SB(b, h) + b_thr + (n * 2 + k) * 1024)
; #define MMA(ai, bj, At, Btf) do { __builtin_amdgcn_s_setprio(1); \
;     for (int m = 0; m < 4; ++m) for (int n = 0; n < 2; ++n) for (int k = 0; k < 2; ++k) \
;       acc[ai][bj][m][n] = __builtin_amdgcn_mfma_f32_16x16x32_bf16(Btf[n][k], At[m][k], acc[ai][bj][m][n], 0, 0, 0); \
;     __builtin_amdgcn_s_setprio(0); } while (0)
; #define WAIT_V(n) asm volatile("s_waitcnt vmcnt(" #n ")" ::: "memory")
; #define WAIT_L(n) asm volatile("s_waitcnt lgkmcnt(" #n ")" ::: "memory")
; #define BAR __builtin_amdgcn_s_barrier()
; #define SCHED __builtin_amdgcn_sched_barrier(0)
; template <bool OVL, bool PANEL = false, class Epi>
; __device__ __forceinline__ void gemm_phase(const bf16_t* __restrict__ A, long lda, const bf16_t* __restrict__ Bt, long ldb, int nM, int nN, int K,
;                                            const Epi& epi, bf16_t* shm, int w0) {
;     ...
;       LDA(At, 1, 1); STAGE(SA(1, 0), A, lda, aoff, brow, t + 3);
;       BAR; WAIT_L(0); MMA(1, 0, At, B0); BAR; SCHED;
;       STAGE(SB(1, 1), Bt, ldb, boff, bcol + HALF, t + 3);
;       WAIT_V(6); BAR; MMA(1, 1, At, B1); BAR;
;     }
;     { LDB(B0, 0, 0); LDA(At, 0, 0); STAGE(SA(1, 1), A, lda, aoff, brow + HALF, nt - 1);
;       BAR; WAIT_L(0); MMA(0, 0, At, B0); BAR;
	ds_read_b128 v[154:157], v241 offset:49152
	ds_read_b128 v[158:161], v241 offset:50176
	ds_read_b128 v[162:165], v241 offset:51200
	ds_read_b128 v[166:169], v241 offset:52224
	ds_read_b128 v[170:173], v241 offset:53248
	ds_read_b128 v[174:177], v241 offset:54272
	ds_read_b128 v[178:181], v241 offset:55296
	ds_read_b128 v[182:185], v241 offset:56320
	s_mov_b32 m0, s54
	s_add_u32 s98, vcc_lo, s94
	s_addc_u32 s99, vcc_hi, s95
	global_load_lds_dwordx4 v221, s[98:99]
	s_mov_b32 m0, s55
	s_add_u32 s98, vcc_lo, s72
	s_addc_u32 s99, vcc_hi, s73
	global_load_lds_dwordx4 v221, s[98:99]
	s_barrier
	s_waitcnt lgkmcnt(0)
	v_mfma_f32_16x16x32_bf16 v[62:65], v[138:141], v[154:157], v[62:65]
	v_mfma_f32_16x16x32_bf16 v[58:61], v[146:149], v[154:157], v[58:61]
	v_mfma_f32_16x16x32_bf16 v[54:57], v[138:141], v[162:165], v[54:57]
	v_mfma_f32_16x16x32_bf16 v[50:53], v[146:149], v[162:165], v[50:53]
	v_mfma_f32_16x16x32_bf16 v[46:49], v[138:141], v[170:173], v[46:49]
	v_mfma_f32_16x16x32_bf16 v[42:45], v[146:149], v[170:173], v[42:45]
	v_mfma_f32_16x16x32_bf16 v[38:41], v[138:141], v[178:181], v[38:41]
	v_mfma_f32_16x16x32_bf16 v[34:37], v[146:149], v[178:181], v[34:37]
	v_mfma_f32_16x16x32_bf16 v[62:65], v[142:145], v[158:161], v[62:65]
	v_mfma_f32_16x16x32_bf16 v[58:61], v[150:153], v[158:161], v[58:61]
	v_mfma_f32_16x16x32_bf16 v[54:57], v[142:145], v[166:169], v[54:57]
	v_mfma_f32_16x16x32_bf16 v[50:53], v[150:153], v[166:169], v[50:53]
	v_mfma_f32_16x16x32_bf16 v[46:49], v[142:145], v[174:177], v[46:49]
	v_mfma_f32_16x16x32_bf16 v[42:45], v[150:153], v[174:177], v[42:45]
	v_mfma_f32_16x16x32_bf16 v[38:41], v[142:145], v[182:185], v[38:41]
	v_mfma_f32_16x16x32_bf16 v[34:37], v[150:153], v[182:185], v[34:37]
	s_barrier
	s_mov_b32 m0, s56
	s_add_u32 s98, s0, s14
	s_addc_u32 s99, s1, s15
	global_load_lds_dwordx4 v221, s[98:99]
	s_mov_b32 m0, s57
	s_add_u32 s98, s0, s18
	s_addc_u32 s99, s1, s19
	global_load_lds_dwordx4 v221, s[98:99]
	s_add_i32 s2, s2, 2
	s_add_u32 s80, s80, 0x100
	s_addc_u32 s81, s81, 0
	s_cmp_gt_u32 s2, 11
	s_waitcnt vmcnt(10)
	s_barrier
	v_mfma_f32_16x16x32_bf16 v[30:33], v[186:189], v[154:157], v[30:33]
	v_mfma_f32_16x16x32_bf16 v[26:29], v[194:197], v[154:157], v[26:29]
	v_mfma_f32_16x16x32_bf16 v[22:25], v[186:189], v[162:165], v[22:25]
	v_mfma_f32_16x16x32_bf16 v[18:21], v[194:197], v[162:165], v[18:21]
	v_mfma_f32_16x16x32_bf16 v[14:17], v[186:189], v[170:173], v[14:17]
	v_mfma_f32_16x16x32_bf16 v[10:13], v[194:197], v[170:173], v[10:13]
	v_mfma_f32_16x16x32_bf16 v[6:9], v[186:189], v[178:181], v[6:9]
	v_mfma_f32_16x16x32_bf16 v[2:5], v[194:197], v[178:181], v[2:5]
	v_mfma_f32_16x16x32_bf16 v[30:33], v[190:193], v[158:161], v[30:33]
	v_mfma_f32_16x16x32_bf16 v[26:29], v[198:201], v[158:161], v[26:29]
	v_mfma_f32_16x16x32_bf16 v[22:25], v[190:193], v[166:169], v[22:25]
	v_mfma_f32_16x16x32_bf16 v[18:21], v[198:201], v[166:169], v[18:21]
	v_mfma_f32_16x16x32_bf16 v[14:17], v[190:193], v[174:177], v[14:17]
	v_mfma_f32_16x16x32_bf16 v[10:13], v[198:201], v[174:177], v[10:13]
	v_mfma_f32_16x16x32_bf16 v[6:9], v[190:193], v[182:185], v[6:9]
	v_mfma_f32_16x16x32_bf16 v[2:5], v[198:201], v[182:185], v[2:5]
	s_barrier
	s_cbranch_scc0 .LBB0_472
	s_waitcnt vmcnt(6)
	s_or_b32 s0, s82, 0x80
	s_ashr_i32 s1, s0, 31
	v_readlane_b32 s44, v252, 20
	s_lshl_b64 s[0:1], s[0:1], 11
	v_readlane_b32 s50, v252, 26
	v_add_u32_e32 v206, 16, v240
	v_readlane_b32 s51, v252, 27
	s_add_u32 s0, s50, s0
	v_add_u32_e32 v0, 0x10000, v206
	s_addc_u32 s1, s51, s1
	ds_read_b128 v[130:133], v0
	ds_read_b128 v[138:141], v0 offset:1024
	ds_read_b128 v[142:145], v0 offset:2048
	ds_read_b128 v[146:149], v0 offset:3072
	ds_read_b128 v[150:153], v241
	ds_read_b128 v[154:157], v241 offset:1024
	ds_read_b128 v[158:161], v241 offset:2048
	ds_read_b128 v[162:165], v241 offset:3072
	ds_read_b128 v[166:169], v241 offset:4096
	ds_read_b128 v[170:173], v241 offset:5120
	ds_read_b128 v[174:177], v241 offset:6144
	ds_read_b128 v[178:181], v241 offset:7168
	v_mov_b32_e32 v0, v221
	v_readlane_b32 s45, v252, 21
	v_lshl_add_u64 v[134:135], s[0:1], 0, v[0:1]
	s_mov_b64 s[0:1], 0x780
	v_lshl_add_u64 v[182:183], v[134:135], 0, s[0:1]
	v_readfirstlane_b32 s0, v136
	s_mov_b32 m0, s0
	s_mov_b64 s[0:1], 0x20780
	v_lshl_add_u64 v[134:135], v[134:135], 0, s[0:1]
	v_readfirstlane_b32 s0, v137
	global_load_lds_dwordx4 v[182:183], off
	s_mov_b32 m0, s0
	v_readlane_b32 s46, v252, 22
	global_load_lds_dwordx4 v[134:135], off
	s_barrier
	s_waitcnt lgkmcnt(0)
	v_readlane_b32 s47, v252, 23
	v_readlane_b32 s48, v252, 24
	v_readlane_b32 s49, v252, 25
	v_readlane_b32 s52, v252, 28
	v_readlane_b32 s53, v252, 29
	v_readlane_b32 s54, v252, 30
	v_readlane_b32 s55, v252, 31
	v_readlane_b32 s56, v252, 32
	v_readlane_b32 s57, v252, 33
	v_readlane_b32 s58, v252, 34
	v_readlane_b32 s59, v252, 35

; #define MMA(ai, bj, At, Btf) do { __builtin_amdgcn_s_setprio(1); \
;     for (int m = 0; m < 4; ++m) for (int n = 0; n < 2; ++n) for (int k = 0; k < 2; ++k) \
;       acc[ai][bj][m][n] = __builtin_amdgcn_mfma_f32_16x16x32_bf16(Btf[n][k], At[m][k], acc[ai][bj][m][n], 0, 0, 0); \
;     __builtin_amdgcn_s_setprio(0); } while (0)
; #define WAIT_L(n) asm volatile("s_waitcnt lgkmcnt(" #n ")" ::: "memory")
; #define BAR __builtin_amdgcn_s_barrier()
; template <bool OVL, bool PANEL = false, class Epi>
; __device__ __forceinline__ void gemm_phase(const bf16_t* __restrict__ A, long lda, const bf16_t* __restrict__ Bt, long ldb, int nM, int nN, int K,
;                                            const Epi& epi, bf16_t* shm, int w0) {
;     ...
;       BAR; WAIT_L(0); MMA(0, 0, At, B0); BAR;
	s_waitcnt lgkmcnt(0)
	v_mfma_f32_16x16x32_bf16 v[126:129], v[130:133], v[150:153], v[126:129]
	v_mfma_f32_16x16x32_bf16 v[122:125], v[142:145], v[150:153], v[122:125]
	v_mfma_f32_16x16x32_bf16 v[118:121], v[130:133], v[158:161], v[118:121]
	v_mfma_f32_16x16x32_bf16 v[114:117], v[142:145], v[158:161], v[114:117]
	v_mfma_f32_16x16x32_bf16 v[106:109], v[142:145], v[166:169], v[106:109]
	v_mfma_f32_16x16x32_bf16 v[102:105], v[130:133], v[174:177], v[102:105]
	v_mfma_f32_16x16x32_bf16 v[98:101], v[142:145], v[174:177], v[98:101]
	v_mfma_f32_16x16x32_bf16 v[126:129], v[138:141], v[154:157], v[126:129]
	v_mfma_f32_16x16x32_bf16 v[122:125], v[146:149], v[154:157], v[122:125]
	v_mfma_f32_16x16x32_bf16 v[118:121], v[138:141], v[162:165], v[118:121]
	v_mfma_f32_16x16x32_bf16 v[114:117], v[146:149], v[162:165], v[114:117]
	v_mfma_f32_16x16x32_bf16 v[110:113], v[130:133], v[166:169], v[110:113]
	v_mfma_f32_16x16x32_bf16 v[106:109], v[146:149], v[170:173], v[106:109]
	v_mfma_f32_16x16x32_bf16 v[102:105], v[138:141], v[178:181], v[102:105]
	v_mfma_f32_16x16x32_bf16 v[98:101], v[146:149], v[178:181], v[98:101]
	v_mfma_f32_16x16x32_bf16 v[134:137], v[138:141], v[170:173], v[110:113]

; #define LDB(dst, b, h) for (int n = 0; n < 2; ++n) for (int k = 0; k < 2; ++k) \
;     dst[n][k] = *reinterpret_cast<const bf16x8*>((char*)SB(b, h) + b_thr + (n * 2 + k) * 1024)
; #define MMA(ai, bj, At, Btf) do { __builtin_amdgcn_s_setprio(1); \
;     for (int m = 0; m < 4; ++m) for (int n = 0; n < 2; ++n) for (int k = 0; k < 2; ++k) \
;       acc[ai][bj][m][n] = __builtin_amdgcn_mfma_f32_16x16x32_bf16(Btf[n][k], At[m][k], acc[ai][bj][m][n], 0, 0, 0); \
;     __builtin_amdgcn_s_setprio(0); } while (0)
; #define WAIT_L(n) asm volatile("s_waitcnt lgkmcnt(" #n ")" ::: "memory")
; #define BAR __builtin_amdgcn_s_barrier()
; template <bool OVL, bool PANEL = false, class Epi>
; __device__ __forceinline__ void gemm_phase(const bf16_t* __restrict__ A, long lda, const bf16_t* __restrict__ Bt, long ldb, int nM, int nN, int K,
;                                            const Epi& epi, bf16_t* shm, int w0) {
;     ...
;       LDB(B1, 0, 1); BAR; WAIT_L(0); MMA(0, 1, At, B1); BAR;
	v_add_u32_e32 v0, 0x14000, v206
	s_barrier
	s_nop 0
	ds_read_b128 v[110:113], v0
	ds_read_b128 v[182:185], v0 offset:1024
	ds_read_b128 v[186:189], v0 offset:2048
	ds_read_b128 v[190:193], v0 offset:3072
	s_barrier
	s_waitcnt lgkmcnt(0)

; #define LDB(dst, b, h) for (int n = 0; n < 2; ++n) for (int k = 0; k < 2; ++k) \
;     dst[n][k] = *reinterpret_cast<const bf16x8*>((char*)SB(b, h) + b_thr + (n * 2 + k) * 1024)
; #define MMA(ai, bj, At, Btf) do { __builtin_amdgcn_s_setprio(1); \
;     for (int m = 0; m < 4; ++m) for (int n = 0; n < 2; ++n) for (int k = 0; k < 2; ++k) \
;       acc[ai][bj][m][n] = __builtin_amdgcn_mfma_f32_16x16x32_bf16(Btf[n][k], At[m][k], acc[ai][bj][m][n], 0, 0, 0); \
;     __builtin_amdgcn_s_setprio(0); } while (0)
; #define WAIT_L(n) asm volatile("s_waitcnt lgkmcnt(" #n ")" ::: "memory")
; #define BAR __builtin_amdgcn_s_barrier()
; template <bool OVL, bool PANEL = false, class Epi>
; __device__ __forceinline__ void gemm_phase(const bf16_t* __restrict__ A, long lda, const bf16_t* __restrict__ Bt, long ldb, int nM, int nN, int K,
;                                            const Epi& epi, bf16_t* shm, int w0) {
;     ...
;       LDB(B1, 0, 1); BAR; WAIT_L(0); MMA(0, 1, At, B1); BAR;
	s_waitcnt lgkmcnt(0)
	v_mfma_f32_16x16x32_bf16 v[90:93], v[186:189], v[150:153], v[90:93]
	v_mfma_f32_16x16x32_bf16 v[74:77], v[186:189], v[166:169], v[74:77]
	v_mfma_f32_16x16x32_bf16 v[70:73], v[110:113], v[174:177], v[70:73]
	v_mfma_f32_16x16x32_bf16 v[66:69], v[186:189], v[174:177], v[66:69]
	v_mfma_f32_16x16x32_bf16 v[94:97], v[110:113], v[150:153], v[94:97]
	v_mfma_f32_16x16x32_bf16 v[90:93], v[190:193], v[154:157], v[90:93]
	v_mfma_f32_16x16x32_bf16 v[86:89], v[110:113], v[158:161], v[86:89]
	v_mfma_f32_16x16x32_bf16 v[82:85], v[186:189], v[158:161], v[82:85]
	v_mfma_f32_16x16x32_bf16 v[78:81], v[110:113], v[166:169], v[78:81]
	v_mfma_f32_16x16x32_bf16 v[74:77], v[190:193], v[170:173], v[74:77]
	v_mfma_f32_16x16x32_bf16 v[70:73], v[182:185], v[178:181], v[70:73]
	v_mfma_f32_16x16x32_bf16 v[66:69], v[190:193], v[178:181], v[66:69]
	v_mfma_f32_16x16x32_bf16 v[194:197], v[182:185], v[154:157], v[94:97]
	v_mfma_f32_16x16x32_bf16 v[150:153], v[182:185], v[162:165], v[86:89]
	v_mfma_f32_16x16x32_bf16 v[154:157], v[190:193], v[162:165], v[82:85]
	v_mfma_f32_16x16x32_bf16 v[158:161], v[182:185], v[170:173], v[78:81]

; #define LDA(dst, b, h) for (int m = 0; m < 4; ++m) for (int k = 0; k < 2; ++k) \
;     dst[m][k] = *reinterpret_cast<const bf16x8*>((char*)SA(b, h) + a_thr + (m * 2 + k) * 1024)
; #define MMA(ai, bj, At, Btf) do { __builtin_amdgcn_s_setprio(1); \
;     for (int m = 0; m < 4; ++m) for (int n = 0; n < 2; ++n) for (int k = 0; k < 2; ++k) \
;       acc[ai][bj][m][n] = __builtin_amdgcn_mfma_f32_16x16x32_bf16(Btf[n][k], At[m][k], acc[ai][bj][m][n], 0, 0, 0); \
;     __builtin_amdgcn_s_setprio(0); } while (0)
; #define WAIT_V(n) asm volatile("s_waitcnt vmcnt(" #n ")" ::: "memory")
; #define WAIT_L(n) asm volatile("s_waitcnt lgkmcnt(" #n ")" ::: "memory")
; #define BAR __builtin_amdgcn_s_barrier()
; template <bool OVL, bool PANEL = false, class Epi>
; __device__ __forceinline__ void gemm_phase(const bf16_t* __restrict__ A, long lda, const bf16_t* __restrict__ Bt, long ldb, int nM, int nN, int K,
;                                            const Epi& epi, bf16_t* shm, int w0) {
;     ...
;       LDA(At, 0, 1); WAIT_V(4); BAR; WAIT_L(0); MMA(1, 0, At, B0); MMA(1, 1, At, B1); BAR; }
	s_barrier
	s_nop 0
	ds_read_b128 v[78:81], v241 offset:16384
	ds_read_b128 v[82:85], v241 offset:17408
	ds_read_b128 v[86:89], v241 offset:18432
	ds_read_b128 v[94:97], v241 offset:19456
	ds_read_b128 v[162:165], v241 offset:20480
	ds_read_b128 v[166:169], v241 offset:21504
	ds_read_b128 v[170:173], v241 offset:22528
	ds_read_b128 v[174:177], v241 offset:23552
	s_waitcnt vmcnt(4)
	s_barrier
	s_waitcnt lgkmcnt(0)

; #define LDA(dst, b, h) for (int m = 0; m < 4; ++m) for (int k = 0; k < 2; ++k) \
;     dst[m][k] = *reinterpret_cast<const bf16x8*>((char*)SA(b, h) + a_thr + (m * 2 + k) * 1024)
; #define MMA(ai, bj, At, Btf) do { __builtin_amdgcn_s_setprio(1); \
;     for (int m = 0; m < 4; ++m) for (int n = 0; n < 2; ++n) for (int k = 0; k < 2; ++k) \
;       acc[ai][bj][m][n] = __builtin_amdgcn_mfma_f32_16x16x32_bf16(Btf[n][k], At[m][k], acc[ai][bj][m][n], 0, 0, 0); \
;     __builtin_amdgcn_s_setprio(0); } while (0)
; #define WAIT_V(n) asm volatile("s_waitcnt vmcnt(" #n ")" ::: "memory")
; #define WAIT_L(n) asm volatile("s_waitcnt lgkmcnt(" #n ")" ::: "memory")
; #define BAR __builtin_amdgcn_s_barrier()
; template <bool OVL, bool PANEL = false, class Epi>
; __device__ __forceinline__ void gemm_phase(const bf16_t* __restrict__ A, long lda, const bf16_t* __restrict__ Bt, long ldb, int nM, int nN, int K,
;                                            const Epi& epi, bf16_t* shm, int w0) {
;     ...
;       LDA(At, 0, 1); WAIT_V(4); BAR; WAIT_L(0); MMA(1, 0, At, B0); MMA(1, 1, At, B1); BAR; }
	s_waitcnt lgkmcnt(0)
	v_mfma_f32_16x16x32_bf16 v[62:65], v[130:133], v[78:81], v[62:65]
	v_mfma_f32_16x16x32_bf16 v[58:61], v[142:145], v[78:81], v[58:61]
	v_mfma_f32_16x16x32_bf16 v[54:57], v[130:133], v[86:89], v[54:57]
	v_mfma_f32_16x16x32_bf16 v[50:53], v[142:145], v[86:89], v[50:53]
	v_mfma_f32_16x16x32_bf16 v[46:49], v[130:133], v[162:165], v[46:49]
	v_mfma_f32_16x16x32_bf16 v[42:45], v[142:145], v[162:165], v[42:45]
	v_mfma_f32_16x16x32_bf16 v[34:37], v[142:145], v[170:173], v[34:37]
	v_mfma_f32_16x16x32_bf16 v[62:65], v[138:141], v[82:85], v[62:65]
	v_mfma_f32_16x16x32_bf16 v[58:61], v[146:149], v[82:85], v[58:61]
	v_mfma_f32_16x16x32_bf16 v[54:57], v[138:141], v[94:97], v[54:57]
	v_mfma_f32_16x16x32_bf16 v[50:53], v[146:149], v[94:97], v[50:53]
	v_mfma_f32_16x16x32_bf16 v[46:49], v[138:141], v[166:169], v[46:49]
	v_mfma_f32_16x16x32_bf16 v[42:45], v[146:149], v[166:169], v[42:45]
	v_mfma_f32_16x16x32_bf16 v[38:41], v[130:133], v[170:173], v[38:41]
	v_mfma_f32_16x16x32_bf16 v[34:37], v[146:149], v[174:177], v[34:37]
	v_mfma_f32_16x16x32_bf16 v[130:133], v[138:141], v[174:177], v[38:41]


; #define LDA(dst, b, h) for (int m = 0; m < 4; ++m) for (int k = 0; k < 2; ++k) \
;     dst[m][k] = *reinterpret_cast<const bf16x8*>((char*)SA(b, h) + a_thr + (m * 2 + k) * 1024)
; #define MMA(ai, bj, At, Btf) do { __builtin_amdgcn_s_setprio(1); \
;     for (int m = 0; m < 4; ++m) for (int n = 0; n < 2; ++n) for (int k = 0; k < 2; ++k) \
;       acc[ai][bj][m][n] = __builtin_amdgcn_mfma_f32_16x16x32_bf16(Btf[n][k], At[m][k], acc[ai][bj][m][n], 0, 0, 0); \
;     __builtin_amdgcn_s_setprio(0); } while (0)
; #define WAIT_V(n) asm volatile("s_waitcnt vmcnt(" #n ")" ::: "memory")
; #define WAIT_L(n) asm volatile("s_waitcnt lgkmcnt(" #n ")" ::: "memory")
; #define BAR __builtin_amdgcn_s_barrier()
; template <bool OVL, bool PANEL = false, class Epi>
; __device__ __forceinline__ void gemm_phase(const bf16_t* __restrict__ A, long lda, const bf16_t* __restrict__ Bt, long ldb, int nM, int nN, int K,
;                                            const Epi& epi, bf16_t* shm, int w0) {
;     ...
;       LDA(At, 0, 1); WAIT_V(4); BAR; WAIT_L(0); MMA(1, 0, At, B0); MMA(1, 1, At, B1); BAR; }
	v_mfma_f32_16x16x32_bf16 v[30:33], v[110:113], v[78:81], v[30:33]
	v_mfma_f32_16x16x32_bf16 v[26:29], v[186:189], v[78:81], v[26:29]
	v_mfma_f32_16x16x32_bf16 v[22:25], v[110:113], v[86:89], v[22:25]
	v_mfma_f32_16x16x32_bf16 v[18:21], v[186:189], v[86:89], v[18:21]
	v_mfma_f32_16x16x32_bf16 v[14:17], v[110:113], v[162:165], v[14:17]
	v_mfma_f32_16x16x32_bf16 v[10:13], v[186:189], v[162:165], v[10:13]
	v_mfma_f32_16x16x32_bf16 v[6:9], v[110:113], v[170:173], v[6:9]
	v_mfma_f32_16x16x32_bf16 v[2:5], v[186:189], v[170:173], v[2:5]
	v_mfma_f32_16x16x32_bf16 v[138:141], v[182:185], v[82:85], v[30:33]
	v_mfma_f32_16x16x32_bf16 v[142:145], v[190:193], v[82:85], v[26:29]
	v_mfma_f32_16x16x32_bf16 v[146:149], v[182:185], v[94:97], v[22:25]
	v_mfma_f32_16x16x32_bf16 v[178:181], v[190:193], v[94:97], v[18:21]
	v_mfma_f32_16x16x32_bf16 v[198:201], v[182:185], v[166:169], v[14:17]
	v_mfma_f32_16x16x32_bf16 v[162:165], v[190:193], v[166:169], v[10:13]
	v_mfma_f32_16x16x32_bf16 v[166:169], v[182:185], v[174:177], v[6:9]
	v_mfma_f32_16x16x32_bf16 v[170:173], v[190:193], v[174:177], v[2:5]

; #define LDA(dst, b, h) for (int m = 0; m < 4; ++m) for (int k = 0; k < 2; ++k) \
;     dst[m][k] = *reinterpret_cast<const bf16x8*>((char*)SA(b, h) + a_thr + (m * 2 + k) * 1024)
; #define LDB(dst, b, h) for (int n = 0; n < 2; ++n) for (int k = 0; k < 2; ++k) \
;     dst[n][k] = *reinterpret_cast<const bf16x8*>((char*)SB(b, h) + b_thr + (n * 2 + k) * 1024)
; #define MMA(ai, bj, At, Btf) do { __builtin_amdgcn_s_setprio(1); \
;     for (int m = 0; m < 4; ++m) for (int n = 0; n < 2; ++n) for (int k = 0; k < 2; ++k) \
;       acc[ai][bj][m][n] = __builtin_amdgcn_mfma_f32_16x16x32_bf16(Btf[n][k], At[m][k], acc[ai][bj][m][n], 0, 0, 0); \
;     __builtin_amdgcn_s_setprio(0); } while (0)
; #define WAIT_V(n) asm volatile("s_waitcnt vmcnt(" #n ")" ::: "memory")
; #define WAIT_L(n) asm volatile("s_waitcnt lgkmcnt(" #n ")" ::: "memory")
; #define BAR __builtin_amdgcn_s_barrier()
; template <bool OVL, bool PANEL = false, class Epi>
; __device__ __forceinline__ void gemm_phase(const bf16_t* __restrict__ A, long lda, const bf16_t* __restrict__ Bt, long ldb, int nM, int nN, int K,
;                                            const Epi& epi, bf16_t* shm, int w0) {
;     ...
;     { LDB(B0, 1, 0); LDA(At, 1, 0); WAIT_V(2); BAR; WAIT_L(0); MMA(0, 0, At, B0); BAR;
	v_add_u32_e32 v0, 0x18000, v206
	s_barrier
	ds_read_b128 v[174:177], v0
	ds_read_b128 v[182:185], v0 offset:1024
	ds_read_b128 v[186:189], v0 offset:2048
	ds_read_b128 v[190:193], v0 offset:3072
	ds_read_b128 v[6:9], v241 offset:32768
	ds_read_b128 v[14:17], v241 offset:33792
	ds_read_b128 v[18:21], v241 offset:34816
	ds_read_b128 v[22:25], v241 offset:35840
	ds_read_b128 v[26:29], v241 offset:36864
	ds_read_b128 v[30:33], v241 offset:37888
	ds_read_b128 v[38:41], v241 offset:38912
	ds_read_b128 v[202:205], v241 offset:39936
	s_waitcnt vmcnt(2)
	s_barrier
	s_waitcnt lgkmcnt(0)

; #define LDA(dst, b, h) for (int m = 0; m < 4; ++m) for (int k = 0; k < 2; ++k) \
;     dst[m][k] = *reinterpret_cast<const bf16x8*>((char*)SA(b, h) + a_thr + (m * 2 + k) * 1024)
; #define LDB(dst, b, h) for (int n = 0; n < 2; ++n) for (int k = 0; k < 2; ++k) \
;     dst[n][k] = *reinterpret_cast<const bf16x8*>((char*)SB(b, h) + b_thr + (n * 2 + k) * 1024)
; #define MMA(ai, bj, At, Btf) do { __builtin_amdgcn_s_setprio(1); \
;     for (int m = 0; m < 4; ++m) for (int n = 0; n < 2; ++n) for (int k = 0; k < 2; ++k) \
;       acc[ai][bj][m][n] = __builtin_amdgcn_mfma_f32_16x16x32_bf16(Btf[n][k], At[m][k], acc[ai][bj][m][n], 0, 0, 0); \
;     __builtin_amdgcn_s_setprio(0); } while (0)
; #define WAIT_V(n) asm volatile("s_waitcnt vmcnt(" #n ")" ::: "memory")
; #define WAIT_L(n) asm volatile("s_waitcnt lgkmcnt(" #n ")" ::: "memory")
; #define BAR __builtin_amdgcn_s_barrier()
; template <bool OVL, bool PANEL = false, class Epi>
; __device__ __forceinline__ void gemm_phase(const bf16_t* __restrict__ A, long lda, const bf16_t* __restrict__ Bt, long ldb, int nM, int nN, int K,
;                                            const Epi& epi, bf16_t* shm, int w0) {
;     ...
;     { LDB(B0, 1, 0); LDA(At, 1, 0); WAIT_V(2); BAR; WAIT_L(0); MMA(0, 0, At, B0); BAR;
	s_waitcnt lgkmcnt(0)
	v_mfma_f32_16x16x32_bf16 v[2:5], v[174:177], v[6:9], v[126:129]
	v_mfma_f32_16x16x32_bf16 v[126:129], v[182:185], v[14:17], v[2:5]
	v_mfma_f32_16x16x32_bf16 v[2:5], v[186:189], v[6:9], v[122:125]
	v_mfma_f32_16x16x32_bf16 v[82:85], v[190:193], v[14:17], v[2:5]
	v_mfma_f32_16x16x32_bf16 v[2:5], v[174:177], v[18:21], v[118:121]
	v_mfma_f32_16x16x32_bf16 v[110:113], v[182:185], v[22:25], v[2:5]
	v_mfma_f32_16x16x32_bf16 v[2:5], v[186:189], v[18:21], v[114:117]
	v_mfma_f32_16x16x32_bf16 v[86:89], v[190:193], v[22:25], v[2:5]
	v_mfma_f32_16x16x32_bf16 v[2:5], v[174:177], v[26:29], v[134:137]
	v_mfma_f32_16x16x32_bf16 v[94:97], v[182:185], v[30:33], v[2:5]
	v_mfma_f32_16x16x32_bf16 v[2:5], v[186:189], v[26:29], v[106:109]
	v_mfma_f32_16x16x32_bf16 v[78:81], v[190:193], v[30:33], v[2:5]
	v_mfma_f32_16x16x32_bf16 v[2:5], v[174:177], v[38:41], v[102:105]
	v_mfma_f32_16x16x32_bf16 v[10:13], v[186:189], v[38:41], v[98:101]
	v_mfma_f32_16x16x32_bf16 v[2:5], v[182:185], v[202:205], v[2:5]
	v_mfma_f32_16x16x32_bf16 v[10:13], v[190:193], v[202:205], v[10:13]

; #define LDB(dst, b, h) for (int n = 0; n < 2; ++n) for (int k = 0; k < 2; ++k) \
;     dst[n][k] = *reinterpret_cast<const bf16x8*>((char*)SB(b, h) + b_thr + (n * 2 + k) * 1024)
; #define MMA(ai, bj, At, Btf) do { __builtin_amdgcn_s_setprio(1); \
;     for (int m = 0; m < 4; ++m) for (int n = 0; n < 2; ++n) for (int k = 0; k < 2; ++k) \
;       acc[ai][bj][m][n] = __builtin_amdgcn_mfma_f32_16x16x32_bf16(Btf[n][k], At[m][k], acc[ai][bj][m][n], 0, 0, 0); \
;     __builtin_amdgcn_s_setprio(0); } while (0)
; #define WAIT_V(n) asm volatile("s_waitcnt vmcnt(" #n ")" ::: "memory")
; #define WAIT_L(n) asm volatile("s_waitcnt lgkmcnt(" #n ")" ::: "memory")
; #define BAR __builtin_amdgcn_s_barrier()
; template <bool OVL, bool PANEL = false, class Epi>
; __device__ __forceinline__ void gemm_phase(const bf16_t* __restrict__ A, long lda, const bf16_t* __restrict__ Bt, long ldb, int nM, int nN, int K,
;                                            const Epi& epi, bf16_t* shm, int w0) {
;     ...
;       LDB(B1, 1, 1); WAIT_V(0); BAR; WAIT_L(0); MMA(0, 1, At, B1); BAR;
	v_add_u32_e32 v0, 0x1c000, v206
	s_barrier
	ds_read_b128 v[122:125], v0
	ds_read_b128 v[134:137], v0 offset:1024
	ds_read_b128 v[206:209], v0 offset:2048
	ds_read_b128 v[210:213], v0 offset:3072
	s_waitcnt vmcnt(0)
	s_barrier
	s_waitcnt lgkmcnt(0)

; #define LDB(dst, b, h) for (int n = 0; n < 2; ++n) for (int k = 0; k < 2; ++k) \
;     dst[n][k] = *reinterpret_cast<const bf16x8*>((char*)SB(b, h) + b_thr + (n * 2 + k) * 1024)
; #define MMA(ai, bj, At, Btf) do { __builtin_amdgcn_s_setprio(1); \
;     for (int m = 0; m < 4; ++m) for (int n = 0; n < 2; ++n) for (int k = 0; k < 2; ++k) \
;       acc[ai][bj][m][n] = __builtin_amdgcn_mfma_f32_16x16x32_bf16(Btf[n][k], At[m][k], acc[ai][bj][m][n], 0, 0, 0); \
;     __builtin_amdgcn_s_setprio(0); } while (0)
; #define WAIT_V(n) asm volatile("s_waitcnt vmcnt(" #n ")" ::: "memory")
; #define WAIT_L(n) asm volatile("s_waitcnt lgkmcnt(" #n ")" ::: "memory")
; #define BAR __builtin_amdgcn_s_barrier()
; template <bool OVL, bool PANEL = false, class Epi>
; __device__ __forceinline__ void gemm_phase(const bf16_t* __restrict__ A, long lda, const bf16_t* __restrict__ Bt, long ldb, int nM, int nN, int K,
;                                            const Epi& epi, bf16_t* shm, int w0) {
;     ...
;       LDB(B1, 1, 1); WAIT_V(0); BAR; WAIT_L(0); MMA(0, 1, At, B1); BAR;
	s_waitcnt lgkmcnt(0)
	v_mfma_f32_16x16x32_bf16 v[98:101], v[122:125], v[6:9], v[194:197]
	v_mfma_f32_16x16x32_bf16 v[6:9], v[206:209], v[6:9], v[90:93]
	v_mfma_f32_16x16x32_bf16 v[114:117], v[210:213], v[14:17], v[6:9]
	v_mfma_f32_16x16x32_bf16 v[6:9], v[122:125], v[18:21], v[150:153]
	v_mfma_f32_16x16x32_bf16 v[102:105], v[134:137], v[22:25], v[6:9]
	v_mfma_f32_16x16x32_bf16 v[6:9], v[206:209], v[18:21], v[154:157]
	v_mfma_f32_16x16x32_bf16 v[118:121], v[210:213], v[22:25], v[6:9]
	v_mfma_f32_16x16x32_bf16 v[6:9], v[122:125], v[26:29], v[158:161]
	v_mfma_f32_16x16x32_bf16 v[90:93], v[134:137], v[30:33], v[6:9]
	v_mfma_f32_16x16x32_bf16 v[6:9], v[206:209], v[26:29], v[74:77]
	v_mfma_f32_16x16x32_bf16 v[106:109], v[210:213], v[30:33], v[6:9]
	v_mfma_f32_16x16x32_bf16 v[6:9], v[122:125], v[38:41], v[70:73]
	v_mfma_f32_16x16x32_bf16 v[22:25], v[134:137], v[202:205], v[6:9]
	v_mfma_f32_16x16x32_bf16 v[6:9], v[206:209], v[38:41], v[66:69]
	v_mfma_f32_16x16x32_bf16 v[98:101], v[134:137], v[14:17], v[98:101]
	v_mfma_f32_16x16x32_bf16 v[38:41], v[210:213], v[202:205], v[6:9]

; #define LDA(dst, b, h) for (int m = 0; m < 4; ++m) for (int k = 0; k < 2; ++k) \
;     dst[m][k] = *reinterpret_cast<const bf16x8*>((char*)SA(b, h) + a_thr + (m * 2 + k) * 1024)
; #define MMA(ai, bj, At, Btf) do { __builtin_amdgcn_s_setprio(1); \
;     for (int m = 0; m < 4; ++m) for (int n = 0; n < 2; ++n) for (int k = 0; k < 2; ++k) \
;       acc[ai][bj][m][n] = __builtin_amdgcn_mfma_f32_16x16x32_bf16(Btf[n][k], At[m][k], acc[ai][bj][m][n], 0, 0, 0); \
;     __builtin_amdgcn_s_setprio(0); } while (0)
; #define WAIT_L(n) asm volatile("s_waitcnt lgkmcnt(" #n ")" ::: "memory")
; #define BAR __builtin_amdgcn_s_barrier()
; template <bool OVL, bool PANEL = false, class Epi>
; __device__ __forceinline__ void gemm_phase(const bf16_t* __restrict__ A, long lda, const bf16_t* __restrict__ Bt, long ldb, int nM, int nN, int K,
;                                            const Epi& epi, bf16_t* shm, int w0) {
;     ...
;       LDA(At, 1, 1); BAR; WAIT_L(0); MMA(1, 0, At, B0); MMA(1, 1, At, B1); BAR; }
	s_barrier
	ds_read_b128 v[70:73], v241 offset:49152
	ds_read_b128 v[74:77], v241 offset:50176
	ds_read_b128 v[150:153], v241 offset:51200
	ds_read_b128 v[154:157], v241 offset:52224
	ds_read_b128 v[158:161], v241 offset:53248
	ds_read_b128 v[194:197], v241 offset:54272
	ds_read_b128 v[202:205], v241 offset:55296
	ds_read_b128 v[214:217], v241 offset:56320
	s_barrier
	s_waitcnt lgkmcnt(0)

; #define LDA(dst, b, h) for (int m = 0; m < 4; ++m) for (int k = 0; k < 2; ++k) \
;     dst[m][k] = *reinterpret_cast<const bf16x8*>((char*)SA(b, h) + a_thr + (m * 2 + k) * 1024)
; #define MMA(ai, bj, At, Btf) do { __builtin_amdgcn_s_setprio(1); \
;     for (int m = 0; m < 4; ++m) for (int n = 0; n < 2; ++n) for (int k = 0; k < 2; ++k) \
;       acc[ai][bj][m][n] = __builtin_amdgcn_mfma_f32_16x16x32_bf16(Btf[n][k], At[m][k], acc[ai][bj][m][n], 0, 0, 0); \
;     __builtin_amdgcn_s_setprio(0); } while (0)
; #define WAIT_L(n) asm volatile("s_waitcnt lgkmcnt(" #n ")" ::: "memory")
; #define BAR __builtin_amdgcn_s_barrier()
; template <bool OVL, bool PANEL = false, class Epi>
; __device__ __forceinline__ void gemm_phase(const bf16_t* __restrict__ A, long lda, const bf16_t* __restrict__ Bt, long ldb, int nM, int nN, int K,
;                                            const Epi& epi, bf16_t* shm, int w0) {
;     ...
;       LDA(At, 1, 1); BAR; WAIT_L(0); MMA(1, 0, At, B0); MMA(1, 1, At, B1); BAR; }
	s_waitcnt lgkmcnt(0)
	v_mfma_f32_16x16x32_bf16 v[14:17], v[186:189], v[70:73], v[58:61]
	v_mfma_f32_16x16x32_bf16 v[42:45], v[186:189], v[158:161], v[42:45]
	v_mfma_f32_16x16x32_bf16 v[6:9], v[174:177], v[70:73], v[62:65]
	v_mfma_f32_16x16x32_bf16 v[18:21], v[190:193], v[74:77], v[14:17]
	v_mfma_f32_16x16x32_bf16 v[14:17], v[174:177], v[150:153], v[54:57]
	v_mfma_f32_16x16x32_bf16 v[26:29], v[186:189], v[150:153], v[50:53]
	v_mfma_f32_16x16x32_bf16 v[30:33], v[174:177], v[158:161], v[46:49]
	v_mfma_f32_16x16x32_bf16 v[46:49], v[190:193], v[194:197], v[42:45]
	v_mfma_f32_16x16x32_bf16 v[42:45], v[174:177], v[202:205], v[130:133]
	v_mfma_f32_16x16x32_bf16 v[34:37], v[186:189], v[202:205], v[34:37]
	v_mfma_f32_16x16x32_bf16 v[6:9], v[182:185], v[74:77], v[6:9]
	v_mfma_f32_16x16x32_bf16 v[14:17], v[182:185], v[154:157], v[14:17]
	v_mfma_f32_16x16x32_bf16 v[26:29], v[190:193], v[154:157], v[26:29]
	v_mfma_f32_16x16x32_bf16 v[30:33], v[182:185], v[194:197], v[30:33]
	v_mfma_f32_16x16x32_bf16 v[54:57], v[182:185], v[214:217], v[42:45]
	v_mfma_f32_16x16x32_bf16 v[66:69], v[190:193], v[214:217], v[34:37]


; #define LDA(dst, b, h) for (int m = 0; m < 4; ++m) for (int k = 0; k < 2; ++k) \
;     dst[m][k] = *reinterpret_cast<const bf16x8*>((char*)SA(b, h) + a_thr + (m * 2 + k) * 1024)
; #define MMA(ai, bj, At, Btf) do { __builtin_amdgcn_s_setprio(1); \
;     for (int m = 0; m < 4; ++m) for (int n = 0; n < 2; ++n) for (int k = 0; k < 2; ++k) \
;       acc[ai][bj][m][n] = __builtin_amdgcn_mfma_f32_16x16x32_bf16(Btf[n][k], At[m][k], acc[ai][bj][m][n], 0, 0, 0); \
;     __builtin_amdgcn_s_setprio(0); } while (0)
; #define WAIT_L(n) asm volatile("s_waitcnt lgkmcnt(" #n ")" ::: "memory")
; #define BAR __builtin_amdgcn_s_barrier()
; template <bool OVL, bool PANEL = false, class Epi>
; __device__ __forceinline__ void gemm_phase(const bf16_t* __restrict__ A, long lda, const bf16_t* __restrict__ Bt, long ldb, int nM, int nN, int K,
;                                            const Epi& epi, bf16_t* shm, int w0) {
;     ...
;       LDA(At, 1, 1); BAR; WAIT_L(0); MMA(1, 0, At, B0); MMA(1, 1, At, B1); BAR; }
	v_mfma_f32_16x16x32_bf16 v[34:37], v[122:125], v[70:73], v[138:141]
	v_mfma_f32_16x16x32_bf16 v[42:45], v[206:209], v[70:73], v[142:145]
	v_mfma_f32_16x16x32_bf16 v[34:37], v[134:137], v[74:77], v[34:37]
	v_mfma_f32_16x16x32_bf16 v[50:53], v[210:213], v[74:77], v[42:45]
	v_mfma_f32_16x16x32_bf16 v[42:45], v[122:125], v[150:153], v[146:149]
	v_mfma_f32_16x16x32_bf16 v[58:61], v[206:209], v[150:153], v[178:181]
	v_mfma_f32_16x16x32_bf16 v[62:65], v[122:125], v[158:161], v[198:201]
	v_mfma_f32_16x16x32_bf16 v[70:73], v[206:209], v[158:161], v[162:165]
	v_mfma_f32_16x16x32_bf16 v[74:77], v[122:125], v[202:205], v[166:169]
	v_mfma_f32_16x16x32_bf16 v[122:125], v[206:209], v[202:205], v[170:173]
	v_mfma_f32_16x16x32_bf16 v[42:45], v[134:137], v[154:157], v[42:45]
	v_mfma_f32_16x16x32_bf16 v[58:61], v[210:213], v[154:157], v[58:61]
	v_mfma_f32_16x16x32_bf16 v[62:65], v[134:137], v[194:197], v[62:65]
	v_mfma_f32_16x16x32_bf16 v[70:73], v[210:213], v[194:197], v[70:73]
	v_mfma_f32_16x16x32_bf16 v[74:77], v[134:137], v[214:217], v[74:77]
	v_mfma_f32_16x16x32_bf16 v[122:125], v[210:213], v[214:217], v[122:125]

; #define LDA(dst, b, h) for (int m = 0; m < 4; ++m) for (int k = 0; k < 2; ++k) \
;     dst[m][k] = *reinterpret_cast<const bf16x8*>((char*)SA(b, h) + a_thr + (m * 2 + k) * 1024)
; #define MMA(ai, bj, At, Btf) do { __builtin_amdgcn_s_setprio(1); \
;     for (int m = 0; m < 4; ++m) for (int n = 0; n < 2; ++n) for (int k = 0; k < 2; ++k) \
;       acc[ai][bj][m][n] = __builtin_amdgcn_mfma_f32_16x16x32_bf16(Btf[n][k], At[m][k], acc[ai][bj][m][n], 0, 0, 0); \
;     __builtin_amdgcn_s_setprio(0); } while (0)
; #define WAIT_L(n) asm volatile("s_waitcnt lgkmcnt(" #n ")" ::: "memory")
; #define BAR __builtin_amdgcn_s_barrier()
; template <bool OVL, bool PANEL = false, class Epi>
; __device__ __forceinline__ void gemm_phase(const bf16_t* __restrict__ A, long lda, const bf16_t* __restrict__ Bt, long ldb, int nM, int nN, int K,
;                                            const Epi& epi, bf16_t* shm, int w0) {
;     ...
;       LDA(At, 1, 1); BAR; WAIT_L(0); MMA(1, 0, At, B0); MMA(1, 1, At, B1); BAR; }
;     if (wr == 0) BAR;
	s_barrier
	s_and_saveexec_b64 s[0:1], s[90:91]
	s_cbranch_execz .LBB0_475
	s_barrier

; #define LDA(dst, b, h) for (int m = 0; m < 4; ++m) for (int k = 0; k < 2; ++k) \
;     dst[m][k] = *reinterpret_cast<const bf16x8*>((char*)SA(b, h) + a_thr + (m * 2 + k) * 1024)
; #define LDB(dst, b, h) for (int n = 0; n < 2; ++n) for (int k = 0; k < 2; ++k) \
;     dst[n][k] = *reinterpret_cast<const bf16x8*>((char*)SB(b, h) + b_thr + (n * 2 + k) * 1024)
; #define MMA(ai, bj, At, Btf) do { __builtin_amdgcn_s_setprio(1); \
;     for (int m = 0; m < 4; ++m) for (int n = 0; n < 2; ++n) for (int k = 0; k < 2; ++k) \
;       acc[ai][bj][m][n] = __builtin_amdgcn_mfma_f32_16x16x32_bf16(Btf[n][k], At[m][k], acc[ai][bj][m][n], 0, 0, 0); \
;     __builtin_amdgcn_s_setprio(0); } while (0)
; #define WAIT_V(n) asm volatile("s_waitcnt vmcnt(" #n ")" ::: "memory")
; #define WAIT_L(n) asm volatile("s_waitcnt lgkmcnt(" #n ")" ::: "memory")
; #define BAR __builtin_amdgcn_s_barrier()
; #define SCHED __builtin_amdgcn_sched_barrier(0)
; template <bool OVL, bool PANEL = false, class Epi>
; __device__ __forceinline__ void gemm_phase(const bf16_t* __restrict__ A, long lda, const bf16_t* __restrict__ Bt, long ldb, int nM, int nN, int K,
;                                            const Epi& epi, bf16_t* shm, int w0) {
;     ...
;     if (wr == 1) BAR;
;     WAIT_V(4); BAR;
;     STAGE(SB(1, 0), Bt, ldb, boff, bcol, 1); STAGE(SA(1, 0), A, lda, aoff, brow, 1); STAGE(SB(1, 1), Bt, ldb, boff, bcol + HALF, 1);
;     WAIT_V(6); BAR;
;     for (int t = 0; t < nt - 2; t += 2) {
;       LDB(B0, 0, 0); SCHED; LDA(At, 0, 0); STAGE(SA(1, 1), A, lda, aoff, brow + HALF, t + 1);
;       WAIT_L(8); BAR; WAIT_L(0); MMA(0, 0, At, B0); BAR; SCHED;
.LBB0_1052:
	s_or_b64 exec, exec, s[0:1]
	s_lshl_b32 s12, s57, 8
	s_ashr_i32 s13, s12, 31
	v_readlane_b32 s16, v252, 3
	s_lshl_b32 s0, s58, 8
	s_lshl_b64 s[8:9], s[12:13], 11
	v_readlane_b32 s22, v252, 9
	v_readlane_b32 s23, v252, 10
	s_add_u32 s8, s22, s8
	v_readlane_b32 s17, v252, 4
	s_addc_u32 s9, s23, s9
	v_mov_b32_e32 v0, v135
	v_add_u32_e32 v130, s96, v134
	s_waitcnt vmcnt(4)
	s_barrier
	s_mov_b64 s[16:17], 0x80
	v_lshl_add_u64 v[2:3], s[8:9], 0, v[0:1]
	v_readfirstlane_b32 s1, v130
	v_add_u32_e32 v131, 0x2000, v130
	v_lshl_add_u64 v[4:5], v[2:3], 0, s[16:17]
	s_mov_b32 m0, s1
	v_readfirstlane_b32 s1, v131
	global_load_lds_dwordx4 v[4:5], off
	s_mov_b32 m0, s1
	s_ashr_i32 s1, s0, 31
	v_readlane_b32 s40, v252, 20
	s_lshl_b64 s[10:11], s[0:1], 11
	v_readlane_b32 s46, v252, 26
	v_readlane_b32 s18, v252, 5
	v_readlane_b32 s19, v252, 6
	v_readlane_b32 s47, v252, 27
	s_add_u32 s10, s46, s10
	s_mov_b64 s[18:19], 0x20080
	s_addc_u32 s11, s47, s11
	s_or_b32 s14, s12, 0x80
	v_lshl_add_u64 v[2:3], v[2:3], 0, s[18:19]
	v_mov_b32_e32 v0, v135
	v_add_u32_e32 v132, 0x8000, v138
	s_ashr_i32 s15, s14, 31
	global_load_lds_dwordx4 v[2:3], off
	v_readfirstlane_b32 s1, v132
	v_lshl_add_u64 v[2:3], s[10:11], 0, v[0:1]
	v_add_u32_e32 v133, 0xa000, v138
	s_lshl_b64 s[14:15], s[14:15], 11
	v_lshl_add_u64 v[4:5], v[2:3], 0, s[16:17]
	s_mov_b32 m0, s1
	v_readfirstlane_b32 s1, v133
	s_add_u32 s14, s22, s14
	global_load_lds_dwordx4 v[4:5], off
	v_lshl_add_u64 v[2:3], v[2:3], 0, s[18:19]
	s_mov_b32 m0, s1
	s_addc_u32 s15, s23, s15
	v_mov_b32_e32 v0, v135
	v_add_u32_e32 v148, s75, v134
	global_load_lds_dwordx4 v[2:3], off
	v_readfirstlane_b32 s1, v148
	v_lshl_add_u64 v[2:3], s[14:15], 0, v[0:1]
	v_add_u32_e32 v149, 0x2000, v148
	v_lshl_add_u64 v[4:5], v[2:3], 0, s[16:17]
	s_mov_b32 m0, s1
	v_readfirstlane_b32 s1, v149
	global_load_lds_dwordx4 v[4:5], off
	v_lshl_add_u64 v[2:3], v[2:3], 0, s[18:19]
	s_mov_b32 m0, s1
	v_readlane_b32 s20, v252, 7
	global_load_lds_dwordx4 v[2:3], off
	s_waitcnt vmcnt(6)
	v_readlane_b32 s21, v252, 8
	s_mov_b32 s1, -2
	s_mov_b64 s[14:15], 0
	s_waitcnt lgkmcnt(0)
	s_mov_b64 s[16:17], 0x40080
	s_mov_b64 s[18:19], 0x40180
	s_mov_b64 s[20:21], 0x60180
	v_readlane_b32 s24, v252, 11
	v_readlane_b32 s25, v252, 12
	v_readlane_b32 s26, v252, 13
	v_readlane_b32 s27, v252, 14
	v_readlane_b32 s28, v252, 15
	v_readlane_b32 s29, v252, 16
	v_readlane_b32 s30, v252, 17
	v_readlane_b32 s31, v252, 18
	v_readlane_b32 s41, v252, 21
	v_readlane_b32 s42, v252, 22
	v_readlane_b32 s43, v252, 23
	v_readlane_b32 s44, v252, 24
	v_readlane_b32 s45, v252, 25
	v_readlane_b32 s48, v252, 28
	v_readlane_b32 s49, v252, 29
	v_readlane_b32 s50, v252, 30
	v_readlane_b32 s51, v252, 31
	v_readlane_b32 s52, v252, 32
	v_readlane_b32 s53, v252, 33
	v_readlane_b32 s54, v252, 34
	v_readlane_b32 s55, v252, 35
	s_barrier
	v_add_u32_e32 v184, s2, v144
	v_readfirstlane_b32 s22, v138
	s_add_u32 s22, s22, 0xc000
	v_readfirstlane_b32 s23, v138
	s_add_u32 s23, s23, 0xe000
	v_add_u32_e32 v185, s33, v144
	v_readfirstlane_b32 s24, v136
	v_readfirstlane_b32 s25, v137
	v_readfirstlane_b32 s26, v138
	v_readfirstlane_b32 s27, v139
	v_readfirstlane_b32 s28, v140
	v_readfirstlane_b32 s29, v141
	v_add_u32_e32 v186, s96, v144
	v_readfirstlane_b32 s30, v142
	v_readfirstlane_b32 s31, v143
	v_add_u32_e32 v187, s75, v144
	v_readfirstlane_b32 s32, v130
	v_readfirstlane_b32 s44, v131
	v_readfirstlane_b32 s45, v132
	v_readfirstlane_b32 s46, v133
	v_readfirstlane_b32 s47, v148
	v_readfirstlane_b32 s48, v149
	v_add_u32_e32 v150, 0xc000, v138
	v_add_u32_e32 v151, 0xe000, v138
	ds_read_b128 v[152:155], v184
	ds_read_b128 v[156:159], v184 offset:1024
	ds_read_b128 v[160:163], v184 offset:2048
	ds_read_b128 v[164:167], v184 offset:3072
	s_add_u32 s40, s10, s14
	s_addc_u32 s41, s11, s15
	ds_read_b128 v[168:171], v147
	ds_read_b128 v[172:175], v147 offset:1024
	ds_read_b128 v[176:179], v147 offset:2048
	ds_read_b128 v[194:197], v147 offset:3072
	ds_read_b128 v[198:201], v147 offset:4096
	ds_read_b128 v[202:205], v147 offset:5120
	ds_read_b128 v[206:209], v147 offset:6144
	ds_read_b128 v[210:213], v147 offset:7168
	s_mov_b32 m0, s22
	s_add_u32 s98, s40, s16
	s_addc_u32 s99, s41, s17
	global_load_lds_dwordx4 v135, s[98:99]
	s_mov_b32 m0, s23
	s_add_u32 s98, s40, s36
	s_addc_u32 s99, s41, s37
	global_load_lds_dwordx4 v135, s[98:99]
	s_waitcnt lgkmcnt(8)
	s_waitcnt vmcnt(10)
	s_barrier
	s_waitcnt lgkmcnt(0)
	v_mfma_f32_16x16x32_bf16 v[126:129], v[152:155], v[168:171], 0
	v_mfma_f32_16x16x32_bf16 v[122:125], v[160:163], v[168:171], 0
	v_mfma_f32_16x16x32_bf16 v[118:121], v[152:155], v[176:179], 0
	v_mfma_f32_16x16x32_bf16 v[114:117], v[160:163], v[176:179], 0
	v_mfma_f32_16x16x32_bf16 v[110:113], v[152:155], v[198:201], 0
	v_mfma_f32_16x16x32_bf16 v[106:109], v[160:163], v[198:201], 0
	v_mfma_f32_16x16x32_bf16 v[102:105], v[152:155], v[206:209], 0
	v_mfma_f32_16x16x32_bf16 v[98:101], v[160:163], v[206:209], 0
	v_mfma_f32_16x16x32_bf16 v[126:129], v[156:159], v[172:175], v[126:129]
	v_mfma_f32_16x16x32_bf16 v[122:125], v[164:167], v[172:175], v[122:125]
	v_mfma_f32_16x16x32_bf16 v[118:121], v[156:159], v[194:197], v[118:121]
	v_mfma_f32_16x16x32_bf16 v[114:117], v[164:167], v[194:197], v[114:117]
	v_mfma_f32_16x16x32_bf16 v[110:113], v[156:159], v[202:205], v[110:113]
	v_mfma_f32_16x16x32_bf16 v[106:109], v[164:167], v[202:205], v[106:109]
	v_mfma_f32_16x16x32_bf16 v[102:105], v[156:159], v[210:213], v[102:105]
	v_mfma_f32_16x16x32_bf16 v[98:101], v[164:167], v[210:213], v[98:101]
	s_barrier
; #define LDA(dst, b, h) for (int m = 0; m < 4; ++m) for (int k = 0; k < 2; ++k) \
;     dst[m][k] = *reinterpret_cast<const bf16x8*>((char*)SA(b, h) + a_thr + (m * 2 + k) * 1024)
; #define LDB(dst, b, h) for (int n = 0; n < 2; ++n) for (int k = 0; k < 2; ++k) \
;     dst[n][k] = *reinterpret_cast<const bf16x8*>((char*)SB(b, h) + b_thr + (n * 2 + k) * 1024)
; #define MMA(ai, bj, At, Btf) do { __builtin_amdgcn_s_setprio(1); \
;     for (int m = 0; m < 4; ++m) for (int n = 0; n < 2; ++n) for (int k = 0; k < 2; ++k) \
;       acc[ai][bj][m][n] = __builtin_amdgcn_mfma_f32_16x16x32_bf16(Btf[n][k], At[m][k], acc[ai][bj][m][n], 0, 0, 0); \
;     __builtin_amdgcn_s_setprio(0); } while (0)
; #define WAIT_V(n) asm volatile("s_waitcnt vmcnt(" #n ")" ::: "memory")
; #define WAIT_L(n) asm volatile("s_waitcnt lgkmcnt(" #n ")" ::: "memory")
; #define BAR __builtin_amdgcn_s_barrier()
; #define SCHED __builtin_amdgcn_sched_barrier(0)
; template <bool OVL, bool PANEL = false, class Epi>
; __device__ __forceinline__ void gemm_phase(const bf16_t* __restrict__ A, long lda, const bf16_t* __restrict__ Bt, long ldb, int nM, int nN, int K,
;                                            const Epi& epi, bf16_t* shm, int w0) {
;     ...
;       LDB(B1, 0, 1); STAGE(SB(0, 0), Bt, ldb, boff, bcol, t + 2);
;       BAR; WAIT_L(0); MMA(0, 1, At, B1); BAR;
;       LDA(At, 0, 1); STAGE(SA(0, 0), A, lda, aoff, brow, t + 2);
;       BAR; WAIT_L(0); MMA(1, 0, At, B0); BAR; SCHED;
;       STAGE(SB(0, 1), Bt, ldb, boff, bcol + HALF, t + 2);
;       WAIT_V(6); BAR; MMA(1, 1, At, B1); BAR;
;       LDB(B0, 1, 0); SCHED; LDA(At, 1, 0); STAGE(SA(0, 1), A, lda, aoff, brow + HALF, t + 2);
;       WAIT_L(8); BAR; WAIT_L(0); MMA(0, 0, At, B0); BAR; SCHED;
	s_add_u32 s42, s8, s14
	ds_read_b128 v[214:217], v185
	ds_read_b128 v[218:221], v185 offset:1024
	ds_read_b128 v[234:237], v185 offset:2048
	ds_read_b128 v[238:241], v185 offset:3072
	s_addc_u32 s43, s9, s15
	s_mov_b32 m0, s24
	s_add_u32 s98, s42, s34
	s_addc_u32 s99, s43, s35
	global_load_lds_dwordx4 v135, s[98:99]
	s_mov_b32 m0, s25
	s_add_u32 s98, s42, s64
	s_addc_u32 s99, s43, s65
	global_load_lds_dwordx4 v135, s[98:99]
	s_waitcnt vmcnt(10)
	s_barrier
	s_waitcnt lgkmcnt(0)
	v_mfma_f32_16x16x32_bf16 v[94:97], v[214:217], v[168:171], 0
	v_mfma_f32_16x16x32_bf16 v[90:93], v[234:237], v[168:171], 0
	v_mfma_f32_16x16x32_bf16 v[86:89], v[214:217], v[176:179], 0
	v_mfma_f32_16x16x32_bf16 v[82:85], v[234:237], v[176:179], 0
	v_mfma_f32_16x16x32_bf16 v[78:81], v[214:217], v[198:201], 0
	v_mfma_f32_16x16x32_bf16 v[74:77], v[234:237], v[198:201], 0
	v_mfma_f32_16x16x32_bf16 v[70:73], v[214:217], v[206:209], 0
	v_mfma_f32_16x16x32_bf16 v[66:69], v[234:237], v[206:209], 0
	v_mfma_f32_16x16x32_bf16 v[94:97], v[218:221], v[172:175], v[94:97]
	v_mfma_f32_16x16x32_bf16 v[90:93], v[238:241], v[172:175], v[90:93]
	v_mfma_f32_16x16x32_bf16 v[86:89], v[218:221], v[194:197], v[86:89]
	v_mfma_f32_16x16x32_bf16 v[82:85], v[238:241], v[194:197], v[82:85]
	v_mfma_f32_16x16x32_bf16 v[78:81], v[218:221], v[202:205], v[78:81]
	v_mfma_f32_16x16x32_bf16 v[74:77], v[238:241], v[202:205], v[74:77]
	v_mfma_f32_16x16x32_bf16 v[70:73], v[218:221], v[210:213], v[70:73]
	v_mfma_f32_16x16x32_bf16 v[66:69], v[238:241], v[210:213], v[66:69]
	s_barrier
	ds_read_b128 v[168:171], v147 offset:16384
	ds_read_b128 v[172:175], v147 offset:17408
	ds_read_b128 v[176:179], v147 offset:18432
	ds_read_b128 v[194:197], v147 offset:19456
	ds_read_b128 v[198:201], v147 offset:20480
	ds_read_b128 v[202:205], v147 offset:21504
	ds_read_b128 v[206:209], v147 offset:22528
	ds_read_b128 v[210:213], v147 offset:23552
	s_mov_b32 m0, s26
	s_add_u32 s98, s40, s34
	s_addc_u32 s99, s41, s35
	global_load_lds_dwordx4 v135, s[98:99]
	s_mov_b32 m0, s27
	s_add_u32 s98, s40, s64
	s_addc_u32 s99, s41, s65
	global_load_lds_dwordx4 v135, s[98:99]
	s_barrier
	s_waitcnt lgkmcnt(0)
	v_mfma_f32_16x16x32_bf16 v[62:65], v[152:155], v[168:171], 0
	v_mfma_f32_16x16x32_bf16 v[58:61], v[160:163], v[168:171], 0
	v_mfma_f32_16x16x32_bf16 v[54:57], v[152:155], v[176:179], 0
	v_mfma_f32_16x16x32_bf16 v[50:53], v[160:163], v[176:179], 0
	v_mfma_f32_16x16x32_bf16 v[46:49], v[152:155], v[198:201], 0
	v_mfma_f32_16x16x32_bf16 v[42:45], v[160:163], v[198:201], 0
	v_mfma_f32_16x16x32_bf16 v[38:41], v[152:155], v[206:209], 0
	v_mfma_f32_16x16x32_bf16 v[34:37], v[160:163], v[206:209], 0
	v_mfma_f32_16x16x32_bf16 v[62:65], v[156:159], v[172:175], v[62:65]
	v_mfma_f32_16x16x32_bf16 v[58:61], v[164:167], v[172:175], v[58:61]
	v_mfma_f32_16x16x32_bf16 v[54:57], v[156:159], v[194:197], v[54:57]
	v_mfma_f32_16x16x32_bf16 v[50:53], v[164:167], v[194:197], v[50:53]
	v_mfma_f32_16x16x32_bf16 v[46:49], v[156:159], v[202:205], v[46:49]
	v_mfma_f32_16x16x32_bf16 v[42:45], v[164:167], v[202:205], v[42:45]
	v_mfma_f32_16x16x32_bf16 v[38:41], v[156:159], v[210:213], v[38:41]
	v_mfma_f32_16x16x32_bf16 v[34:37], v[164:167], v[210:213], v[34:37]
	s_barrier
	s_mov_b32 m0, s28
	s_add_u32 s98, s42, s68
	s_addc_u32 s99, s43, s69
	global_load_lds_dwordx4 v135, s[98:99]
	s_mov_b32 m0, s29
	s_add_u32 s98, s42, s70
	s_addc_u32 s99, s43, s71
	global_load_lds_dwordx4 v135, s[98:99]
	s_waitcnt vmcnt(10)
	s_barrier
	v_mfma_f32_16x16x32_bf16 v[30:33], v[214:217], v[168:171], 0
	v_mfma_f32_16x16x32_bf16 v[26:29], v[234:237], v[168:171], 0
	v_mfma_f32_16x16x32_bf16 v[22:25], v[214:217], v[176:179], 0
	v_mfma_f32_16x16x32_bf16 v[18:21], v[234:237], v[176:179], 0
	v_mfma_f32_16x16x32_bf16 v[14:17], v[214:217], v[198:201], 0
	v_mfma_f32_16x16x32_bf16 v[10:13], v[234:237], v[198:201], 0
	v_mfma_f32_16x16x32_bf16 v[6:9], v[214:217], v[206:209], 0
	v_mfma_f32_16x16x32_bf16 v[2:5], v[234:237], v[206:209], 0
	v_mfma_f32_16x16x32_bf16 v[30:33], v[218:221], v[172:175], v[30:33]
	v_mfma_f32_16x16x32_bf16 v[26:29], v[238:241], v[172:175], v[26:29]
	v_mfma_f32_16x16x32_bf16 v[22:25], v[218:221], v[194:197], v[22:25]
	v_mfma_f32_16x16x32_bf16 v[18:21], v[238:241], v[194:197], v[18:21]
	v_mfma_f32_16x16x32_bf16 v[14:17], v[218:221], v[202:205], v[14:17]
	v_mfma_f32_16x16x32_bf16 v[10:13], v[238:241], v[202:205], v[10:13]
	v_mfma_f32_16x16x32_bf16 v[6:9], v[218:221], v[210:213], v[6:9]
	v_mfma_f32_16x16x32_bf16 v[2:5], v[238:241], v[210:213], v[2:5]
	s_barrier
	ds_read_b128 v[152:155], v186
	ds_read_b128 v[156:159], v186 offset:1024
	ds_read_b128 v[160:163], v186 offset:2048
	ds_read_b128 v[164:167], v186 offset:3072
	ds_read_b128 v[168:171], v147 offset:32768
	ds_read_b128 v[172:175], v147 offset:33792
	ds_read_b128 v[176:179], v147 offset:34816
	ds_read_b128 v[194:197], v147 offset:35840
	ds_read_b128 v[198:201], v147 offset:36864
	ds_read_b128 v[202:205], v147 offset:37888
	ds_read_b128 v[206:209], v147 offset:38912
	ds_read_b128 v[210:213], v147 offset:39936
	s_mov_b32 m0, s30
	s_add_u32 s98, s40, s68
	s_addc_u32 s99, s41, s69
	global_load_lds_dwordx4 v135, s[98:99]
	s_mov_b32 m0, s31
	s_add_u32 s98, s40, s70
	s_addc_u32 s99, s41, s71
	global_load_lds_dwordx4 v135, s[98:99]
	s_waitcnt lgkmcnt(8)
	s_waitcnt vmcnt(10)
	s_barrier
; #define LDA(dst, b, h) for (int m = 0; m < 4; ++m) for (int k = 0; k < 2; ++k) \
;     dst[m][k] = *reinterpret_cast<const bf16x8*>((char*)SA(b, h) + a_thr + (m * 2 + k) * 1024)
; #define LDB(dst, b, h) for (int n = 0; n < 2; ++n) for (int k = 0; k < 2; ++k) \
;     dst[n][k] = *reinterpret_cast<const bf16x8*>((char*)SB(b, h) + b_thr + (n * 2 + k) * 1024)
; #define MMA(ai, bj, At, Btf) do { __builtin_amdgcn_s_setprio(1); \
;     for (int m = 0; m < 4; ++m) for (int n = 0; n < 2; ++n) for (int k = 0; k < 2; ++k) \
;       acc[ai][bj][m][n] = __builtin_amdgcn_mfma_f32_16x16x32_bf16(Btf[n][k], At[m][k], acc[ai][bj][m][n], 0, 0, 0); \
;     __builtin_amdgcn_s_setprio(0); } while (0)
; #define WAIT_V(n) asm volatile("s_waitcnt vmcnt(" #n ")" ::: "memory")
; #define WAIT_L(n) asm volatile("s_waitcnt lgkmcnt(" #n ")" ::: "memory")
; #define BAR __builtin_amdgcn_s_barrier()
; #define SCHED __builtin_amdgcn_sched_barrier(0)
; template <bool OVL, bool PANEL = false, class Epi>
; __device__ __forceinline__ void gemm_phase(const bf16_t* __restrict__ A, long lda, const bf16_t* __restrict__ Bt, long ldb, int nM, int nN, int K,
;                                            const Epi& epi, bf16_t* shm, int w0) {
;     ...
;       WAIT_L(8); BAR; WAIT_L(0); MMA(0, 0, At, B0); BAR; SCHED;
;       LDB(B1, 1, 1); STAGE(SB(1, 0), Bt, ldb, boff, bcol, t + 3);
;       BAR; WAIT_L(0); MMA(0, 1, At, B1); BAR;
;       LDA(At, 1, 1); STAGE(SA(1, 0), A, lda, aoff, brow, t + 3);
;       BAR; WAIT_L(0); MMA(1, 0, At, B0); BAR; SCHED;
;       STAGE(SB(1, 1), Bt, ldb, boff, bcol + HALF, t + 3);
;       WAIT_V(6); BAR; MMA(1, 1, At, B1); BAR;
	s_waitcnt lgkmcnt(0)
	v_mfma_f32_16x16x32_bf16 v[126:129], v[152:155], v[168:171], v[126:129]
	v_mfma_f32_16x16x32_bf16 v[122:125], v[160:163], v[168:171], v[122:125]
	v_mfma_f32_16x16x32_bf16 v[118:121], v[152:155], v[176:179], v[118:121]
	v_mfma_f32_16x16x32_bf16 v[114:117], v[160:163], v[176:179], v[114:117]
	v_mfma_f32_16x16x32_bf16 v[110:113], v[152:155], v[198:201], v[110:113]
	v_mfma_f32_16x16x32_bf16 v[106:109], v[160:163], v[198:201], v[106:109]
	v_mfma_f32_16x16x32_bf16 v[102:105], v[152:155], v[206:209], v[102:105]
	v_mfma_f32_16x16x32_bf16 v[98:101], v[160:163], v[206:209], v[98:101]
	v_mfma_f32_16x16x32_bf16 v[126:129], v[156:159], v[172:175], v[126:129]
	v_mfma_f32_16x16x32_bf16 v[122:125], v[164:167], v[172:175], v[122:125]
	v_mfma_f32_16x16x32_bf16 v[118:121], v[156:159], v[194:197], v[118:121]
	v_mfma_f32_16x16x32_bf16 v[114:117], v[164:167], v[194:197], v[114:117]
	v_mfma_f32_16x16x32_bf16 v[110:113], v[156:159], v[202:205], v[110:113]
	v_mfma_f32_16x16x32_bf16 v[106:109], v[164:167], v[202:205], v[106:109]
	v_mfma_f32_16x16x32_bf16 v[102:105], v[156:159], v[210:213], v[102:105]
	v_mfma_f32_16x16x32_bf16 v[98:101], v[164:167], v[210:213], v[98:101]
	s_barrier
	ds_read_b128 v[214:217], v187
	ds_read_b128 v[218:221], v187 offset:1024
	ds_read_b128 v[234:237], v187 offset:2048
	ds_read_b128 v[238:241], v187 offset:3072
	s_mov_b32 m0, s32
	s_add_u32 s98, s42, s94
	s_addc_u32 s99, s43, s95
	global_load_lds_dwordx4 v135, s[98:99]
	s_mov_b32 m0, s44
	s_add_u32 s98, s42, s72
	s_addc_u32 s99, s43, s73
	global_load_lds_dwordx4 v135, s[98:99]
	s_waitcnt vmcnt(10)
	s_barrier
	s_waitcnt lgkmcnt(0)
	v_mfma_f32_16x16x32_bf16 v[94:97], v[214:217], v[168:171], v[94:97]
	v_mfma_f32_16x16x32_bf16 v[90:93], v[234:237], v[168:171], v[90:93]
	v_mfma_f32_16x16x32_bf16 v[86:89], v[214:217], v[176:179], v[86:89]
	v_mfma_f32_16x16x32_bf16 v[82:85], v[234:237], v[176:179], v[82:85]
	v_mfma_f32_16x16x32_bf16 v[78:81], v[214:217], v[198:201], v[78:81]
	v_mfma_f32_16x16x32_bf16 v[74:77], v[234:237], v[198:201], v[74:77]
	v_mfma_f32_16x16x32_bf16 v[70:73], v[214:217], v[206:209], v[70:73]
	v_mfma_f32_16x16x32_bf16 v[66:69], v[234:237], v[206:209], v[66:69]
	v_mfma_f32_16x16x32_bf16 v[94:97], v[218:221], v[172:175], v[94:97]
	v_mfma_f32_16x16x32_bf16 v[90:93], v[238:241], v[172:175], v[90:93]
	v_mfma_f32_16x16x32_bf16 v[86:89], v[218:221], v[194:197], v[86:89]
	v_mfma_f32_16x16x32_bf16 v[82:85], v[238:241], v[194:197], v[82:85]
	v_mfma_f32_16x16x32_bf16 v[78:81], v[218:221], v[202:205], v[78:81]
	v_mfma_f32_16x16x32_bf16 v[74:77], v[238:241], v[202:205], v[74:77]
	v_mfma_f32_16x16x32_bf16 v[70:73], v[218:221], v[210:213], v[70:73]
	v_mfma_f32_16x16x32_bf16 v[66:69], v[238:241], v[210:213], v[66:69]
	s_barrier
	ds_read_b128 v[168:171], v147 offset:49152
	ds_read_b128 v[172:175], v147 offset:50176
	ds_read_b128 v[176:179], v147 offset:51200
	ds_read_b128 v[194:197], v147 offset:52224
	ds_read_b128 v[198:201], v147 offset:53248
	ds_read_b128 v[202:205], v147 offset:54272
	ds_read_b128 v[206:209], v147 offset:55296
	ds_read_b128 v[210:213], v147 offset:56320
	s_mov_b32 m0, s45
	s_add_u32 s98, s40, s94
	s_addc_u32 s99, s41, s95
	global_load_lds_dwordx4 v135, s[98:99]
	s_mov_b32 m0, s46
	s_add_u32 s98, s40, s72
	s_addc_u32 s99, s41, s73
	global_load_lds_dwordx4 v135, s[98:99]
	s_barrier
	s_waitcnt lgkmcnt(0)
	v_mfma_f32_16x16x32_bf16 v[62:65], v[152:155], v[168:171], v[62:65]
	v_mfma_f32_16x16x32_bf16 v[58:61], v[160:163], v[168:171], v[58:61]
	v_mfma_f32_16x16x32_bf16 v[54:57], v[152:155], v[176:179], v[54:57]
	v_mfma_f32_16x16x32_bf16 v[50:53], v[160:163], v[176:179], v[50:53]
	v_mfma_f32_16x16x32_bf16 v[46:49], v[152:155], v[198:201], v[46:49]
	v_mfma_f32_16x16x32_bf16 v[42:45], v[160:163], v[198:201], v[42:45]
	v_mfma_f32_16x16x32_bf16 v[38:41], v[152:155], v[206:209], v[38:41]
	v_mfma_f32_16x16x32_bf16 v[34:37], v[160:163], v[206:209], v[34:37]
	v_mfma_f32_16x16x32_bf16 v[62:65], v[156:159], v[172:175], v[62:65]
	v_mfma_f32_16x16x32_bf16 v[58:61], v[164:167], v[172:175], v[58:61]
	v_mfma_f32_16x16x32_bf16 v[54:57], v[156:159], v[194:197], v[54:57]
	v_mfma_f32_16x16x32_bf16 v[50:53], v[164:167], v[194:197], v[50:53]
	v_mfma_f32_16x16x32_bf16 v[46:49], v[156:159], v[202:205], v[46:49]
	v_mfma_f32_16x16x32_bf16 v[42:45], v[164:167], v[202:205], v[42:45]
	v_mfma_f32_16x16x32_bf16 v[38:41], v[156:159], v[210:213], v[38:41]
	v_mfma_f32_16x16x32_bf16 v[34:37], v[164:167], v[210:213], v[34:37]
	s_barrier
	s_mov_b32 m0, s47
	s_add_u32 s98, s42, s18
	s_addc_u32 s99, s43, s19
	global_load_lds_dwordx4 v135, s[98:99]
	s_mov_b32 m0, s48
	s_add_u32 s98, s42, s20
	s_addc_u32 s99, s43, s21
	global_load_lds_dwordx4 v135, s[98:99]
	s_add_i32 s1, s1, 2
	s_add_u32 s14, s14, 0x100
	s_addc_u32 s15, s15, 0
	s_cmp_lt_u32 s1, 12
	s_waitcnt vmcnt(10)
	s_barrier
	v_mfma_f32_16x16x32_bf16 v[30:33], v[214:217], v[168:171], v[30:33]
	v_mfma_f32_16x16x32_bf16 v[26:29], v[234:237], v[168:171], v[26:29]
	v_mfma_f32_16x16x32_bf16 v[22:25], v[214:217], v[176:179], v[22:25]
	v_mfma_f32_16x16x32_bf16 v[18:21], v[234:237], v[176:179], v[18:21]
	v_mfma_f32_16x16x32_bf16 v[14:17], v[214:217], v[198:201], v[14:17]
	v_mfma_f32_16x16x32_bf16 v[10:13], v[234:237], v[198:201], v[10:13]
	v_mfma_f32_16x16x32_bf16 v[6:9], v[214:217], v[206:209], v[6:9]
	v_mfma_f32_16x16x32_bf16 v[2:5], v[234:237], v[206:209], v[2:5]
	v_mfma_f32_16x16x32_bf16 v[30:33], v[218:221], v[172:175], v[30:33]
	v_mfma_f32_16x16x32_bf16 v[26:29], v[238:241], v[172:175], v[26:29]
	v_mfma_f32_16x16x32_bf16 v[22:25], v[218:221], v[194:197], v[22:25]
	v_mfma_f32_16x16x32_bf16 v[18:21], v[238:241], v[194:197], v[18:21]
	v_mfma_f32_16x16x32_bf16 v[14:17], v[218:221], v[202:205], v[14:17]
	v_mfma_f32_16x16x32_bf16 v[10:13], v[238:241], v[202:205], v[10:13]
	v_mfma_f32_16x16x32_bf16 v[6:9], v[218:221], v[210:213], v[6:9]
	v_mfma_f32_16x16x32_bf16 v[2:5], v[238:241], v[210:213], v[2:5]
	s_barrier
; #define LDA(dst, b, h) for (int m = 0; m < 4; ++m) for (int k = 0; k < 2; ++k) \
;     dst[m][k] = *reinterpret_cast<const bf16x8*>((char*)SA(b, h) + a_thr + (m * 2 + k) * 1024)
; #define LDB(dst, b, h) for (int n = 0; n < 2; ++n) for (int k = 0; k < 2; ++k) \
;     dst[n][k] = *reinterpret_cast<const bf16x8*>((char*)SB(b, h) + b_thr + (n * 2 + k) * 1024)
; #define MMA(ai, bj, At, Btf) do { __builtin_amdgcn_s_setprio(1); \
;     for (int m = 0; m < 4; ++m) for (int n = 0; n < 2; ++n) for (int k = 0; k < 2; ++k) \
;       acc[ai][bj][m][n] = __builtin_amdgcn_mfma_f32_16x16x32_bf16(Btf[n][k], At[m][k], acc[ai][bj][m][n], 0, 0, 0); \
;     __builtin_amdgcn_s_setprio(0); } while (0)
; #define WAIT_V(n) asm volatile("s_waitcnt vmcnt(" #n ")" ::: "memory")
; #define WAIT_L(n) asm volatile("s_waitcnt lgkmcnt(" #n ")" ::: "memory")
; #define BAR __builtin_amdgcn_s_barrier()
; #define SCHED __builtin_amdgcn_sched_barrier(0)
; template <bool OVL, bool PANEL = false, class Epi>
; __device__ __forceinline__ void gemm_phase(const bf16_t* __restrict__ A, long lda, const bf16_t* __restrict__ Bt, long ldb, int nM, int nN, int K,
;                                            const Epi& epi, bf16_t* shm, int w0) {
;     ...
;       LDB(B0, 0, 0); SCHED; LDA(At, 0, 0); STAGE(SA(1, 1), A, lda, aoff, brow + HALF, t + 1);
;       WAIT_L(8); BAR; WAIT_L(0); MMA(0, 0, At, B0); BAR; SCHED;
;       LDB(B1, 0, 1); STAGE(SB(0, 0), Bt, ldb, boff, bcol, t + 2);
;       BAR; WAIT_L(0); MMA(0, 1, At, B1); BAR;
;       LDA(At, 0, 1); STAGE(SA(0, 0), A, lda, aoff, brow, t + 2);
;       BAR; WAIT_L(0); MMA(1, 0, At, B0); BAR; SCHED;
;       STAGE(SB(0, 1), Bt, ldb, boff, bcol + HALF, t + 2);
;       WAIT_V(6); BAR; MMA(1, 1, At, B1); BAR;
.LBB0_1053:
	ds_read_b128 v[152:155], v184
	ds_read_b128 v[156:159], v184 offset:1024
	ds_read_b128 v[160:163], v184 offset:2048
	ds_read_b128 v[164:167], v184 offset:3072
	s_add_u32 s40, s10, s14
	s_addc_u32 s41, s11, s15
	ds_read_b128 v[168:171], v147
	ds_read_b128 v[172:175], v147 offset:1024
	ds_read_b128 v[176:179], v147 offset:2048
	ds_read_b128 v[194:197], v147 offset:3072
	ds_read_b128 v[198:201], v147 offset:4096
	ds_read_b128 v[202:205], v147 offset:5120
	ds_read_b128 v[206:209], v147 offset:6144
	ds_read_b128 v[210:213], v147 offset:7168
	s_mov_b32 m0, s22
	s_add_u32 s98, s40, s16
	s_addc_u32 s99, s41, s17
	global_load_lds_dwordx4 v135, s[98:99]
	s_mov_b32 m0, s23
	s_add_u32 s98, s40, s36
	s_addc_u32 s99, s41, s37
	global_load_lds_dwordx4 v135, s[98:99]
	s_waitcnt lgkmcnt(8)
	s_waitcnt vmcnt(10)
	s_barrier
	s_waitcnt lgkmcnt(0)
	v_mfma_f32_16x16x32_bf16 v[126:129], v[152:155], v[168:171], v[126:129]
	v_mfma_f32_16x16x32_bf16 v[122:125], v[160:163], v[168:171], v[122:125]
	v_mfma_f32_16x16x32_bf16 v[118:121], v[152:155], v[176:179], v[118:121]
	v_mfma_f32_16x16x32_bf16 v[114:117], v[160:163], v[176:179], v[114:117]
	v_mfma_f32_16x16x32_bf16 v[110:113], v[152:155], v[198:201], v[110:113]
	v_mfma_f32_16x16x32_bf16 v[106:109], v[160:163], v[198:201], v[106:109]
	v_mfma_f32_16x16x32_bf16 v[102:105], v[152:155], v[206:209], v[102:105]
	v_mfma_f32_16x16x32_bf16 v[98:101], v[160:163], v[206:209], v[98:101]
	v_mfma_f32_16x16x32_bf16 v[126:129], v[156:159], v[172:175], v[126:129]
	v_mfma_f32_16x16x32_bf16 v[122:125], v[164:167], v[172:175], v[122:125]
	v_mfma_f32_16x16x32_bf16 v[118:121], v[156:159], v[194:197], v[118:121]
	v_mfma_f32_16x16x32_bf16 v[114:117], v[164:167], v[194:197], v[114:117]
	v_mfma_f32_16x16x32_bf16 v[110:113], v[156:159], v[202:205], v[110:113]
	v_mfma_f32_16x16x32_bf16 v[106:109], v[164:167], v[202:205], v[106:109]
	v_mfma_f32_16x16x32_bf16 v[102:105], v[156:159], v[210:213], v[102:105]
	v_mfma_f32_16x16x32_bf16 v[98:101], v[164:167], v[210:213], v[98:101]
	s_barrier
	s_add_u32 s42, s8, s14
	ds_read_b128 v[214:217], v185
	ds_read_b128 v[218:221], v185 offset:1024
	ds_read_b128 v[234:237], v185 offset:2048
	ds_read_b128 v[238:241], v185 offset:3072
	s_addc_u32 s43, s9, s15
	s_mov_b32 m0, s24
	s_add_u32 s98, s42, s34
	s_addc_u32 s99, s43, s35
	global_load_lds_dwordx4 v135, s[98:99]
	s_mov_b32 m0, s25
	s_add_u32 s98, s42, s64
	s_addc_u32 s99, s43, s65
	global_load_lds_dwordx4 v135, s[98:99]
	s_waitcnt vmcnt(10)
	s_barrier
	s_waitcnt lgkmcnt(0)
	v_mfma_f32_16x16x32_bf16 v[94:97], v[214:217], v[168:171], v[94:97]
	v_mfma_f32_16x16x32_bf16 v[90:93], v[234:237], v[168:171], v[90:93]
	v_mfma_f32_16x16x32_bf16 v[86:89], v[214:217], v[176:179], v[86:89]
	v_mfma_f32_16x16x32_bf16 v[82:85], v[234:237], v[176:179], v[82:85]
	v_mfma_f32_16x16x32_bf16 v[78:81], v[214:217], v[198:201], v[78:81]
	v_mfma_f32_16x16x32_bf16 v[74:77], v[234:237], v[198:201], v[74:77]
	v_mfma_f32_16x16x32_bf16 v[70:73], v[214:217], v[206:209], v[70:73]
	v_mfma_f32_16x16x32_bf16 v[66:69], v[234:237], v[206:209], v[66:69]
	v_mfma_f32_16x16x32_bf16 v[94:97], v[218:221], v[172:175], v[94:97]
	v_mfma_f32_16x16x32_bf16 v[90:93], v[238:241], v[172:175], v[90:93]
	v_mfma_f32_16x16x32_bf16 v[86:89], v[218:221], v[194:197], v[86:89]
	v_mfma_f32_16x16x32_bf16 v[82:85], v[238:241], v[194:197], v[82:85]
	v_mfma_f32_16x16x32_bf16 v[78:81], v[218:221], v[202:205], v[78:81]
	v_mfma_f32_16x16x32_bf16 v[74:77], v[238:241], v[202:205], v[74:77]
	v_mfma_f32_16x16x32_bf16 v[70:73], v[218:221], v[210:213], v[70:73]
	v_mfma_f32_16x16x32_bf16 v[66:69], v[238:241], v[210:213], v[66:69]
	s_barrier
	ds_read_b128 v[168:171], v147 offset:16384
	ds_read_b128 v[172:175], v147 offset:17408
	ds_read_b128 v[176:179], v147 offset:18432
	ds_read_b128 v[194:197], v147 offset:19456
	ds_read_b128 v[198:201], v147 offset:20480
	ds_read_b128 v[202:205], v147 offset:21504
	ds_read_b128 v[206:209], v147 offset:22528
	ds_read_b128 v[210:213], v147 offset:23552
	s_mov_b32 m0, s26
	s_add_u32 s98, s40, s34
	s_addc_u32 s99, s41, s35
	global_load_lds_dwordx4 v135, s[98:99]
	s_mov_b32 m0, s27
	s_add_u32 s98, s40, s64
	s_addc_u32 s99, s41, s65
	global_load_lds_dwordx4 v135, s[98:99]
	s_barrier
	s_waitcnt lgkmcnt(0)
	v_mfma_f32_16x16x32_bf16 v[62:65], v[152:155], v[168:171], v[62:65]
	v_mfma_f32_16x16x32_bf16 v[58:61], v[160:163], v[168:171], v[58:61]
	v_mfma_f32_16x16x32_bf16 v[54:57], v[152:155], v[176:179], v[54:57]
	v_mfma_f32_16x16x32_bf16 v[50:53], v[160:163], v[176:179], v[50:53]
	v_mfma_f32_16x16x32_bf16 v[46:49], v[152:155], v[198:201], v[46:49]
	v_mfma_f32_16x16x32_bf16 v[42:45], v[160:163], v[198:201], v[42:45]
	v_mfma_f32_16x16x32_bf16 v[38:41], v[152:155], v[206:209], v[38:41]
	v_mfma_f32_16x16x32_bf16 v[34:37], v[160:163], v[206:209], v[34:37]
	v_mfma_f32_16x16x32_bf16 v[62:65], v[156:159], v[172:175], v[62:65]
	v_mfma_f32_16x16x32_bf16 v[58:61], v[164:167], v[172:175], v[58:61]
	v_mfma_f32_16x16x32_bf16 v[54:57], v[156:159], v[194:197], v[54:57]
	v_mfma_f32_16x16x32_bf16 v[50:53], v[164:167], v[194:197], v[50:53]
	v_mfma_f32_16x16x32_bf16 v[46:49], v[156:159], v[202:205], v[46:49]
	v_mfma_f32_16x16x32_bf16 v[42:45], v[164:167], v[202:205], v[42:45]
	v_mfma_f32_16x16x32_bf16 v[38:41], v[156:159], v[210:213], v[38:41]
	v_mfma_f32_16x16x32_bf16 v[34:37], v[164:167], v[210:213], v[34:37]
	s_barrier
	s_mov_b32 m0, s28
	s_add_u32 s98, s42, s68
	s_addc_u32 s99, s43, s69
	global_load_lds_dwordx4 v135, s[98:99]
	s_mov_b32 m0, s29
	s_add_u32 s98, s42, s70
	s_addc_u32 s99, s43, s71
	global_load_lds_dwordx4 v135, s[98:99]
	s_waitcnt vmcnt(10)
	s_barrier
; #define LDA(dst, b, h) for (int m = 0; m < 4; ++m) for (int k = 0; k < 2; ++k) \
;     dst[m][k] = *reinterpret_cast<const bf16x8*>((char*)SA(b, h) + a_thr + (m * 2 + k) * 1024)
; #define LDB(dst, b, h) for (int n = 0; n < 2; ++n) for (int k = 0; k < 2; ++k) \
;     dst[n][k] = *reinterpret_cast<const bf16x8*>((char*)SB(b, h) + b_thr + (n * 2 + k) * 1024)
; #define MMA(ai, bj, At, Btf) do { __builtin_amdgcn_s_setprio(1); \
;     for (int m = 0; m < 4; ++m) for (int n = 0; n < 2; ++n) for (int k = 0; k < 2; ++k) \
;       acc[ai][bj][m][n] = __builtin_amdgcn_mfma_f32_16x16x32_bf16(Btf[n][k], At[m][k], acc[ai][bj][m][n], 0, 0, 0); \
;     __builtin_amdgcn_s_setprio(0); } while (0)
; #define WAIT_V(n) asm volatile("s_waitcnt vmcnt(" #n ")" ::: "memory")
; #define WAIT_L(n) asm volatile("s_waitcnt lgkmcnt(" #n ")" ::: "memory")
; #define BAR __builtin_amdgcn_s_barrier()
; #define SCHED __builtin_amdgcn_sched_barrier(0)
; template <bool OVL, bool PANEL = false, class Epi>
; __device__ __forceinline__ void gemm_phase(const bf16_t* __restrict__ A, long lda, const bf16_t* __restrict__ Bt, long ldb, int nM, int nN, int K,
;                                            const Epi& epi, bf16_t* shm, int w0) {
;     ...
;       WAIT_V(6); BAR; MMA(1, 1, At, B1); BAR;
;       LDB(B0, 1, 0); SCHED; LDA(At, 1, 0); STAGE(SA(0, 1), A, lda, aoff, brow + HALF, t + 2);
;       WAIT_L(8); BAR; WAIT_L(0); MMA(0, 0, At, B0); BAR; SCHED;
;       LDB(B1, 1, 1); STAGE(SB(1, 0), Bt, ldb, boff, bcol, t + 3);
;       BAR; WAIT_L(0); MMA(0, 1, At, B1); BAR;
	v_mfma_f32_16x16x32_bf16 v[30:33], v[214:217], v[168:171], v[30:33]
	v_mfma_f32_16x16x32_bf16 v[26:29], v[234:237], v[168:171], v[26:29]
	v_mfma_f32_16x16x32_bf16 v[22:25], v[214:217], v[176:179], v[22:25]
	v_mfma_f32_16x16x32_bf16 v[18:21], v[234:237], v[176:179], v[18:21]
	v_mfma_f32_16x16x32_bf16 v[14:17], v[214:217], v[198:201], v[14:17]
	v_mfma_f32_16x16x32_bf16 v[10:13], v[234:237], v[198:201], v[10:13]
	v_mfma_f32_16x16x32_bf16 v[6:9], v[214:217], v[206:209], v[6:9]
	v_mfma_f32_16x16x32_bf16 v[2:5], v[234:237], v[206:209], v[2:5]
	v_mfma_f32_16x16x32_bf16 v[30:33], v[218:221], v[172:175], v[30:33]
	v_mfma_f32_16x16x32_bf16 v[26:29], v[238:241], v[172:175], v[26:29]
	v_mfma_f32_16x16x32_bf16 v[22:25], v[218:221], v[194:197], v[22:25]
	v_mfma_f32_16x16x32_bf16 v[18:21], v[238:241], v[194:197], v[18:21]
	v_mfma_f32_16x16x32_bf16 v[14:17], v[218:221], v[202:205], v[14:17]
	v_mfma_f32_16x16x32_bf16 v[10:13], v[238:241], v[202:205], v[10:13]
	v_mfma_f32_16x16x32_bf16 v[6:9], v[218:221], v[210:213], v[6:9]
	v_mfma_f32_16x16x32_bf16 v[2:5], v[238:241], v[210:213], v[2:5]
	s_barrier
	ds_read_b128 v[152:155], v186
	ds_read_b128 v[156:159], v186 offset:1024
	ds_read_b128 v[160:163], v186 offset:2048
	ds_read_b128 v[164:167], v186 offset:3072
	ds_read_b128 v[168:171], v147 offset:32768
	ds_read_b128 v[172:175], v147 offset:33792
	ds_read_b128 v[176:179], v147 offset:34816
	ds_read_b128 v[194:197], v147 offset:35840
	ds_read_b128 v[198:201], v147 offset:36864
	ds_read_b128 v[202:205], v147 offset:37888
	ds_read_b128 v[206:209], v147 offset:38912
	ds_read_b128 v[210:213], v147 offset:39936
	s_mov_b32 m0, s30
	s_add_u32 s98, s40, s68
	s_addc_u32 s99, s41, s69
	global_load_lds_dwordx4 v135, s[98:99]
	s_mov_b32 m0, s31
	s_add_u32 s98, s40, s70
	s_addc_u32 s99, s41, s71
	global_load_lds_dwordx4 v135, s[98:99]
	s_waitcnt lgkmcnt(8)
	s_waitcnt vmcnt(10)
	s_barrier
	s_waitcnt lgkmcnt(0)
	v_mfma_f32_16x16x32_bf16 v[126:129], v[152:155], v[168:171], v[126:129]
	v_mfma_f32_16x16x32_bf16 v[122:125], v[160:163], v[168:171], v[122:125]
	v_mfma_f32_16x16x32_bf16 v[118:121], v[152:155], v[176:179], v[118:121]
	v_mfma_f32_16x16x32_bf16 v[114:117], v[160:163], v[176:179], v[114:117]
	v_mfma_f32_16x16x32_bf16 v[110:113], v[152:155], v[198:201], v[110:113]
	v_mfma_f32_16x16x32_bf16 v[106:109], v[160:163], v[198:201], v[106:109]
	v_mfma_f32_16x16x32_bf16 v[102:105], v[152:155], v[206:209], v[102:105]
	v_mfma_f32_16x16x32_bf16 v[98:101], v[160:163], v[206:209], v[98:101]
	v_mfma_f32_16x16x32_bf16 v[126:129], v[156:159], v[172:175], v[126:129]
	v_mfma_f32_16x16x32_bf16 v[122:125], v[164:167], v[172:175], v[122:125]
	v_mfma_f32_16x16x32_bf16 v[118:121], v[156:159], v[194:197], v[118:121]
	v_mfma_f32_16x16x32_bf16 v[114:117], v[164:167], v[194:197], v[114:117]
	v_mfma_f32_16x16x32_bf16 v[110:113], v[156:159], v[202:205], v[110:113]
	v_mfma_f32_16x16x32_bf16 v[106:109], v[164:167], v[202:205], v[106:109]
	v_mfma_f32_16x16x32_bf16 v[102:105], v[156:159], v[210:213], v[102:105]
	v_mfma_f32_16x16x32_bf16 v[98:101], v[164:167], v[210:213], v[98:101]
	s_barrier
	ds_read_b128 v[214:217], v187
	ds_read_b128 v[218:221], v187 offset:1024
	ds_read_b128 v[234:237], v187 offset:2048
	ds_read_b128 v[238:241], v187 offset:3072
	s_mov_b32 m0, s32
	s_add_u32 s98, s42, s94
	s_addc_u32 s99, s43, s95
	global_load_lds_dwordx4 v135, s[98:99]
	s_mov_b32 m0, s44
	s_add_u32 s98, s42, s72
	s_addc_u32 s99, s43, s73
	global_load_lds_dwordx4 v135, s[98:99]
	s_waitcnt vmcnt(10)
	s_barrier
	s_waitcnt lgkmcnt(0)
	v_mfma_f32_16x16x32_bf16 v[94:97], v[214:217], v[168:171], v[94:97]
	v_mfma_f32_16x16x32_bf16 v[90:93], v[234:237], v[168:171], v[90:93]
	v_mfma_f32_16x16x32_bf16 v[86:89], v[214:217], v[176:179], v[86:89]
	v_mfma_f32_16x16x32_bf16 v[82:85], v[234:237], v[176:179], v[82:85]
	v_mfma_f32_16x16x32_bf16 v[78:81], v[214:217], v[198:201], v[78:81]
	v_mfma_f32_16x16x32_bf16 v[74:77], v[234:237], v[198:201], v[74:77]
	v_mfma_f32_16x16x32_bf16 v[70:73], v[214:217], v[206:209], v[70:73]
	v_mfma_f32_16x16x32_bf16 v[66:69], v[234:237], v[206:209], v[66:69]
	v_mfma_f32_16x16x32_bf16 v[94:97], v[218:221], v[172:175], v[94:97]
	v_mfma_f32_16x16x32_bf16 v[90:93], v[238:241], v[172:175], v[90:93]
	v_mfma_f32_16x16x32_bf16 v[86:89], v[218:221], v[194:197], v[86:89]
	v_mfma_f32_16x16x32_bf16 v[82:85], v[238:241], v[194:197], v[82:85]
	v_mfma_f32_16x16x32_bf16 v[78:81], v[218:221], v[202:205], v[78:81]
	v_mfma_f32_16x16x32_bf16 v[74:77], v[238:241], v[202:205], v[74:77]
	v_mfma_f32_16x16x32_bf16 v[70:73], v[218:221], v[210:213], v[70:73]
	v_mfma_f32_16x16x32_bf16 v[66:69], v[238:241], v[210:213], v[66:69]
	s_barrier
; #define LDA(dst, b, h) for (int m = 0; m < 4; ++m) for (int k = 0; k < 2; ++k) \
;     dst[m][k] = *reinterpret_cast<const bf16x8*>((char*)SA(b, h) + a_thr + (m * 2 + k) * 1024)
; #define LDB(dst, b, h) for (int n = 0; n < 2; ++n) for (int k = 0; k < 2; ++k) \
;     dst[n][k] = *reinterpret_cast<const bf16x8*>((char*)SB(b, h) + b_thr + (n * 2 + k) * 1024)
; #define MMA(ai, bj, At, Btf) do { __builtin_amdgcn_s_setprio(1); \
;     for (int m = 0; m < 4; ++m) for (int n = 0; n < 2; ++n) for (int k = 0; k < 2; ++k) \
;       acc[ai][bj][m][n] = __builtin_amdgcn_mfma_f32_16x16x32_bf16(Btf[n][k], At[m][k], acc[ai][bj][m][n], 0, 0, 0); \
;     __builtin_amdgcn_s_setprio(0); } while (0)
; #define WAIT_V(n) asm volatile("s_waitcnt vmcnt(" #n ")" ::: "memory")
; #define WAIT_L(n) asm volatile("s_waitcnt lgkmcnt(" #n ")" ::: "memory")
; #define BAR __builtin_amdgcn_s_barrier()
; #define SCHED __builtin_amdgcn_sched_barrier(0)
; template <bool OVL, bool PANEL = false, class Epi>
; __device__ __forceinline__ void gemm_phase(const bf16_t* __restrict__ A, long lda, const bf16_t* __restrict__ Bt, long ldb, int nM, int nN, int K,
;                                            const Epi& epi, bf16_t* shm, int w0) {
;     ...
;       LDA(At, 1, 1); STAGE(SA(1, 0), A, lda, aoff, brow, t + 3);
;       BAR; WAIT_L(0); MMA(1, 0, At, B0); BAR; SCHED;
;       STAGE(SB(1, 1), Bt, ldb, boff, bcol + HALF, t + 3);
;       WAIT_V(6); BAR; MMA(1, 1, At, B1); BAR;
;     }
;     { LDB(B0, 0, 0); LDA(At, 0, 0); STAGE(SA(1, 1), A, lda, aoff, brow + HALF, nt - 1);
;       BAR; WAIT_L(0); MMA(0, 0, At, B0); BAR;
	ds_read_b128 v[168:171], v147 offset:49152
	ds_read_b128 v[172:175], v147 offset:50176
	ds_read_b128 v[176:179], v147 offset:51200
	ds_read_b128 v[194:197], v147 offset:52224
	ds_read_b128 v[198:201], v147 offset:53248
	ds_read_b128 v[202:205], v147 offset:54272
	ds_read_b128 v[206:209], v147 offset:55296
	ds_read_b128 v[210:213], v147 offset:56320
	s_mov_b32 m0, s45
	s_add_u32 s98, s40, s94
	s_addc_u32 s99, s41, s95
	global_load_lds_dwordx4 v135, s[98:99]
	s_mov_b32 m0, s46
	s_add_u32 s98, s40, s72
	s_addc_u32 s99, s41, s73
	global_load_lds_dwordx4 v135, s[98:99]
	s_barrier
	s_waitcnt lgkmcnt(0)
	v_mfma_f32_16x16x32_bf16 v[62:65], v[152:155], v[168:171], v[62:65]
	v_mfma_f32_16x16x32_bf16 v[58:61], v[160:163], v[168:171], v[58:61]
	v_mfma_f32_16x16x32_bf16 v[54:57], v[152:155], v[176:179], v[54:57]
	v_mfma_f32_16x16x32_bf16 v[50:53], v[160:163], v[176:179], v[50:53]
	v_mfma_f32_16x16x32_bf16 v[46:49], v[152:155], v[198:201], v[46:49]
	v_mfma_f32_16x16x32_bf16 v[42:45], v[160:163], v[198:201], v[42:45]
	v_mfma_f32_16x16x32_bf16 v[38:41], v[152:155], v[206:209], v[38:41]
	v_mfma_f32_16x16x32_bf16 v[34:37], v[160:163], v[206:209], v[34:37]
	v_mfma_f32_16x16x32_bf16 v[62:65], v[156:159], v[172:175], v[62:65]
	v_mfma_f32_16x16x32_bf16 v[58:61], v[164:167], v[172:175], v[58:61]
	v_mfma_f32_16x16x32_bf16 v[54:57], v[156:159], v[194:197], v[54:57]
	v_mfma_f32_16x16x32_bf16 v[50:53], v[164:167], v[194:197], v[50:53]
	v_mfma_f32_16x16x32_bf16 v[46:49], v[156:159], v[202:205], v[46:49]
	v_mfma_f32_16x16x32_bf16 v[42:45], v[164:167], v[202:205], v[42:45]
	v_mfma_f32_16x16x32_bf16 v[38:41], v[156:159], v[210:213], v[38:41]
	v_mfma_f32_16x16x32_bf16 v[34:37], v[164:167], v[210:213], v[34:37]
	s_barrier
	s_mov_b32 m0, s47
	s_add_u32 s98, s42, s18
	s_addc_u32 s99, s43, s19
	global_load_lds_dwordx4 v135, s[98:99]
	s_mov_b32 m0, s48
	s_add_u32 s98, s42, s20
	s_addc_u32 s99, s43, s21
	global_load_lds_dwordx4 v135, s[98:99]
	s_add_i32 s1, s1, 2
	s_add_u32 s14, s14, 0x100
	s_addc_u32 s15, s15, 0
	s_cmp_lt_u32 s1, 12
	s_waitcnt vmcnt(10)
	s_barrier
	v_mfma_f32_16x16x32_bf16 v[30:33], v[214:217], v[168:171], v[30:33]
	v_mfma_f32_16x16x32_bf16 v[26:29], v[234:237], v[168:171], v[26:29]
	v_mfma_f32_16x16x32_bf16 v[22:25], v[214:217], v[176:179], v[22:25]
	v_mfma_f32_16x16x32_bf16 v[18:21], v[234:237], v[176:179], v[18:21]
	v_mfma_f32_16x16x32_bf16 v[14:17], v[214:217], v[198:201], v[14:17]
	v_mfma_f32_16x16x32_bf16 v[10:13], v[234:237], v[198:201], v[10:13]
	v_mfma_f32_16x16x32_bf16 v[6:9], v[214:217], v[206:209], v[6:9]
	v_mfma_f32_16x16x32_bf16 v[2:5], v[234:237], v[206:209], v[2:5]
	v_mfma_f32_16x16x32_bf16 v[30:33], v[218:221], v[172:175], v[30:33]
	v_mfma_f32_16x16x32_bf16 v[26:29], v[238:241], v[172:175], v[26:29]
	v_mfma_f32_16x16x32_bf16 v[22:25], v[218:221], v[194:197], v[22:25]
	v_mfma_f32_16x16x32_bf16 v[18:21], v[238:241], v[194:197], v[18:21]
	v_mfma_f32_16x16x32_bf16 v[14:17], v[218:221], v[202:205], v[14:17]
	v_mfma_f32_16x16x32_bf16 v[10:13], v[238:241], v[202:205], v[10:13]
	v_mfma_f32_16x16x32_bf16 v[6:9], v[218:221], v[210:213], v[6:9]
	v_mfma_f32_16x16x32_bf16 v[2:5], v[238:241], v[210:213], v[2:5]
	s_barrier
	s_cbranch_scc1 .LBB0_1053
	s_waitcnt vmcnt(6)
	s_or_b32 s8, s0, 0x80
	s_ashr_i32 s9, s8, 31
	v_readlane_b32 s40, v252, 20
	s_lshl_b64 s[8:9], s[8:9], 11
	v_readlane_b32 s46, v252, 26
	v_add_u32_e32 v182, 16, v144
	v_readlane_b32 s47, v252, 27
	s_add_u32 s8, s46, s8
	v_add_u32_e32 v0, 0x10000, v182
	s_addc_u32 s9, s47, s9
	ds_read_b128 v[130:133], v0
	ds_read_b128 v[152:155], v0 offset:1024
	ds_read_b128 v[156:159], v0 offset:2048
	ds_read_b128 v[160:163], v0 offset:3072
	ds_read_b128 v[164:167], v147
	ds_read_b128 v[168:171], v147 offset:1024
	ds_read_b128 v[172:175], v147 offset:2048
	ds_read_b128 v[176:179], v147 offset:3072
	ds_read_b128 v[194:197], v147 offset:4096
	ds_read_b128 v[198:201], v147 offset:5120
	ds_read_b128 v[202:205], v147 offset:6144
	ds_read_b128 v[206:209], v147 offset:7168
	v_mov_b32_e32 v0, v135
	v_readfirstlane_b32 s1, v150
	v_lshl_add_u64 v[148:149], s[8:9], 0, v[0:1]
	s_mov_b64 s[8:9], 0x780
	v_lshl_add_u64 v[180:181], v[148:149], 0, s[8:9]
	s_mov_b32 m0, s1
	s_mov_b64 s[8:9], 0x20780
	v_readfirstlane_b32 s1, v151
	global_load_lds_dwordx4 v[180:181], off
	v_lshl_add_u64 v[148:149], v[148:149], 0, s[8:9]
	s_mov_b32 m0, s1
	v_readlane_b32 s41, v252, 21
	global_load_lds_dwordx4 v[148:149], off
	s_barrier
	s_waitcnt lgkmcnt(0)
	v_readlane_b32 s42, v252, 22
	v_readlane_b32 s43, v252, 23
	v_readlane_b32 s44, v252, 24
	v_readlane_b32 s45, v252, 25
	v_readlane_b32 s48, v252, 28
	v_readlane_b32 s49, v252, 29
	v_readlane_b32 s50, v252, 30
	v_readlane_b32 s51, v252, 31
	v_readlane_b32 s52, v252, 32
	v_readlane_b32 s53, v252, 33
	v_readlane_b32 s54, v252, 34
	v_readlane_b32 s55, v252, 35

; #define MMA(ai, bj, At, Btf) do { __builtin_amdgcn_s_setprio(1); \
;     for (int m = 0; m < 4; ++m) for (int n = 0; n < 2; ++n) for (int k = 0; k < 2; ++k) \
;       acc[ai][bj][m][n] = __builtin_amdgcn_mfma_f32_16x16x32_bf16(Btf[n][k], At[m][k], acc[ai][bj][m][n], 0, 0, 0); \
;     __builtin_amdgcn_s_setprio(0); } while (0)
; #define WAIT_L(n) asm volatile("s_waitcnt lgkmcnt(" #n ")" ::: "memory")
; #define BAR __builtin_amdgcn_s_barrier()
; template <bool OVL, bool PANEL = false, class Epi>
; __device__ __forceinline__ void gemm_phase(const bf16_t* __restrict__ A, long lda, const bf16_t* __restrict__ Bt, long ldb, int nM, int nN, int K,
;                                            const Epi& epi, bf16_t* shm, int w0) {
;     ...
;       BAR; WAIT_L(0); MMA(0, 0, At, B0); BAR;
	s_waitcnt lgkmcnt(0)
	v_mfma_f32_16x16x32_bf16 v[126:129], v[130:133], v[164:167], v[126:129]
	v_mfma_f32_16x16x32_bf16 v[122:125], v[156:159], v[164:167], v[122:125]
	v_mfma_f32_16x16x32_bf16 v[118:121], v[130:133], v[172:175], v[118:121]
	v_mfma_f32_16x16x32_bf16 v[114:117], v[156:159], v[172:175], v[114:117]
	v_mfma_f32_16x16x32_bf16 v[110:113], v[130:133], v[194:197], v[110:113]
	v_mfma_f32_16x16x32_bf16 v[106:109], v[156:159], v[194:197], v[106:109]
	v_mfma_f32_16x16x32_bf16 v[102:105], v[130:133], v[202:205], v[102:105]
	v_mfma_f32_16x16x32_bf16 v[98:101], v[156:159], v[202:205], v[98:101]
	v_mfma_f32_16x16x32_bf16 v[126:129], v[152:155], v[168:171], v[126:129]
	v_mfma_f32_16x16x32_bf16 v[122:125], v[160:163], v[168:171], v[122:125]
	v_mfma_f32_16x16x32_bf16 v[118:121], v[152:155], v[176:179], v[118:121]
	v_mfma_f32_16x16x32_bf16 v[114:117], v[160:163], v[176:179], v[114:117]
	v_mfma_f32_16x16x32_bf16 v[110:113], v[152:155], v[198:201], v[110:113]
	v_mfma_f32_16x16x32_bf16 v[106:109], v[160:163], v[198:201], v[106:109]
	v_mfma_f32_16x16x32_bf16 v[102:105], v[152:155], v[206:209], v[102:105]
	v_mfma_f32_16x16x32_bf16 v[98:101], v[160:163], v[206:209], v[98:101]

; #define LDB(dst, b, h) for (int n = 0; n < 2; ++n) for (int k = 0; k < 2; ++k) \
;     dst[n][k] = *reinterpret_cast<const bf16x8*>((char*)SB(b, h) + b_thr + (n * 2 + k) * 1024)
; #define MMA(ai, bj, At, Btf) do { __builtin_amdgcn_s_setprio(1); \
;     for (int m = 0; m < 4; ++m) for (int n = 0; n < 2; ++n) for (int k = 0; k < 2; ++k) \
;       acc[ai][bj][m][n] = __builtin_amdgcn_mfma_f32_16x16x32_bf16(Btf[n][k], At[m][k], acc[ai][bj][m][n], 0, 0, 0); \
;     __builtin_amdgcn_s_setprio(0); } while (0)
; #define WAIT_L(n) asm volatile("s_waitcnt lgkmcnt(" #n ")" ::: "memory")
; #define BAR __builtin_amdgcn_s_barrier()
; template <bool OVL, bool PANEL = false, class Epi>
; __device__ __forceinline__ void gemm_phase(const bf16_t* __restrict__ A, long lda, const bf16_t* __restrict__ Bt, long ldb, int nM, int nN, int K,
;                                            const Epi& epi, bf16_t* shm, int w0) {
;     ...
;       LDB(B1, 0, 1); BAR; WAIT_L(0); MMA(0, 1, At, B1); BAR;
	v_add_u32_e32 v0, 0x14000, v182
	s_barrier
	ds_read_b128 v[148:151], v0
	ds_read_b128 v[210:213], v0 offset:1024
	ds_read_b128 v[214:217], v0 offset:2048
	ds_read_b128 v[218:221], v0 offset:3072
	s_barrier
	s_waitcnt lgkmcnt(0)

; #define LDB(dst, b, h) for (int n = 0; n < 2; ++n) for (int k = 0; k < 2; ++k) \
;     dst[n][k] = *reinterpret_cast<const bf16x8*>((char*)SB(b, h) + b_thr + (n * 2 + k) * 1024)
; #define MMA(ai, bj, At, Btf) do { __builtin_amdgcn_s_setprio(1); \
;     for (int m = 0; m < 4; ++m) for (int n = 0; n < 2; ++n) for (int k = 0; k < 2; ++k) \
;       acc[ai][bj][m][n] = __builtin_amdgcn_mfma_f32_16x16x32_bf16(Btf[n][k], At[m][k], acc[ai][bj][m][n], 0, 0, 0); \
;     __builtin_amdgcn_s_setprio(0); } while (0)
; #define WAIT_L(n) asm volatile("s_waitcnt lgkmcnt(" #n ")" ::: "memory")
; #define BAR __builtin_amdgcn_s_barrier()
; template <bool OVL, bool PANEL = false, class Epi>
; __device__ __forceinline__ void gemm_phase(const bf16_t* __restrict__ A, long lda, const bf16_t* __restrict__ Bt, long ldb, int nM, int nN, int K,
;                                            const Epi& epi, bf16_t* shm, int w0) {
;     ...
;       LDB(B1, 0, 1); BAR; WAIT_L(0); MMA(0, 1, At, B1); BAR;
	s_waitcnt lgkmcnt(0)
	v_mfma_f32_16x16x32_bf16 v[94:97], v[148:151], v[164:167], v[94:97]
	v_mfma_f32_16x16x32_bf16 v[90:93], v[214:217], v[164:167], v[90:93]
	v_mfma_f32_16x16x32_bf16 v[86:89], v[148:151], v[172:175], v[86:89]
	v_mfma_f32_16x16x32_bf16 v[82:85], v[214:217], v[172:175], v[82:85]
	v_mfma_f32_16x16x32_bf16 v[78:81], v[148:151], v[194:197], v[78:81]
	v_mfma_f32_16x16x32_bf16 v[74:77], v[214:217], v[194:197], v[74:77]
	v_mfma_f32_16x16x32_bf16 v[70:73], v[148:151], v[202:205], v[70:73]
	v_mfma_f32_16x16x32_bf16 v[66:69], v[214:217], v[202:205], v[66:69]
	v_mfma_f32_16x16x32_bf16 v[94:97], v[210:213], v[168:171], v[94:97]
	v_mfma_f32_16x16x32_bf16 v[90:93], v[218:221], v[168:171], v[90:93]
	v_mfma_f32_16x16x32_bf16 v[86:89], v[210:213], v[176:179], v[86:89]
	v_mfma_f32_16x16x32_bf16 v[82:85], v[218:221], v[176:179], v[82:85]
	v_mfma_f32_16x16x32_bf16 v[78:81], v[210:213], v[198:201], v[78:81]
	v_mfma_f32_16x16x32_bf16 v[74:77], v[218:221], v[198:201], v[74:77]
	v_mfma_f32_16x16x32_bf16 v[70:73], v[210:213], v[206:209], v[70:73]
	v_mfma_f32_16x16x32_bf16 v[66:69], v[218:221], v[206:209], v[66:69]

; #define LDA(dst, b, h) for (int m = 0; m < 4; ++m) for (int k = 0; k < 2; ++k) \
;     dst[m][k] = *reinterpret_cast<const bf16x8*>((char*)SA(b, h) + a_thr + (m * 2 + k) * 1024)
; #define MMA(ai, bj, At, Btf) do { __builtin_amdgcn_s_setprio(1); \
;     for (int m = 0; m < 4; ++m) for (int n = 0; n < 2; ++n) for (int k = 0; k < 2; ++k) \
;       acc[ai][bj][m][n] = __builtin_amdgcn_mfma_f32_16x16x32_bf16(Btf[n][k], At[m][k], acc[ai][bj][m][n], 0, 0, 0); \
;     __builtin_amdgcn_s_setprio(0); } while (0)
; #define WAIT_V(n) asm volatile("s_waitcnt vmcnt(" #n ")" ::: "memory")
; #define WAIT_L(n) asm volatile("s_waitcnt lgkmcnt(" #n ")" ::: "memory")
; #define BAR __builtin_amdgcn_s_barrier()
; template <bool OVL, bool PANEL = false, class Epi>
; __device__ __forceinline__ void gemm_phase(const bf16_t* __restrict__ A, long lda, const bf16_t* __restrict__ Bt, long ldb, int nM, int nN, int K,
;                                            const Epi& epi, bf16_t* shm, int w0) {
;     ...
;       LDA(At, 0, 1); WAIT_V(4); BAR; WAIT_L(0); MMA(1, 0, At, B0); MMA(1, 1, At, B1); BAR; }
	s_barrier
	ds_read_b128 v[164:167], v147 offset:16384
	ds_read_b128 v[168:171], v147 offset:17408
	ds_read_b128 v[172:175], v147 offset:18432
	ds_read_b128 v[176:179], v147 offset:19456
	ds_read_b128 v[194:197], v147 offset:20480
	ds_read_b128 v[198:201], v147 offset:21504
	ds_read_b128 v[202:205], v147 offset:22528
	ds_read_b128 v[206:209], v147 offset:23552
	s_waitcnt vmcnt(4)
	s_barrier
	s_waitcnt lgkmcnt(0)

; #define LDA(dst, b, h) for (int m = 0; m < 4; ++m) for (int k = 0; k < 2; ++k) \
;     dst[m][k] = *reinterpret_cast<const bf16x8*>((char*)SA(b, h) + a_thr + (m * 2 + k) * 1024)
; #define MMA(ai, bj, At, Btf) do { __builtin_amdgcn_s_setprio(1); \
;     for (int m = 0; m < 4; ++m) for (int n = 0; n < 2; ++n) for (int k = 0; k < 2; ++k) \
;       acc[ai][bj][m][n] = __builtin_amdgcn_mfma_f32_16x16x32_bf16(Btf[n][k], At[m][k], acc[ai][bj][m][n], 0, 0, 0); \
;     __builtin_amdgcn_s_setprio(0); } while (0)
; #define WAIT_V(n) asm volatile("s_waitcnt vmcnt(" #n ")" ::: "memory")
; #define WAIT_L(n) asm volatile("s_waitcnt lgkmcnt(" #n ")" ::: "memory")
; #define BAR __builtin_amdgcn_s_barrier()
; template <bool OVL, bool PANEL = false, class Epi>
; __device__ __forceinline__ void gemm_phase(const bf16_t* __restrict__ A, long lda, const bf16_t* __restrict__ Bt, long ldb, int nM, int nN, int K,
;                                            const Epi& epi, bf16_t* shm, int w0) {
;     ...
;       LDA(At, 0, 1); WAIT_V(4); BAR; WAIT_L(0); MMA(1, 0, At, B0); MMA(1, 1, At, B1); BAR; }
	s_waitcnt lgkmcnt(0)
	v_mfma_f32_16x16x32_bf16 v[62:65], v[130:133], v[164:167], v[62:65]
	v_mfma_f32_16x16x32_bf16 v[58:61], v[156:159], v[164:167], v[58:61]
	v_mfma_f32_16x16x32_bf16 v[54:57], v[130:133], v[172:175], v[54:57]
	v_mfma_f32_16x16x32_bf16 v[50:53], v[156:159], v[172:175], v[50:53]
	v_mfma_f32_16x16x32_bf16 v[46:49], v[130:133], v[194:197], v[46:49]
	v_mfma_f32_16x16x32_bf16 v[42:45], v[156:159], v[194:197], v[42:45]
	v_mfma_f32_16x16x32_bf16 v[38:41], v[130:133], v[202:205], v[38:41]
	v_mfma_f32_16x16x32_bf16 v[34:37], v[156:159], v[202:205], v[34:37]
	v_mfma_f32_16x16x32_bf16 v[62:65], v[152:155], v[168:171], v[62:65]
	v_mfma_f32_16x16x32_bf16 v[58:61], v[160:163], v[168:171], v[58:61]
	v_mfma_f32_16x16x32_bf16 v[54:57], v[152:155], v[176:179], v[54:57]
	v_mfma_f32_16x16x32_bf16 v[50:53], v[160:163], v[176:179], v[50:53]
	v_mfma_f32_16x16x32_bf16 v[46:49], v[152:155], v[198:201], v[46:49]
	v_mfma_f32_16x16x32_bf16 v[42:45], v[160:163], v[198:201], v[42:45]
	v_mfma_f32_16x16x32_bf16 v[38:41], v[152:155], v[206:209], v[38:41]
	v_mfma_f32_16x16x32_bf16 v[34:37], v[160:163], v[206:209], v[34:37]


; #define LDA(dst, b, h) for (int m = 0; m < 4; ++m) for (int k = 0; k < 2; ++k) \
;     dst[m][k] = *reinterpret_cast<const bf16x8*>((char*)SA(b, h) + a_thr + (m * 2 + k) * 1024)
; #define MMA(ai, bj, At, Btf) do { __builtin_amdgcn_s_setprio(1); \
;     for (int m = 0; m < 4; ++m) for (int n = 0; n < 2; ++n) for (int k = 0; k < 2; ++k) \
;       acc[ai][bj][m][n] = __builtin_amdgcn_mfma_f32_16x16x32_bf16(Btf[n][k], At[m][k], acc[ai][bj][m][n], 0, 0, 0); \
;     __builtin_amdgcn_s_setprio(0); } while (0)
; #define WAIT_V(n) asm volatile("s_waitcnt vmcnt(" #n ")" ::: "memory")
; #define WAIT_L(n) asm volatile("s_waitcnt lgkmcnt(" #n ")" ::: "memory")
; #define BAR __builtin_amdgcn_s_barrier()
; template <bool OVL, bool PANEL = false, class Epi>
; __device__ __forceinline__ void gemm_phase(const bf16_t* __restrict__ A, long lda, const bf16_t* __restrict__ Bt, long ldb, int nM, int nN, int K,
;                                            const Epi& epi, bf16_t* shm, int w0) {
;     ...
;       LDA(At, 0, 1); WAIT_V(4); BAR; WAIT_L(0); MMA(1, 0, At, B0); MMA(1, 1, At, B1); BAR; }
	v_mfma_f32_16x16x32_bf16 v[30:33], v[148:151], v[164:167], v[30:33]
	v_mfma_f32_16x16x32_bf16 v[26:29], v[214:217], v[164:167], v[26:29]
	v_mfma_f32_16x16x32_bf16 v[22:25], v[148:151], v[172:175], v[22:25]
	v_mfma_f32_16x16x32_bf16 v[18:21], v[214:217], v[172:175], v[18:21]
	v_mfma_f32_16x16x32_bf16 v[14:17], v[148:151], v[194:197], v[14:17]
	v_mfma_f32_16x16x32_bf16 v[10:13], v[214:217], v[194:197], v[10:13]
	v_mfma_f32_16x16x32_bf16 v[6:9], v[148:151], v[202:205], v[6:9]
	v_mfma_f32_16x16x32_bf16 v[2:5], v[214:217], v[202:205], v[2:5]
	v_mfma_f32_16x16x32_bf16 v[30:33], v[210:213], v[168:171], v[30:33]
	v_mfma_f32_16x16x32_bf16 v[26:29], v[218:221], v[168:171], v[26:29]
	v_mfma_f32_16x16x32_bf16 v[22:25], v[210:213], v[176:179], v[22:25]
	v_mfma_f32_16x16x32_bf16 v[18:21], v[218:221], v[176:179], v[18:21]
	v_mfma_f32_16x16x32_bf16 v[14:17], v[210:213], v[198:201], v[14:17]
	v_mfma_f32_16x16x32_bf16 v[10:13], v[218:221], v[198:201], v[10:13]
	v_mfma_f32_16x16x32_bf16 v[6:9], v[210:213], v[206:209], v[6:9]
	v_mfma_f32_16x16x32_bf16 v[2:5], v[218:221], v[206:209], v[2:5]

; #define LDA(dst, b, h) for (int m = 0; m < 4; ++m) for (int k = 0; k < 2; ++k) \
;     dst[m][k] = *reinterpret_cast<const bf16x8*>((char*)SA(b, h) + a_thr + (m * 2 + k) * 1024)
; #define LDB(dst, b, h) for (int n = 0; n < 2; ++n) for (int k = 0; k < 2; ++k) \
;     dst[n][k] = *reinterpret_cast<const bf16x8*>((char*)SB(b, h) + b_thr + (n * 2 + k) * 1024)
; #define MMA(ai, bj, At, Btf) do { __builtin_amdgcn_s_setprio(1); \
;     for (int m = 0; m < 4; ++m) for (int n = 0; n < 2; ++n) for (int k = 0; k < 2; ++k) \
;       acc[ai][bj][m][n] = __builtin_amdgcn_mfma_f32_16x16x32_bf16(Btf[n][k], At[m][k], acc[ai][bj][m][n], 0, 0, 0); \
;     __builtin_amdgcn_s_setprio(0); } while (0)
; #define WAIT_V(n) asm volatile("s_waitcnt vmcnt(" #n ")" ::: "memory")
; #define WAIT_L(n) asm volatile("s_waitcnt lgkmcnt(" #n ")" ::: "memory")
; #define BAR __builtin_amdgcn_s_barrier()
; template <bool OVL, bool PANEL = false, class Epi>
; __device__ __forceinline__ void gemm_phase(const bf16_t* __restrict__ A, long lda, const bf16_t* __restrict__ Bt, long ldb, int nM, int nN, int K,
;                                            const Epi& epi, bf16_t* shm, int w0) {
;     ...
;     { LDB(B0, 1, 0); LDA(At, 1, 0); WAIT_V(2); BAR; WAIT_L(0); MMA(0, 0, At, B0); BAR;
	v_add_u32_e32 v0, 0x18000, v182
	s_barrier
	ds_read_b128 v[130:133], v0
	ds_read_b128 v[148:151], v0 offset:1024
	ds_read_b128 v[152:155], v0 offset:2048
	ds_read_b128 v[156:159], v0 offset:3072
	ds_read_b128 v[160:163], v147 offset:32768
	ds_read_b128 v[164:167], v147 offset:33792
	ds_read_b128 v[168:171], v147 offset:34816
	ds_read_b128 v[172:175], v147 offset:35840
	ds_read_b128 v[176:179], v147 offset:36864
	ds_read_b128 v[194:197], v147 offset:37888
	ds_read_b128 v[198:201], v147 offset:38912
	ds_read_b128 v[202:205], v147 offset:39936
	s_waitcnt vmcnt(2)
	s_barrier
	s_waitcnt lgkmcnt(0)

; #define LDA(dst, b, h) for (int m = 0; m < 4; ++m) for (int k = 0; k < 2; ++k) \
;     dst[m][k] = *reinterpret_cast<const bf16x8*>((char*)SA(b, h) + a_thr + (m * 2 + k) * 1024)
; #define LDB(dst, b, h) for (int n = 0; n < 2; ++n) for (int k = 0; k < 2; ++k) \
;     dst[n][k] = *reinterpret_cast<const bf16x8*>((char*)SB(b, h) + b_thr + (n * 2 + k) * 1024)
; #define MMA(ai, bj, At, Btf) do { __builtin_amdgcn_s_setprio(1); \
;     for (int m = 0; m < 4; ++m) for (int n = 0; n < 2; ++n) for (int k = 0; k < 2; ++k) \
;       acc[ai][bj][m][n] = __builtin_amdgcn_mfma_f32_16x16x32_bf16(Btf[n][k], At[m][k], acc[ai][bj][m][n], 0, 0, 0); \
;     __builtin_amdgcn_s_setprio(0); } while (0)
; #define WAIT_V(n) asm volatile("s_waitcnt vmcnt(" #n ")" ::: "memory")
; #define WAIT_L(n) asm volatile("s_waitcnt lgkmcnt(" #n ")" ::: "memory")
; #define BAR __builtin_amdgcn_s_barrier()
; template <bool OVL, bool PANEL = false, class Epi>
; __device__ __forceinline__ void gemm_phase(const bf16_t* __restrict__ A, long lda, const bf16_t* __restrict__ Bt, long ldb, int nM, int nN, int K,
;                                            const Epi& epi, bf16_t* shm, int w0) {
;     ...
;     { LDB(B0, 1, 0); LDA(At, 1, 0); WAIT_V(2); BAR; WAIT_L(0); MMA(0, 0, At, B0); BAR;
	s_waitcnt lgkmcnt(0)
	v_mfma_f32_16x16x32_bf16 v[126:129], v[130:133], v[160:163], v[126:129]
	v_mfma_f32_16x16x32_bf16 v[122:125], v[152:155], v[160:163], v[122:125]
	v_mfma_f32_16x16x32_bf16 v[118:121], v[130:133], v[168:171], v[118:121]
	v_mfma_f32_16x16x32_bf16 v[114:117], v[152:155], v[168:171], v[114:117]
	v_mfma_f32_16x16x32_bf16 v[110:113], v[130:133], v[176:179], v[110:113]
	v_mfma_f32_16x16x32_bf16 v[106:109], v[152:155], v[176:179], v[106:109]
	v_mfma_f32_16x16x32_bf16 v[102:105], v[130:133], v[198:201], v[102:105]
	v_mfma_f32_16x16x32_bf16 v[98:101], v[152:155], v[198:201], v[98:101]
	v_mfma_f32_16x16x32_bf16 v[126:129], v[148:151], v[164:167], v[126:129]
	v_mfma_f32_16x16x32_bf16 v[122:125], v[156:159], v[164:167], v[122:125]
	v_mfma_f32_16x16x32_bf16 v[118:121], v[148:151], v[172:175], v[118:121]
	v_mfma_f32_16x16x32_bf16 v[114:117], v[156:159], v[172:175], v[114:117]
	v_mfma_f32_16x16x32_bf16 v[110:113], v[148:151], v[194:197], v[110:113]
	v_mfma_f32_16x16x32_bf16 v[106:109], v[156:159], v[194:197], v[106:109]
	v_mfma_f32_16x16x32_bf16 v[102:105], v[148:151], v[202:205], v[102:105]
	v_mfma_f32_16x16x32_bf16 v[98:101], v[156:159], v[202:205], v[98:101]

; #define LDB(dst, b, h) for (int n = 0; n < 2; ++n) for (int k = 0; k < 2; ++k) \
;     dst[n][k] = *reinterpret_cast<const bf16x8*>((char*)SB(b, h) + b_thr + (n * 2 + k) * 1024)
; #define MMA(ai, bj, At, Btf) do { __builtin_amdgcn_s_setprio(1); \
;     for (int m = 0; m < 4; ++m) for (int n = 0; n < 2; ++n) for (int k = 0; k < 2; ++k) \
;       acc[ai][bj][m][n] = __builtin_amdgcn_mfma_f32_16x16x32_bf16(Btf[n][k], At[m][k], acc[ai][bj][m][n], 0, 0, 0); \
;     __builtin_amdgcn_s_setprio(0); } while (0)
; #define WAIT_V(n) asm volatile("s_waitcnt vmcnt(" #n ")" ::: "memory")
; #define WAIT_L(n) asm volatile("s_waitcnt lgkmcnt(" #n ")" ::: "memory")
; #define BAR __builtin_amdgcn_s_barrier()
; template <bool OVL, bool PANEL = false, class Epi>
; __device__ __forceinline__ void gemm_phase(const bf16_t* __restrict__ A, long lda, const bf16_t* __restrict__ Bt, long ldb, int nM, int nN, int K,
;                                            const Epi& epi, bf16_t* shm, int w0) {
;     ...
;       LDB(B1, 1, 1); WAIT_V(0); BAR; WAIT_L(0); MMA(0, 1, At, B1); BAR;
	v_add_u32_e32 v0, 0x1c000, v182
	s_barrier
	ds_read_b128 v[206:209], v0
	ds_read_b128 v[210:213], v0 offset:1024
	ds_read_b128 v[214:217], v0 offset:2048
	ds_read_b128 v[218:221], v0 offset:3072
	s_waitcnt vmcnt(0)
	s_barrier
	s_waitcnt lgkmcnt(0)

; #define LDB(dst, b, h) for (int n = 0; n < 2; ++n) for (int k = 0; k < 2; ++k) \
;     dst[n][k] = *reinterpret_cast<const bf16x8*>((char*)SB(b, h) + b_thr + (n * 2 + k) * 1024)
; #define MMA(ai, bj, At, Btf) do { __builtin_amdgcn_s_setprio(1); \
;     for (int m = 0; m < 4; ++m) for (int n = 0; n < 2; ++n) for (int k = 0; k < 2; ++k) \
;       acc[ai][bj][m][n] = __builtin_amdgcn_mfma_f32_16x16x32_bf16(Btf[n][k], At[m][k], acc[ai][bj][m][n], 0, 0, 0); \
;     __builtin_amdgcn_s_setprio(0); } while (0)
; #define WAIT_V(n) asm volatile("s_waitcnt vmcnt(" #n ")" ::: "memory")
; #define WAIT_L(n) asm volatile("s_waitcnt lgkmcnt(" #n ")" ::: "memory")
; #define BAR __builtin_amdgcn_s_barrier()
; template <bool OVL, bool PANEL = false, class Epi>
; __device__ __forceinline__ void gemm_phase(const bf16_t* __restrict__ A, long lda, const bf16_t* __restrict__ Bt, long ldb, int nM, int nN, int K,
;                                            const Epi& epi, bf16_t* shm, int w0) {
;     ...
;       LDB(B1, 1, 1); WAIT_V(0); BAR; WAIT_L(0); MMA(0, 1, At, B1); BAR;
	s_waitcnt lgkmcnt(0)
	v_mfma_f32_16x16x32_bf16 v[94:97], v[206:209], v[160:163], v[94:97]
	v_mfma_f32_16x16x32_bf16 v[90:93], v[214:217], v[160:163], v[90:93]
	v_mfma_f32_16x16x32_bf16 v[86:89], v[206:209], v[168:171], v[86:89]
	v_mfma_f32_16x16x32_bf16 v[82:85], v[214:217], v[168:171], v[82:85]
	v_mfma_f32_16x16x32_bf16 v[78:81], v[206:209], v[176:179], v[78:81]
	v_mfma_f32_16x16x32_bf16 v[74:77], v[214:217], v[176:179], v[74:77]
	v_mfma_f32_16x16x32_bf16 v[70:73], v[206:209], v[198:201], v[70:73]
	v_mfma_f32_16x16x32_bf16 v[66:69], v[214:217], v[198:201], v[66:69]
	v_mfma_f32_16x16x32_bf16 v[94:97], v[210:213], v[164:167], v[94:97]
	v_mfma_f32_16x16x32_bf16 v[90:93], v[218:221], v[164:167], v[90:93]
	v_mfma_f32_16x16x32_bf16 v[86:89], v[210:213], v[172:175], v[86:89]
	v_mfma_f32_16x16x32_bf16 v[82:85], v[218:221], v[172:175], v[82:85]
	v_mfma_f32_16x16x32_bf16 v[78:81], v[210:213], v[194:197], v[78:81]
	v_mfma_f32_16x16x32_bf16 v[74:77], v[218:221], v[194:197], v[74:77]
	v_mfma_f32_16x16x32_bf16 v[70:73], v[210:213], v[202:205], v[70:73]
	v_mfma_f32_16x16x32_bf16 v[66:69], v[218:221], v[202:205], v[66:69]

; #define LDA(dst, b, h) for (int m = 0; m < 4; ++m) for (int k = 0; k < 2; ++k) \
;     dst[m][k] = *reinterpret_cast<const bf16x8*>((char*)SA(b, h) + a_thr + (m * 2 + k) * 1024)
; #define MMA(ai, bj, At, Btf) do { __builtin_amdgcn_s_setprio(1); \
;     for (int m = 0; m < 4; ++m) for (int n = 0; n < 2; ++n) for (int k = 0; k < 2; ++k) \
;       acc[ai][bj][m][n] = __builtin_amdgcn_mfma_f32_16x16x32_bf16(Btf[n][k], At[m][k], acc[ai][bj][m][n], 0, 0, 0); \
;     __builtin_amdgcn_s_setprio(0); } while (0)
; #define WAIT_L(n) asm volatile("s_waitcnt lgkmcnt(" #n ")" ::: "memory")
; #define BAR __builtin_amdgcn_s_barrier()
; template <bool OVL, bool PANEL = false, class Epi>
; __device__ __forceinline__ void gemm_phase(const bf16_t* __restrict__ A, long lda, const bf16_t* __restrict__ Bt, long ldb, int nM, int nN, int K,
;                                            const Epi& epi, bf16_t* shm, int w0) {
;     ...
;       LDA(At, 1, 1); BAR; WAIT_L(0); MMA(1, 0, At, B0); MMA(1, 1, At, B1); BAR; }
	s_barrier
	ds_read_b128 v[160:163], v147 offset:49152
	ds_read_b128 v[164:167], v147 offset:50176
	ds_read_b128 v[168:171], v147 offset:51200
	ds_read_b128 v[172:175], v147 offset:52224
	ds_read_b128 v[176:179], v147 offset:53248
	ds_read_b128 v[194:197], v147 offset:54272
	ds_read_b128 v[198:201], v147 offset:55296
	ds_read_b128 v[202:205], v147 offset:56320
	s_barrier
	s_waitcnt lgkmcnt(0)

; #define LDA(dst, b, h) for (int m = 0; m < 4; ++m) for (int k = 0; k < 2; ++k) \
;     dst[m][k] = *reinterpret_cast<const bf16x8*>((char*)SA(b, h) + a_thr + (m * 2 + k) * 1024)
; #define MMA(ai, bj, At, Btf) do { __builtin_amdgcn_s_setprio(1); \
;     for (int m = 0; m < 4; ++m) for (int n = 0; n < 2; ++n) for (int k = 0; k < 2; ++k) \
;       acc[ai][bj][m][n] = __builtin_amdgcn_mfma_f32_16x16x32_bf16(Btf[n][k], At[m][k], acc[ai][bj][m][n], 0, 0, 0); \
;     __builtin_amdgcn_s_setprio(0); } while (0)
; #define WAIT_L(n) asm volatile("s_waitcnt lgkmcnt(" #n ")" ::: "memory")
; #define BAR __builtin_amdgcn_s_barrier()
; template <bool OVL, bool PANEL = false, class Epi>
; __device__ __forceinline__ void gemm_phase(const bf16_t* __restrict__ A, long lda, const bf16_t* __restrict__ Bt, long ldb, int nM, int nN, int K,
;                                            const Epi& epi, bf16_t* shm, int w0) {
;     ...
;       LDA(At, 1, 1); BAR; WAIT_L(0); MMA(1, 0, At, B0); MMA(1, 1, At, B1); BAR; }
	s_waitcnt lgkmcnt(0)
	v_mfma_f32_16x16x32_bf16 v[62:65], v[130:133], v[160:163], v[62:65]
	v_mfma_f32_16x16x32_bf16 v[58:61], v[152:155], v[160:163], v[58:61]
	v_mfma_f32_16x16x32_bf16 v[54:57], v[130:133], v[168:171], v[54:57]
	v_mfma_f32_16x16x32_bf16 v[50:53], v[152:155], v[168:171], v[50:53]
	v_mfma_f32_16x16x32_bf16 v[46:49], v[130:133], v[176:179], v[46:49]
	v_mfma_f32_16x16x32_bf16 v[42:45], v[152:155], v[176:179], v[42:45]
	v_mfma_f32_16x16x32_bf16 v[38:41], v[130:133], v[198:201], v[38:41]
	v_mfma_f32_16x16x32_bf16 v[34:37], v[152:155], v[198:201], v[34:37]
	v_mfma_f32_16x16x32_bf16 v[62:65], v[148:151], v[164:167], v[62:65]
	v_mfma_f32_16x16x32_bf16 v[58:61], v[156:159], v[164:167], v[58:61]
	v_mfma_f32_16x16x32_bf16 v[54:57], v[148:151], v[172:175], v[54:57]
	v_mfma_f32_16x16x32_bf16 v[50:53], v[156:159], v[172:175], v[50:53]
	v_mfma_f32_16x16x32_bf16 v[46:49], v[148:151], v[194:197], v[46:49]
	v_mfma_f32_16x16x32_bf16 v[42:45], v[156:159], v[194:197], v[42:45]
	v_mfma_f32_16x16x32_bf16 v[38:41], v[148:151], v[202:205], v[38:41]
	v_mfma_f32_16x16x32_bf16 v[34:37], v[156:159], v[202:205], v[34:37]


; #define LDA(dst, b, h) for (int m = 0; m < 4; ++m) for (int k = 0; k < 2; ++k) \
;     dst[m][k] = *reinterpret_cast<const bf16x8*>((char*)SA(b, h) + a_thr + (m * 2 + k) * 1024)
; #define MMA(ai, bj, At, Btf) do { __builtin_amdgcn_s_setprio(1); \
;     for (int m = 0; m < 4; ++m) for (int n = 0; n < 2; ++n) for (int k = 0; k < 2; ++k) \
;       acc[ai][bj][m][n] = __builtin_amdgcn_mfma_f32_16x16x32_bf16(Btf[n][k], At[m][k], acc[ai][bj][m][n], 0, 0, 0); \
;     __builtin_amdgcn_s_setprio(0); } while (0)
; #define WAIT_L(n) asm volatile("s_waitcnt lgkmcnt(" #n ")" ::: "memory")
; #define BAR __builtin_amdgcn_s_barrier()
; template <bool OVL, bool PANEL = false, class Epi>
; __device__ __forceinline__ void gemm_phase(const bf16_t* __restrict__ A, long lda, const bf16_t* __restrict__ Bt, long ldb, int nM, int nN, int K,
;                                            const Epi& epi, bf16_t* shm, int w0) {
;     ...
;       LDA(At, 1, 1); BAR; WAIT_L(0); MMA(1, 0, At, B0); MMA(1, 1, At, B1); BAR; }
	v_mfma_f32_16x16x32_bf16 v[30:33], v[206:209], v[160:163], v[30:33]
	v_mfma_f32_16x16x32_bf16 v[26:29], v[214:217], v[160:163], v[26:29]
	v_mfma_f32_16x16x32_bf16 v[22:25], v[206:209], v[168:171], v[22:25]
	v_mfma_f32_16x16x32_bf16 v[18:21], v[214:217], v[168:171], v[18:21]
	v_mfma_f32_16x16x32_bf16 v[14:17], v[206:209], v[176:179], v[14:17]
	v_mfma_f32_16x16x32_bf16 v[10:13], v[214:217], v[176:179], v[10:13]
	v_mfma_f32_16x16x32_bf16 v[6:9], v[206:209], v[198:201], v[6:9]
	v_mfma_f32_16x16x32_bf16 v[2:5], v[214:217], v[198:201], v[2:5]
	v_mfma_f32_16x16x32_bf16 v[30:33], v[210:213], v[164:167], v[30:33]
	v_mfma_f32_16x16x32_bf16 v[26:29], v[218:221], v[164:167], v[26:29]
	v_mfma_f32_16x16x32_bf16 v[22:25], v[210:213], v[172:175], v[22:25]
	v_mfma_f32_16x16x32_bf16 v[18:21], v[218:221], v[172:175], v[18:21]
	v_mfma_f32_16x16x32_bf16 v[14:17], v[210:213], v[194:197], v[14:17]
	v_mfma_f32_16x16x32_bf16 v[10:13], v[218:221], v[194:197], v[10:13]
	v_mfma_f32_16x16x32_bf16 v[6:9], v[210:213], v[202:205], v[6:9]
	v_mfma_f32_16x16x32_bf16 v[2:5], v[218:221], v[202:205], v[2:5]

; #define LDA(dst, b, h) for (int m = 0; m < 4; ++m) for (int k = 0; k < 2; ++k) \
;     dst[m][k] = *reinterpret_cast<const bf16x8*>((char*)SA(b, h) + a_thr + (m * 2 + k) * 1024)
; #define MMA(ai, bj, At, Btf) do { __builtin_amdgcn_s_setprio(1); \
;     for (int m = 0; m < 4; ++m) for (int n = 0; n < 2; ++n) for (int k = 0; k < 2; ++k) \
;       acc[ai][bj][m][n] = __builtin_amdgcn_mfma_f32_16x16x32_bf16(Btf[n][k], At[m][k], acc[ai][bj][m][n], 0, 0, 0); \
;     __builtin_amdgcn_s_setprio(0); } while (0)
; #define WAIT_L(n) asm volatile("s_waitcnt lgkmcnt(" #n ")" ::: "memory")
; #define BAR __builtin_amdgcn_s_barrier()
; template <bool OVL, bool PANEL = false, class Epi>
; __device__ __forceinline__ void gemm_phase(const bf16_t* __restrict__ A, long lda, const bf16_t* __restrict__ Bt, long ldb, int nM, int nN, int K,
;                                            const Epi& epi, bf16_t* shm, int w0) {
;     ...
;       LDA(At, 1, 1); BAR; WAIT_L(0); MMA(1, 0, At, B0); MMA(1, 1, At, B1); BAR; }
;     if (wr == 0) BAR;
	s_barrier
	s_and_saveexec_b64 s[8:9], s[6:7]
	s_cbranch_execz .LBB0_1056
	s_barrier
